# fixed-hoist version + one static s_setprio 1 for waves 0-3 before each GEMM K-loop (reset after), measurement 1
# baseline (speedup 1.0000x reference)
; #define PG8_STAGE(bufoff, gbase, voff) do { _Pragma("unroll") for (int _i = 0; _i < 2; ++_i) \
;         __builtin_amdgcn_global_load_lds((const unsigned*)((const char*)(gbase) + (voff)[_i]), (LAS unsigned*)(lds + (bufoff) + ldsw + _i * 8192), 16, 0, 0); } while (0)
; #define PG8_LDA(dst, b, h) do { _Pragma("unroll") for (int m = 0; m < 4; ++m) _Pragma("unroll") for (int k = 0; k < 2; ++k) dst[m][k] = *(const LAS bf16x8*)(lds + PG8_SA(b, h) + aoff + m * 2048 + k * 1024); } while (0)
; #define PG8_LDB(dst, b, h) do { _Pragma("unroll") for (int n = 0; n < 2; ++n) _Pragma("unroll") for (int k = 0; k < 2; ++k) dst[n][k] = *(const LAS bf16x8*)(lds + PG8_SB(b, h) + boff + n * 2048 + k * 1024); } while (0)
; #define PG8_MMA(ai, bj, At, Bt) do { __builtin_amdgcn_s_setprio(1); _Pragma("unroll") for (int m = 0; m < 4; ++m) _Pragma("unroll") for (int n = 0; n < 2; ++n) _Pragma("unroll") for (int k = 0; k < 2; ++k) \
;         acc[ai][bj][m][n] = __builtin_amdgcn_mfma_f32_16x16x32_bf16(Bt[n][k], At[m][k], acc[ai][bj][m][n], 0, 0, 0); __builtin_amdgcn_s_setprio(0); } while (0)
; #define PG8_WAIT_L(n) asm volatile("s_waitcnt lgkmcnt(" #n ")" ::: "memory")
; #define PG8_BAR __builtin_amdgcn_s_barrier()
; template <class Epi>
; __device__ __forceinline__ void gemm_phase(LAS unsigned char* lds, const Gemm g, const StaticOrder& S, const Epi& E) {
;     ...
; #pragma unroll
;     for (int a = 0; a < 2; ++a)
; #pragma unroll
;         for (int b = 0; b < 2; ++b)
; #pragma unroll
;             for (int m = 0; m < 4; ++m)
; #pragma unroll
;                 for (int n = 0; n < 2; ++n) acc[a][b][m][n] = (f32x4){0.f, 0.f, 0.f, 0.f};
;     ...
;         const char* nA = has_next ? (const char*)g.A + (size_t)nxt.pm * tstepA + (size_t)(nxt.pn >> 2) * gstepA : cA; const char* nB = has_next ? (const char*)g.Bt + (size_t)nxt.pn * tstepB : cB;
;         for (int t = 0; t < nt; t += 2) {
;             const bool last = (t == nt - 2);
;             const char* a1 = cA + (size_t)(t + 1) * kstepA;
;             const char* a2 = last ? nA : cA + (size_t)(t + 2) * kstepA; const char* b2 = last ? nB : cB + (size_t)(t + 2) * kstep;
;             const char* a3 = a2 + kstepA; const char* b3 = b2 + kstep;
;             PG8_LDB(B0, 0, 0); PG8_SCHED; PG8_LDA(At, 0, 0); PG8_STAGE(PG8_SA(1, 1), a1 + hstepA, voffA);
;             PG8_WAIT_L(8); PG8_BAR; PG8_WAIT_L(0); PG8_MMA(0, 0, At, B0); PG8_BAR; PG8_SCHED;
.LBB0_157:
	s_ashr_i32 s23, s22, 31
	s_lshl_b64 s[24:25], s[22:23], 20
	s_add_u32 s26, s10, s24
	s_addc_u32 s27, s11, s25
	s_and_b64 s[24:25], s[40:41], exec
	s_cselect_b32 s23, s27, s39
	s_cselect_b32 s55, s26, s38
	s_ashr_i32 s21, s20, 31
	s_lshl_b64 s[24:25], s[20:21], 20
	s_add_u32 s36, s35, s24
	s_addc_u32 s37, s44, s25
	s_and_b64 s[24:25], s[40:41], exec
	s_cselect_b32 s21, s37, s5
	s_cselect_b32 s56, s36, s4
	s_add_u32 s57, s4, 0x100
	v_mov_b32_e32 v2, 0
	s_addc_u32 s58, s5, 0
	s_mov_b32 s59, -2
	v_mov_b32_e32 v3, v2
	v_mov_b32_e32 v4, v2
	v_mov_b32_e32 v5, v2
	v_mov_b32_e32 v6, v2
	v_mov_b32_e32 v7, v2
	v_mov_b32_e32 v8, v2
	v_mov_b32_e32 v9, v2
	v_mov_b32_e32 v18, v2
	v_mov_b32_e32 v19, v2
	v_mov_b32_e32 v20, v2
	v_mov_b32_e32 v21, v2
	v_mov_b32_e32 v22, v2
	v_mov_b32_e32 v23, v2
	v_mov_b32_e32 v24, v2
	v_mov_b32_e32 v25, v2
	v_mov_b32_e32 v34, v2
	v_mov_b32_e32 v35, v2
	v_mov_b32_e32 v36, v2
	v_mov_b32_e32 v37, v2
	v_mov_b32_e32 v38, v2
	v_mov_b32_e32 v39, v2
	v_mov_b32_e32 v40, v2
	v_mov_b32_e32 v41, v2
	v_mov_b32_e32 v50, v2
	v_mov_b32_e32 v51, v2
	v_mov_b32_e32 v52, v2
	v_mov_b32_e32 v53, v2
	v_mov_b32_e32 v54, v2
	v_mov_b32_e32 v55, v2
	v_mov_b32_e32 v56, v2
	v_mov_b32_e32 v57, v2
	v_mov_b32_e32 v10, v2
	v_mov_b32_e32 v11, v2
	v_mov_b32_e32 v12, v2
	v_mov_b32_e32 v13, v2
	v_mov_b32_e32 v14, v2
	v_mov_b32_e32 v15, v2
	v_mov_b32_e32 v16, v2
	v_mov_b32_e32 v17, v2
	s_waitcnt vmcnt(0)
	v_mov_b32_e32 v26, v2
	v_mov_b32_e32 v27, v2
	v_mov_b32_e32 v28, v2
	v_mov_b32_e32 v29, v2
	v_mov_b32_e32 v30, v2
	v_mov_b32_e32 v31, v2
	v_mov_b32_e32 v32, v2
	v_mov_b32_e32 v33, v2
	v_mov_b32_e32 v42, v2
	v_mov_b32_e32 v43, v2
	v_mov_b32_e32 v44, v2
	v_mov_b32_e32 v45, v2
	v_mov_b32_e32 v46, v2
	v_mov_b32_e32 v47, v2
	v_mov_b32_e32 v48, v2
	v_mov_b32_e32 v49, v2
	v_mov_b32_e32 v58, v2
	v_mov_b32_e32 v59, v2
	v_mov_b32_e32 v60, v2
	v_mov_b32_e32 v61, v2
	v_mov_b32_e32 v62, v2
	v_mov_b32_e32 v63, v2
	v_mov_b32_e32 v64, v2
	v_mov_b32_e32 v65, v2
	v_mov_b32_e32 v66, v2
	v_mov_b32_e32 v67, v2
	v_mov_b32_e32 v68, v2
	v_mov_b32_e32 v69, v2
	v_mov_b32_e32 v70, v2
	v_mov_b32_e32 v71, v2
	v_mov_b32_e32 v72, v2
	v_mov_b32_e32 v73, v2
	v_mov_b32_e32 v82, v2
	v_mov_b32_e32 v83, v2
	v_mov_b32_e32 v84, v2
	v_mov_b32_e32 v85, v2
	v_mov_b32_e32 v86, v2
	v_mov_b32_e32 v87, v2
	v_mov_b32_e32 v88, v2
	v_mov_b32_e32 v89, v2
	v_mov_b32_e32 v98, v2
	v_mov_b32_e32 v99, v2
	v_mov_b32_e32 v100, v2
	v_mov_b32_e32 v101, v2
	v_mov_b32_e32 v102, v2
	v_mov_b32_e32 v103, v2
	v_mov_b32_e32 v104, v2
	v_mov_b32_e32 v105, v2
	v_mov_b32_e32 v114, v2
	v_mov_b32_e32 v115, v2
	v_mov_b32_e32 v116, v2
	v_mov_b32_e32 v117, v2
	v_mov_b32_e32 v118, v2
	v_mov_b32_e32 v119, v2
	v_mov_b32_e32 v120, v2
	v_mov_b32_e32 v121, v2
	v_mov_b32_e32 v74, v2
	v_mov_b32_e32 v75, v2
	v_mov_b32_e32 v76, v2
	v_mov_b32_e32 v77, v2
	v_mov_b32_e32 v78, v2
	v_mov_b32_e32 v79, v2
	v_mov_b32_e32 v80, v2
	v_mov_b32_e32 v81, v2
	v_mov_b32_e32 v90, v2
	v_mov_b32_e32 v91, v2
	v_mov_b32_e32 v92, v2
	v_mov_b32_e32 v93, v2
	v_mov_b32_e32 v94, v2
	v_mov_b32_e32 v95, v2
	v_mov_b32_e32 v96, v2
	v_mov_b32_e32 v97, v2
	v_mov_b32_e32 v106, v2
	v_mov_b32_e32 v107, v2
	v_mov_b32_e32 v108, v2
	v_mov_b32_e32 v109, v2
	v_mov_b32_e32 v110, v2
	v_mov_b32_e32 v111, v2
	v_mov_b32_e32 v112, v2
	v_mov_b32_e32 v113, v2
	v_mov_b32_e32 v122, v2
	v_mov_b32_e32 v123, v2
	v_mov_b32_e32 v124, v2
	v_mov_b32_e32 v125, v2
	v_mov_b32_e32 v126, v2
	v_mov_b32_e32 v127, v2
	v_mov_b32_e32 v128, v2
	v_mov_b32_e32 v129, v2
	v_add_u32_e32 v250, 0x10000, v152
	v_readfirstlane_b32 s100, v232
	s_nop 3
	s_cmp_ge_u32 s100, 0x100
	s_cbranch_scc1 .Lprio_lo_0
	s_setprio 1
.Lprio_lo_0:
.LBB0_158:
	s_add_u32 s42, s38, 0x100
	s_addc_u32 s43, s39, 0
	s_add_i32 s60, 0, 0x10000
	ds_read_b128 v[146:149], v250
	ds_read_b128 v[162:165], v250 offset:1024
	ds_read_b128 v[166:169], v250 offset:2048
	ds_read_b128 v[170:173], v250 offset:3072
	s_cmp_eq_u32 s59, 28
	s_cselect_b32 s25, s23, s43
	s_cselect_b32 s24, s55, s42
	s_cselect_b32 s5, s21, s58
	s_cselect_b32 s4, s56, s57
	s_add_i32 m0, s46, 0xc000
	ds_read_b128 v[174:177], v154
	ds_read_b128 v[188:191], v154 offset:1024
	ds_read_b128 v[192:195], v154 offset:2048
	ds_read_b128 v[196:199], v154 offset:3072
	ds_read_b128 v[200:203], v154 offset:4096
	ds_read_b128 v[204:207], v154 offset:5120
	ds_read_b128 v[208:211], v154 offset:6144
	ds_read_b128 v[212:215], v154 offset:7168
	global_load_lds_dwordx4 v140, s[38:39]
	s_add_i32 m0, s46, 0xe000
	s_nop 0
	global_load_lds_dwordx4 v142, s[38:39]
	s_waitcnt lgkmcnt(8)
	s_barrier
	s_waitcnt lgkmcnt(0)
	v_mfma_f32_16x16x32_bf16 v[126:129], v[146:149], v[174:177], v[126:129]
	v_mfma_f32_16x16x32_bf16 v[122:125], v[166:169], v[174:177], v[122:125]
	v_mfma_f32_16x16x32_bf16 v[110:113], v[146:149], v[192:195], v[110:113]
	v_mfma_f32_16x16x32_bf16 v[106:109], v[166:169], v[192:195], v[106:109]
	v_mfma_f32_16x16x32_bf16 v[94:97], v[146:149], v[200:203], v[94:97]
	v_mfma_f32_16x16x32_bf16 v[90:93], v[166:169], v[200:203], v[90:93]
	v_mfma_f32_16x16x32_bf16 v[78:81], v[146:149], v[208:211], v[78:81]
	v_mfma_f32_16x16x32_bf16 v[74:77], v[166:169], v[208:211], v[74:77]
	v_mfma_f32_16x16x32_bf16 v[126:129], v[162:165], v[188:191], v[126:129]
	v_mfma_f32_16x16x32_bf16 v[122:125], v[170:173], v[188:191], v[122:125]
	v_mfma_f32_16x16x32_bf16 v[110:113], v[162:165], v[196:199], v[110:113]
	v_mfma_f32_16x16x32_bf16 v[106:109], v[170:173], v[196:199], v[106:109]
	v_mfma_f32_16x16x32_bf16 v[94:97], v[162:165], v[204:207], v[94:97]
	v_mfma_f32_16x16x32_bf16 v[90:93], v[170:173], v[204:207], v[90:93]
	v_mfma_f32_16x16x32_bf16 v[78:81], v[162:165], v[212:215], v[78:81]
	v_mfma_f32_16x16x32_bf16 v[74:77], v[170:173], v[212:215], v[74:77]
	s_barrier
; #define PG8_STAGE(bufoff, gbase, voff) do { _Pragma("unroll") for (int _i = 0; _i < 2; ++_i) \
;         __builtin_amdgcn_global_load_lds((const unsigned*)((const char*)(gbase) + (voff)[_i]), (LAS unsigned*)(lds + (bufoff) + ldsw + _i * 8192), 16, 0, 0); } while (0)
; #define PG8_LDA(dst, b, h) do { _Pragma("unroll") for (int m = 0; m < 4; ++m) _Pragma("unroll") for (int k = 0; k < 2; ++k) dst[m][k] = *(const LAS bf16x8*)(lds + PG8_SA(b, h) + aoff + m * 2048 + k * 1024); } while (0)
; #define PG8_LDB(dst, b, h) do { _Pragma("unroll") for (int n = 0; n < 2; ++n) _Pragma("unroll") for (int k = 0; k < 2; ++k) dst[n][k] = *(const LAS bf16x8*)(lds + PG8_SB(b, h) + boff + n * 2048 + k * 1024); } while (0)
; #define PG8_MMA(ai, bj, At, Bt) do { __builtin_amdgcn_s_setprio(1); _Pragma("unroll") for (int m = 0; m < 4; ++m) _Pragma("unroll") for (int n = 0; n < 2; ++n) _Pragma("unroll") for (int k = 0; k < 2; ++k) \
;         acc[ai][bj][m][n] = __builtin_amdgcn_mfma_f32_16x16x32_bf16(Bt[n][k], At[m][k], acc[ai][bj][m][n], 0, 0, 0); __builtin_amdgcn_s_setprio(0); } while (0)
; #define PG8_WAIT_V(n) asm volatile("s_waitcnt vmcnt(" #n ")" ::: "memory")
; #define PG8_WAIT_L(n) asm volatile("s_waitcnt lgkmcnt(" #n ")" ::: "memory")
; #define PG8_BAR __builtin_amdgcn_s_barrier()
; #define PG8_SCHED __builtin_amdgcn_sched_barrier(0)
; template <class Epi>
; __device__ __forceinline__ void gemm_phase(LAS unsigned char* lds, const Gemm g, const StaticOrder& S, const Epi& E) {
;     ...
;             PG8_LDB(B1, 0, 1); PG8_STAGE(PG8_SB(0, 0), b2, voffB);
;             PG8_BAR; PG8_WAIT_L(0); PG8_MMA(0, 1, At, B1); PG8_BAR;
;             PG8_LDA(At, 0, 1); PG8_STAGE(PG8_SA(0, 0), a2, voffA);
;             PG8_BAR; PG8_WAIT_L(0); PG8_MMA(1, 0, At, B0); PG8_BAR; PG8_SCHED;
;             PG8_STAGE(PG8_SB(0, 1), b2 + hstepB, voffB);
;             PG8_WAIT_V(6); PG8_BAR; PG8_MMA(1, 1, At, B1); PG8_BAR;
;             PG8_LDB(B0, 1, 0); PG8_SCHED; PG8_LDA(At, 1, 0); PG8_STAGE(PG8_SA(0, 1), a2 + hstepA, voffA);
;             PG8_WAIT_L(8); PG8_BAR; PG8_WAIT_L(0); PG8_MMA(0, 0, At, B0); PG8_BAR; PG8_SCHED;
;             PG8_LDB(B1, 1, 1); PG8_STAGE(PG8_SB(1, 0), b3, voffB);
;             PG8_BAR; PG8_WAIT_L(0); PG8_MMA(0, 1, At, B1); PG8_BAR;
;             PG8_LDA(At, 1, 1); PG8_STAGE(PG8_SA(1, 0), a3, voffA);
;             PG8_BAR; PG8_WAIT_L(0); PG8_MMA(1, 0, At, B0); PG8_BAR; PG8_SCHED;
	s_add_i32 s61, 0, 0x14000
	s_add_i32 s38, s60, s45
	s_add_u32 s100, s4, s6
	s_addc_u32 s101, s5, s7
	s_mov_b32 m0, s38
	ds_read_b128 v[216:219], v250 offset:16384
	ds_read_b128 v[220:223], v250 offset:17408
	ds_read_b128 v[224:227], v250 offset:18432
	ds_read_b128 v[228:231], v250 offset:19456
	global_load_lds_dwordx4 v134, s[4:5]
	s_add_i32 m0, s38, 0x2000
	s_nop 0
	global_load_lds_dwordx4 v130, s[4:5]
	s_barrier
	s_waitcnt lgkmcnt(0)
	v_mfma_f32_16x16x32_bf16 v[118:121], v[216:219], v[174:177], v[118:121]
	v_mfma_f32_16x16x32_bf16 v[114:117], v[224:227], v[174:177], v[114:117]
	v_mfma_f32_16x16x32_bf16 v[102:105], v[216:219], v[192:195], v[102:105]
	v_mfma_f32_16x16x32_bf16 v[98:101], v[224:227], v[192:195], v[98:101]
	v_mfma_f32_16x16x32_bf16 v[86:89], v[216:219], v[200:203], v[86:89]
	v_mfma_f32_16x16x32_bf16 v[82:85], v[224:227], v[200:203], v[82:85]
	v_mfma_f32_16x16x32_bf16 v[70:73], v[216:219], v[208:211], v[70:73]
	v_mfma_f32_16x16x32_bf16 v[66:69], v[224:227], v[208:211], v[66:69]
	v_mfma_f32_16x16x32_bf16 v[118:121], v[220:223], v[188:191], v[118:121]
	v_mfma_f32_16x16x32_bf16 v[114:117], v[228:231], v[188:191], v[114:117]
	v_mfma_f32_16x16x32_bf16 v[102:105], v[220:223], v[196:199], v[102:105]
	v_mfma_f32_16x16x32_bf16 v[98:101], v[228:231], v[196:199], v[98:101]
	v_mfma_f32_16x16x32_bf16 v[86:89], v[220:223], v[204:207], v[86:89]
	v_mfma_f32_16x16x32_bf16 v[82:85], v[228:231], v[204:207], v[82:85]
	v_mfma_f32_16x16x32_bf16 v[70:73], v[220:223], v[212:215], v[70:73]
	v_mfma_f32_16x16x32_bf16 v[66:69], v[228:231], v[212:215], v[66:69]
	s_mov_b32 m0, s46
	s_add_u32 vcc_lo, s24, s6
	s_addc_u32 vcc_hi, s25, s7
	s_barrier
	ds_read_b128 v[174:177], v154 offset:16384
	ds_read_b128 v[188:191], v154 offset:17408
	ds_read_b128 v[192:195], v154 offset:18432
	ds_read_b128 v[196:199], v154 offset:19456
	ds_read_b128 v[200:203], v154 offset:20480
	ds_read_b128 v[204:207], v154 offset:21504
	ds_read_b128 v[208:211], v154 offset:22528
	ds_read_b128 v[212:215], v154 offset:23552
	global_load_lds_dwordx4 v136, s[24:25]
	s_mov_b32 m0, s47
	s_nop 0
	global_load_lds_dwordx4 v132, s[24:25]
	s_barrier
	s_waitcnt lgkmcnt(0)
	v_mfma_f32_16x16x32_bf16 v[62:65], v[146:149], v[174:177], v[62:65]
	v_mfma_f32_16x16x32_bf16 v[58:61], v[166:169], v[174:177], v[58:61]
	v_mfma_f32_16x16x32_bf16 v[46:49], v[146:149], v[192:195], v[46:49]
	v_mfma_f32_16x16x32_bf16 v[42:45], v[166:169], v[192:195], v[42:45]
	v_mfma_f32_16x16x32_bf16 v[30:33], v[146:149], v[200:203], v[30:33]
	v_mfma_f32_16x16x32_bf16 v[26:29], v[166:169], v[200:203], v[26:29]
	v_mfma_f32_16x16x32_bf16 v[14:17], v[146:149], v[208:211], v[14:17]
	v_mfma_f32_16x16x32_bf16 v[10:13], v[166:169], v[208:211], v[10:13]
	v_mfma_f32_16x16x32_bf16 v[62:65], v[162:165], v[188:191], v[62:65]
	v_mfma_f32_16x16x32_bf16 v[58:61], v[170:173], v[188:191], v[58:61]
	v_mfma_f32_16x16x32_bf16 v[46:49], v[162:165], v[196:199], v[46:49]
	v_mfma_f32_16x16x32_bf16 v[42:45], v[170:173], v[196:199], v[42:45]
	v_mfma_f32_16x16x32_bf16 v[30:33], v[162:165], v[204:207], v[30:33]
	v_mfma_f32_16x16x32_bf16 v[26:29], v[170:173], v[204:207], v[26:29]
	v_mfma_f32_16x16x32_bf16 v[14:17], v[162:165], v[212:215], v[14:17]
	v_mfma_f32_16x16x32_bf16 v[10:13], v[170:173], v[212:215], v[10:13]
	s_barrier
	s_add_u32 s38, s4, 0x80000
	s_addc_u32 s39, s5, 0
	s_add_i32 s60, s61, s45
	s_mov_b32 m0, s60
	s_nop 0
	global_load_lds_dwordx4 v134, s[38:39]
	s_add_i32 m0, s60, 0x2000
	s_nop 0
	global_load_lds_dwordx4 v130, s[38:39]
	s_waitcnt vmcnt(6)
	s_barrier
	v_mfma_f32_16x16x32_bf16 v[54:57], v[216:219], v[174:177], v[54:57]
	v_mfma_f32_16x16x32_bf16 v[50:53], v[224:227], v[174:177], v[50:53]
	v_mfma_f32_16x16x32_bf16 v[38:41], v[216:219], v[192:195], v[38:41]
	v_mfma_f32_16x16x32_bf16 v[34:37], v[224:227], v[192:195], v[34:37]
	v_mfma_f32_16x16x32_bf16 v[22:25], v[216:219], v[200:203], v[22:25]
	v_mfma_f32_16x16x32_bf16 v[18:21], v[224:227], v[200:203], v[18:21]
	v_mfma_f32_16x16x32_bf16 v[6:9], v[216:219], v[208:211], v[6:9]
	v_mfma_f32_16x16x32_bf16 v[2:5], v[224:227], v[208:211], v[2:5]
	v_mfma_f32_16x16x32_bf16 v[54:57], v[220:223], v[188:191], v[54:57]
	v_mfma_f32_16x16x32_bf16 v[50:53], v[228:231], v[188:191], v[50:53]
	v_mfma_f32_16x16x32_bf16 v[38:41], v[220:223], v[196:199], v[38:41]
	v_mfma_f32_16x16x32_bf16 v[34:37], v[228:231], v[196:199], v[34:37]
	v_mfma_f32_16x16x32_bf16 v[22:25], v[220:223], v[204:207], v[22:25]
	v_mfma_f32_16x16x32_bf16 v[18:21], v[228:231], v[204:207], v[18:21]
	v_mfma_f32_16x16x32_bf16 v[6:9], v[220:223], v[212:215], v[6:9]
	v_mfma_f32_16x16x32_bf16 v[2:5], v[228:231], v[212:215], v[2:5]
	s_add_i32 s38, 0, 0x18000
	s_barrier
	ds_read_b128 v[146:149], v250 offset:32768
	ds_read_b128 v[162:165], v250 offset:33792
	ds_read_b128 v[166:169], v250 offset:34816
	ds_read_b128 v[170:173], v250 offset:35840
	s_add_u32 s24, s24, 0x80000
	s_addc_u32 s25, s25, 0
	s_mov_b32 m0, s48
	ds_read_b128 v[174:177], v154 offset:32768
	ds_read_b128 v[188:191], v154 offset:33792
	ds_read_b128 v[192:195], v154 offset:34816
	ds_read_b128 v[196:199], v154 offset:35840
	ds_read_b128 v[200:203], v154 offset:36864
	ds_read_b128 v[204:207], v154 offset:37888
	ds_read_b128 v[208:211], v154 offset:38912
	ds_read_b128 v[212:215], v154 offset:39936
	global_load_lds_dwordx4 v136, s[24:25]
	s_mov_b32 m0, s49
	s_nop 0
	global_load_lds_dwordx4 v132, s[24:25]
	s_waitcnt lgkmcnt(8)
	s_barrier
; __device__ __forceinline__ unsigned cvt_pk_bf16(float lo, float hi) { unsigned r; asm volatile("v_cvt_pk_bf16_f32 %0, %1, %2" : "=v"(r) : "v"(lo), "v"(hi)); return r; }
; #define PG8_STAGE(bufoff, gbase, voff) do { _Pragma("unroll") for (int _i = 0; _i < 2; ++_i) \
;         __builtin_amdgcn_global_load_lds((const unsigned*)((const char*)(gbase) + (voff)[_i]), (LAS unsigned*)(lds + (bufoff) + ldsw + _i * 8192), 16, 0, 0); } while (0)
; #define PG8_MMA(ai, bj, At, Bt) do { __builtin_amdgcn_s_setprio(1); _Pragma("unroll") for (int m = 0; m < 4; ++m) _Pragma("unroll") for (int n = 0; n < 2; ++n) _Pragma("unroll") for (int k = 0; k < 2; ++k) \
;         acc[ai][bj][m][n] = __builtin_amdgcn_mfma_f32_16x16x32_bf16(Bt[n][k], At[m][k], acc[ai][bj][m][n], 0, 0, 0); __builtin_amdgcn_s_setprio(0); } while (0)
; #define PG8_WAIT_V(n) asm volatile("s_waitcnt vmcnt(" #n ")" ::: "memory")
; #define PG8_WAIT_L(n) asm volatile("s_waitcnt lgkmcnt(" #n ")" ::: "memory")
; template <class Epi>
; __device__ __forceinline__ void gemm_phase(LAS unsigned char* lds, const Gemm g, const StaticOrder& S, const Epi& E) {
;     ...
;             PG8_BAR; PG8_WAIT_L(0); PG8_MMA(1, 0, At, B0); PG8_BAR; PG8_SCHED;
;             PG8_STAGE(PG8_SB(1, 1), b3 + hstepB, voffB);
;             PG8_WAIT_V(6); PG8_BAR; PG8_MMA(1, 1, At, B1); PG8_BAR;
;         }
;     __device__ __forceinline__ void operator()(const f32x4 (&acc)[2][2][4][2], const Unit& u, int wr, int wc, int fr, int fq, const Pre& pp) const {
;         const int row0 = u.pm * BM + wr * 64 + fr, col0 = u.pn * BM + wc * 32 + 8 * fq;
;         const bool gm = (UG != nullptr) && (u.pn < DE / BM);
;         const float (&rs)[8] = pp.rs;
; #pragma unroll
;         for (int ai = 0; ai < 2; ++ai)
; #pragma unroll
;             for (int m = 0; m < 4; ++m) { const int r = row0 + ai * HALF + m * 16; const float inv = rsqrtf(rs[ai * 4 + m] * (1.0f / DM) + EPS);
; #pragma unroll
;                 for (int bj = 0; bj < 2; ++bj) { const f32x4 v0 = acc[ai][bj][m][0] * inv, v1 = acc[ai][bj][m][1] * inv; const int c = col0 + bj * HALF;
;                     u32x4 w; w.x = cvt_pk_bf16(v0[0], v0[1]); w.y = cvt_pk_bf16(v0[2], v0[3]); w.z = cvt_pk_bf16(v1[0], v1[1]); w.w = cvt_pk_bf16(v1[2], v1[3]);
;                     bf16_t* dst = gm ? UG + (size_t)(c >> 4) * GSTR + r * 16 + (c & 15) : O + (size_t)r * DE2 + c;
;                     *(u32x4*)dst = w; } }
	s_waitcnt lgkmcnt(0)
	v_mfma_f32_16x16x32_bf16 v[126:129], v[146:149], v[174:177], v[126:129]
	v_mfma_f32_16x16x32_bf16 v[122:125], v[166:169], v[174:177], v[122:125]
	v_mfma_f32_16x16x32_bf16 v[110:113], v[146:149], v[192:195], v[110:113]
	v_mfma_f32_16x16x32_bf16 v[106:109], v[166:169], v[192:195], v[106:109]
	v_mfma_f32_16x16x32_bf16 v[94:97], v[146:149], v[200:203], v[94:97]
	v_mfma_f32_16x16x32_bf16 v[90:93], v[166:169], v[200:203], v[90:93]
	v_mfma_f32_16x16x32_bf16 v[78:81], v[146:149], v[208:211], v[78:81]
	v_mfma_f32_16x16x32_bf16 v[74:77], v[166:169], v[208:211], v[74:77]
	v_mfma_f32_16x16x32_bf16 v[126:129], v[162:165], v[188:191], v[126:129]
	v_mfma_f32_16x16x32_bf16 v[122:125], v[170:173], v[188:191], v[122:125]
	v_mfma_f32_16x16x32_bf16 v[110:113], v[162:165], v[196:199], v[110:113]
	v_mfma_f32_16x16x32_bf16 v[106:109], v[170:173], v[196:199], v[106:109]
	v_mfma_f32_16x16x32_bf16 v[94:97], v[162:165], v[204:207], v[94:97]
	v_mfma_f32_16x16x32_bf16 v[90:93], v[170:173], v[204:207], v[90:93]
	v_mfma_f32_16x16x32_bf16 v[78:81], v[162:165], v[212:215], v[78:81]
	v_mfma_f32_16x16x32_bf16 v[74:77], v[170:173], v[212:215], v[74:77]
	s_barrier
	s_add_i32 s24, 0, 0x1c000
	s_add_i32 s25, s38, s45
	s_mov_b32 m0, s25
	ds_read_b128 v[216:219], v250 offset:49152
	ds_read_b128 v[220:223], v250 offset:50176
	ds_read_b128 v[224:227], v250 offset:51200
	ds_read_b128 v[228:231], v250 offset:52224
	global_load_lds_dwordx4 v134, s[100:101]
	s_add_i32 m0, s25, 0x2000
	s_nop 0
	global_load_lds_dwordx4 v130, s[100:101]
	s_barrier
	s_waitcnt lgkmcnt(0)
	v_mfma_f32_16x16x32_bf16 v[118:121], v[216:219], v[174:177], v[118:121]
	v_mfma_f32_16x16x32_bf16 v[114:117], v[224:227], v[174:177], v[114:117]
	v_mfma_f32_16x16x32_bf16 v[102:105], v[216:219], v[192:195], v[102:105]
	v_mfma_f32_16x16x32_bf16 v[98:101], v[224:227], v[192:195], v[98:101]
	v_mfma_f32_16x16x32_bf16 v[86:89], v[216:219], v[200:203], v[86:89]
	v_mfma_f32_16x16x32_bf16 v[82:85], v[224:227], v[200:203], v[82:85]
	v_mfma_f32_16x16x32_bf16 v[70:73], v[216:219], v[208:211], v[70:73]
	v_mfma_f32_16x16x32_bf16 v[66:69], v[224:227], v[208:211], v[66:69]
	v_mfma_f32_16x16x32_bf16 v[118:121], v[220:223], v[188:191], v[118:121]
	v_mfma_f32_16x16x32_bf16 v[114:117], v[228:231], v[188:191], v[114:117]
	v_mfma_f32_16x16x32_bf16 v[102:105], v[220:223], v[196:199], v[102:105]
	v_mfma_f32_16x16x32_bf16 v[98:101], v[228:231], v[196:199], v[98:101]
	v_mfma_f32_16x16x32_bf16 v[86:89], v[220:223], v[204:207], v[86:89]
	v_mfma_f32_16x16x32_bf16 v[82:85], v[228:231], v[204:207], v[82:85]
	v_mfma_f32_16x16x32_bf16 v[70:73], v[220:223], v[212:215], v[70:73]
	v_mfma_f32_16x16x32_bf16 v[66:69], v[228:231], v[212:215], v[66:69]
	s_mov_b32 m0, s50
	s_barrier
	ds_read_b128 v[174:177], v154 offset:49152
	ds_read_b128 v[188:191], v154 offset:50176
	ds_read_b128 v[192:195], v154 offset:51200
	ds_read_b128 v[196:199], v154 offset:52224
	ds_read_b128 v[200:203], v154 offset:53248
	ds_read_b128 v[204:207], v154 offset:54272
	ds_read_b128 v[208:211], v154 offset:55296
	ds_read_b128 v[212:215], v154 offset:56320
	global_load_lds_dwordx4 v136, vcc
	s_mov_b32 m0, s51
	s_nop 0
	global_load_lds_dwordx4 v132, vcc
	s_barrier
	s_waitcnt lgkmcnt(0)
	v_mfma_f32_16x16x32_bf16 v[62:65], v[146:149], v[174:177], v[62:65]
	v_mfma_f32_16x16x32_bf16 v[58:61], v[166:169], v[174:177], v[58:61]
	v_mfma_f32_16x16x32_bf16 v[46:49], v[146:149], v[192:195], v[46:49]
	v_mfma_f32_16x16x32_bf16 v[42:45], v[166:169], v[192:195], v[42:45]
	v_mfma_f32_16x16x32_bf16 v[30:33], v[146:149], v[200:203], v[30:33]
	v_mfma_f32_16x16x32_bf16 v[26:29], v[166:169], v[200:203], v[26:29]
	v_mfma_f32_16x16x32_bf16 v[14:17], v[146:149], v[208:211], v[14:17]
	v_mfma_f32_16x16x32_bf16 v[10:13], v[166:169], v[208:211], v[10:13]
	v_mfma_f32_16x16x32_bf16 v[62:65], v[162:165], v[188:191], v[62:65]
	v_mfma_f32_16x16x32_bf16 v[58:61], v[170:173], v[188:191], v[58:61]
	v_mfma_f32_16x16x32_bf16 v[46:49], v[162:165], v[196:199], v[46:49]
	v_mfma_f32_16x16x32_bf16 v[42:45], v[170:173], v[196:199], v[42:45]
	v_mfma_f32_16x16x32_bf16 v[30:33], v[162:165], v[204:207], v[30:33]
	v_mfma_f32_16x16x32_bf16 v[26:29], v[170:173], v[204:207], v[26:29]
	v_mfma_f32_16x16x32_bf16 v[14:17], v[162:165], v[212:215], v[14:17]
	v_mfma_f32_16x16x32_bf16 v[10:13], v[170:173], v[212:215], v[10:13]
	s_barrier
	s_add_u32 s4, s4, 0x80080
	s_addc_u32 s5, s5, 0
	s_add_i32 s24, s24, s45
	s_mov_b32 m0, s24
	s_nop 0
	global_load_lds_dwordx4 v134, s[4:5]
	s_add_i32 m0, s24, 0x2000
	s_nop 0
	global_load_lds_dwordx4 v130, s[4:5]
	s_waitcnt vmcnt(6)
	s_barrier
	v_mfma_f32_16x16x32_bf16 v[54:57], v[216:219], v[174:177], v[54:57]
	v_mfma_f32_16x16x32_bf16 v[50:53], v[224:227], v[174:177], v[50:53]
	v_mfma_f32_16x16x32_bf16 v[38:41], v[216:219], v[192:195], v[38:41]
	v_mfma_f32_16x16x32_bf16 v[34:37], v[224:227], v[192:195], v[34:37]
	v_mfma_f32_16x16x32_bf16 v[22:25], v[216:219], v[200:203], v[22:25]
	v_mfma_f32_16x16x32_bf16 v[18:21], v[224:227], v[200:203], v[18:21]
	v_mfma_f32_16x16x32_bf16 v[6:9], v[216:219], v[208:211], v[6:9]
	v_mfma_f32_16x16x32_bf16 v[2:5], v[224:227], v[208:211], v[2:5]
	v_mfma_f32_16x16x32_bf16 v[54:57], v[220:223], v[188:191], v[54:57]
	v_mfma_f32_16x16x32_bf16 v[50:53], v[228:231], v[188:191], v[50:53]
	v_mfma_f32_16x16x32_bf16 v[38:41], v[220:223], v[196:199], v[38:41]
	v_mfma_f32_16x16x32_bf16 v[34:37], v[228:231], v[196:199], v[34:37]
	v_mfma_f32_16x16x32_bf16 v[22:25], v[220:223], v[204:207], v[22:25]
	v_mfma_f32_16x16x32_bf16 v[18:21], v[228:231], v[204:207], v[18:21]
	v_mfma_f32_16x16x32_bf16 v[6:9], v[220:223], v[212:215], v[6:9]
	v_mfma_f32_16x16x32_bf16 v[2:5], v[228:231], v[212:215], v[2:5]
	s_add_i32 s59, s59, 2
	s_add_u32 s57, s57, 0x100
	s_addc_u32 s58, s58, 0
	s_cmp_gt_u32 s59, 29
	s_mov_b64 s[38:39], s[42:43]
	s_barrier
	s_cbranch_scc0 .LBB0_158
	s_setprio 0
	v_fmamk_f32 v0, v145, 0x3a000000, v233
	v_cmp_gt_f32_e32 vcc, s66, v0
	v_mul_f32_e32 v145, 0x4b800000, v0
	v_readlane_b32 s38, v254, 47
	v_cndmask_b32_e32 v0, v0, v145, vcc
	v_rsq_f32_e32 v0, v0
	v_lshl_add_u32 v146, s54, 8, v139
	s_cmp_gt_i32 s53, 15
	v_readlane_b32 s39, v254, 48
	v_mul_f32_e32 v145, 0x45800000, v0
	s_cselect_b64 s[4:5], -1, 0
	s_xor_b64 s[38:39], s[38:39], -1
	v_cndmask_b32_e32 v148, v0, v145, vcc
	v_ashrrev_i32_e32 v147, 31, v146
	s_or_b64 s[4:5], s[38:39], s[4:5]
	v_lshl_or_b32 v144, s53, 8, v153
	v_lshlrev_b64 v[150:151], 14, v[146:147]
	v_pk_mul_f32 v[128:129], v[148:149], v[128:129] op_sel_hi:[0,1]
	s_mov_b64 s[24:25], -1
	v_pk_mul_f32 v[126:127], v[148:149], v[126:127] op_sel_hi:[0,1]
	v_pk_mul_f32 v[162:163], v[148:149], v[124:125] op_sel_hi:[0,1]
	v_pk_mul_f32 v[124:125], v[148:149], v[122:123] op_sel_hi:[0,1]
	v_cvt_pk_bf16_f32 v122, v126, v127
	v_cvt_pk_bf16_f32 v123, v128, v129
	s_and_b64 vcc, exec, s[4:5]
	v_lshl_add_u64 v[128:129], s[16:17], 0, v[150:151]
	v_ashrrev_i32_e32 v145, 31, v144
	v_cvt_pk_bf16_f32 v124, v124, v125
	v_cvt_pk_bf16_f32 v125, v162, v163
	s_cbranch_vccz .LBB0_161
	v_lshl_add_u64 v[150:151], v[144:145], 1, v[128:129]
	s_mov_b64 s[24:25], 0

; #define PG8_STAGE(bufoff, gbase, voff) do { _Pragma("unroll") for (int _i = 0; _i < 2; ++_i) \
;         __builtin_amdgcn_global_load_lds((const unsigned*)((const char*)(gbase) + (voff)[_i]), (LAS unsigned*)(lds + (bufoff) + ldsw + _i * 8192), 16, 0, 0); } while (0)
; #define PG8_LDA(dst, b, h) do { _Pragma("unroll") for (int m = 0; m < 4; ++m) _Pragma("unroll") for (int k = 0; k < 2; ++k) dst[m][k] = *(const LAS bf16x8*)(lds + PG8_SA(b, h) + aoff + m * 2048 + k * 1024); } while (0)
; #define PG8_LDB(dst, b, h) do { _Pragma("unroll") for (int n = 0; n < 2; ++n) _Pragma("unroll") for (int k = 0; k < 2; ++k) dst[n][k] = *(const LAS bf16x8*)(lds + PG8_SB(b, h) + boff + n * 2048 + k * 1024); } while (0)
; #define PG8_MMA(ai, bj, At, Bt) do { __builtin_amdgcn_s_setprio(1); _Pragma("unroll") for (int m = 0; m < 4; ++m) _Pragma("unroll") for (int n = 0; n < 2; ++n) _Pragma("unroll") for (int k = 0; k < 2; ++k) \
;         acc[ai][bj][m][n] = __builtin_amdgcn_mfma_f32_16x16x32_bf16(Bt[n][k], At[m][k], acc[ai][bj][m][n], 0, 0, 0); __builtin_amdgcn_s_setprio(0); } while (0)
; #define PG8_WAIT_L(n) asm volatile("s_waitcnt lgkmcnt(" #n ")" ::: "memory")
; #define PG8_BAR __builtin_amdgcn_s_barrier()
; template <class Epi>
; __device__ __forceinline__ void gemm_phase(LAS unsigned char* lds, const Gemm g, const StaticOrder& S, const Epi& E) {
;     ...
; #pragma unroll
;     for (int a = 0; a < 2; ++a)
; #pragma unroll
;         for (int b = 0; b < 2; ++b)
; #pragma unroll
;             for (int m = 0; m < 4; ++m)
; #pragma unroll
;                 for (int n = 0; n < 2; ++n) acc[a][b][m][n] = (f32x4){0.f, 0.f, 0.f, 0.f};
;     ...
;         const char* nA = has_next ? (const char*)g.A + (size_t)nxt.pm * tstepA + (size_t)(nxt.pn >> 2) * gstepA : cA; const char* nB = has_next ? (const char*)g.Bt + (size_t)nxt.pn * tstepB : cB;
;         for (int t = 0; t < nt; t += 2) {
;             const bool last = (t == nt - 2);
;             const char* a1 = cA + (size_t)(t + 1) * kstepA;
;             const char* a2 = last ? nA : cA + (size_t)(t + 2) * kstepA; const char* b2 = last ? nB : cB + (size_t)(t + 2) * kstep;
;             const char* a3 = a2 + kstepA; const char* b3 = b2 + kstep;
;             PG8_LDB(B0, 0, 0); PG8_SCHED; PG8_LDA(At, 0, 0); PG8_STAGE(PG8_SA(1, 1), a1 + hstepA, voffA);
;             PG8_WAIT_L(8); PG8_BAR; PG8_WAIT_L(0); PG8_MMA(0, 0, At, B0); PG8_BAR; PG8_SCHED;
.LBB0_358:
	v_mov_b64_e32 v[2:3], 0x100
	s_ashr_i32 s17, s16, 31
	v_cmp_lt_i64_e32 vcc, s[18:19], v[2:3]
	s_lshl_b64 s[18:19], s[16:17], 21
	s_add_u32 s18, s38, s18
	s_addc_u32 s19, s39, s19
	s_and_b64 s[20:21], vcc, exec
	s_cselect_b32 s17, s19, s23
	s_cselect_b32 s60, s18, s22
	s_ashr_i32 s15, s14, 31
	s_lshl_b64 s[20:21], s[14:15], 21
	s_add_u32 s20, s46, s20
	s_addc_u32 s21, s47, s21
	s_and_b64 s[24:25], vcc, exec
	s_cselect_b32 s15, s21, s27
	s_cselect_b32 s61, s20, s26
	s_add_u32 s62, s26, 0x100
	v_mov_b32_e32 v2, 0
	s_addc_u32 s63, s27, 0
	s_mov_b32 s64, -2
	v_mov_b32_e32 v3, v2
	v_mov_b32_e32 v4, v2
	v_mov_b32_e32 v5, v2
	v_mov_b32_e32 v6, v2
	v_mov_b32_e32 v7, v2
	v_mov_b32_e32 v8, v2
	v_mov_b32_e32 v9, v2
	v_mov_b32_e32 v18, v2
	v_mov_b32_e32 v19, v2
	v_mov_b32_e32 v20, v2
	v_mov_b32_e32 v21, v2
	v_mov_b32_e32 v22, v2
	v_mov_b32_e32 v23, v2
	v_mov_b32_e32 v24, v2
	v_mov_b32_e32 v25, v2
	v_mov_b32_e32 v34, v2
	v_mov_b32_e32 v35, v2
	v_mov_b32_e32 v36, v2
	v_mov_b32_e32 v37, v2
	v_mov_b32_e32 v38, v2
	v_mov_b32_e32 v39, v2
	v_mov_b32_e32 v40, v2
	v_mov_b32_e32 v41, v2
	v_mov_b32_e32 v50, v2
	v_mov_b32_e32 v51, v2
	v_mov_b32_e32 v52, v2
	v_mov_b32_e32 v53, v2
	v_mov_b32_e32 v54, v2
	v_mov_b32_e32 v55, v2
	v_mov_b32_e32 v56, v2
	v_mov_b32_e32 v57, v2
	v_mov_b32_e32 v10, v2
	v_mov_b32_e32 v11, v2
	v_mov_b32_e32 v12, v2
	v_mov_b32_e32 v13, v2
	v_mov_b32_e32 v14, v2
	v_mov_b32_e32 v15, v2
	v_mov_b32_e32 v16, v2
	v_mov_b32_e32 v17, v2
	v_mov_b32_e32 v26, v2
	v_mov_b32_e32 v27, v2
	v_mov_b32_e32 v28, v2
	v_mov_b32_e32 v29, v2
	v_mov_b32_e32 v30, v2
	v_mov_b32_e32 v31, v2
	v_mov_b32_e32 v32, v2
	v_mov_b32_e32 v33, v2
	v_mov_b32_e32 v42, v2
	v_mov_b32_e32 v43, v2
	v_mov_b32_e32 v44, v2
	v_mov_b32_e32 v45, v2
	v_mov_b32_e32 v46, v2
	v_mov_b32_e32 v47, v2
	v_mov_b32_e32 v48, v2
	v_mov_b32_e32 v49, v2
	v_mov_b32_e32 v58, v2
	v_mov_b32_e32 v59, v2
	v_mov_b32_e32 v60, v2
	v_mov_b32_e32 v61, v2
	v_mov_b32_e32 v62, v2
	v_mov_b32_e32 v63, v2
	v_mov_b32_e32 v64, v2
	v_mov_b32_e32 v65, v2
	v_mov_b32_e32 v66, v2
	v_mov_b32_e32 v67, v2
	v_mov_b32_e32 v68, v2
	v_mov_b32_e32 v69, v2
	v_mov_b32_e32 v78, v2
	v_mov_b32_e32 v79, v2
	v_mov_b32_e32 v80, v2
	v_mov_b32_e32 v81, v2
	v_mov_b32_e32 v98, v2
	v_mov_b32_e32 v99, v2
	v_mov_b32_e32 v100, v2
	v_mov_b32_e32 v101, v2
	v_mov_b32_e32 v102, v2
	v_mov_b32_e32 v103, v2
	v_mov_b32_e32 v104, v2
	v_mov_b32_e32 v105, v2
	v_mov_b32_e32 v114, v2
	v_mov_b32_e32 v115, v2
	v_mov_b32_e32 v116, v2
	v_mov_b32_e32 v117, v2
	v_mov_b32_e32 v118, v2
	v_mov_b32_e32 v119, v2
	v_mov_b32_e32 v120, v2
	v_mov_b32_e32 v121, v2
	v_mov_b32_e32 v130, v2
	v_mov_b32_e32 v131, v2
	v_mov_b32_e32 v132, v2
	v_mov_b32_e32 v133, v2
	v_mov_b32_e32 v134, v2
	v_mov_b32_e32 v135, v2
	v_mov_b32_e32 v136, v2
	v_mov_b32_e32 v137, v2
	v_mov_b32_e32 v90, v2
	v_mov_b32_e32 v91, v2
	v_mov_b32_e32 v92, v2
	v_mov_b32_e32 v93, v2
	v_mov_b32_e32 v94, v2
	v_mov_b32_e32 v95, v2
	v_mov_b32_e32 v96, v2
	v_mov_b32_e32 v97, v2
	v_mov_b32_e32 v106, v2
	v_mov_b32_e32 v107, v2
	v_mov_b32_e32 v108, v2
	v_mov_b32_e32 v109, v2
	v_mov_b32_e32 v110, v2
	v_mov_b32_e32 v111, v2
	v_mov_b32_e32 v112, v2
	v_mov_b32_e32 v113, v2
	v_mov_b32_e32 v122, v2
	v_mov_b32_e32 v123, v2
	v_mov_b32_e32 v124, v2
	v_mov_b32_e32 v125, v2
	v_mov_b32_e32 v126, v2
	v_mov_b32_e32 v127, v2
	v_mov_b32_e32 v128, v2
	v_mov_b32_e32 v129, v2
	v_mov_b32_e32 v138, v2
	v_mov_b32_e32 v139, v2
	v_mov_b32_e32 v140, v2
	v_mov_b32_e32 v141, v2
	v_mov_b32_e32 v142, v2
	v_mov_b32_e32 v143, v2
	v_mov_b32_e32 v144, v2
	v_mov_b32_e32 v145, v2
	v_add_u32_e32 v250, 0x10000, v209
	v_readfirstlane_b32 s100, v232
	s_nop 3
	s_cmp_ge_u32 s100, 0x100
	s_cbranch_scc1 .Lprio_lo_1
	s_setprio 1
.Lprio_lo_1:
.LBB0_359:
	s_add_u32 s26, s22, 0x100
	s_addc_u32 s27, s23, 0
	s_add_i32 s65, 0, 0x10000
	ds_read_b128 v[70:73], v250
	ds_read_b128 v[74:77], v250 offset:1024
	ds_read_b128 v[82:85], v250 offset:2048
	ds_read_b128 v[86:89], v250 offset:3072
	s_cmp_eq_u32 s64, 60
	s_cselect_b32 s25, s17, s27
	s_cselect_b32 s24, s60, s26
	s_cselect_b32 s37, s15, s63
	s_cselect_b32 s36, s61, s62
	s_add_i32 m0, s53, 0xc000
	ds_read_b128 v[146:149], v211
	ds_read_b128 v[150:153], v211 offset:1024
	ds_read_b128 v[154:157], v211 offset:2048
	ds_read_b128 v[158:161], v211 offset:3072
	ds_read_b128 v[162:165], v211 offset:4096
	ds_read_b128 v[166:169], v211 offset:5120
	ds_read_b128 v[170:173], v211 offset:6144
	ds_read_b128 v[184:187], v211 offset:7168
	global_load_lds_dwordx4 v190, s[22:23]
	s_add_i32 m0, s53, 0xe000
	s_nop 0
	global_load_lds_dwordx4 v192, s[22:23]
	s_waitcnt lgkmcnt(8)
	s_barrier
	s_waitcnt lgkmcnt(0)
	v_mfma_f32_16x16x32_bf16 v[142:145], v[70:73], v[146:149], v[142:145]
	v_mfma_f32_16x16x32_bf16 v[138:141], v[82:85], v[146:149], v[138:141]
	v_mfma_f32_16x16x32_bf16 v[126:129], v[70:73], v[154:157], v[126:129]
	v_mfma_f32_16x16x32_bf16 v[122:125], v[82:85], v[154:157], v[122:125]
	v_mfma_f32_16x16x32_bf16 v[110:113], v[70:73], v[162:165], v[110:113]
	v_mfma_f32_16x16x32_bf16 v[106:109], v[82:85], v[162:165], v[106:109]
	v_mfma_f32_16x16x32_bf16 v[94:97], v[70:73], v[170:173], v[94:97]
	v_mfma_f32_16x16x32_bf16 v[90:93], v[82:85], v[170:173], v[90:93]
	v_mfma_f32_16x16x32_bf16 v[142:145], v[74:77], v[150:153], v[142:145]
	v_mfma_f32_16x16x32_bf16 v[138:141], v[86:89], v[150:153], v[138:141]
	v_mfma_f32_16x16x32_bf16 v[126:129], v[74:77], v[158:161], v[126:129]
	v_mfma_f32_16x16x32_bf16 v[122:125], v[86:89], v[158:161], v[122:125]
	v_mfma_f32_16x16x32_bf16 v[110:113], v[74:77], v[166:169], v[110:113]
	v_mfma_f32_16x16x32_bf16 v[106:109], v[86:89], v[166:169], v[106:109]
	v_mfma_f32_16x16x32_bf16 v[94:97], v[74:77], v[184:187], v[94:97]
	v_mfma_f32_16x16x32_bf16 v[90:93], v[86:89], v[184:187], v[90:93]
	s_barrier
; #define PG8_STAGE(bufoff, gbase, voff) do { _Pragma("unroll") for (int _i = 0; _i < 2; ++_i) \
;         __builtin_amdgcn_global_load_lds((const unsigned*)((const char*)(gbase) + (voff)[_i]), (LAS unsigned*)(lds + (bufoff) + ldsw + _i * 8192), 16, 0, 0); } while (0)
; #define PG8_LDA(dst, b, h) do { _Pragma("unroll") for (int m = 0; m < 4; ++m) _Pragma("unroll") for (int k = 0; k < 2; ++k) dst[m][k] = *(const LAS bf16x8*)(lds + PG8_SA(b, h) + aoff + m * 2048 + k * 1024); } while (0)
; #define PG8_LDB(dst, b, h) do { _Pragma("unroll") for (int n = 0; n < 2; ++n) _Pragma("unroll") for (int k = 0; k < 2; ++k) dst[n][k] = *(const LAS bf16x8*)(lds + PG8_SB(b, h) + boff + n * 2048 + k * 1024); } while (0)
; #define PG8_MMA(ai, bj, At, Bt) do { __builtin_amdgcn_s_setprio(1); _Pragma("unroll") for (int m = 0; m < 4; ++m) _Pragma("unroll") for (int n = 0; n < 2; ++n) _Pragma("unroll") for (int k = 0; k < 2; ++k) \
;         acc[ai][bj][m][n] = __builtin_amdgcn_mfma_f32_16x16x32_bf16(Bt[n][k], At[m][k], acc[ai][bj][m][n], 0, 0, 0); __builtin_amdgcn_s_setprio(0); } while (0)
; #define PG8_WAIT_V(n) asm volatile("s_waitcnt vmcnt(" #n ")" ::: "memory")
; #define PG8_WAIT_L(n) asm volatile("s_waitcnt lgkmcnt(" #n ")" ::: "memory")
; #define PG8_BAR __builtin_amdgcn_s_barrier()
; #define PG8_SCHED __builtin_amdgcn_sched_barrier(0)
; template <class Epi>
; __device__ __forceinline__ void gemm_phase(LAS unsigned char* lds, const Gemm g, const StaticOrder& S, const Epi& E) {
;     ...
;             PG8_LDB(B1, 0, 1); PG8_STAGE(PG8_SB(0, 0), b2, voffB);
;             PG8_BAR; PG8_WAIT_L(0); PG8_MMA(0, 1, At, B1); PG8_BAR;
;             PG8_LDA(At, 0, 1); PG8_STAGE(PG8_SA(0, 0), a2, voffA);
;             PG8_BAR; PG8_WAIT_L(0); PG8_MMA(1, 0, At, B0); PG8_BAR; PG8_SCHED;
;             PG8_STAGE(PG8_SB(0, 1), b2 + hstepB, voffB);
;             PG8_WAIT_V(6); PG8_BAR; PG8_MMA(1, 1, At, B1); PG8_BAR;
;             PG8_LDB(B0, 1, 0); PG8_SCHED; PG8_LDA(At, 1, 0); PG8_STAGE(PG8_SA(0, 1), a2 + hstepA, voffA);
;             PG8_WAIT_L(8); PG8_BAR; PG8_WAIT_L(0); PG8_MMA(0, 0, At, B0); PG8_BAR; PG8_SCHED;
;             PG8_LDB(B1, 1, 1); PG8_STAGE(PG8_SB(1, 0), b3, voffB);
;             PG8_BAR; PG8_WAIT_L(0); PG8_MMA(0, 1, At, B1); PG8_BAR;
;             PG8_LDA(At, 1, 1); PG8_STAGE(PG8_SA(1, 0), a3, voffA);
;             PG8_BAR; PG8_WAIT_L(0); PG8_MMA(1, 0, At, B0); PG8_BAR; PG8_SCHED;
	s_add_i32 s66, 0, 0x14000
	s_add_i32 s22, s65, s52
	ds_read_b128 v[194:197], v250 offset:16384
	ds_read_b128 v[198:201], v250 offset:17408
	ds_read_b128 v[202:205], v250 offset:18432
	ds_read_b128 v[212:215], v250 offset:19456
	s_add_u32 s100, s36, s6
	s_addc_u32 s101, s37, s7
	s_mov_b32 m0, s22
	s_nop 0
	global_load_lds_dwordx4 v0, s[36:37]
	s_add_i32 m0, s22, 0x2000
	s_nop 0
	global_load_lds_dwordx4 v174, s[36:37]
	s_barrier
	s_waitcnt lgkmcnt(0)
	v_mfma_f32_16x16x32_bf16 v[134:137], v[194:197], v[146:149], v[134:137]
	v_mfma_f32_16x16x32_bf16 v[130:133], v[202:205], v[146:149], v[130:133]
	v_mfma_f32_16x16x32_bf16 v[118:121], v[194:197], v[154:157], v[118:121]
	v_mfma_f32_16x16x32_bf16 v[114:117], v[202:205], v[154:157], v[114:117]
	v_mfma_f32_16x16x32_bf16 v[102:105], v[194:197], v[162:165], v[102:105]
	v_mfma_f32_16x16x32_bf16 v[98:101], v[202:205], v[162:165], v[98:101]
	v_mfma_f32_16x16x32_bf16 v[78:81], v[194:197], v[170:173], v[78:81]
	v_mfma_f32_16x16x32_bf16 v[66:69], v[202:205], v[170:173], v[66:69]
	v_mfma_f32_16x16x32_bf16 v[134:137], v[198:201], v[150:153], v[134:137]
	v_mfma_f32_16x16x32_bf16 v[130:133], v[212:215], v[150:153], v[130:133]
	v_mfma_f32_16x16x32_bf16 v[118:121], v[198:201], v[158:161], v[118:121]
	v_mfma_f32_16x16x32_bf16 v[114:117], v[212:215], v[158:161], v[114:117]
	v_mfma_f32_16x16x32_bf16 v[102:105], v[198:201], v[166:169], v[102:105]
	v_mfma_f32_16x16x32_bf16 v[98:101], v[212:215], v[166:169], v[98:101]
	v_mfma_f32_16x16x32_bf16 v[78:81], v[198:201], v[184:187], v[78:81]
	v_mfma_f32_16x16x32_bf16 v[66:69], v[212:215], v[184:187], v[66:69]
	s_mov_b32 m0, s53
	s_add_u32 vcc_lo, s24, s6
	s_addc_u32 vcc_hi, s25, s7
	s_barrier
	ds_read_b128 v[146:149], v211 offset:16384
	ds_read_b128 v[150:153], v211 offset:17408
	ds_read_b128 v[154:157], v211 offset:18432
	ds_read_b128 v[158:161], v211 offset:19456
	ds_read_b128 v[162:165], v211 offset:20480
	ds_read_b128 v[166:169], v211 offset:21504
	ds_read_b128 v[170:173], v211 offset:22528
	ds_read_b128 v[184:187], v211 offset:23552
	global_load_lds_dwordx4 v188, s[24:25]
	s_mov_b32 m0, s54
	s_nop 0
	global_load_lds_dwordx4 v176, s[24:25]
	s_barrier
	s_waitcnt lgkmcnt(0)
	v_mfma_f32_16x16x32_bf16 v[62:65], v[70:73], v[146:149], v[62:65]
	v_mfma_f32_16x16x32_bf16 v[58:61], v[82:85], v[146:149], v[58:61]
	v_mfma_f32_16x16x32_bf16 v[46:49], v[70:73], v[154:157], v[46:49]
	v_mfma_f32_16x16x32_bf16 v[42:45], v[82:85], v[154:157], v[42:45]
	v_mfma_f32_16x16x32_bf16 v[30:33], v[70:73], v[162:165], v[30:33]
	v_mfma_f32_16x16x32_bf16 v[26:29], v[82:85], v[162:165], v[26:29]
	v_mfma_f32_16x16x32_bf16 v[14:17], v[70:73], v[170:173], v[14:17]
	v_mfma_f32_16x16x32_bf16 v[10:13], v[82:85], v[170:173], v[10:13]
	v_mfma_f32_16x16x32_bf16 v[62:65], v[74:77], v[150:153], v[62:65]
	v_mfma_f32_16x16x32_bf16 v[58:61], v[86:89], v[150:153], v[58:61]
	v_mfma_f32_16x16x32_bf16 v[46:49], v[74:77], v[158:161], v[46:49]
	v_mfma_f32_16x16x32_bf16 v[42:45], v[86:89], v[158:161], v[42:45]
	v_mfma_f32_16x16x32_bf16 v[30:33], v[74:77], v[166:169], v[30:33]
	v_mfma_f32_16x16x32_bf16 v[26:29], v[86:89], v[166:169], v[26:29]
	v_mfma_f32_16x16x32_bf16 v[14:17], v[74:77], v[184:187], v[14:17]
	v_mfma_f32_16x16x32_bf16 v[10:13], v[86:89], v[184:187], v[10:13]
	s_barrier
	s_add_u32 s22, s36, 0x100000
	s_addc_u32 s23, s37, 0
	s_add_i32 s65, s66, s52
	s_mov_b32 m0, s65
	s_nop 0
	global_load_lds_dwordx4 v0, s[22:23]
	s_add_i32 m0, s65, 0x2000
	s_nop 0
	global_load_lds_dwordx4 v174, s[22:23]
	s_waitcnt vmcnt(6)
	s_barrier
	v_mfma_f32_16x16x32_bf16 v[54:57], v[194:197], v[146:149], v[54:57]
	v_mfma_f32_16x16x32_bf16 v[50:53], v[202:205], v[146:149], v[50:53]
	v_mfma_f32_16x16x32_bf16 v[38:41], v[194:197], v[154:157], v[38:41]
	v_mfma_f32_16x16x32_bf16 v[34:37], v[202:205], v[154:157], v[34:37]
	v_mfma_f32_16x16x32_bf16 v[22:25], v[194:197], v[162:165], v[22:25]
	v_mfma_f32_16x16x32_bf16 v[18:21], v[202:205], v[162:165], v[18:21]
	v_mfma_f32_16x16x32_bf16 v[6:9], v[194:197], v[170:173], v[6:9]
	v_mfma_f32_16x16x32_bf16 v[2:5], v[202:205], v[170:173], v[2:5]
	v_mfma_f32_16x16x32_bf16 v[54:57], v[198:201], v[150:153], v[54:57]
	v_mfma_f32_16x16x32_bf16 v[50:53], v[212:215], v[150:153], v[50:53]
	v_mfma_f32_16x16x32_bf16 v[38:41], v[198:201], v[158:161], v[38:41]
	v_mfma_f32_16x16x32_bf16 v[34:37], v[212:215], v[158:161], v[34:37]
	v_mfma_f32_16x16x32_bf16 v[22:25], v[198:201], v[166:169], v[22:25]
	v_mfma_f32_16x16x32_bf16 v[18:21], v[212:215], v[166:169], v[18:21]
	v_mfma_f32_16x16x32_bf16 v[6:9], v[198:201], v[184:187], v[6:9]
	v_mfma_f32_16x16x32_bf16 v[2:5], v[212:215], v[184:187], v[2:5]
	s_add_i32 s65, 0, 0x18000
	s_barrier
	ds_read_b128 v[70:73], v250 offset:32768
	ds_read_b128 v[74:77], v250 offset:33792
	ds_read_b128 v[82:85], v250 offset:34816
	ds_read_b128 v[86:89], v250 offset:35840
	s_add_u32 s22, s24, 0x100000
	s_addc_u32 s23, s25, 0
	s_mov_b32 m0, s55
	ds_read_b128 v[146:149], v211 offset:32768
	ds_read_b128 v[150:153], v211 offset:33792
	ds_read_b128 v[154:157], v211 offset:34816
	ds_read_b128 v[158:161], v211 offset:35840
	ds_read_b128 v[162:165], v211 offset:36864
	ds_read_b128 v[166:169], v211 offset:37888
	ds_read_b128 v[170:173], v211 offset:38912
	ds_read_b128 v[184:187], v211 offset:39936
	global_load_lds_dwordx4 v188, s[22:23]
	s_mov_b32 m0, s56
	s_nop 0
	global_load_lds_dwordx4 v176, s[22:23]
	s_waitcnt lgkmcnt(8)
	s_barrier
; #define PG8_STAGE(bufoff, gbase, voff) do { _Pragma("unroll") for (int _i = 0; _i < 2; ++_i) \
;         __builtin_amdgcn_global_load_lds((const unsigned*)((const char*)(gbase) + (voff)[_i]), (LAS unsigned*)(lds + (bufoff) + ldsw + _i * 8192), 16, 0, 0); } while (0)
; #define PG8_LDA(dst, b, h) do { _Pragma("unroll") for (int m = 0; m < 4; ++m) _Pragma("unroll") for (int k = 0; k < 2; ++k) dst[m][k] = *(const LAS bf16x8*)(lds + PG8_SA(b, h) + aoff + m * 2048 + k * 1024); } while (0)
; #define PG8_LDB(dst, b, h) do { _Pragma("unroll") for (int n = 0; n < 2; ++n) _Pragma("unroll") for (int k = 0; k < 2; ++k) dst[n][k] = *(const LAS bf16x8*)(lds + PG8_SB(b, h) + boff + n * 2048 + k * 1024); } while (0)
; #define PG8_MMA(ai, bj, At, Bt) do { __builtin_amdgcn_s_setprio(1); _Pragma("unroll") for (int m = 0; m < 4; ++m) _Pragma("unroll") for (int n = 0; n < 2; ++n) _Pragma("unroll") for (int k = 0; k < 2; ++k) \
;         acc[ai][bj][m][n] = __builtin_amdgcn_mfma_f32_16x16x32_bf16(Bt[n][k], At[m][k], acc[ai][bj][m][n], 0, 0, 0); __builtin_amdgcn_s_setprio(0); } while (0)
; #define PG8_WAIT_L(n) asm volatile("s_waitcnt lgkmcnt(" #n ")" ::: "memory")
; #define PG8_BAR __builtin_amdgcn_s_barrier()
; #define PG8_SCHED __builtin_amdgcn_sched_barrier(0)
; template <class Epi>
; __device__ __forceinline__ void gemm_phase(LAS unsigned char* lds, const Gemm g, const StaticOrder& S, const Epi& E) {
;     ...
;             PG8_WAIT_L(8); PG8_BAR; PG8_WAIT_L(0); PG8_MMA(0, 0, At, B0); PG8_BAR; PG8_SCHED;
;             PG8_LDB(B1, 1, 1); PG8_STAGE(PG8_SB(1, 0), b3, voffB);
;             PG8_BAR; PG8_WAIT_L(0); PG8_MMA(0, 1, At, B1); PG8_BAR;
;             PG8_LDA(At, 1, 1); PG8_STAGE(PG8_SA(1, 0), a3, voffA);
;             PG8_BAR; PG8_WAIT_L(0); PG8_MMA(1, 0, At, B0); PG8_BAR; PG8_SCHED;
	s_waitcnt lgkmcnt(0)
	v_mfma_f32_16x16x32_bf16 v[142:145], v[70:73], v[146:149], v[142:145]
	v_mfma_f32_16x16x32_bf16 v[138:141], v[82:85], v[146:149], v[138:141]
	v_mfma_f32_16x16x32_bf16 v[126:129], v[70:73], v[154:157], v[126:129]
	v_mfma_f32_16x16x32_bf16 v[122:125], v[82:85], v[154:157], v[122:125]
	v_mfma_f32_16x16x32_bf16 v[110:113], v[70:73], v[162:165], v[110:113]
	v_mfma_f32_16x16x32_bf16 v[106:109], v[82:85], v[162:165], v[106:109]
	v_mfma_f32_16x16x32_bf16 v[94:97], v[70:73], v[170:173], v[94:97]
	v_mfma_f32_16x16x32_bf16 v[90:93], v[82:85], v[170:173], v[90:93]
	v_mfma_f32_16x16x32_bf16 v[142:145], v[74:77], v[150:153], v[142:145]
	v_mfma_f32_16x16x32_bf16 v[138:141], v[86:89], v[150:153], v[138:141]
	v_mfma_f32_16x16x32_bf16 v[126:129], v[74:77], v[158:161], v[126:129]
	v_mfma_f32_16x16x32_bf16 v[122:125], v[86:89], v[158:161], v[122:125]
	v_mfma_f32_16x16x32_bf16 v[110:113], v[74:77], v[166:169], v[110:113]
	v_mfma_f32_16x16x32_bf16 v[106:109], v[86:89], v[166:169], v[106:109]
	v_mfma_f32_16x16x32_bf16 v[94:97], v[74:77], v[184:187], v[94:97]
	v_mfma_f32_16x16x32_bf16 v[90:93], v[86:89], v[184:187], v[90:93]
	s_barrier
	s_add_i32 s24, 0, 0x1c000
	s_add_i32 s22, s65, s52
	s_mov_b32 m0, s22
	ds_read_b128 v[194:197], v250 offset:49152
	ds_read_b128 v[198:201], v250 offset:50176
	ds_read_b128 v[202:205], v250 offset:51200
	ds_read_b128 v[212:215], v250 offset:52224
	global_load_lds_dwordx4 v0, s[100:101]
	s_add_i32 m0, s22, 0x2000
	s_nop 0
	global_load_lds_dwordx4 v174, s[100:101]
	s_barrier
	s_waitcnt lgkmcnt(0)
	v_mfma_f32_16x16x32_bf16 v[134:137], v[194:197], v[146:149], v[134:137]
	v_mfma_f32_16x16x32_bf16 v[130:133], v[202:205], v[146:149], v[130:133]
	v_mfma_f32_16x16x32_bf16 v[118:121], v[194:197], v[154:157], v[118:121]
	v_mfma_f32_16x16x32_bf16 v[114:117], v[202:205], v[154:157], v[114:117]
	v_mfma_f32_16x16x32_bf16 v[102:105], v[194:197], v[162:165], v[102:105]
	v_mfma_f32_16x16x32_bf16 v[98:101], v[202:205], v[162:165], v[98:101]
	v_mfma_f32_16x16x32_bf16 v[78:81], v[194:197], v[170:173], v[78:81]
	v_mfma_f32_16x16x32_bf16 v[66:69], v[202:205], v[170:173], v[66:69]
	v_mfma_f32_16x16x32_bf16 v[134:137], v[198:201], v[150:153], v[134:137]
	v_mfma_f32_16x16x32_bf16 v[130:133], v[212:215], v[150:153], v[130:133]
	v_mfma_f32_16x16x32_bf16 v[118:121], v[198:201], v[158:161], v[118:121]
	v_mfma_f32_16x16x32_bf16 v[114:117], v[212:215], v[158:161], v[114:117]
	v_mfma_f32_16x16x32_bf16 v[102:105], v[198:201], v[166:169], v[102:105]
	v_mfma_f32_16x16x32_bf16 v[98:101], v[212:215], v[166:169], v[98:101]
	v_mfma_f32_16x16x32_bf16 v[78:81], v[198:201], v[184:187], v[78:81]
	v_mfma_f32_16x16x32_bf16 v[66:69], v[212:215], v[184:187], v[66:69]
	s_mov_b32 m0, s58
	s_barrier
	ds_read_b128 v[146:149], v211 offset:49152
	ds_read_b128 v[150:153], v211 offset:50176
	ds_read_b128 v[154:157], v211 offset:51200
	ds_read_b128 v[158:161], v211 offset:52224
	ds_read_b128 v[162:165], v211 offset:53248
	ds_read_b128 v[166:169], v211 offset:54272
	ds_read_b128 v[170:173], v211 offset:55296
	ds_read_b128 v[184:187], v211 offset:56320
	global_load_lds_dwordx4 v188, vcc
	s_mov_b32 m0, s59
	s_nop 0
	global_load_lds_dwordx4 v176, vcc
	s_barrier
	s_waitcnt lgkmcnt(0)
	v_mfma_f32_16x16x32_bf16 v[62:65], v[70:73], v[146:149], v[62:65]
	v_mfma_f32_16x16x32_bf16 v[58:61], v[82:85], v[146:149], v[58:61]
	v_mfma_f32_16x16x32_bf16 v[46:49], v[70:73], v[154:157], v[46:49]
	v_mfma_f32_16x16x32_bf16 v[42:45], v[82:85], v[154:157], v[42:45]
	v_mfma_f32_16x16x32_bf16 v[30:33], v[70:73], v[162:165], v[30:33]
	v_mfma_f32_16x16x32_bf16 v[26:29], v[82:85], v[162:165], v[26:29]
	v_mfma_f32_16x16x32_bf16 v[14:17], v[70:73], v[170:173], v[14:17]
	v_mfma_f32_16x16x32_bf16 v[10:13], v[82:85], v[170:173], v[10:13]
	v_mfma_f32_16x16x32_bf16 v[62:65], v[74:77], v[150:153], v[62:65]
	v_mfma_f32_16x16x32_bf16 v[58:61], v[86:89], v[150:153], v[58:61]
	v_mfma_f32_16x16x32_bf16 v[46:49], v[74:77], v[158:161], v[46:49]
	v_mfma_f32_16x16x32_bf16 v[42:45], v[86:89], v[158:161], v[42:45]
	v_mfma_f32_16x16x32_bf16 v[30:33], v[74:77], v[166:169], v[30:33]
	v_mfma_f32_16x16x32_bf16 v[26:29], v[86:89], v[166:169], v[26:29]
	v_mfma_f32_16x16x32_bf16 v[14:17], v[74:77], v[184:187], v[14:17]
	v_mfma_f32_16x16x32_bf16 v[10:13], v[86:89], v[184:187], v[10:13]
	s_barrier
; __device__ __forceinline__ unsigned cvt_pk_bf16(float lo, float hi) { unsigned r; asm volatile("v_cvt_pk_bf16_f32 %0, %1, %2" : "=v"(r) : "v"(lo), "v"(hi)); return r; }
; #define PG8_WAIT_V(n) asm volatile("s_waitcnt vmcnt(" #n ")" ::: "memory")
; #define PG8_BAR __builtin_amdgcn_s_barrier()
; template <class Epi>
; __device__ __forceinline__ void gemm_phase(LAS unsigned char* lds, const Gemm g, const StaticOrder& S, const Epi& E) {
;     ...
;             PG8_STAGE(PG8_SB(1, 1), b3 + hstepB, voffB);
;             PG8_WAIT_V(6); PG8_BAR; PG8_MMA(1, 1, At, B1); PG8_BAR;
;     __device__ __forceinline__ void operator()(const f32x4 (&acc)[2][2][4][2], const Unit& u, int wr, int wc, int fr, int fq, const Pre&) const {
;         const int row0 = u.pm * BM + wr * 64 + fr, col0 = u.pn * BM + wc * 32 + 4 * fq;
;         f32x4 gv[2][2];
; #pragma unroll
;         for (int bj = 0; bj < 2; ++bj)
; #pragma unroll
;             for (int n = 0; n < 2; ++n) gv[bj][n] = *(const f32x4*)(gnext + col0 + bj * HALF + n * 16);
;         f32x4 xb[2][2][2];
; #pragma unroll
;         for (int bj = 0; bj < 2; ++bj)
; #pragma unroll
;             for (int n = 0; n < 2; ++n) xb[0][bj][n] = *(const f32x4*)(Xin + (size_t)row0 * DM + col0 + bj * HALF + n * 16);
; #pragma unroll
;         for (int grp = 0; grp < 8; ++grp) { const int ai = grp >> 2, m = grp & 3, cur = grp & 1; const int r = row0 + ai * HALF + m * 16; float ss = 0.f;
;             if (grp < 7) { const int rn = row0 + ((grp + 1) >> 2) * HALF + ((grp + 1) & 3) * 16;
; #pragma unroll
;                 for (int bj = 0; bj < 2; ++bj)
; #pragma unroll
;                     for (int n = 0; n < 2; ++n) xb[cur ^ 1][bj][n] = *(const f32x4*)(Xin + (size_t)rn * DM + col0 + bj * HALF + n * 16); }
; #pragma unroll
;             for (int bj = 0; bj < 2; ++bj)
; #pragma unroll
;                 for (int n = 0; n < 2; ++n) { const int c = col0 + bj * HALF + n * 16;
;                     const f32x4 xv = xb[cur][bj][n] + acc[ai][bj][m][n]; *(f32x4*)(X + (size_t)r * DM + c) = xv;
;                     ss += (xv[0] * xv[0] + xv[1] * xv[1]) + (xv[2] * xv[2] + xv[3] * xv[3]);
;                     if (H) { const f32x4 hv = xv * gv[bj][n]; u32x2 w; w.x = cvt_pk_bf16(hv[0], hv[1]); w.y = cvt_pk_bf16(hv[2], hv[3]);
;                         *(u32x2*)(H + (size_t)r * DM + c) = w; } }
	s_add_u32 s22, s36, 0x100080
	s_addc_u32 s23, s37, 0
	s_add_i32 s24, s24, s52
	s_mov_b32 m0, s24
	s_nop 0
	global_load_lds_dwordx4 v0, s[22:23]
	s_add_i32 m0, s24, 0x2000
	s_nop 0
	global_load_lds_dwordx4 v174, s[22:23]
	s_waitcnt vmcnt(6)
	s_barrier
	v_mfma_f32_16x16x32_bf16 v[54:57], v[194:197], v[146:149], v[54:57]
	v_mfma_f32_16x16x32_bf16 v[50:53], v[202:205], v[146:149], v[50:53]
	v_mfma_f32_16x16x32_bf16 v[38:41], v[194:197], v[154:157], v[38:41]
	v_mfma_f32_16x16x32_bf16 v[34:37], v[202:205], v[154:157], v[34:37]
	v_mfma_f32_16x16x32_bf16 v[22:25], v[194:197], v[162:165], v[22:25]
	v_mfma_f32_16x16x32_bf16 v[18:21], v[202:205], v[162:165], v[18:21]
	v_mfma_f32_16x16x32_bf16 v[6:9], v[194:197], v[170:173], v[6:9]
	v_mfma_f32_16x16x32_bf16 v[2:5], v[202:205], v[170:173], v[2:5]
	v_mfma_f32_16x16x32_bf16 v[54:57], v[198:201], v[150:153], v[54:57]
	v_mfma_f32_16x16x32_bf16 v[50:53], v[212:215], v[150:153], v[50:53]
	v_mfma_f32_16x16x32_bf16 v[38:41], v[198:201], v[158:161], v[38:41]
	v_mfma_f32_16x16x32_bf16 v[34:37], v[212:215], v[158:161], v[34:37]
	v_mfma_f32_16x16x32_bf16 v[22:25], v[198:201], v[166:169], v[22:25]
	v_mfma_f32_16x16x32_bf16 v[18:21], v[212:215], v[166:169], v[18:21]
	v_mfma_f32_16x16x32_bf16 v[6:9], v[198:201], v[184:187], v[6:9]
	v_mfma_f32_16x16x32_bf16 v[2:5], v[212:215], v[184:187], v[2:5]
	s_add_i32 s64, s64, 2
	s_add_u32 s62, s62, 0x100
	s_addc_u32 s63, s63, 0
	s_cmp_gt_u32 s64, 61
	s_mov_b64 s[22:23], s[26:27]
	s_barrier
	s_cbranch_scc0 .LBB0_359
	s_setprio 0
	v_lshl_add_u32 v198, s44, 8, v208
	v_lshl_or_b32 v194, s45, 8, v210
	v_ashrrev_i32_e32 v199, 31, v198
	v_ashrrev_i32_e32 v195, 31, v194
	v_lshlrev_b64 v[204:205], 13, v[198:199]
	v_or_b32_e32 v202, 16, v198
	v_lshlrev_b64 v[196:197], 2, v[194:195]
	v_lshl_add_u64 v[146:147], s[0:1], 0, v[204:205]
	v_ashrrev_i32_e32 v203, 31, v202
	v_lshl_add_u64 v[70:71], s[4:5], 0, v[196:197]
	v_lshl_add_u64 v[146:147], v[146:147], 0, v[196:197]
	v_lshlrev_b64 v[200:201], 13, v[202:203]
	global_load_dwordx4 v[86:89], v[70:71], off
	global_load_dwordx4 v[82:85], v[70:71], off offset:64
	global_load_dwordx4 v[74:77], v[70:71], off offset:512
	s_nop 0
	global_load_dwordx4 v[70:73], v[70:71], off offset:576
	s_nop 0
	global_load_dwordx4 v[184:187], v[146:147], off
	global_load_dwordx4 v[170:173], v[146:147], off offset:64
	global_load_dwordx4 v[166:169], v[146:147], off offset:512
	global_load_dwordx4 v[162:165], v[146:147], off offset:576
	v_lshl_add_u64 v[146:147], s[0:1], 0, v[200:201]
	v_lshl_add_u64 v[146:147], v[146:147], 0, v[196:197]
	global_load_dwordx4 v[158:161], v[146:147], off
	global_load_dwordx4 v[154:157], v[146:147], off offset:64
	global_load_dwordx4 v[150:153], v[146:147], off offset:512
	s_nop 0
	global_load_dwordx4 v[146:149], v[146:147], off offset:576
	v_cndmask_b32_e64 v206, 0, 1, s[10:11]
	v_lshlrev_b64 v[212:213], 11, v[198:199]
	v_lshl_add_u64 v[204:205], s[48:49], 0, v[204:205]
	v_cmp_ne_u32_e64 s[44:45], 1, v206
	s_andn2_b64 vcc, exec, s[10:11]
	v_lshl_add_u64 v[206:207], v[204:205], 0, v[196:197]
	v_lshl_add_u64 v[204:205], v[212:213], 1, s[50:51]
	s_waitcnt vmcnt(0)
	v_pk_add_f32 v[144:145], v[144:145], v[186:187]
	v_pk_add_f32 v[142:143], v[142:143], v[184:185]
	global_store_dwordx4 v[206:207], v[142:145], off
	s_cbranch_vccnz .LBB0_362
	v_pk_mul_f32 v[184:185], v[88:89], v[144:145]
	v_pk_mul_f32 v[186:187], v[86:87], v[142:143]
	s_nop 0
	v_cvt_pk_bf16_f32 v186, v186, v187
	v_cvt_pk_bf16_f32 v187, v184, v185
	v_lshl_add_u64 v[184:185], v[194:195], 1, v[204:205]
	global_store_dwordx2 v[184:185], v[186:187], off

; #define PG8_STAGE(bufoff, gbase, voff) do { _Pragma("unroll") for (int _i = 0; _i < 2; ++_i) \
;         __builtin_amdgcn_global_load_lds((const unsigned*)((const char*)(gbase) + (voff)[_i]), (LAS unsigned*)(lds + (bufoff) + ldsw + _i * 8192), 16, 0, 0); } while (0)
; #define PG8_LDA(dst, b, h) do { _Pragma("unroll") for (int m = 0; m < 4; ++m) _Pragma("unroll") for (int k = 0; k < 2; ++k) dst[m][k] = *(const LAS bf16x8*)(lds + PG8_SA(b, h) + aoff + m * 2048 + k * 1024); } while (0)
; #define PG8_LDB(dst, b, h) do { _Pragma("unroll") for (int n = 0; n < 2; ++n) _Pragma("unroll") for (int k = 0; k < 2; ++k) dst[n][k] = *(const LAS bf16x8*)(lds + PG8_SB(b, h) + boff + n * 2048 + k * 1024); } while (0)
; #define PG8_WAIT_V(n) asm volatile("s_waitcnt vmcnt(" #n ")" ::: "memory")
; #define PG8_WAIT_L(n) asm volatile("s_waitcnt lgkmcnt(" #n ")" ::: "memory")
; #define PG8_BAR __builtin_amdgcn_s_barrier()
; #define PG8_SCHED __builtin_amdgcn_sched_barrier(0)
; template <class Epi>
; __device__ __forceinline__ void gemm_phase(LAS unsigned char* lds, const Gemm g, const StaticOrder& S, const Epi& E) {
;     ...
;         const bool has_next = S.next(ui + 1, nxt);
;         const char* nA = has_next ? (const char*)g.A + (size_t)nxt.pm * tstepA + (size_t)(nxt.pn >> 2) * gstepA : cA; const char* nB = has_next ? (const char*)g.Bt + (size_t)nxt.pn * tstepB : cB;
;         for (int t = 0; t < nt; t += 2) {
;             const bool last = (t == nt - 2);
;             const char* a1 = cA + (size_t)(t + 1) * kstepA;
;             const char* a2 = last ? nA : cA + (size_t)(t + 2) * kstepA; const char* b2 = last ? nB : cB + (size_t)(t + 2) * kstep;
;             const char* a3 = a2 + kstepA; const char* b3 = b2 + kstep;
;             PG8_LDB(B0, 0, 0); PG8_SCHED; PG8_LDA(At, 0, 0); PG8_STAGE(PG8_SA(1, 1), a1 + hstepA, voffA);
;             PG8_WAIT_L(8); PG8_BAR; PG8_WAIT_L(0); PG8_MMA(0, 0, At, B0); PG8_BAR; PG8_SCHED;
;             PG8_LDB(B1, 0, 1); PG8_STAGE(PG8_SB(0, 0), b2, voffB);
;             PG8_BAR; PG8_WAIT_L(0); PG8_MMA(0, 1, At, B1); PG8_BAR;
;             PG8_LDA(At, 0, 1); PG8_STAGE(PG8_SA(0, 0), a2, voffA);
;             PG8_BAR; PG8_WAIT_L(0); PG8_MMA(1, 0, At, B0); PG8_BAR; PG8_SCHED;
;             PG8_STAGE(PG8_SB(0, 1), b2 + hstepB, voffB);
;             PG8_WAIT_V(6); PG8_BAR; PG8_MMA(1, 1, At, B1); PG8_BAR;
.LBB0_471:
	s_add_u32 s17, s20, 0x100
	s_addc_u32 s58, s21, 0
	s_ashr_i32 s11, s10, 31
	s_lshl_b64 s[14:15], s[10:11], 21
	s_add_u32 s18, s35, s14
	s_addc_u32 s19, s36, s15
	s_and_b64 s[14:15], s[42:43], exec
	s_cselect_b32 s11, s19, s5
	s_cselect_b32 s59, s18, s4
	s_ashr_i32 s9, s8, 31
	s_lshl_b64 s[14:15], s[8:9], 21
	s_add_u32 s14, s37, s14
	s_addc_u32 s15, s38, s15
	s_and_b64 s[22:23], s[42:43], exec
	s_cselect_b32 s9, s15, s21
	s_cselect_b32 s60, s14, s20
	s_add_u32 s20, s4, 0x100080
	s_addc_u32 s21, s5, 0
	v_lshl_add_u64 v[140:141], s[20:21], 0, v[136:137]
	v_lshl_add_u64 v[142:143], s[20:21], 0, v[138:139]
	s_mov_b32 s61, -2
	s_mov_b64 s[20:21], 0
	v_add_u32_e32 v250, 0x10000, v146
	v_readfirstlane_b32 s100, v232
	s_nop 3
	s_cmp_ge_u32 s100, 0x100
	s_cbranch_scc1 .Lprio_lo_2
	s_setprio 1
.Lprio_lo_2:
.LBB0_472:
	s_add_u32 s22, s4, s20
	s_addc_u32 s23, s5, s21
	s_add_u32 s22, s22, 0x100
	s_addc_u32 s23, s23, 0
	s_add_u32 s62, s17, s20
	s_addc_u32 s63, s58, s21
	s_add_i32 s64, 0, 0x10000
	ds_read_b128 v[148:151], v250
	ds_read_b128 v[152:155], v250 offset:1024
	ds_read_b128 v[156:159], v250 offset:2048
	ds_read_b128 v[160:163], v250 offset:3072
	s_cmpk_eq_i32 s20, 0x1f00
	s_cselect_b32 s25, s11, s23
	s_cselect_b32 s24, s59, s22
	s_cselect_b32 s23, s9, s63
	s_cselect_b32 s22, s60, s62
	v_lshl_add_u64 v[176:177], v[140:141], 0, s[20:21]
	s_add_i32 m0, s48, 0xc000
	ds_read_b128 v[164:167], v147
	ds_read_b128 v[168:171], v147 offset:1024
	ds_read_b128 v[172:175], v147 offset:2048
	ds_read_b128 v[184:187], v147 offset:3072
	ds_read_b128 v[188:191], v147 offset:4096
	ds_read_b128 v[192:195], v147 offset:5120
	ds_read_b128 v[196:199], v147 offset:6144
	ds_read_b128 v[200:203], v147 offset:7168
	global_load_lds_dwordx4 v[176:177], off
	v_lshl_add_u64 v[176:177], v[142:143], 0, s[20:21]
	s_add_i32 m0, s48, 0xe000
	s_nop 0
	global_load_lds_dwordx4 v[176:177], off
	s_waitcnt lgkmcnt(8)
	s_barrier
	s_waitcnt lgkmcnt(0)
	v_mfma_f32_16x16x32_bf16 v[126:129], v[148:151], v[164:167], v[126:129]
	v_mfma_f32_16x16x32_bf16 v[122:125], v[156:159], v[164:167], v[122:125]
	v_mfma_f32_16x16x32_bf16 v[110:113], v[148:151], v[172:175], v[110:113]
	v_mfma_f32_16x16x32_bf16 v[106:109], v[156:159], v[172:175], v[106:109]
	v_mfma_f32_16x16x32_bf16 v[94:97], v[148:151], v[188:191], v[94:97]
	v_mfma_f32_16x16x32_bf16 v[90:93], v[156:159], v[188:191], v[90:93]
	v_mfma_f32_16x16x32_bf16 v[78:81], v[148:151], v[196:199], v[78:81]
	v_mfma_f32_16x16x32_bf16 v[74:77], v[156:159], v[196:199], v[74:77]
	v_mfma_f32_16x16x32_bf16 v[126:129], v[152:155], v[168:171], v[126:129]
	v_mfma_f32_16x16x32_bf16 v[122:125], v[160:163], v[168:171], v[122:125]
	v_mfma_f32_16x16x32_bf16 v[110:113], v[152:155], v[184:187], v[110:113]
	v_mfma_f32_16x16x32_bf16 v[106:109], v[160:163], v[184:187], v[106:109]
	v_mfma_f32_16x16x32_bf16 v[94:97], v[152:155], v[192:195], v[94:97]
	v_mfma_f32_16x16x32_bf16 v[90:93], v[160:163], v[192:195], v[90:93]
	v_mfma_f32_16x16x32_bf16 v[78:81], v[152:155], v[200:203], v[78:81]
	v_mfma_f32_16x16x32_bf16 v[74:77], v[160:163], v[200:203], v[74:77]
	s_barrier
	s_add_i32 s65, 0, 0x14000
	s_add_i32 s62, s64, s39
	ds_read_b128 v[204:207], v250 offset:16384
	ds_read_b128 v[208:211], v250 offset:17408
	ds_read_b128 v[212:215], v250 offset:18432
	ds_read_b128 v[216:219], v250 offset:19456
	s_add_u32 s100, s22, s6
	s_addc_u32 s101, s23, s7
	s_mov_b32 m0, s62
	s_nop 0
	global_load_lds_dwordx4 v0, s[22:23]
	s_add_i32 m0, s62, 0x2000
	s_nop 0
	global_load_lds_dwordx4 v130, s[22:23]
	s_barrier
	s_waitcnt lgkmcnt(0)
	v_mfma_f32_16x16x32_bf16 v[118:121], v[204:207], v[164:167], v[118:121]
	v_mfma_f32_16x16x32_bf16 v[114:117], v[212:215], v[164:167], v[114:117]
	v_mfma_f32_16x16x32_bf16 v[102:105], v[204:207], v[172:175], v[102:105]
	v_mfma_f32_16x16x32_bf16 v[98:101], v[212:215], v[172:175], v[98:101]
	v_mfma_f32_16x16x32_bf16 v[86:89], v[204:207], v[188:191], v[86:89]
	v_mfma_f32_16x16x32_bf16 v[82:85], v[212:215], v[188:191], v[82:85]
	v_mfma_f32_16x16x32_bf16 v[70:73], v[204:207], v[196:199], v[70:73]
	v_mfma_f32_16x16x32_bf16 v[66:69], v[212:215], v[196:199], v[66:69]
	v_mfma_f32_16x16x32_bf16 v[118:121], v[208:211], v[168:171], v[118:121]
	v_mfma_f32_16x16x32_bf16 v[114:117], v[216:219], v[168:171], v[114:117]
	v_mfma_f32_16x16x32_bf16 v[102:105], v[208:211], v[184:187], v[102:105]
	v_mfma_f32_16x16x32_bf16 v[98:101], v[216:219], v[184:187], v[98:101]
	v_mfma_f32_16x16x32_bf16 v[86:89], v[208:211], v[192:195], v[86:89]
	v_mfma_f32_16x16x32_bf16 v[82:85], v[216:219], v[192:195], v[82:85]
	v_mfma_f32_16x16x32_bf16 v[70:73], v[208:211], v[200:203], v[70:73]
	v_mfma_f32_16x16x32_bf16 v[66:69], v[216:219], v[200:203], v[66:69]
	s_mov_b32 m0, s48
	s_add_u32 vcc_lo, s24, s6
	s_addc_u32 vcc_hi, s25, s7
	s_barrier
	ds_read_b128 v[164:167], v147 offset:16384
	ds_read_b128 v[168:171], v147 offset:17408
	ds_read_b128 v[172:175], v147 offset:18432
	ds_read_b128 v[184:187], v147 offset:19456
	ds_read_b128 v[188:191], v147 offset:20480
	ds_read_b128 v[192:195], v147 offset:21504
	ds_read_b128 v[196:199], v147 offset:22528
	ds_read_b128 v[200:203], v147 offset:23552
	global_load_lds_dwordx4 v134, s[24:25]
	s_mov_b32 m0, s49
	s_nop 0
	global_load_lds_dwordx4 v132, s[24:25]
	s_barrier
; #define PG8_STAGE(bufoff, gbase, voff) do { _Pragma("unroll") for (int _i = 0; _i < 2; ++_i) \
;         __builtin_amdgcn_global_load_lds((const unsigned*)((const char*)(gbase) + (voff)[_i]), (LAS unsigned*)(lds + (bufoff) + ldsw + _i * 8192), 16, 0, 0); } while (0)
; #define PG8_LDA(dst, b, h) do { _Pragma("unroll") for (int m = 0; m < 4; ++m) _Pragma("unroll") for (int k = 0; k < 2; ++k) dst[m][k] = *(const LAS bf16x8*)(lds + PG8_SA(b, h) + aoff + m * 2048 + k * 1024); } while (0)
; #define PG8_LDB(dst, b, h) do { _Pragma("unroll") for (int n = 0; n < 2; ++n) _Pragma("unroll") for (int k = 0; k < 2; ++k) dst[n][k] = *(const LAS bf16x8*)(lds + PG8_SB(b, h) + boff + n * 2048 + k * 1024); } while (0)
; #define PG8_MMA(ai, bj, At, Bt) do { __builtin_amdgcn_s_setprio(1); _Pragma("unroll") for (int m = 0; m < 4; ++m) _Pragma("unroll") for (int n = 0; n < 2; ++n) _Pragma("unroll") for (int k = 0; k < 2; ++k) \
;         acc[ai][bj][m][n] = __builtin_amdgcn_mfma_f32_16x16x32_bf16(Bt[n][k], At[m][k], acc[ai][bj][m][n], 0, 0, 0); __builtin_amdgcn_s_setprio(0); } while (0)
; #define PG8_WAIT_V(n) asm volatile("s_waitcnt vmcnt(" #n ")" ::: "memory")
; #define PG8_WAIT_L(n) asm volatile("s_waitcnt lgkmcnt(" #n ")" ::: "memory")
; #define PG8_BAR __builtin_amdgcn_s_barrier()
; #define PG8_SCHED __builtin_amdgcn_sched_barrier(0)
; template <class Epi>
; __device__ __forceinline__ void gemm_phase(LAS unsigned char* lds, const Gemm g, const StaticOrder& S, const Epi& E) {
;     ...
;             PG8_WAIT_V(6); PG8_BAR; PG8_MMA(1, 1, At, B1); PG8_BAR;
;             PG8_LDB(B0, 1, 0); PG8_SCHED; PG8_LDA(At, 1, 0); PG8_STAGE(PG8_SA(0, 1), a2 + hstepA, voffA);
;             PG8_WAIT_L(8); PG8_BAR; PG8_WAIT_L(0); PG8_MMA(0, 0, At, B0); PG8_BAR; PG8_SCHED;
;             PG8_LDB(B1, 1, 1); PG8_STAGE(PG8_SB(1, 0), b3, voffB);
;             PG8_BAR; PG8_WAIT_L(0); PG8_MMA(0, 1, At, B1); PG8_BAR;
;             PG8_LDA(At, 1, 1); PG8_STAGE(PG8_SA(1, 0), a3, voffA);
;             PG8_BAR; PG8_WAIT_L(0); PG8_MMA(1, 0, At, B0); PG8_BAR; PG8_SCHED;
	s_waitcnt lgkmcnt(0)
	v_mfma_f32_16x16x32_bf16 v[62:65], v[148:151], v[164:167], v[62:65]
	v_mfma_f32_16x16x32_bf16 v[58:61], v[156:159], v[164:167], v[58:61]
	v_mfma_f32_16x16x32_bf16 v[46:49], v[148:151], v[172:175], v[46:49]
	v_mfma_f32_16x16x32_bf16 v[42:45], v[156:159], v[172:175], v[42:45]
	v_mfma_f32_16x16x32_bf16 v[30:33], v[148:151], v[188:191], v[30:33]
	v_mfma_f32_16x16x32_bf16 v[26:29], v[156:159], v[188:191], v[26:29]
	v_mfma_f32_16x16x32_bf16 v[18:21], v[148:151], v[196:199], v[18:21]
	v_mfma_f32_16x16x32_bf16 v[10:13], v[156:159], v[196:199], v[10:13]
	v_mfma_f32_16x16x32_bf16 v[62:65], v[152:155], v[168:171], v[62:65]
	v_mfma_f32_16x16x32_bf16 v[58:61], v[160:163], v[168:171], v[58:61]
	v_mfma_f32_16x16x32_bf16 v[46:49], v[152:155], v[184:187], v[46:49]
	v_mfma_f32_16x16x32_bf16 v[42:45], v[160:163], v[184:187], v[42:45]
	v_mfma_f32_16x16x32_bf16 v[30:33], v[152:155], v[192:195], v[30:33]
	v_mfma_f32_16x16x32_bf16 v[26:29], v[160:163], v[192:195], v[26:29]
	v_mfma_f32_16x16x32_bf16 v[18:21], v[152:155], v[200:203], v[18:21]
	v_mfma_f32_16x16x32_bf16 v[10:13], v[160:163], v[200:203], v[10:13]
	s_barrier
	s_add_u32 s62, s22, 0x100000
	s_addc_u32 s63, s23, 0
	s_add_i32 s64, s65, s39
	s_mov_b32 m0, s64
	s_nop 0
	global_load_lds_dwordx4 v0, s[62:63]
	s_add_i32 m0, s64, 0x2000
	s_nop 0
	global_load_lds_dwordx4 v130, s[62:63]
	s_waitcnt vmcnt(6)
	s_barrier
	v_mfma_f32_16x16x32_bf16 v[54:57], v[204:207], v[164:167], v[54:57]
	v_mfma_f32_16x16x32_bf16 v[50:53], v[212:215], v[164:167], v[50:53]
	v_mfma_f32_16x16x32_bf16 v[38:41], v[204:207], v[172:175], v[38:41]
	v_mfma_f32_16x16x32_bf16 v[34:37], v[212:215], v[172:175], v[34:37]
	v_mfma_f32_16x16x32_bf16 v[22:25], v[204:207], v[188:191], v[22:25]
	v_mfma_f32_16x16x32_bf16 v[14:17], v[212:215], v[188:191], v[14:17]
	v_mfma_f32_16x16x32_bf16 v[6:9], v[204:207], v[196:199], v[6:9]
	v_mfma_f32_16x16x32_bf16 v[2:5], v[212:215], v[196:199], v[2:5]
	v_mfma_f32_16x16x32_bf16 v[54:57], v[208:211], v[168:171], v[54:57]
	v_mfma_f32_16x16x32_bf16 v[50:53], v[216:219], v[168:171], v[50:53]
	v_mfma_f32_16x16x32_bf16 v[38:41], v[208:211], v[184:187], v[38:41]
	v_mfma_f32_16x16x32_bf16 v[34:37], v[216:219], v[184:187], v[34:37]
	v_mfma_f32_16x16x32_bf16 v[22:25], v[208:211], v[192:195], v[22:25]
	v_mfma_f32_16x16x32_bf16 v[14:17], v[216:219], v[192:195], v[14:17]
	v_mfma_f32_16x16x32_bf16 v[6:9], v[208:211], v[200:203], v[6:9]
	v_mfma_f32_16x16x32_bf16 v[2:5], v[216:219], v[200:203], v[2:5]
	s_add_i32 s62, 0, 0x18000
	s_barrier
	ds_read_b128 v[148:151], v250 offset:32768
	ds_read_b128 v[152:155], v250 offset:33792
	ds_read_b128 v[156:159], v250 offset:34816
	ds_read_b128 v[160:163], v250 offset:35840
	s_add_u32 s24, s24, 0x100000
	s_addc_u32 s25, s25, 0
	s_mov_b32 m0, s50
	ds_read_b128 v[164:167], v147 offset:32768
	ds_read_b128 v[168:171], v147 offset:33792
	ds_read_b128 v[172:175], v147 offset:34816
	ds_read_b128 v[184:187], v147 offset:35840
	ds_read_b128 v[188:191], v147 offset:36864
	ds_read_b128 v[192:195], v147 offset:37888
	ds_read_b128 v[196:199], v147 offset:38912
	ds_read_b128 v[200:203], v147 offset:39936
	global_load_lds_dwordx4 v134, s[24:25]
	s_mov_b32 m0, s51
	s_nop 0
	global_load_lds_dwordx4 v132, s[24:25]
	s_waitcnt lgkmcnt(8)
	s_barrier
	s_waitcnt lgkmcnt(0)
	v_mfma_f32_16x16x32_bf16 v[126:129], v[148:151], v[164:167], v[126:129]
	v_mfma_f32_16x16x32_bf16 v[122:125], v[156:159], v[164:167], v[122:125]
	v_mfma_f32_16x16x32_bf16 v[110:113], v[148:151], v[172:175], v[110:113]
	v_mfma_f32_16x16x32_bf16 v[106:109], v[156:159], v[172:175], v[106:109]
	v_mfma_f32_16x16x32_bf16 v[94:97], v[148:151], v[188:191], v[94:97]
	v_mfma_f32_16x16x32_bf16 v[90:93], v[156:159], v[188:191], v[90:93]
	v_mfma_f32_16x16x32_bf16 v[78:81], v[148:151], v[196:199], v[78:81]
	v_mfma_f32_16x16x32_bf16 v[74:77], v[156:159], v[196:199], v[74:77]
	v_mfma_f32_16x16x32_bf16 v[126:129], v[152:155], v[168:171], v[126:129]
	v_mfma_f32_16x16x32_bf16 v[122:125], v[160:163], v[168:171], v[122:125]
	v_mfma_f32_16x16x32_bf16 v[110:113], v[152:155], v[184:187], v[110:113]
	v_mfma_f32_16x16x32_bf16 v[106:109], v[160:163], v[184:187], v[106:109]
	v_mfma_f32_16x16x32_bf16 v[94:97], v[152:155], v[192:195], v[94:97]
	v_mfma_f32_16x16x32_bf16 v[90:93], v[160:163], v[192:195], v[90:93]
	v_mfma_f32_16x16x32_bf16 v[78:81], v[152:155], v[200:203], v[78:81]
	v_mfma_f32_16x16x32_bf16 v[74:77], v[160:163], v[200:203], v[74:77]
	s_barrier
	s_add_i32 s24, 0, 0x1c000
	s_add_i32 s25, s62, s39
	s_mov_b32 m0, s25
	ds_read_b128 v[204:207], v250 offset:49152
	ds_read_b128 v[208:211], v250 offset:50176
	ds_read_b128 v[212:215], v250 offset:51200
	ds_read_b128 v[216:219], v250 offset:52224
	global_load_lds_dwordx4 v0, s[100:101]
	s_add_i32 m0, s25, 0x2000
	s_nop 0
	global_load_lds_dwordx4 v130, s[100:101]
	s_barrier
	s_waitcnt lgkmcnt(0)
	v_mfma_f32_16x16x32_bf16 v[118:121], v[204:207], v[164:167], v[118:121]
	v_mfma_f32_16x16x32_bf16 v[114:117], v[212:215], v[164:167], v[114:117]
	v_mfma_f32_16x16x32_bf16 v[102:105], v[204:207], v[172:175], v[102:105]
	v_mfma_f32_16x16x32_bf16 v[98:101], v[212:215], v[172:175], v[98:101]
	v_mfma_f32_16x16x32_bf16 v[86:89], v[204:207], v[188:191], v[86:89]
	v_mfma_f32_16x16x32_bf16 v[82:85], v[212:215], v[188:191], v[82:85]
	v_mfma_f32_16x16x32_bf16 v[70:73], v[204:207], v[196:199], v[70:73]
	v_mfma_f32_16x16x32_bf16 v[66:69], v[212:215], v[196:199], v[66:69]
	v_mfma_f32_16x16x32_bf16 v[118:121], v[208:211], v[168:171], v[118:121]
	v_mfma_f32_16x16x32_bf16 v[114:117], v[216:219], v[168:171], v[114:117]
	v_mfma_f32_16x16x32_bf16 v[102:105], v[208:211], v[184:187], v[102:105]
	v_mfma_f32_16x16x32_bf16 v[98:101], v[216:219], v[184:187], v[98:101]
	v_mfma_f32_16x16x32_bf16 v[86:89], v[208:211], v[192:195], v[86:89]
	v_mfma_f32_16x16x32_bf16 v[82:85], v[216:219], v[192:195], v[82:85]
	v_mfma_f32_16x16x32_bf16 v[70:73], v[208:211], v[200:203], v[70:73]
	v_mfma_f32_16x16x32_bf16 v[66:69], v[216:219], v[200:203], v[66:69]
	s_mov_b32 m0, s54
	s_barrier
; #define PG8_STAGE(bufoff, gbase, voff) do { _Pragma("unroll") for (int _i = 0; _i < 2; ++_i) \
;         __builtin_amdgcn_global_load_lds((const unsigned*)((const char*)(gbase) + (voff)[_i]), (LAS unsigned*)(lds + (bufoff) + ldsw + _i * 8192), 16, 0, 0); } while (0)
; #define PG8_MMA(ai, bj, At, Bt) do { __builtin_amdgcn_s_setprio(1); _Pragma("unroll") for (int m = 0; m < 4; ++m) _Pragma("unroll") for (int n = 0; n < 2; ++n) _Pragma("unroll") for (int k = 0; k < 2; ++k) \
;         acc[ai][bj][m][n] = __builtin_amdgcn_mfma_f32_16x16x32_bf16(Bt[n][k], At[m][k], acc[ai][bj][m][n], 0, 0, 0); __builtin_amdgcn_s_setprio(0); } while (0)
; #define PG8_WAIT_V(n) asm volatile("s_waitcnt vmcnt(" #n ")" ::: "memory")
; #define PG8_WAIT_L(n) asm volatile("s_waitcnt lgkmcnt(" #n ")" ::: "memory")
; #define PG8_BAR __builtin_amdgcn_s_barrier()
; #define PG8_SCHED __builtin_amdgcn_sched_barrier(0)
; template <class Epi>
; __device__ __forceinline__ void gemm_phase(LAS unsigned char* lds, const Gemm g, const StaticOrder& S, const Epi& E) {
;     ...
;             PG8_BAR; PG8_WAIT_L(0); PG8_MMA(1, 0, At, B0); PG8_BAR; PG8_SCHED;
;             PG8_STAGE(PG8_SB(1, 1), b3 + hstepB, voffB);
;             PG8_WAIT_V(6); PG8_BAR; PG8_MMA(1, 1, At, B1); PG8_BAR;
;         }
;         if constexpr (!Epi::AFTER_DRAIN) E(acc, cur, wr, wc, fr, fq, pre);
;         if (!has_next) break;
; #pragma unroll
;         for (int a = 0; a < 2; ++a)
; #pragma unroll
;             for (int b = 0; b < 2; ++b)
; #pragma unroll
;                 for (int m = 0; m < 4; ++m)
; #pragma unroll
;                     for (int n = 0; n < 2; ++n) acc[a][b][m][n] = (f32x4){0.f, 0.f, 0.f, 0.f};
;         cur = nxt; cA = nA; cB = nB; ++ui;
	ds_read_b128 v[164:167], v147 offset:49152
	ds_read_b128 v[168:171], v147 offset:50176
	ds_read_b128 v[172:175], v147 offset:51200
	ds_read_b128 v[184:187], v147 offset:52224
	ds_read_b128 v[188:191], v147 offset:53248
	ds_read_b128 v[192:195], v147 offset:54272
	ds_read_b128 v[196:199], v147 offset:55296
	ds_read_b128 v[200:203], v147 offset:56320
	global_load_lds_dwordx4 v134, vcc
	s_mov_b32 m0, s55
	s_nop 0
	global_load_lds_dwordx4 v132, vcc
	s_barrier
	s_waitcnt lgkmcnt(0)
	v_mfma_f32_16x16x32_bf16 v[62:65], v[148:151], v[164:167], v[62:65]
	v_mfma_f32_16x16x32_bf16 v[58:61], v[156:159], v[164:167], v[58:61]
	v_mfma_f32_16x16x32_bf16 v[46:49], v[148:151], v[172:175], v[46:49]
	v_mfma_f32_16x16x32_bf16 v[42:45], v[156:159], v[172:175], v[42:45]
	v_mfma_f32_16x16x32_bf16 v[30:33], v[148:151], v[188:191], v[30:33]
	v_mfma_f32_16x16x32_bf16 v[26:29], v[156:159], v[188:191], v[26:29]
	v_mfma_f32_16x16x32_bf16 v[18:21], v[148:151], v[196:199], v[18:21]
	v_mfma_f32_16x16x32_bf16 v[10:13], v[156:159], v[196:199], v[10:13]
	v_mfma_f32_16x16x32_bf16 v[62:65], v[152:155], v[168:171], v[62:65]
	v_mfma_f32_16x16x32_bf16 v[58:61], v[160:163], v[168:171], v[58:61]
	v_mfma_f32_16x16x32_bf16 v[46:49], v[152:155], v[184:187], v[46:49]
	v_mfma_f32_16x16x32_bf16 v[42:45], v[160:163], v[184:187], v[42:45]
	v_mfma_f32_16x16x32_bf16 v[30:33], v[152:155], v[192:195], v[30:33]
	v_mfma_f32_16x16x32_bf16 v[26:29], v[160:163], v[192:195], v[26:29]
	v_mfma_f32_16x16x32_bf16 v[18:21], v[152:155], v[200:203], v[18:21]
	v_mfma_f32_16x16x32_bf16 v[10:13], v[160:163], v[200:203], v[10:13]
	s_barrier
	s_add_u32 s22, s22, 0x100080
	s_addc_u32 s23, s23, 0
	s_add_i32 s24, s24, s39
	s_mov_b32 m0, s24
	s_nop 0
	global_load_lds_dwordx4 v0, s[22:23]
	s_add_i32 m0, s24, 0x2000
	s_nop 0
	global_load_lds_dwordx4 v130, s[22:23]
	s_waitcnt vmcnt(6)
	s_barrier
	v_mfma_f32_16x16x32_bf16 v[54:57], v[204:207], v[164:167], v[54:57]
	v_mfma_f32_16x16x32_bf16 v[50:53], v[212:215], v[164:167], v[50:53]
	v_mfma_f32_16x16x32_bf16 v[38:41], v[204:207], v[172:175], v[38:41]
	v_mfma_f32_16x16x32_bf16 v[34:37], v[212:215], v[172:175], v[34:37]
	v_mfma_f32_16x16x32_bf16 v[22:25], v[204:207], v[188:191], v[22:25]
	v_mfma_f32_16x16x32_bf16 v[14:17], v[212:215], v[188:191], v[14:17]
	v_mfma_f32_16x16x32_bf16 v[6:9], v[204:207], v[196:199], v[6:9]
	v_mfma_f32_16x16x32_bf16 v[2:5], v[212:215], v[196:199], v[2:5]
	v_mfma_f32_16x16x32_bf16 v[54:57], v[208:211], v[168:171], v[54:57]
	v_mfma_f32_16x16x32_bf16 v[50:53], v[216:219], v[168:171], v[50:53]
	v_mfma_f32_16x16x32_bf16 v[38:41], v[208:211], v[184:187], v[38:41]
	v_mfma_f32_16x16x32_bf16 v[34:37], v[216:219], v[184:187], v[34:37]
	v_mfma_f32_16x16x32_bf16 v[22:25], v[208:211], v[192:195], v[22:25]
	v_mfma_f32_16x16x32_bf16 v[14:17], v[216:219], v[192:195], v[14:17]
	v_mfma_f32_16x16x32_bf16 v[6:9], v[208:211], v[200:203], v[6:9]
	v_mfma_f32_16x16x32_bf16 v[2:5], v[216:219], v[200:203], v[2:5]
	s_add_i32 s61, s61, 2
	s_add_u32 s20, s20, 0x100
	s_addc_u32 s21, s21, 0
	s_cmp_gt_u32 s61, 61
	s_barrier
	s_cbranch_scc0 .LBB0_472
	s_setprio 0
	s_add_u32 s20, s17, 0xffffff00
	s_addc_u32 s21, s58, -1
	s_andn2_b64 vcc, exec, s[42:43]
	s_cbranch_vccnz .LBB0_463
	v_mov_b32_e32 v2, 0
	s_mov_b32 s57, s8
	s_mov_b32 s26, s10
	s_mov_b64 s[4:5], s[18:19]
	s_mov_b32 s56, s16
	v_mov_b32_e32 v3, v2
	v_mov_b32_e32 v4, v2
	v_mov_b32_e32 v5, v2
	v_mov_b32_e32 v6, v2
	v_mov_b32_e32 v7, v2
	v_mov_b32_e32 v8, v2
	v_mov_b32_e32 v9, v2
	v_mov_b32_e32 v14, v2
	v_mov_b32_e32 v15, v2
	v_mov_b32_e32 v16, v2
	v_mov_b32_e32 v17, v2
	v_mov_b32_e32 v22, v2
	v_mov_b32_e32 v23, v2
	v_mov_b32_e32 v24, v2
	v_mov_b32_e32 v25, v2
	v_mov_b32_e32 v34, v2
	v_mov_b32_e32 v35, v2
	v_mov_b32_e32 v36, v2
	v_mov_b32_e32 v37, v2
	v_mov_b32_e32 v38, v2
	v_mov_b32_e32 v39, v2
	v_mov_b32_e32 v40, v2
	v_mov_b32_e32 v41, v2
	v_mov_b32_e32 v50, v2
	v_mov_b32_e32 v51, v2
	v_mov_b32_e32 v52, v2
	v_mov_b32_e32 v53, v2
	v_mov_b32_e32 v54, v2
	v_mov_b32_e32 v55, v2
	v_mov_b32_e32 v56, v2
	v_mov_b32_e32 v57, v2
	v_mov_b32_e32 v10, v2
	v_mov_b32_e32 v11, v2
	v_mov_b32_e32 v12, v2
	v_mov_b32_e32 v13, v2
	v_mov_b32_e32 v18, v2
	v_mov_b32_e32 v19, v2
	v_mov_b32_e32 v20, v2
	v_mov_b32_e32 v21, v2
	v_mov_b32_e32 v26, v2
	v_mov_b32_e32 v27, v2
	v_mov_b32_e32 v28, v2
	v_mov_b32_e32 v29, v2
	v_mov_b32_e32 v30, v2
	v_mov_b32_e32 v31, v2
	v_mov_b32_e32 v32, v2
	v_mov_b32_e32 v33, v2
	v_mov_b32_e32 v42, v2
	v_mov_b32_e32 v43, v2
	v_mov_b32_e32 v44, v2
	v_mov_b32_e32 v45, v2
	v_mov_b32_e32 v46, v2
	v_mov_b32_e32 v47, v2
	v_mov_b32_e32 v48, v2
	v_mov_b32_e32 v49, v2
	v_mov_b32_e32 v58, v2
	v_mov_b32_e32 v59, v2
	v_mov_b32_e32 v60, v2
	v_mov_b32_e32 v61, v2
	v_mov_b32_e32 v62, v2
	v_mov_b32_e32 v63, v2
	v_mov_b32_e32 v64, v2
	v_mov_b32_e32 v65, v2
	v_mov_b32_e32 v66, v2
	v_mov_b32_e32 v67, v2
	v_mov_b32_e32 v68, v2
	v_mov_b32_e32 v69, v2
	v_mov_b32_e32 v70, v2
	v_mov_b32_e32 v71, v2
	v_mov_b32_e32 v72, v2
	v_mov_b32_e32 v73, v2
	v_mov_b32_e32 v82, v2
	v_mov_b32_e32 v83, v2
	v_mov_b32_e32 v84, v2
	v_mov_b32_e32 v85, v2
	v_mov_b32_e32 v86, v2
	v_mov_b32_e32 v87, v2
	v_mov_b32_e32 v88, v2
	v_mov_b32_e32 v89, v2
	v_mov_b32_e32 v98, v2
	v_mov_b32_e32 v99, v2
	v_mov_b32_e32 v100, v2
	v_mov_b32_e32 v101, v2
	v_mov_b32_e32 v102, v2
	v_mov_b32_e32 v103, v2
	v_mov_b32_e32 v104, v2
	v_mov_b32_e32 v105, v2
	v_mov_b32_e32 v114, v2
	v_mov_b32_e32 v115, v2
	v_mov_b32_e32 v116, v2
	v_mov_b32_e32 v117, v2
	v_mov_b32_e32 v118, v2
	v_mov_b32_e32 v119, v2
	v_mov_b32_e32 v120, v2
	v_mov_b32_e32 v121, v2
	v_mov_b32_e32 v74, v2
	v_mov_b32_e32 v75, v2
	v_mov_b32_e32 v76, v2
	v_mov_b32_e32 v77, v2
	v_mov_b32_e32 v78, v2
	v_mov_b32_e32 v79, v2
	v_mov_b32_e32 v80, v2
	v_mov_b32_e32 v81, v2
	v_mov_b32_e32 v90, v2
	v_mov_b32_e32 v91, v2
	v_mov_b32_e32 v92, v2
	v_mov_b32_e32 v93, v2
	v_mov_b32_e32 v94, v2
	v_mov_b32_e32 v95, v2
	v_mov_b32_e32 v96, v2
	v_mov_b32_e32 v97, v2
	v_mov_b32_e32 v106, v2
	v_mov_b32_e32 v107, v2
	v_mov_b32_e32 v108, v2
	v_mov_b32_e32 v109, v2
	v_mov_b32_e32 v110, v2
	v_mov_b32_e32 v111, v2
	v_mov_b32_e32 v112, v2
	v_mov_b32_e32 v113, v2
	v_mov_b32_e32 v122, v2
	v_mov_b32_e32 v123, v2
	v_mov_b32_e32 v124, v2
	v_mov_b32_e32 v125, v2
	v_mov_b32_e32 v126, v2
	v_mov_b32_e32 v127, v2
	v_mov_b32_e32 v128, v2
	v_mov_b32_e32 v129, v2
	s_andn2_b64 vcc, exec, s[40:41]
	s_cbranch_vccnz .LBB0_464

; #define PG8_STAGE(bufoff, gbase, voff) do { _Pragma("unroll") for (int _i = 0; _i < 2; ++_i) \
;         __builtin_amdgcn_global_load_lds((const unsigned*)((const char*)(gbase) + (voff)[_i]), (LAS unsigned*)(lds + (bufoff) + ldsw + _i * 8192), 16, 0, 0); } while (0)
; #define PG8_LDA(dst, b, h) do { _Pragma("unroll") for (int m = 0; m < 4; ++m) _Pragma("unroll") for (int k = 0; k < 2; ++k) dst[m][k] = *(const LAS bf16x8*)(lds + PG8_SA(b, h) + aoff + m * 2048 + k * 1024); } while (0)
; #define PG8_LDB(dst, b, h) do { _Pragma("unroll") for (int n = 0; n < 2; ++n) _Pragma("unroll") for (int k = 0; k < 2; ++k) dst[n][k] = *(const LAS bf16x8*)(lds + PG8_SB(b, h) + boff + n * 2048 + k * 1024); } while (0)
; #define PG8_MMA(ai, bj, At, Bt) do { __builtin_amdgcn_s_setprio(1); _Pragma("unroll") for (int m = 0; m < 4; ++m) _Pragma("unroll") for (int n = 0; n < 2; ++n) _Pragma("unroll") for (int k = 0; k < 2; ++k) \
;         acc[ai][bj][m][n] = __builtin_amdgcn_mfma_f32_16x16x32_bf16(Bt[n][k], At[m][k], acc[ai][bj][m][n], 0, 0, 0); __builtin_amdgcn_s_setprio(0); } while (0)
; #define PG8_WAIT_L(n) asm volatile("s_waitcnt lgkmcnt(" #n ")" ::: "memory")
; #define PG8_BAR __builtin_amdgcn_s_barrier()
; template <class Epi>
; __device__ __forceinline__ void gemm_phase(LAS unsigned char* lds, const Gemm g, const StaticOrder& S, const Epi& E) {
;     ...
; #pragma unroll
;     for (int a = 0; a < 2; ++a)
; #pragma unroll
;         for (int b = 0; b < 2; ++b)
; #pragma unroll
;             for (int m = 0; m < 4; ++m)
; #pragma unroll
;                 for (int n = 0; n < 2; ++n) acc[a][b][m][n] = (f32x4){0.f, 0.f, 0.f, 0.f};
;     ...
;         const char* nA = has_next ? (const char*)g.A + (size_t)nxt.pm * tstepA + (size_t)(nxt.pn >> 2) * gstepA : cA; const char* nB = has_next ? (const char*)g.Bt + (size_t)nxt.pn * tstepB : cB;
;         for (int t = 0; t < nt; t += 2) {
;             const bool last = (t == nt - 2);
;             const char* a1 = cA + (size_t)(t + 1) * kstepA;
;             const char* a2 = last ? nA : cA + (size_t)(t + 2) * kstepA; const char* b2 = last ? nB : cB + (size_t)(t + 2) * kstep;
;             const char* a3 = a2 + kstepA; const char* b3 = b2 + kstep;
;             PG8_LDB(B0, 0, 0); PG8_SCHED; PG8_LDA(At, 0, 0); PG8_STAGE(PG8_SA(1, 1), a1 + hstepA, voffA);
;             PG8_WAIT_L(8); PG8_BAR; PG8_WAIT_L(0); PG8_MMA(0, 0, At, B0); PG8_BAR; PG8_SCHED;
.LBB0_602:
	s_ashr_i32 s53, s52, 31
	v_cmp_lt_i64_e32 vcc, s[4:5], v[182:183]
	s_lshl_b64 s[4:5], s[52:53], 21
	s_add_u32 s10, s15, s4
	s_addc_u32 s11, s16, s5
	s_ashr_i32 s4, s50, 2
	s_ashr_i32 s5, s4, 31
	s_lshl_b64 s[4:5], s[4:5], 11
	s_add_u32 s54, s10, s4
	s_addc_u32 s55, s11, s5
	s_and_b64 s[4:5], vcc, exec
	s_cselect_b32 s35, s55, s1
	s_cselect_b32 s36, s54, s0
	s_ashr_i32 s51, s50, 31
	s_lshl_b64 s[4:5], s[50:51], 19
	s_add_u32 s56, s17, s4
	s_addc_u32 s57, s18, s5
	s_and_b64 s[4:5], vcc, exec
	s_cselect_b32 s37, s57, s9
	s_cselect_b32 s51, s56, s8
	s_add_u32 s53, s8, 0x100
	v_mov_b32_e32 v2, 0
	s_addc_u32 s58, s9, 0
	s_mov_b32 s59, -2
	v_mov_b32_e32 v3, v2
	v_mov_b32_e32 v4, v2
	v_mov_b32_e32 v5, v2
	v_mov_b32_e32 v6, v2
	v_mov_b32_e32 v7, v2
	v_mov_b32_e32 v8, v2
	v_mov_b32_e32 v9, v2
	v_mov_b32_e32 v10, v2
	v_mov_b32_e32 v11, v2
	v_mov_b32_e32 v12, v2
	v_mov_b32_e32 v13, v2
	v_mov_b32_e32 v14, v2
	v_mov_b32_e32 v15, v2
	v_mov_b32_e32 v16, v2
	v_mov_b32_e32 v17, v2
	v_mov_b32_e32 v18, v2
	v_mov_b32_e32 v19, v2
	v_mov_b32_e32 v20, v2
	v_mov_b32_e32 v21, v2
	v_mov_b32_e32 v22, v2
	v_mov_b32_e32 v23, v2
	v_mov_b32_e32 v24, v2
	v_mov_b32_e32 v25, v2
	v_mov_b32_e32 v26, v2
	v_mov_b32_e32 v27, v2
	v_mov_b32_e32 v28, v2
	v_mov_b32_e32 v29, v2
	v_mov_b32_e32 v30, v2
	v_mov_b32_e32 v31, v2
	v_mov_b32_e32 v32, v2
	v_mov_b32_e32 v33, v2
	v_mov_b32_e32 v74, v2
	v_mov_b32_e32 v75, v2
	v_mov_b32_e32 v76, v2
	v_mov_b32_e32 v77, v2
	v_mov_b32_e32 v78, v2
	v_mov_b32_e32 v79, v2
	v_mov_b32_e32 v80, v2
	v_mov_b32_e32 v81, v2
	v_mov_b32_e32 v82, v2
	v_mov_b32_e32 v83, v2
	v_mov_b32_e32 v84, v2
	v_mov_b32_e32 v85, v2
	v_mov_b32_e32 v86, v2
	v_mov_b32_e32 v87, v2
	v_mov_b32_e32 v88, v2
	v_mov_b32_e32 v89, v2
	v_mov_b32_e32 v90, v2
	v_mov_b32_e32 v91, v2
	v_mov_b32_e32 v92, v2
	v_mov_b32_e32 v93, v2
	v_mov_b32_e32 v94, v2
	v_mov_b32_e32 v95, v2
	v_mov_b32_e32 v96, v2
	v_mov_b32_e32 v97, v2
	v_mov_b32_e32 v110, v2
	v_mov_b32_e32 v111, v2
	v_mov_b32_e32 v112, v2
	v_mov_b32_e32 v113, v2
	v_mov_b32_e32 v114, v2
	v_mov_b32_e32 v115, v2
	v_mov_b32_e32 v116, v2
	v_mov_b32_e32 v117, v2
	v_mov_b32_e32 v42, v2
	v_mov_b32_e32 v43, v2
	v_mov_b32_e32 v44, v2
	v_mov_b32_e32 v45, v2
	v_mov_b32_e32 v46, v2
	v_mov_b32_e32 v47, v2
	v_mov_b32_e32 v48, v2
	v_mov_b32_e32 v49, v2
	v_mov_b32_e32 v50, v2
	v_mov_b32_e32 v51, v2
	v_mov_b32_e32 v52, v2
	v_mov_b32_e32 v53, v2
	v_mov_b32_e32 v54, v2
	v_mov_b32_e32 v55, v2
	v_mov_b32_e32 v56, v2
	v_mov_b32_e32 v57, v2
	v_mov_b32_e32 v58, v2
	v_mov_b32_e32 v59, v2
	v_mov_b32_e32 v60, v2
	v_mov_b32_e32 v61, v2
	v_mov_b32_e32 v62, v2
	v_mov_b32_e32 v63, v2
	v_mov_b32_e32 v64, v2
	v_mov_b32_e32 v65, v2
	v_mov_b32_e32 v66, v2
	v_mov_b32_e32 v67, v2
	v_mov_b32_e32 v68, v2
	v_mov_b32_e32 v69, v2
	v_mov_b32_e32 v70, v2
	v_mov_b32_e32 v71, v2
	v_mov_b32_e32 v72, v2
	v_mov_b32_e32 v73, v2
	v_mov_b32_e32 v122, v2
	v_mov_b32_e32 v123, v2
	v_mov_b32_e32 v124, v2
	v_mov_b32_e32 v125, v2
	v_mov_b32_e32 v126, v2
	v_mov_b32_e32 v127, v2
	v_mov_b32_e32 v128, v2
	v_mov_b32_e32 v129, v2
	v_mov_b32_e32 v134, v2
	v_mov_b32_e32 v135, v2
	v_mov_b32_e32 v136, v2
	v_mov_b32_e32 v137, v2
	v_mov_b32_e32 v138, v2
	v_mov_b32_e32 v139, v2
	v_mov_b32_e32 v140, v2
	v_mov_b32_e32 v141, v2
	v_mov_b32_e32 v146, v2
	v_mov_b32_e32 v147, v2
	v_mov_b32_e32 v148, v2
	v_mov_b32_e32 v149, v2
	v_mov_b32_e32 v150, v2
	v_mov_b32_e32 v151, v2
	v_mov_b32_e32 v152, v2
	v_mov_b32_e32 v153, v2
	v_mov_b32_e32 v162, v2
	v_mov_b32_e32 v163, v2
	v_mov_b32_e32 v164, v2
	v_mov_b32_e32 v165, v2
	v_mov_b32_e32 v166, v2
	v_mov_b32_e32 v167, v2
	v_mov_b32_e32 v168, v2
	v_mov_b32_e32 v169, v2
	v_add_u32_e32 v250, 0x10000, v229
	v_readfirstlane_b32 s100, v232
	s_nop 3
	s_cmp_ge_u32 s100, 0x100
	s_cbranch_scc1 .Lprio_lo_3
	s_setprio 1
.Lprio_lo_3:
.LBB0_603:
	s_add_u32 s8, s0, 0x100
	s_addc_u32 s9, s1, 0
	s_add_i32 s60, 0, 0x10000
	ds_read_b128 v[34:37], v250
	ds_read_b128 v[38:41], v250 offset:1024
	ds_read_b128 v[98:101], v250 offset:2048
	ds_read_b128 v[102:105], v250 offset:3072
	s_cmp_eq_u32 s59, 12
	s_cselect_b32 s11, s35, s9
	s_cselect_b32 s10, s36, s8
	s_cselect_b32 s5, s37, s58
	s_cselect_b32 s4, s51, s53
	s_add_i32 m0, s20, 0xc000
	ds_read_b128 v[106:109], v231
	ds_read_b128 v[118:121], v231 offset:1024
	ds_read_b128 v[130:133], v231 offset:2048
	ds_read_b128 v[142:145], v231 offset:3072
	ds_read_b128 v[154:157], v231 offset:4096
	ds_read_b128 v[158:161], v231 offset:5120
	ds_read_b128 v[170:173], v231 offset:6144
	ds_read_b128 v[174:177], v231 offset:7168
	global_load_lds_dwordx4 v194, s[0:1]
	s_add_i32 m0, s20, 0xe000
	s_nop 0
	global_load_lds_dwordx4 v196, s[0:1]
	s_waitcnt lgkmcnt(8)
	s_barrier
	s_waitcnt lgkmcnt(0)
	v_mfma_f32_16x16x32_bf16 v[166:169], v[34:37], v[106:109], v[166:169]
	v_mfma_f32_16x16x32_bf16 v[162:165], v[98:101], v[106:109], v[162:165]
	v_mfma_f32_16x16x32_bf16 v[150:153], v[34:37], v[130:133], v[150:153]
	v_mfma_f32_16x16x32_bf16 v[146:149], v[98:101], v[130:133], v[146:149]
	v_mfma_f32_16x16x32_bf16 v[138:141], v[34:37], v[154:157], v[138:141]
	v_mfma_f32_16x16x32_bf16 v[134:137], v[98:101], v[154:157], v[134:137]
	v_mfma_f32_16x16x32_bf16 v[126:129], v[34:37], v[170:173], v[126:129]
	v_mfma_f32_16x16x32_bf16 v[122:125], v[98:101], v[170:173], v[122:125]
	v_mfma_f32_16x16x32_bf16 v[166:169], v[38:41], v[118:121], v[166:169]
	v_mfma_f32_16x16x32_bf16 v[162:165], v[102:105], v[118:121], v[162:165]
	v_mfma_f32_16x16x32_bf16 v[150:153], v[38:41], v[142:145], v[150:153]
	v_mfma_f32_16x16x32_bf16 v[146:149], v[102:105], v[142:145], v[146:149]
	v_mfma_f32_16x16x32_bf16 v[138:141], v[38:41], v[158:161], v[138:141]
	v_mfma_f32_16x16x32_bf16 v[134:137], v[102:105], v[158:161], v[134:137]
	v_mfma_f32_16x16x32_bf16 v[126:129], v[38:41], v[174:177], v[126:129]
	v_mfma_f32_16x16x32_bf16 v[122:125], v[102:105], v[174:177], v[122:125]
	s_barrier
; #define PG8_STAGE(bufoff, gbase, voff) do { _Pragma("unroll") for (int _i = 0; _i < 2; ++_i) \
;         __builtin_amdgcn_global_load_lds((const unsigned*)((const char*)(gbase) + (voff)[_i]), (LAS unsigned*)(lds + (bufoff) + ldsw + _i * 8192), 16, 0, 0); } while (0)
; #define PG8_LDA(dst, b, h) do { _Pragma("unroll") for (int m = 0; m < 4; ++m) _Pragma("unroll") for (int k = 0; k < 2; ++k) dst[m][k] = *(const LAS bf16x8*)(lds + PG8_SA(b, h) + aoff + m * 2048 + k * 1024); } while (0)
; #define PG8_LDB(dst, b, h) do { _Pragma("unroll") for (int n = 0; n < 2; ++n) _Pragma("unroll") for (int k = 0; k < 2; ++k) dst[n][k] = *(const LAS bf16x8*)(lds + PG8_SB(b, h) + boff + n * 2048 + k * 1024); } while (0)
; #define PG8_MMA(ai, bj, At, Bt) do { __builtin_amdgcn_s_setprio(1); _Pragma("unroll") for (int m = 0; m < 4; ++m) _Pragma("unroll") for (int n = 0; n < 2; ++n) _Pragma("unroll") for (int k = 0; k < 2; ++k) \
;         acc[ai][bj][m][n] = __builtin_amdgcn_mfma_f32_16x16x32_bf16(Bt[n][k], At[m][k], acc[ai][bj][m][n], 0, 0, 0); __builtin_amdgcn_s_setprio(0); } while (0)
; #define PG8_WAIT_V(n) asm volatile("s_waitcnt vmcnt(" #n ")" ::: "memory")
; #define PG8_WAIT_L(n) asm volatile("s_waitcnt lgkmcnt(" #n ")" ::: "memory")
; #define PG8_BAR __builtin_amdgcn_s_barrier()
; #define PG8_SCHED __builtin_amdgcn_sched_barrier(0)
; template <class Epi>
; __device__ __forceinline__ void gemm_phase(LAS unsigned char* lds, const Gemm g, const StaticOrder& S, const Epi& E) {
;     ...
;             PG8_LDB(B1, 0, 1); PG8_STAGE(PG8_SB(0, 0), b2, voffB);
;             PG8_BAR; PG8_WAIT_L(0); PG8_MMA(0, 1, At, B1); PG8_BAR;
;             PG8_LDA(At, 0, 1); PG8_STAGE(PG8_SA(0, 0), a2, voffA);
;             PG8_BAR; PG8_WAIT_L(0); PG8_MMA(1, 0, At, B0); PG8_BAR; PG8_SCHED;
;             PG8_STAGE(PG8_SB(0, 1), b2 + hstepB, voffB);
;             PG8_WAIT_V(6); PG8_BAR; PG8_MMA(1, 1, At, B1); PG8_BAR;
;             PG8_LDB(B0, 1, 0); PG8_SCHED; PG8_LDA(At, 1, 0); PG8_STAGE(PG8_SA(0, 1), a2 + hstepA, voffA);
;             PG8_WAIT_L(8); PG8_BAR; PG8_WAIT_L(0); PG8_MMA(0, 0, At, B0); PG8_BAR; PG8_SCHED;
;             PG8_LDB(B1, 1, 1); PG8_STAGE(PG8_SB(1, 0), b3, voffB);
;             PG8_BAR; PG8_WAIT_L(0); PG8_MMA(0, 1, At, B1); PG8_BAR;
;             PG8_LDA(At, 1, 1); PG8_STAGE(PG8_SA(1, 0), a3, voffA);
;             PG8_BAR; PG8_WAIT_L(0); PG8_MMA(1, 0, At, B0); PG8_BAR; PG8_SCHED;
	s_add_i32 s61, 0, 0x14000
	s_add_i32 s0, s60, s19
	ds_read_b128 v[198:201], v250 offset:16384
	ds_read_b128 v[202:205], v250 offset:17408
	ds_read_b128 v[206:209], v250 offset:18432
	ds_read_b128 v[210:213], v250 offset:19456
	s_add_u32 s100, s4, s6
	s_addc_u32 s101, s5, s7
	s_mov_b32 m0, s0
	s_nop 0
	global_load_lds_dwordx4 v0, s[4:5]
	s_add_i32 m0, s0, 0x2000
	s_nop 0
	global_load_lds_dwordx4 v188, s[4:5]
	s_barrier
	s_waitcnt lgkmcnt(0)
	v_mfma_f32_16x16x32_bf16 v[70:73], v[198:201], v[106:109], v[70:73]
	v_mfma_f32_16x16x32_bf16 v[66:69], v[206:209], v[106:109], v[66:69]
	v_mfma_f32_16x16x32_bf16 v[62:65], v[198:201], v[130:133], v[62:65]
	v_mfma_f32_16x16x32_bf16 v[58:61], v[206:209], v[130:133], v[58:61]
	v_mfma_f32_16x16x32_bf16 v[54:57], v[198:201], v[154:157], v[54:57]
	v_mfma_f32_16x16x32_bf16 v[50:53], v[206:209], v[154:157], v[50:53]
	v_mfma_f32_16x16x32_bf16 v[46:49], v[198:201], v[170:173], v[46:49]
	v_mfma_f32_16x16x32_bf16 v[42:45], v[206:209], v[170:173], v[42:45]
	v_mfma_f32_16x16x32_bf16 v[70:73], v[202:205], v[118:121], v[70:73]
	v_mfma_f32_16x16x32_bf16 v[66:69], v[210:213], v[118:121], v[66:69]
	v_mfma_f32_16x16x32_bf16 v[62:65], v[202:205], v[142:145], v[62:65]
	v_mfma_f32_16x16x32_bf16 v[58:61], v[210:213], v[142:145], v[58:61]
	v_mfma_f32_16x16x32_bf16 v[54:57], v[202:205], v[158:161], v[54:57]
	v_mfma_f32_16x16x32_bf16 v[50:53], v[210:213], v[158:161], v[50:53]
	v_mfma_f32_16x16x32_bf16 v[46:49], v[202:205], v[174:177], v[46:49]
	v_mfma_f32_16x16x32_bf16 v[42:45], v[210:213], v[174:177], v[42:45]
	s_mov_b32 m0, s20
	s_add_u32 vcc_lo, s10, s6
	s_addc_u32 vcc_hi, s11, s7
	s_barrier
	ds_read_b128 v[106:109], v231 offset:16384
	ds_read_b128 v[118:121], v231 offset:17408
	ds_read_b128 v[130:133], v231 offset:18432
	ds_read_b128 v[142:145], v231 offset:19456
	ds_read_b128 v[154:157], v231 offset:20480
	ds_read_b128 v[158:161], v231 offset:21504
	ds_read_b128 v[170:173], v231 offset:22528
	ds_read_b128 v[174:177], v231 offset:23552
	global_load_lds_dwordx4 v192, s[10:11]
	s_mov_b32 m0, s21
	s_nop 0
	global_load_lds_dwordx4 v190, s[10:11]
	s_barrier
	s_waitcnt lgkmcnt(0)
	v_mfma_f32_16x16x32_bf16 v[114:117], v[34:37], v[106:109], v[114:117]
	v_mfma_f32_16x16x32_bf16 v[110:113], v[98:101], v[106:109], v[110:113]
	v_mfma_f32_16x16x32_bf16 v[94:97], v[34:37], v[130:133], v[94:97]
	v_mfma_f32_16x16x32_bf16 v[90:93], v[98:101], v[130:133], v[90:93]
	v_mfma_f32_16x16x32_bf16 v[86:89], v[34:37], v[154:157], v[86:89]
	v_mfma_f32_16x16x32_bf16 v[82:85], v[98:101], v[154:157], v[82:85]
	v_mfma_f32_16x16x32_bf16 v[34:37], v[34:37], v[170:173], v[78:81]
	v_mfma_f32_16x16x32_bf16 v[114:117], v[38:41], v[118:121], v[114:117]
	v_mfma_f32_16x16x32_bf16 v[110:113], v[102:105], v[118:121], v[110:113]
	v_mfma_f32_16x16x32_bf16 v[94:97], v[38:41], v[142:145], v[94:97]
	v_mfma_f32_16x16x32_bf16 v[90:93], v[102:105], v[142:145], v[90:93]
	v_mfma_f32_16x16x32_bf16 v[86:89], v[38:41], v[158:161], v[86:89]
	v_mfma_f32_16x16x32_bf16 v[82:85], v[102:105], v[158:161], v[82:85]
	v_mfma_f32_16x16x32_bf16 v[34:37], v[38:41], v[174:177], v[34:37]
	v_mfma_f32_16x16x32_bf16 v[38:41], v[98:101], v[170:173], v[74:77]
	v_mfma_f32_16x16x32_bf16 v[38:41], v[102:105], v[174:177], v[38:41]
	s_barrier
	s_add_u32 s0, s4, 0x40000
	s_addc_u32 s1, s5, 0
	s_add_i32 s60, s61, s19
	s_mov_b32 m0, s60
	s_nop 0
	global_load_lds_dwordx4 v0, s[0:1]
	s_add_i32 m0, s60, 0x2000
	s_nop 0
	global_load_lds_dwordx4 v188, s[0:1]
	s_waitcnt vmcnt(6)
	s_barrier
	v_mfma_f32_16x16x32_bf16 v[30:33], v[198:201], v[106:109], v[30:33]
	v_mfma_f32_16x16x32_bf16 v[26:29], v[206:209], v[106:109], v[26:29]
	v_mfma_f32_16x16x32_bf16 v[22:25], v[198:201], v[130:133], v[22:25]
	v_mfma_f32_16x16x32_bf16 v[18:21], v[206:209], v[130:133], v[18:21]
	v_mfma_f32_16x16x32_bf16 v[14:17], v[198:201], v[154:157], v[14:17]
	v_mfma_f32_16x16x32_bf16 v[10:13], v[206:209], v[154:157], v[10:13]
	v_mfma_f32_16x16x32_bf16 v[6:9], v[198:201], v[170:173], v[6:9]
	v_mfma_f32_16x16x32_bf16 v[2:5], v[206:209], v[170:173], v[2:5]
	v_mfma_f32_16x16x32_bf16 v[30:33], v[202:205], v[118:121], v[30:33]
	v_mfma_f32_16x16x32_bf16 v[26:29], v[210:213], v[118:121], v[26:29]
	v_mfma_f32_16x16x32_bf16 v[22:25], v[202:205], v[142:145], v[22:25]
	v_mfma_f32_16x16x32_bf16 v[18:21], v[210:213], v[142:145], v[18:21]
	v_mfma_f32_16x16x32_bf16 v[14:17], v[202:205], v[158:161], v[14:17]
	v_mfma_f32_16x16x32_bf16 v[10:13], v[210:213], v[158:161], v[10:13]
	v_mfma_f32_16x16x32_bf16 v[6:9], v[202:205], v[174:177], v[6:9]
	v_mfma_f32_16x16x32_bf16 v[2:5], v[210:213], v[174:177], v[2:5]
	s_add_i32 s60, 0, 0x18000
	s_barrier
	ds_read_b128 v[74:77], v250 offset:32768
	ds_read_b128 v[78:81], v250 offset:33792
	ds_read_b128 v[98:101], v250 offset:34816
	ds_read_b128 v[102:105], v250 offset:35840
	s_add_u32 s0, s10, 0x100000
	s_addc_u32 s1, s11, 0
	s_mov_b32 m0, s22
	ds_read_b128 v[106:109], v231 offset:32768
	ds_read_b128 v[118:121], v231 offset:33792
	ds_read_b128 v[130:133], v231 offset:34816
	ds_read_b128 v[142:145], v231 offset:35840
	ds_read_b128 v[154:157], v231 offset:36864
	ds_read_b128 v[158:161], v231 offset:37888
	ds_read_b128 v[170:173], v231 offset:38912
	ds_read_b128 v[174:177], v231 offset:39936
	global_load_lds_dwordx4 v192, s[0:1]
	s_mov_b32 m0, s23
	s_nop 0
	global_load_lds_dwordx4 v190, s[0:1]
	s_waitcnt lgkmcnt(8)
	s_barrier
; #define PG8_STAGE(bufoff, gbase, voff) do { _Pragma("unroll") for (int _i = 0; _i < 2; ++_i) \
;         __builtin_amdgcn_global_load_lds((const unsigned*)((const char*)(gbase) + (voff)[_i]), (LAS unsigned*)(lds + (bufoff) + ldsw + _i * 8192), 16, 0, 0); } while (0)
; #define PG8_LDA(dst, b, h) do { _Pragma("unroll") for (int m = 0; m < 4; ++m) _Pragma("unroll") for (int k = 0; k < 2; ++k) dst[m][k] = *(const LAS bf16x8*)(lds + PG8_SA(b, h) + aoff + m * 2048 + k * 1024); } while (0)
; #define PG8_LDB(dst, b, h) do { _Pragma("unroll") for (int n = 0; n < 2; ++n) _Pragma("unroll") for (int k = 0; k < 2; ++k) dst[n][k] = *(const LAS bf16x8*)(lds + PG8_SB(b, h) + boff + n * 2048 + k * 1024); } while (0)
; #define PG8_MMA(ai, bj, At, Bt) do { __builtin_amdgcn_s_setprio(1); _Pragma("unroll") for (int m = 0; m < 4; ++m) _Pragma("unroll") for (int n = 0; n < 2; ++n) _Pragma("unroll") for (int k = 0; k < 2; ++k) \
;         acc[ai][bj][m][n] = __builtin_amdgcn_mfma_f32_16x16x32_bf16(Bt[n][k], At[m][k], acc[ai][bj][m][n], 0, 0, 0); __builtin_amdgcn_s_setprio(0); } while (0)
; #define PG8_WAIT_V(n) asm volatile("s_waitcnt vmcnt(" #n ")" ::: "memory")
; #define PG8_WAIT_L(n) asm volatile("s_waitcnt lgkmcnt(" #n ")" ::: "memory")
; #define PG8_BAR __builtin_amdgcn_s_barrier()
; #define PG8_SCHED __builtin_amdgcn_sched_barrier(0)
; template <class Epi>
; __device__ __forceinline__ void gemm_phase(LAS unsigned char* lds, const Gemm g, const StaticOrder& S, const Epi& E) {
;     ...
;             PG8_LDB(B1, 1, 1); PG8_STAGE(PG8_SB(1, 0), b3, voffB);
;             PG8_BAR; PG8_WAIT_L(0); PG8_MMA(0, 1, At, B1); PG8_BAR;
;             PG8_LDA(At, 1, 1); PG8_STAGE(PG8_SA(1, 0), a3, voffA);
;             PG8_BAR; PG8_WAIT_L(0); PG8_MMA(1, 0, At, B0); PG8_BAR; PG8_SCHED;
;             PG8_STAGE(PG8_SB(1, 1), b3 + hstepB, voffB);
;             PG8_WAIT_V(6); PG8_BAR; PG8_MMA(1, 1, At, B1); PG8_BAR;
	s_waitcnt lgkmcnt(0)
	v_mfma_f32_16x16x32_bf16 v[166:169], v[74:77], v[106:109], v[166:169]
	v_mfma_f32_16x16x32_bf16 v[162:165], v[98:101], v[106:109], v[162:165]
	v_mfma_f32_16x16x32_bf16 v[150:153], v[74:77], v[130:133], v[150:153]
	v_mfma_f32_16x16x32_bf16 v[146:149], v[98:101], v[130:133], v[146:149]
	v_mfma_f32_16x16x32_bf16 v[138:141], v[74:77], v[154:157], v[138:141]
	v_mfma_f32_16x16x32_bf16 v[134:137], v[98:101], v[154:157], v[134:137]
	v_mfma_f32_16x16x32_bf16 v[126:129], v[74:77], v[170:173], v[126:129]
	v_mfma_f32_16x16x32_bf16 v[122:125], v[98:101], v[170:173], v[122:125]
	v_mfma_f32_16x16x32_bf16 v[166:169], v[78:81], v[118:121], v[166:169]
	v_mfma_f32_16x16x32_bf16 v[162:165], v[102:105], v[118:121], v[162:165]
	v_mfma_f32_16x16x32_bf16 v[150:153], v[78:81], v[142:145], v[150:153]
	v_mfma_f32_16x16x32_bf16 v[146:149], v[102:105], v[142:145], v[146:149]
	v_mfma_f32_16x16x32_bf16 v[138:141], v[78:81], v[158:161], v[138:141]
	v_mfma_f32_16x16x32_bf16 v[134:137], v[102:105], v[158:161], v[134:137]
	v_mfma_f32_16x16x32_bf16 v[126:129], v[78:81], v[174:177], v[126:129]
	v_mfma_f32_16x16x32_bf16 v[122:125], v[102:105], v[174:177], v[122:125]
	s_barrier
	s_add_i32 s10, 0, 0x1c000
	s_add_i32 s0, s60, s19
	s_mov_b32 m0, s0
	ds_read_b128 v[198:201], v250 offset:49152
	ds_read_b128 v[202:205], v250 offset:50176
	ds_read_b128 v[206:209], v250 offset:51200
	ds_read_b128 v[210:213], v250 offset:52224
	global_load_lds_dwordx4 v0, s[100:101]
	s_add_i32 m0, s0, 0x2000
	s_nop 0
	global_load_lds_dwordx4 v188, s[100:101]
	s_barrier
	s_waitcnt lgkmcnt(0)
	v_mfma_f32_16x16x32_bf16 v[70:73], v[198:201], v[106:109], v[70:73]
	v_mfma_f32_16x16x32_bf16 v[66:69], v[206:209], v[106:109], v[66:69]
	v_mfma_f32_16x16x32_bf16 v[62:65], v[198:201], v[130:133], v[62:65]
	v_mfma_f32_16x16x32_bf16 v[58:61], v[206:209], v[130:133], v[58:61]
	v_mfma_f32_16x16x32_bf16 v[54:57], v[198:201], v[154:157], v[54:57]
	v_mfma_f32_16x16x32_bf16 v[50:53], v[206:209], v[154:157], v[50:53]
	v_mfma_f32_16x16x32_bf16 v[46:49], v[198:201], v[170:173], v[46:49]
	v_mfma_f32_16x16x32_bf16 v[42:45], v[206:209], v[170:173], v[42:45]
	v_mfma_f32_16x16x32_bf16 v[70:73], v[202:205], v[118:121], v[70:73]
	v_mfma_f32_16x16x32_bf16 v[66:69], v[210:213], v[118:121], v[66:69]
	v_mfma_f32_16x16x32_bf16 v[62:65], v[202:205], v[142:145], v[62:65]
	v_mfma_f32_16x16x32_bf16 v[58:61], v[210:213], v[142:145], v[58:61]
	v_mfma_f32_16x16x32_bf16 v[54:57], v[202:205], v[158:161], v[54:57]
	v_mfma_f32_16x16x32_bf16 v[50:53], v[210:213], v[158:161], v[50:53]
	v_mfma_f32_16x16x32_bf16 v[46:49], v[202:205], v[174:177], v[46:49]
	v_mfma_f32_16x16x32_bf16 v[42:45], v[210:213], v[174:177], v[42:45]
	s_mov_b32 m0, s24
	s_barrier
	ds_read_b128 v[106:109], v231 offset:49152
	ds_read_b128 v[118:121], v231 offset:50176
	ds_read_b128 v[130:133], v231 offset:51200
	ds_read_b128 v[142:145], v231 offset:52224
	ds_read_b128 v[154:157], v231 offset:53248
	ds_read_b128 v[158:161], v231 offset:54272
	ds_read_b128 v[170:173], v231 offset:55296
	ds_read_b128 v[174:177], v231 offset:56320
	global_load_lds_dwordx4 v192, vcc
	s_mov_b32 m0, s25
	s_nop 0
	global_load_lds_dwordx4 v190, vcc
	s_barrier
	s_waitcnt lgkmcnt(0)
	v_mfma_f32_16x16x32_bf16 v[114:117], v[74:77], v[106:109], v[114:117]
	v_mfma_f32_16x16x32_bf16 v[94:97], v[74:77], v[130:133], v[94:97]
	v_mfma_f32_16x16x32_bf16 v[86:89], v[74:77], v[154:157], v[86:89]
	v_mfma_f32_16x16x32_bf16 v[34:37], v[74:77], v[170:173], v[34:37]
	v_mfma_f32_16x16x32_bf16 v[114:117], v[78:81], v[118:121], v[114:117]
	v_mfma_f32_16x16x32_bf16 v[110:113], v[98:101], v[106:109], v[110:113]
	v_mfma_f32_16x16x32_bf16 v[94:97], v[78:81], v[142:145], v[94:97]
	v_mfma_f32_16x16x32_bf16 v[90:93], v[98:101], v[130:133], v[90:93]
	v_mfma_f32_16x16x32_bf16 v[86:89], v[78:81], v[158:161], v[86:89]
	v_mfma_f32_16x16x32_bf16 v[82:85], v[98:101], v[154:157], v[82:85]
	v_mfma_f32_16x16x32_bf16 v[78:81], v[78:81], v[174:177], v[34:37]
	v_mfma_f32_16x16x32_bf16 v[34:37], v[98:101], v[170:173], v[38:41]
	v_mfma_f32_16x16x32_bf16 v[110:113], v[102:105], v[118:121], v[110:113]
	v_mfma_f32_16x16x32_bf16 v[90:93], v[102:105], v[142:145], v[90:93]
	v_mfma_f32_16x16x32_bf16 v[82:85], v[102:105], v[158:161], v[82:85]
	v_mfma_f32_16x16x32_bf16 v[74:77], v[102:105], v[174:177], v[34:37]
	s_barrier
	s_add_u32 s0, s4, 0x40080
	s_addc_u32 s1, s5, 0
	s_add_i32 s4, s10, s19
	s_mov_b32 m0, s4
	s_nop 0
	global_load_lds_dwordx4 v0, s[0:1]
	s_add_i32 m0, s4, 0x2000
	s_nop 0
	global_load_lds_dwordx4 v188, s[0:1]
	s_waitcnt vmcnt(6)
	s_barrier
	v_mfma_f32_16x16x32_bf16 v[30:33], v[198:201], v[106:109], v[30:33]
	v_mfma_f32_16x16x32_bf16 v[26:29], v[206:209], v[106:109], v[26:29]
	v_mfma_f32_16x16x32_bf16 v[22:25], v[198:201], v[130:133], v[22:25]
	v_mfma_f32_16x16x32_bf16 v[18:21], v[206:209], v[130:133], v[18:21]
	v_mfma_f32_16x16x32_bf16 v[14:17], v[198:201], v[154:157], v[14:17]
	v_mfma_f32_16x16x32_bf16 v[10:13], v[206:209], v[154:157], v[10:13]
	v_mfma_f32_16x16x32_bf16 v[6:9], v[198:201], v[170:173], v[6:9]
	v_mfma_f32_16x16x32_bf16 v[2:5], v[206:209], v[170:173], v[2:5]
	v_mfma_f32_16x16x32_bf16 v[30:33], v[202:205], v[118:121], v[30:33]
	v_mfma_f32_16x16x32_bf16 v[26:29], v[210:213], v[118:121], v[26:29]
	v_mfma_f32_16x16x32_bf16 v[22:25], v[202:205], v[142:145], v[22:25]
	v_mfma_f32_16x16x32_bf16 v[18:21], v[210:213], v[142:145], v[18:21]
	v_mfma_f32_16x16x32_bf16 v[14:17], v[202:205], v[158:161], v[14:17]
	v_mfma_f32_16x16x32_bf16 v[10:13], v[210:213], v[158:161], v[10:13]
	v_mfma_f32_16x16x32_bf16 v[6:9], v[202:205], v[174:177], v[6:9]
	v_mfma_f32_16x16x32_bf16 v[2:5], v[210:213], v[174:177], v[2:5]
	s_add_i32 s59, s59, 2
	s_add_u32 s53, s53, 0x100
	s_addc_u32 s58, s58, 0
	s_cmp_gt_u32 s59, 13
	s_mov_b64 s[0:1], s[8:9]
	s_barrier
; __device__ __forceinline__ unsigned cvt_pk_bf16(float lo, float hi) { unsigned r; asm volatile("v_cvt_pk_bf16_f32 %0, %1, %2" : "=v"(r) : "v"(lo), "v"(hi)); return r; }
; __device__ __forceinline__ float bf_lo(unsigned w) { return __uint_as_float(w << 16); }
; __device__ __forceinline__ float bf_hi(unsigned w) { return __uint_as_float(w & 0xffff0000u); }
; __device__ __forceinline__ float silu_f(float z) { return z * fast_rcp(1.0f + __builtin_amdgcn_exp2f(z * -1.44269504f)); }
; #define PG8_WAIT_V(n) asm volatile("s_waitcnt vmcnt(" #n ")" ::: "memory")
; template <class Epi>
; __device__ __forceinline__ void gemm_phase(LAS unsigned char* lds, const Gemm g, const StaticOrder& S, const Epi& E) {
;     ...
;             PG8_STAGE(PG8_SB(1, 1), b3 + hstepB, voffB);
;             PG8_WAIT_V(6); PG8_BAR; PG8_MMA(1, 1, At, B1); PG8_BAR;
;         }
;     __device__ __forceinline__ void operator()(const f32x4 (&acc)[2][2][4][2], const Unit& u, int wr, int wc, int fr, int fq, const Pre&) const {
;         const int row0 = u.pm * BM + wr * 64 + fr, col0 = u.pn * BM + wc * 32 + 8 * fq;
;         f32x4 sc[2][2];
; #pragma unroll
;         for (int bj = 0; bj < 2; ++bj) { sc[bj][0] = *(const f32x4*)(scale + col0 + bj * HALF); sc[bj][1] = *(const f32x4*)(scale + col0 + bj * HALF + 4); }
; #pragma unroll
;         for (int bj = 0; bj < 2; ++bj) { const int c = col0 + bj * HALF;
;             u32x4 zv[8];
; #pragma unroll
;             for (int g8 = 0; g8 < 8; ++g8) zv[g8] = *(const u32x4*)(Z + (size_t)(row0 + (g8 >> 2) * HALF + (g8 & 3) * 16) * DE2 + c);
; #pragma unroll
;             for (int ai = 0; ai < 2; ++ai)
; #pragma unroll
;                 for (int m = 0; m < 4; ++m) { const int r = row0 + ai * HALF + m * 16;
;                     const u32x4 zw = zv[ai * 4 + m];
;                     const f32x4 a0 = acc[ai][bj][m][0] * sc[bj][0], a1 = acc[ai][bj][m][1] * sc[bj][1];
;                     u32x4 w;
;                     w.x = cvt_pk_bf16(a0[0] * silu_f(bf_lo(zw.x)), a0[1] * silu_f(bf_hi(zw.x)));
;                     w.y = cvt_pk_bf16(a0[2] * silu_f(bf_lo(zw.y)), a0[3] * silu_f(bf_hi(zw.y)));
;                     w.z = cvt_pk_bf16(a1[0] * silu_f(bf_lo(zw.z)), a1[1] * silu_f(bf_hi(zw.z)));
;                     w.w = cvt_pk_bf16(a1[2] * silu_f(bf_lo(zw.w)), a1[3] * silu_f(bf_hi(zw.w)));
;                     *(u32x4*)(O + (size_t)r * DE + c) = w; } }
	s_cbranch_scc0 .LBB0_603
	s_setprio 0
	v_lshl_or_b32 v200, s34, 8, v230
	v_ashrrev_i32_e32 v201, 31, v200
	v_lshl_add_u32 v226, s27, 8, v228
	v_lshlrev_b64 v[216:217], 1, v[200:201]
	v_ashrrev_i32_e32 v227, 31, v226
	v_lshl_add_u64 v[106:107], s[46:47], 0, v[216:217]
	v_lshlrev_b64 v[204:205], 14, v[226:227]
	v_lshl_add_u64 v[38:39], v[200:201], 2, s[48:49]
	v_lshl_add_u64 v[108:109], v[106:107], 0, v[204:205]
	global_load_dwordx4 v[98:101], v[38:39], off offset:16
	global_load_dwordx4 v[102:105], v[38:39], off
	global_load_dwordx4 v[34:37], v[38:39], off offset:528
	s_nop 0
	global_load_dwordx4 v[38:41], v[38:39], off offset:512
	v_or_b32_e32 v224, 16, v226
	global_load_dwordx4 v[174:177], v[108:109], off
	v_ashrrev_i32_e32 v225, 31, v224
	v_or_b32_e32 v222, 32, v226
	v_lshlrev_b64 v[198:199], 14, v[224:225]
	v_ashrrev_i32_e32 v223, 31, v222
	v_or_b32_e32 v220, 48, v226
	v_lshl_add_u64 v[108:109], v[106:107], 0, v[198:199]
	v_lshlrev_b64 v[202:203], 14, v[222:223]
	v_ashrrev_i32_e32 v221, 31, v220
	v_add_u32_e32 v218, 0x80, v226
	global_load_dwordx4 v[170:173], v[108:109], off
	v_lshl_add_u64 v[108:109], v[106:107], 0, v[202:203]
	v_lshlrev_b64 v[206:207], 14, v[220:221]
	v_ashrrev_i32_e32 v219, 31, v218
	global_load_dwordx4 v[158:161], v[108:109], off
	v_lshl_add_u64 v[108:109], v[106:107], 0, v[206:207]
	v_lshlrev_b64 v[208:209], 14, v[218:219]
	global_load_dwordx4 v[154:157], v[108:109], off
	v_lshl_add_u64 v[108:109], v[106:107], 0, v[208:209]
	global_load_dwordx4 v[142:145], v[108:109], off
	v_add_u32_e32 v108, 0x90, v226
	v_ashrrev_i32_e32 v109, 31, v108
	v_lshlrev_b64 v[210:211], 14, v[108:109]
	v_lshl_add_u64 v[108:109], v[106:107], 0, v[210:211]
	global_load_dwordx4 v[130:133], v[108:109], off
	v_add_u32_e32 v108, 0xa0, v226
	v_ashrrev_i32_e32 v109, 31, v108
	v_lshlrev_b64 v[212:213], 14, v[108:109]
	v_lshl_add_u64 v[108:109], v[106:107], 0, v[212:213]
	global_load_dwordx4 v[118:121], v[108:109], off
	v_add_u32_e32 v108, 0xb0, v226
	v_ashrrev_i32_e32 v109, 31, v108
	v_lshlrev_b64 v[214:215], 14, v[108:109]
	v_lshl_add_u64 v[106:107], v[106:107], 0, v[214:215]
	global_load_dwordx4 v[106:109], v[106:107], off
	s_mov_b64 s[0:1], 0x120000
	s_mov_b32 s27, s52
	s_mov_b32 s34, s50
	s_mov_b64 s[8:9], s[56:57]
	s_waitcnt vmcnt(0)
	v_pk_mul_f32 v[146:147], v[146:147], v[98:99]
	v_pk_mul_f32 v[184:185], v[166:167], v[102:103]
	v_pk_mul_f32 v[166:167], v[164:165], v[100:101]
	v_pk_mul_f32 v[164:165], v[162:163], v[98:99]
	v_pk_mul_f32 v[168:169], v[168:169], v[104:105]
	v_lshlrev_b32_e32 v162, 16, v174
	v_mul_f32_e32 v163, 0xbfb8aa3b, v162
	v_exp_f32_e32 v163, v163
	v_pk_mul_f32 v[150:151], v[150:151], v[102:103]
	v_pk_mul_f32 v[152:153], v[152:153], v[104:105]
	v_pk_mul_f32 v[148:149], v[148:149], v[100:101]
	v_add_f32_e32 v163, 1.0, v163
	v_rcp_f32_e32 v163, v163
	v_pk_mul_f32 v[138:139], v[138:139], v[102:103]
	v_pk_mul_f32 v[140:141], v[140:141], v[104:105]
	v_pk_mul_f32 v[134:135], v[134:135], v[98:99]
	v_mul_f32_e32 v162, v163, v162
	v_and_b32_e32 v163, 0xffff0000, v174
	v_mul_f32_e32 v174, 0xbfb8aa3b, v163
	v_exp_f32_e32 v174, v174
	v_mul_f32_e32 v162, v184, v162
	v_pk_mul_f32 v[136:137], v[136:137], v[100:101]
	v_pk_mul_f32 v[126:127], v[126:127], v[102:103]
	v_add_f32_e32 v174, 1.0, v174
	v_rcp_f32_e32 v174, v174
	v_pk_mul_f32 v[128:129], v[128:129], v[104:105]
	v_pk_mul_f32 v[122:123], v[122:123], v[98:99]
	v_pk_mul_f32 v[124:125], v[124:125], v[100:101]
	v_mul_f32_e32 v163, v174, v163
	v_mul_f32_e32 v163, v185, v163
	v_cvt_pk_bf16_f32 v162, v162, v163
	v_lshlrev_b32_e32 v163, 16, v175
	v_mul_f32_e32 v174, 0xbfb8aa3b, v163
	v_exp_f32_e32 v174, v174
	v_pk_mul_f32 v[114:115], v[114:115], v[102:103]
	v_pk_mul_f32 v[116:117], v[116:117], v[104:105]
	v_pk_mul_f32 v[110:111], v[110:111], v[98:99]
	v_add_f32_e32 v174, 1.0, v174
	v_rcp_f32_e32 v174, v174
	v_pk_mul_f32 v[112:113], v[112:113], v[100:101]
	v_pk_mul_f32 v[94:95], v[94:95], v[102:103]
	v_pk_mul_f32 v[96:97], v[96:97], v[104:105]
	v_mul_f32_e32 v163, v174, v163
	v_mul_f32_e32 v163, v168, v163
	v_and_b32_e32 v168, 0xffff0000, v175
	v_mul_f32_e32 v174, 0xbfb8aa3b, v168
	v_exp_f32_e32 v174, v174
	v_pk_mul_f32 v[90:91], v[90:91], v[98:99]
	v_pk_mul_f32 v[92:93], v[92:93], v[100:101]
	v_pk_mul_f32 v[86:87], v[86:87], v[102:103]
	v_add_f32_e32 v174, 1.0, v174
	v_rcp_f32_e32 v174, v174
	v_pk_mul_f32 v[88:89], v[88:89], v[104:105]
	v_pk_mul_f32 v[82:83], v[82:83], v[98:99]
	v_pk_mul_f32 v[84:85], v[84:85], v[100:101]
	v_mul_f32_e32 v168, v174, v168
	v_mul_f32_e32 v168, v169, v168
	v_cvt_pk_bf16_f32 v163, v163, v168
	v_lshlrev_b32_e32 v168, 16, v176
	v_mul_f32_e32 v169, 0xbfb8aa3b, v168
	v_exp_f32_e32 v169, v169
	v_pk_mul_f32 v[78:79], v[78:79], v[102:103]
	v_pk_mul_f32 v[80:81], v[80:81], v[104:105]
	v_pk_mul_f32 v[74:75], v[74:75], v[98:99]
	v_add_f32_e32 v169, 1.0, v169
	v_rcp_f32_e32 v169, v169
	v_pk_mul_f32 v[76:77], v[76:77], v[100:101]
	v_pk_mul_f32 v[70:71], v[70:71], v[38:39]
	v_pk_mul_f32 v[72:73], v[72:73], v[40:41]
	v_mul_f32_e32 v168, v169, v168
	v_mul_f32_e32 v164, v164, v168
	v_and_b32_e32 v168, 0xffff0000, v176
	v_mul_f32_e32 v169, 0xbfb8aa3b, v168
	v_exp_f32_e32 v169, v169
	v_pk_mul_f32 v[66:67], v[66:67], v[34:35]
	v_pk_mul_f32 v[68:69], v[68:69], v[36:37]
	v_pk_mul_f32 v[62:63], v[62:63], v[38:39]
	v_add_f32_e32 v169, 1.0, v169
	v_rcp_f32_e32 v169, v169
	v_pk_mul_f32 v[64:65], v[64:65], v[40:41]
	v_pk_mul_f32 v[58:59], v[58:59], v[34:35]
	v_pk_mul_f32 v[60:61], v[60:61], v[36:37]
	v_mul_f32_e32 v168, v169, v168
	v_mul_f32_e32 v165, v165, v168
	v_cvt_pk_bf16_f32 v164, v164, v165
	v_lshlrev_b32_e32 v165, 16, v177
	v_mul_f32_e32 v168, 0xbfb8aa3b, v165
	v_exp_f32_e32 v168, v168
; __device__ __forceinline__ unsigned cvt_pk_bf16(float lo, float hi) { unsigned r; asm volatile("v_cvt_pk_bf16_f32 %0, %1, %2" : "=v"(r) : "v"(lo), "v"(hi)); return r; }
; __device__ __forceinline__ float bf_lo(unsigned w) { return __uint_as_float(w << 16); }
; __device__ __forceinline__ float bf_hi(unsigned w) { return __uint_as_float(w & 0xffff0000u); }
; __device__ __forceinline__ float silu_f(float z) { return z * fast_rcp(1.0f + __builtin_amdgcn_exp2f(z * -1.44269504f)); }
;     __device__ __forceinline__ void operator()(const f32x4 (&acc)[2][2][4][2], const Unit& u, int wr, int wc, int fr, int fq, const Pre&) const {
;     ...
;             for (int g8 = 0; g8 < 8; ++g8) zv[g8] = *(const u32x4*)(Z + (size_t)(row0 + (g8 >> 2) * HALF + (g8 & 3) * 16) * DE2 + c);
; #pragma unroll
;             for (int ai = 0; ai < 2; ++ai)
; #pragma unroll
;                 for (int m = 0; m < 4; ++m) { const int r = row0 + ai * HALF + m * 16;
;                     const u32x4 zw = zv[ai * 4 + m];
;                     const f32x4 a0 = acc[ai][bj][m][0] * sc[bj][0], a1 = acc[ai][bj][m][1] * sc[bj][1];
;                     u32x4 w;
;                     w.x = cvt_pk_bf16(a0[0] * silu_f(bf_lo(zw.x)), a0[1] * silu_f(bf_hi(zw.x)));
;                     w.y = cvt_pk_bf16(a0[2] * silu_f(bf_lo(zw.y)), a0[3] * silu_f(bf_hi(zw.y)));
;                     w.z = cvt_pk_bf16(a1[0] * silu_f(bf_lo(zw.z)), a1[1] * silu_f(bf_hi(zw.z)));
;                     w.w = cvt_pk_bf16(a1[2] * silu_f(bf_lo(zw.w)), a1[3] * silu_f(bf_hi(zw.w)));
;                     *(u32x4*)(O + (size_t)r * DE + c) = w; } }
	v_pk_mul_f32 v[54:55], v[54:55], v[38:39]
	v_pk_mul_f32 v[56:57], v[56:57], v[40:41]
	v_pk_mul_f32 v[50:51], v[50:51], v[34:35]
	v_add_f32_e32 v168, 1.0, v168
	v_rcp_f32_e32 v168, v168
	v_pk_mul_f32 v[52:53], v[52:53], v[36:37]
	v_pk_mul_f32 v[46:47], v[46:47], v[38:39]
	v_pk_mul_f32 v[48:49], v[48:49], v[40:41]
	v_mul_f32_e32 v165, v168, v165
	v_mul_f32_e32 v165, v166, v165
	v_and_b32_e32 v166, 0xffff0000, v177
	v_mul_f32_e32 v168, 0xbfb8aa3b, v166
	v_exp_f32_e32 v168, v168
	v_pk_mul_f32 v[42:43], v[42:43], v[34:35]
	v_pk_mul_f32 v[44:45], v[44:45], v[36:37]
	v_pk_mul_f32 v[30:31], v[30:31], v[38:39]
	v_add_f32_e32 v168, 1.0, v168
	v_rcp_f32_e32 v168, v168
	v_pk_mul_f32 v[32:33], v[32:33], v[40:41]
	v_pk_mul_f32 v[26:27], v[26:27], v[34:35]
	v_pk_mul_f32 v[28:29], v[28:29], v[36:37]
	v_mul_f32_e32 v166, v168, v166
	v_mul_f32_e32 v166, v167, v166
	v_cvt_pk_bf16_f32 v165, v165, v166
	v_lshlrev_b64 v[166:167], 13, v[226:227]
	v_lshl_add_u64 v[166:167], s[44:45], 0, v[166:167]
	v_lshl_add_u64 v[166:167], v[166:167], 0, v[216:217]
	global_store_dwordx4 v[166:167], v[162:165], off
	v_pk_mul_f32 v[22:23], v[22:23], v[38:39]
	v_pk_mul_f32 v[24:25], v[24:25], v[40:41]
	v_lshlrev_b32_e32 v162, 16, v170
	v_mul_f32_e32 v163, 0xbfb8aa3b, v162
	v_exp_f32_e32 v163, v163
	v_pk_mul_f32 v[18:19], v[18:19], v[34:35]
	v_pk_mul_f32 v[20:21], v[20:21], v[36:37]
	v_pk_mul_f32 v[14:15], v[14:15], v[38:39]
	v_add_f32_e32 v163, 1.0, v163
	v_rcp_f32_e32 v163, v163
	v_pk_mul_f32 v[16:17], v[16:17], v[40:41]
	v_pk_mul_f32 v[10:11], v[10:11], v[34:35]
	v_pk_mul_f32 v[12:13], v[12:13], v[36:37]
	v_mul_f32_e32 v162, v163, v162
	v_mul_f32_e32 v150, v150, v162
	v_and_b32_e32 v162, 0xffff0000, v170
	v_mul_f32_e32 v163, 0xbfb8aa3b, v162
	v_exp_f32_e32 v163, v163
	v_pk_mul_f32 v[6:7], v[6:7], v[38:39]
	v_pk_mul_f32 v[8:9], v[8:9], v[40:41]
	v_pk_mul_f32 v[2:3], v[2:3], v[34:35]
	v_add_f32_e32 v163, 1.0, v163
	v_rcp_f32_e32 v163, v163
	v_pk_mul_f32 v[4:5], v[4:5], v[36:37]
	v_mul_f32_e32 v162, v163, v162
	v_mul_f32_e32 v151, v151, v162
	v_cvt_pk_bf16_f32 v150, v150, v151
	v_lshlrev_b32_e32 v151, 16, v171
	v_mul_f32_e32 v162, 0xbfb8aa3b, v151
	v_exp_f32_e32 v162, v162
	s_nop 0
	v_add_f32_e32 v162, 1.0, v162
	v_rcp_f32_e32 v162, v162
	s_nop 0
	v_mul_f32_e32 v151, v162, v151
	v_mul_f32_e32 v151, v152, v151
	v_and_b32_e32 v152, 0xffff0000, v171
	v_mul_f32_e32 v162, 0xbfb8aa3b, v152
	v_exp_f32_e32 v162, v162
	s_nop 0
	v_add_f32_e32 v162, 1.0, v162
	v_rcp_f32_e32 v162, v162
	s_nop 0
	v_mul_f32_e32 v152, v162, v152
	v_mul_f32_e32 v152, v153, v152
	v_cvt_pk_bf16_f32 v151, v151, v152
	v_lshlrev_b32_e32 v152, 16, v172
	v_mul_f32_e32 v153, 0xbfb8aa3b, v152
	v_exp_f32_e32 v153, v153
	s_nop 0
	v_add_f32_e32 v153, 1.0, v153
	v_rcp_f32_e32 v153, v153
	s_nop 0
	v_mul_f32_e32 v152, v153, v152
	v_mul_f32_e32 v146, v146, v152
	v_and_b32_e32 v152, 0xffff0000, v172
	v_mul_f32_e32 v153, 0xbfb8aa3b, v152
	v_exp_f32_e32 v153, v153
	s_nop 0
	v_add_f32_e32 v153, 1.0, v153
	v_rcp_f32_e32 v153, v153
	s_nop 0
	v_mul_f32_e32 v152, v153, v152
	v_mul_f32_e32 v147, v147, v152
	v_cvt_pk_bf16_f32 v152, v146, v147
	v_lshlrev_b32_e32 v146, 16, v173
	v_mul_f32_e32 v147, 0xbfb8aa3b, v146
	v_exp_f32_e32 v147, v147
	s_nop 0
	v_add_f32_e32 v147, 1.0, v147
	v_rcp_f32_e32 v147, v147
	s_nop 0
	v_mul_f32_e32 v146, v147, v146
	v_and_b32_e32 v147, 0xffff0000, v173
	v_mul_f32_e32 v146, v148, v146
	v_mul_f32_e32 v148, 0xbfb8aa3b, v147
	v_exp_f32_e32 v148, v148
	s_nop 0
	v_add_f32_e32 v148, 1.0, v148
	v_rcp_f32_e32 v148, v148
	s_nop 0
	v_mul_f32_e32 v147, v148, v147
	v_lshlrev_b32_e32 v148, 16, v158
	v_mul_f32_e32 v147, v149, v147
	v_mul_f32_e32 v149, 0xbfb8aa3b, v148
	v_exp_f32_e32 v149, v149
	v_cvt_pk_bf16_f32 v153, v146, v147
	v_lshlrev_b64 v[146:147], 13, v[224:225]
	v_lshl_add_u64 v[146:147], s[44:45], 0, v[146:147]
	v_add_f32_e32 v149, 1.0, v149
	v_rcp_f32_e32 v149, v149
	v_lshl_add_u64 v[146:147], v[146:147], 0, v[216:217]
	global_store_dwordx4 v[146:147], v[150:153], off
	v_mul_f32_e32 v148, v149, v148
	v_mul_f32_e32 v138, v138, v148
	v_and_b32_e32 v148, 0xffff0000, v158
	v_mul_f32_e32 v149, 0xbfb8aa3b, v148
	v_exp_f32_e32 v149, v149
	s_nop 0
	v_add_f32_e32 v149, 1.0, v149
	v_rcp_f32_e32 v149, v149
	s_nop 0
	v_mul_f32_e32 v148, v149, v148
	v_mul_f32_e32 v139, v139, v148
	v_cvt_pk_bf16_f32 v138, v138, v139
	v_lshlrev_b32_e32 v139, 16, v159
	v_mul_f32_e32 v148, 0xbfb8aa3b, v139
	v_exp_f32_e32 v148, v148
	s_nop 0
	v_add_f32_e32 v148, 1.0, v148
	v_rcp_f32_e32 v148, v148
	s_nop 0
	v_mul_f32_e32 v139, v148, v139
	v_mul_f32_e32 v139, v140, v139
	v_and_b32_e32 v140, 0xffff0000, v159
	v_mul_f32_e32 v148, 0xbfb8aa3b, v140
	v_exp_f32_e32 v148, v148
	s_nop 0
	v_add_f32_e32 v148, 1.0, v148
	v_rcp_f32_e32 v148, v148
	s_nop 0
	v_mul_f32_e32 v140, v148, v140
	v_mul_f32_e32 v140, v141, v140
	v_cvt_pk_bf16_f32 v139, v139, v140
	v_lshlrev_b32_e32 v140, 16, v160
	v_mul_f32_e32 v141, 0xbfb8aa3b, v140
	v_exp_f32_e32 v141, v141
	s_nop 0
	v_add_f32_e32 v141, 1.0, v141
	v_rcp_f32_e32 v141, v141
	s_nop 0
	v_mul_f32_e32 v140, v141, v140
	v_mul_f32_e32 v134, v134, v140
	v_and_b32_e32 v140, 0xffff0000, v160
	v_mul_f32_e32 v141, 0xbfb8aa3b, v140
	v_exp_f32_e32 v141, v141
	s_nop 0
	v_add_f32_e32 v141, 1.0, v141
	v_rcp_f32_e32 v141, v141
	s_nop 0
	v_mul_f32_e32 v140, v141, v140
	v_mul_f32_e32 v135, v135, v140
	v_cvt_pk_bf16_f32 v140, v134, v135
	v_lshlrev_b32_e32 v134, 16, v161
	v_mul_f32_e32 v135, 0xbfb8aa3b, v134
	v_exp_f32_e32 v135, v135
	s_nop 0
	v_add_f32_e32 v135, 1.0, v135
	v_rcp_f32_e32 v135, v135
	s_nop 0
	v_mul_f32_e32 v134, v135, v134
	v_and_b32_e32 v135, 0xffff0000, v161
	v_mul_f32_e32 v134, v136, v134
	v_mul_f32_e32 v136, 0xbfb8aa3b, v135
; __device__ __forceinline__ unsigned cvt_pk_bf16(float lo, float hi) { unsigned r; asm volatile("v_cvt_pk_bf16_f32 %0, %1, %2" : "=v"(r) : "v"(lo), "v"(hi)); return r; }
; __device__ __forceinline__ float bf_lo(unsigned w) { return __uint_as_float(w << 16); }
; __device__ __forceinline__ float bf_hi(unsigned w) { return __uint_as_float(w & 0xffff0000u); }
; __device__ __forceinline__ float silu_f(float z) { return z * fast_rcp(1.0f + __builtin_amdgcn_exp2f(z * -1.44269504f)); }
;     __device__ __forceinline__ void operator()(const f32x4 (&acc)[2][2][4][2], const Unit& u, int wr, int wc, int fr, int fq, const Pre&) const {
;     ...
;             for (int g8 = 0; g8 < 8; ++g8) zv[g8] = *(const u32x4*)(Z + (size_t)(row0 + (g8 >> 2) * HALF + (g8 & 3) * 16) * DE2 + c);
; #pragma unroll
;             for (int ai = 0; ai < 2; ++ai)
; #pragma unroll
;                 for (int m = 0; m < 4; ++m) { const int r = row0 + ai * HALF + m * 16;
;                     const u32x4 zw = zv[ai * 4 + m];
;                     const f32x4 a0 = acc[ai][bj][m][0] * sc[bj][0], a1 = acc[ai][bj][m][1] * sc[bj][1];
;                     u32x4 w;
;                     w.x = cvt_pk_bf16(a0[0] * silu_f(bf_lo(zw.x)), a0[1] * silu_f(bf_hi(zw.x)));
;                     w.y = cvt_pk_bf16(a0[2] * silu_f(bf_lo(zw.y)), a0[3] * silu_f(bf_hi(zw.y)));
;                     w.z = cvt_pk_bf16(a1[0] * silu_f(bf_lo(zw.z)), a1[1] * silu_f(bf_hi(zw.z)));
;                     w.w = cvt_pk_bf16(a1[2] * silu_f(bf_lo(zw.w)), a1[3] * silu_f(bf_hi(zw.w)));
;                     *(u32x4*)(O + (size_t)r * DE + c) = w; } }
	v_exp_f32_e32 v136, v136
	s_nop 0
	v_add_f32_e32 v136, 1.0, v136
	v_rcp_f32_e32 v136, v136
	s_nop 0
	v_mul_f32_e32 v135, v136, v135
	v_lshlrev_b32_e32 v136, 16, v154
	v_mul_f32_e32 v135, v137, v135
	v_mul_f32_e32 v137, 0xbfb8aa3b, v136
	v_exp_f32_e32 v137, v137
	v_cvt_pk_bf16_f32 v141, v134, v135
	v_lshlrev_b64 v[134:135], 13, v[222:223]
	v_lshl_add_u64 v[134:135], s[44:45], 0, v[134:135]
	v_add_f32_e32 v137, 1.0, v137
	v_rcp_f32_e32 v137, v137
	v_lshl_add_u64 v[134:135], v[134:135], 0, v[216:217]
	global_store_dwordx4 v[134:135], v[138:141], off
	v_mul_f32_e32 v136, v137, v136
	v_mul_f32_e32 v126, v126, v136
	v_and_b32_e32 v136, 0xffff0000, v154
	v_mul_f32_e32 v137, 0xbfb8aa3b, v136
	v_exp_f32_e32 v137, v137
	s_nop 0
	v_add_f32_e32 v137, 1.0, v137
	v_rcp_f32_e32 v137, v137
	s_nop 0
	v_mul_f32_e32 v136, v137, v136
	v_mul_f32_e32 v127, v127, v136
	v_cvt_pk_bf16_f32 v126, v126, v127
	v_lshlrev_b32_e32 v127, 16, v155
	v_mul_f32_e32 v136, 0xbfb8aa3b, v127
	v_exp_f32_e32 v136, v136
	s_nop 0
	v_add_f32_e32 v136, 1.0, v136
	v_rcp_f32_e32 v136, v136
	s_nop 0
	v_mul_f32_e32 v127, v136, v127
	v_mul_f32_e32 v127, v128, v127
	v_and_b32_e32 v128, 0xffff0000, v155
	v_mul_f32_e32 v136, 0xbfb8aa3b, v128
	v_exp_f32_e32 v136, v136
	s_nop 0
	v_add_f32_e32 v136, 1.0, v136
	v_rcp_f32_e32 v136, v136
	s_nop 0
	v_mul_f32_e32 v128, v136, v128
	v_mul_f32_e32 v128, v129, v128
	v_cvt_pk_bf16_f32 v127, v127, v128
	v_lshlrev_b32_e32 v128, 16, v156
	v_mul_f32_e32 v129, 0xbfb8aa3b, v128
	v_exp_f32_e32 v129, v129
	s_nop 0
	v_add_f32_e32 v129, 1.0, v129
	v_rcp_f32_e32 v129, v129
	s_nop 0
	v_mul_f32_e32 v128, v129, v128
	v_mul_f32_e32 v122, v122, v128
	v_and_b32_e32 v128, 0xffff0000, v156
	v_mul_f32_e32 v129, 0xbfb8aa3b, v128
	v_exp_f32_e32 v129, v129
	s_nop 0
	v_add_f32_e32 v129, 1.0, v129
	v_rcp_f32_e32 v129, v129
	s_nop 0
	v_mul_f32_e32 v128, v129, v128
	v_mul_f32_e32 v123, v123, v128
	v_cvt_pk_bf16_f32 v128, v122, v123
	v_lshlrev_b32_e32 v122, 16, v157
	v_mul_f32_e32 v123, 0xbfb8aa3b, v122
	v_exp_f32_e32 v123, v123
	s_nop 0
	v_add_f32_e32 v123, 1.0, v123
	v_rcp_f32_e32 v123, v123
	s_nop 0
	v_mul_f32_e32 v122, v123, v122
	v_and_b32_e32 v123, 0xffff0000, v157
	v_mul_f32_e32 v122, v124, v122
	v_mul_f32_e32 v124, 0xbfb8aa3b, v123
	v_exp_f32_e32 v124, v124
	s_nop 0
	v_add_f32_e32 v124, 1.0, v124
	v_rcp_f32_e32 v124, v124
	s_nop 0
	v_mul_f32_e32 v123, v124, v123
	v_lshlrev_b32_e32 v124, 16, v142
	v_mul_f32_e32 v123, v125, v123
	v_mul_f32_e32 v125, 0xbfb8aa3b, v124
	v_exp_f32_e32 v125, v125
	v_cvt_pk_bf16_f32 v129, v122, v123
	v_lshlrev_b64 v[122:123], 13, v[220:221]
	v_lshl_add_u64 v[122:123], s[44:45], 0, v[122:123]
	v_add_f32_e32 v125, 1.0, v125
	v_rcp_f32_e32 v125, v125
	v_lshl_add_u64 v[122:123], v[122:123], 0, v[216:217]
	global_store_dwordx4 v[122:123], v[126:129], off
	v_mul_f32_e32 v124, v125, v124
	v_mul_f32_e32 v114, v114, v124
	v_and_b32_e32 v124, 0xffff0000, v142
	v_mul_f32_e32 v125, 0xbfb8aa3b, v124
	v_exp_f32_e32 v125, v125
	s_nop 0
	v_add_f32_e32 v125, 1.0, v125
	v_rcp_f32_e32 v125, v125
	s_nop 0
	v_mul_f32_e32 v124, v125, v124
	v_mul_f32_e32 v115, v115, v124
	v_cvt_pk_bf16_f32 v114, v114, v115
	v_lshlrev_b32_e32 v115, 16, v143
	v_mul_f32_e32 v124, 0xbfb8aa3b, v115
	v_exp_f32_e32 v124, v124
	s_nop 0
	v_add_f32_e32 v124, 1.0, v124
	v_rcp_f32_e32 v124, v124
	s_nop 0
	v_mul_f32_e32 v115, v124, v115
	v_mul_f32_e32 v115, v116, v115
	v_and_b32_e32 v116, 0xffff0000, v143
	v_mul_f32_e32 v124, 0xbfb8aa3b, v116
	v_exp_f32_e32 v124, v124
	s_nop 0
	v_add_f32_e32 v124, 1.0, v124
	v_rcp_f32_e32 v124, v124
	s_nop 0
	v_mul_f32_e32 v116, v124, v116
	v_mul_f32_e32 v116, v117, v116
	v_cvt_pk_bf16_f32 v115, v115, v116
	v_lshlrev_b32_e32 v116, 16, v144
	v_mul_f32_e32 v117, 0xbfb8aa3b, v116
	v_exp_f32_e32 v117, v117
	s_nop 0
	v_add_f32_e32 v117, 1.0, v117
	v_rcp_f32_e32 v117, v117
	s_nop 0
	v_mul_f32_e32 v116, v117, v116
	v_mul_f32_e32 v110, v110, v116
	v_and_b32_e32 v116, 0xffff0000, v144
	v_mul_f32_e32 v117, 0xbfb8aa3b, v116
	v_exp_f32_e32 v117, v117
	s_nop 0
	v_add_f32_e32 v117, 1.0, v117
	v_rcp_f32_e32 v117, v117
	s_nop 0
	v_mul_f32_e32 v116, v117, v116
	v_mul_f32_e32 v111, v111, v116
	v_cvt_pk_bf16_f32 v116, v110, v111
	v_lshlrev_b32_e32 v110, 16, v145
	v_mul_f32_e32 v111, 0xbfb8aa3b, v110
	v_exp_f32_e32 v111, v111
	s_nop 0
	v_add_f32_e32 v111, 1.0, v111
	v_rcp_f32_e32 v111, v111
	s_nop 0
	v_mul_f32_e32 v110, v111, v110
	v_and_b32_e32 v111, 0xffff0000, v145
	v_mul_f32_e32 v110, v112, v110
	v_mul_f32_e32 v112, 0xbfb8aa3b, v111
	v_exp_f32_e32 v112, v112
	s_nop 0
	v_add_f32_e32 v112, 1.0, v112
	v_rcp_f32_e32 v112, v112
	s_nop 0
	v_mul_f32_e32 v111, v112, v111
	v_mul_f32_e32 v111, v113, v111
	v_cvt_pk_bf16_f32 v117, v110, v111
	v_lshlrev_b64 v[110:111], 13, v[218:219]
	v_lshl_add_u64 v[110:111], s[44:45], 0, v[110:111]
	v_lshl_add_u64 v[112:113], v[110:111], 0, v[216:217]
	v_lshlrev_b32_e32 v110, 16, v130
	v_mul_f32_e32 v111, 0xbfb8aa3b, v110
	v_exp_f32_e32 v111, v111
	global_store_dwordx4 v[112:113], v[114:117], off
	v_add_f32_e32 v111, 1.0, v111
	v_rcp_f32_e32 v111, v111
	s_nop 0
	v_mul_f32_e32 v110, v111, v110
	v_mul_f32_e32 v94, v94, v110
	v_and_b32_e32 v110, 0xffff0000, v130
	v_mul_f32_e32 v111, 0xbfb8aa3b, v110
	v_exp_f32_e32 v111, v111
	s_nop 0
	v_add_f32_e32 v111, 1.0, v111
	v_rcp_f32_e32 v111, v111
	s_nop 0
	v_mul_f32_e32 v110, v111, v110
	v_mul_f32_e32 v95, v95, v110
	v_cvt_pk_bf16_f32 v94, v94, v95
	v_lshlrev_b32_e32 v95, 16, v131
	v_mul_f32_e32 v110, 0xbfb8aa3b, v95
	v_exp_f32_e32 v110, v110
	s_nop 0
	v_add_f32_e32 v110, 1.0, v110
	v_rcp_f32_e32 v110, v110
	s_nop 0
	v_mul_f32_e32 v95, v110, v95
	v_mul_f32_e32 v95, v96, v95
	v_and_b32_e32 v96, 0xffff0000, v131
; __device__ __forceinline__ unsigned cvt_pk_bf16(float lo, float hi) { unsigned r; asm volatile("v_cvt_pk_bf16_f32 %0, %1, %2" : "=v"(r) : "v"(lo), "v"(hi)); return r; }
; __device__ __forceinline__ float bf_lo(unsigned w) { return __uint_as_float(w << 16); }
; __device__ __forceinline__ float bf_hi(unsigned w) { return __uint_as_float(w & 0xffff0000u); }
; __device__ __forceinline__ float silu_f(float z) { return z * fast_rcp(1.0f + __builtin_amdgcn_exp2f(z * -1.44269504f)); }
;     __device__ __forceinline__ void operator()(const f32x4 (&acc)[2][2][4][2], const Unit& u, int wr, int wc, int fr, int fq, const Pre&) const {
;     ...
;             for (int g8 = 0; g8 < 8; ++g8) zv[g8] = *(const u32x4*)(Z + (size_t)(row0 + (g8 >> 2) * HALF + (g8 & 3) * 16) * DE2 + c);
; #pragma unroll
;             for (int ai = 0; ai < 2; ++ai)
; #pragma unroll
;                 for (int m = 0; m < 4; ++m) { const int r = row0 + ai * HALF + m * 16;
;                     const u32x4 zw = zv[ai * 4 + m];
;                     const f32x4 a0 = acc[ai][bj][m][0] * sc[bj][0], a1 = acc[ai][bj][m][1] * sc[bj][1];
;                     u32x4 w;
;                     w.x = cvt_pk_bf16(a0[0] * silu_f(bf_lo(zw.x)), a0[1] * silu_f(bf_hi(zw.x)));
;                     w.y = cvt_pk_bf16(a0[2] * silu_f(bf_lo(zw.y)), a0[3] * silu_f(bf_hi(zw.y)));
;                     w.z = cvt_pk_bf16(a1[0] * silu_f(bf_lo(zw.z)), a1[1] * silu_f(bf_hi(zw.z)));
;                     w.w = cvt_pk_bf16(a1[2] * silu_f(bf_lo(zw.w)), a1[3] * silu_f(bf_hi(zw.w)));
;                     *(u32x4*)(O + (size_t)r * DE + c) = w; } }
	v_mul_f32_e32 v110, 0xbfb8aa3b, v96
	v_exp_f32_e32 v110, v110
	s_nop 0
	v_add_f32_e32 v110, 1.0, v110
	v_rcp_f32_e32 v110, v110
	s_nop 0
	v_mul_f32_e32 v96, v110, v96
	v_mul_f32_e32 v96, v97, v96
	v_cvt_pk_bf16_f32 v95, v95, v96
	v_lshlrev_b32_e32 v96, 16, v132
	v_mul_f32_e32 v97, 0xbfb8aa3b, v96
	v_exp_f32_e32 v97, v97
	v_lshl_add_u64 v[110:111], v[166:167], 0, s[0:1]
	s_mov_b64 s[0:1], 0x140000
	v_lshl_add_u64 v[114:115], v[166:167], 0, s[0:1]
	v_add_f32_e32 v97, 1.0, v97
	v_rcp_f32_e32 v97, v97
	s_mov_b64 s[0:1], 0x160000
	v_mul_f32_e32 v96, v97, v96
	v_mul_f32_e32 v90, v90, v96
	v_and_b32_e32 v96, 0xffff0000, v132
	v_mul_f32_e32 v97, 0xbfb8aa3b, v96
	v_exp_f32_e32 v97, v97
	s_nop 0
	v_add_f32_e32 v97, 1.0, v97
	v_rcp_f32_e32 v97, v97
	s_nop 0
	v_mul_f32_e32 v96, v97, v96
	v_mul_f32_e32 v91, v91, v96
	v_cvt_pk_bf16_f32 v96, v90, v91
	v_lshlrev_b32_e32 v90, 16, v133
	v_mul_f32_e32 v91, 0xbfb8aa3b, v90
	v_exp_f32_e32 v91, v91
	s_nop 0
	v_add_f32_e32 v91, 1.0, v91
	v_rcp_f32_e32 v91, v91
	s_nop 0
	v_mul_f32_e32 v90, v91, v90
	v_and_b32_e32 v91, 0xffff0000, v133
	v_mul_f32_e32 v90, v92, v90
	v_mul_f32_e32 v92, 0xbfb8aa3b, v91
	v_exp_f32_e32 v92, v92
	s_nop 0
	v_add_f32_e32 v92, 1.0, v92
	v_rcp_f32_e32 v92, v92
	s_nop 0
	v_mul_f32_e32 v91, v92, v91
	v_mul_f32_e32 v91, v93, v91
	v_cvt_pk_bf16_f32 v97, v90, v91
	v_add_co_u32_e32 v90, vcc, s41, v166
	s_nop 1
	v_addc_co_u32_e32 v91, vcc, 0, v167, vcc
	global_store_dwordx4 v[90:91], v[94:97], off
	v_lshlrev_b32_e32 v90, 16, v118
	v_mul_f32_e32 v91, 0xbfb8aa3b, v90
	v_exp_f32_e32 v91, v91
	s_nop 0
	v_add_f32_e32 v91, 1.0, v91
	v_rcp_f32_e32 v91, v91
	s_nop 0
	v_mul_f32_e32 v90, v91, v90
	v_mul_f32_e32 v86, v86, v90
	v_and_b32_e32 v90, 0xffff0000, v118
	v_mul_f32_e32 v91, 0xbfb8aa3b, v90
	v_exp_f32_e32 v91, v91
	s_nop 0
	v_add_f32_e32 v91, 1.0, v91
	v_rcp_f32_e32 v91, v91
	s_nop 0
	v_mul_f32_e32 v90, v91, v90
	v_mul_f32_e32 v87, v87, v90
	v_cvt_pk_bf16_f32 v86, v86, v87
	v_lshlrev_b32_e32 v87, 16, v119
	v_mul_f32_e32 v90, 0xbfb8aa3b, v87
	v_exp_f32_e32 v90, v90
	s_nop 0
	v_add_f32_e32 v90, 1.0, v90
	v_rcp_f32_e32 v90, v90
	s_nop 0
	v_mul_f32_e32 v87, v90, v87
	v_mul_f32_e32 v87, v88, v87
	v_and_b32_e32 v88, 0xffff0000, v119
	v_mul_f32_e32 v90, 0xbfb8aa3b, v88
	v_exp_f32_e32 v90, v90
	s_nop 0
	v_add_f32_e32 v90, 1.0, v90
	v_rcp_f32_e32 v90, v90
	s_nop 0
	v_mul_f32_e32 v88, v90, v88
	v_mul_f32_e32 v88, v89, v88
	v_cvt_pk_bf16_f32 v87, v87, v88
	v_lshlrev_b32_e32 v88, 16, v120
	v_mul_f32_e32 v89, 0xbfb8aa3b, v88
	v_exp_f32_e32 v89, v89
	s_nop 0
	v_add_f32_e32 v89, 1.0, v89
	v_rcp_f32_e32 v89, v89
	s_nop 0
	v_mul_f32_e32 v88, v89, v88
	v_mul_f32_e32 v82, v82, v88
	v_and_b32_e32 v88, 0xffff0000, v120
	v_mul_f32_e32 v89, 0xbfb8aa3b, v88
	v_exp_f32_e32 v89, v89
	s_nop 0
	v_add_f32_e32 v89, 1.0, v89
	v_rcp_f32_e32 v89, v89
	s_nop 0
	v_mul_f32_e32 v88, v89, v88
	v_mul_f32_e32 v83, v83, v88
	v_cvt_pk_bf16_f32 v88, v82, v83
	v_lshlrev_b32_e32 v82, 16, v121
	v_mul_f32_e32 v83, 0xbfb8aa3b, v82
	v_exp_f32_e32 v83, v83
	s_nop 0
	v_add_f32_e32 v83, 1.0, v83
	v_rcp_f32_e32 v83, v83
	s_nop 0
	v_mul_f32_e32 v82, v83, v82
	v_and_b32_e32 v83, 0xffff0000, v121
	v_mul_f32_e32 v82, v84, v82
	v_mul_f32_e32 v84, 0xbfb8aa3b, v83
	v_exp_f32_e32 v84, v84
	s_nop 0
	v_add_f32_e32 v84, 1.0, v84
	v_rcp_f32_e32 v84, v84
	s_nop 0
	v_mul_f32_e32 v83, v84, v83
	v_mul_f32_e32 v83, v85, v83
	v_cvt_pk_bf16_f32 v89, v82, v83
	v_add_co_u32_e32 v82, vcc, s65, v166
	s_nop 1
	v_addc_co_u32_e32 v83, vcc, 0, v167, vcc
	global_store_dwordx4 v[82:83], v[86:89], off
	v_lshlrev_b32_e32 v82, 16, v106
	v_mul_f32_e32 v83, 0xbfb8aa3b, v82
	v_exp_f32_e32 v83, v83
	s_nop 0
	v_add_f32_e32 v83, 1.0, v83
	v_rcp_f32_e32 v83, v83
	s_nop 0
	v_mul_f32_e32 v82, v83, v82
	v_mul_f32_e32 v78, v78, v82
	v_and_b32_e32 v82, 0xffff0000, v106
	v_mul_f32_e32 v83, 0xbfb8aa3b, v82
	v_exp_f32_e32 v83, v83
	s_nop 0
	v_add_f32_e32 v83, 1.0, v83
	v_rcp_f32_e32 v83, v83
	s_nop 0
	v_mul_f32_e32 v82, v83, v82
	v_mul_f32_e32 v79, v79, v82
	v_cvt_pk_bf16_f32 v78, v78, v79
	v_lshlrev_b32_e32 v79, 16, v107
	v_mul_f32_e32 v82, 0xbfb8aa3b, v79
	v_exp_f32_e32 v82, v82
	s_nop 0
	v_add_f32_e32 v82, 1.0, v82
	v_rcp_f32_e32 v82, v82
	s_nop 0
	v_mul_f32_e32 v79, v82, v79
	v_mul_f32_e32 v79, v80, v79
	v_and_b32_e32 v80, 0xffff0000, v107
	v_mul_f32_e32 v82, 0xbfb8aa3b, v80
	v_exp_f32_e32 v82, v82
	v_lshl_add_u64 v[106:107], v[166:167], 0, s[0:1]
	s_mov_b64 s[0:1], s[54:55]
	v_add_f32_e32 v82, 1.0, v82
	v_rcp_f32_e32 v82, v82
	s_nop 0
	v_mul_f32_e32 v80, v82, v80
	v_mul_f32_e32 v80, v81, v80
	v_cvt_pk_bf16_f32 v79, v79, v80
	v_lshlrev_b32_e32 v80, 16, v108
	v_mul_f32_e32 v81, 0xbfb8aa3b, v80
	v_exp_f32_e32 v81, v81
	s_nop 0
	v_add_f32_e32 v81, 1.0, v81
	v_rcp_f32_e32 v81, v81
	s_nop 0
	v_mul_f32_e32 v80, v81, v80
	v_mul_f32_e32 v74, v74, v80
	v_and_b32_e32 v80, 0xffff0000, v108
	v_mul_f32_e32 v81, 0xbfb8aa3b, v80
	v_exp_f32_e32 v81, v81
	s_nop 0
	v_add_f32_e32 v81, 1.0, v81
	v_rcp_f32_e32 v81, v81
	s_nop 0
	v_mul_f32_e32 v80, v81, v80
	v_mul_f32_e32 v75, v75, v80
	v_cvt_pk_bf16_f32 v80, v74, v75
	v_lshlrev_b32_e32 v74, 16, v109
	v_mul_f32_e32 v75, 0xbfb8aa3b, v74
	v_exp_f32_e32 v75, v75
	s_nop 0
	v_add_f32_e32 v75, 1.0, v75
	v_rcp_f32_e32 v75, v75
	s_nop 0
	v_mul_f32_e32 v74, v75, v74
	v_and_b32_e32 v75, 0xffff0000, v109
	v_mul_f32_e32 v74, v76, v74
	v_mul_f32_e32 v76, 0xbfb8aa3b, v75
	v_exp_f32_e32 v76, v76
	s_nop 0
	v_add_f32_e32 v76, 1.0, v76
	v_rcp_f32_e32 v76, v76
	s_nop 0
	v_mul_f32_e32 v75, v76, v75
	v_mul_f32_e32 v75, v77, v75
	v_cvt_pk_bf16_f32 v81, v74, v75
	v_add_co_u32_e32 v74, vcc, s70, v166
	v_lshl_add_u64 v[76:77], s[46:47], 0, v[204:205]
	s_nop 0
	v_addc_co_u32_e32 v75, vcc, 0, v167, vcc
	global_store_dwordx4 v[74:75], v[78:81], off
	v_or_b32_e32 v74, 0x80, v200
	v_ashrrev_i32_e32 v75, 31, v74
	v_lshlrev_b64 v[74:75], 1, v[74:75]
	v_lshl_add_u64 v[76:77], v[76:77], 0, v[74:75]
	global_load_dwordx4 v[102:105], v[76:77], off
	v_lshl_add_u64 v[76:77], s[46:47], 0, v[198:199]
	v_lshl_add_u64 v[76:77], v[76:77], 0, v[74:75]
	global_load_dwordx4 v[98:101], v[76:77], off
	v_lshl_add_u64 v[76:77], s[46:47], 0, v[202:203]
	v_lshl_add_u64 v[76:77], v[76:77], 0, v[74:75]
	global_load_dwordx4 v[94:97], v[76:77], off
	v_lshl_add_u64 v[76:77], s[46:47], 0, v[206:207]
	v_lshl_add_u64 v[76:77], v[76:77], 0, v[74:75]
	global_load_dwordx4 v[90:93], v[76:77], off
	v_lshl_add_u64 v[76:77], s[46:47], 0, v[208:209]
	v_lshl_add_u64 v[76:77], v[76:77], 0, v[74:75]
	global_load_dwordx4 v[86:89], v[76:77], off
	v_lshl_add_u64 v[76:77], s[46:47], 0, v[210:211]
	v_lshl_add_u64 v[76:77], v[76:77], 0, v[74:75]
	global_load_dwordx4 v[82:85], v[76:77], off
	v_lshl_add_u64 v[76:77], s[46:47], 0, v[212:213]
	v_lshl_add_u64 v[76:77], v[76:77], 0, v[74:75]
	global_load_dwordx4 v[78:81], v[76:77], off
	v_lshl_add_u64 v[76:77], s[46:47], 0, v[214:215]
	v_lshl_add_u64 v[74:75], v[76:77], 0, v[74:75]
	global_load_dwordx4 v[74:77], v[74:75], off
	s_and_b64 vcc, exec, s[42:43]
	s_waitcnt vmcnt(0)
; __device__ __forceinline__ unsigned cvt_pk_bf16(float lo, float hi) { unsigned r; asm volatile("v_cvt_pk_bf16_f32 %0, %1, %2" : "=v"(r) : "v"(lo), "v"(hi)); return r; }
; __device__ __forceinline__ float bf_lo(unsigned w) { return __uint_as_float(w << 16); }
; __device__ __forceinline__ float bf_hi(unsigned w) { return __uint_as_float(w & 0xffff0000u); }
; __device__ __forceinline__ float silu_f(float z) { return z * fast_rcp(1.0f + __builtin_amdgcn_exp2f(z * -1.44269504f)); }
;     __device__ __forceinline__ void operator()(const f32x4 (&acc)[2][2][4][2], const Unit& u, int wr, int wc, int fr, int fq, const Pre&) const {
;     ...
;             for (int g8 = 0; g8 < 8; ++g8) zv[g8] = *(const u32x4*)(Z + (size_t)(row0 + (g8 >> 2) * HALF + (g8 & 3) * 16) * DE2 + c);
; #pragma unroll
;             for (int ai = 0; ai < 2; ++ai)
; #pragma unroll
;                 for (int m = 0; m < 4; ++m) { const int r = row0 + ai * HALF + m * 16;
;                     const u32x4 zw = zv[ai * 4 + m];
;                     const f32x4 a0 = acc[ai][bj][m][0] * sc[bj][0], a1 = acc[ai][bj][m][1] * sc[bj][1];
;                     u32x4 w;
;                     w.x = cvt_pk_bf16(a0[0] * silu_f(bf_lo(zw.x)), a0[1] * silu_f(bf_hi(zw.x)));
;                     w.y = cvt_pk_bf16(a0[2] * silu_f(bf_lo(zw.y)), a0[3] * silu_f(bf_hi(zw.y)));
;                     w.z = cvt_pk_bf16(a1[0] * silu_f(bf_lo(zw.z)), a1[1] * silu_f(bf_hi(zw.z)));
;                     w.w = cvt_pk_bf16(a1[2] * silu_f(bf_lo(zw.w)), a1[3] * silu_f(bf_hi(zw.w)));
;                     *(u32x4*)(O + (size_t)r * DE + c) = w; } }
	v_lshlrev_b32_e32 v108, 16, v102
	v_mul_f32_e32 v109, 0xbfb8aa3b, v108
	v_exp_f32_e32 v109, v109
	v_and_b32_e32 v102, 0xffff0000, v102
	v_add_f32_e32 v109, 1.0, v109
	v_rcp_f32_e32 v109, v109
	s_nop 0
	v_mul_f32_e32 v108, v109, v108
	v_mul_f32_e32 v70, v70, v108
	v_mul_f32_e32 v108, 0xbfb8aa3b, v102
	v_exp_f32_e32 v108, v108
	s_nop 0
	v_add_f32_e32 v108, 1.0, v108
	v_rcp_f32_e32 v108, v108
	s_nop 0
	v_mul_f32_e32 v102, v108, v102
	v_mul_f32_e32 v71, v71, v102
	v_cvt_pk_bf16_f32 v70, v70, v71
	v_lshlrev_b32_e32 v71, 16, v103
	v_mul_f32_e32 v102, 0xbfb8aa3b, v71
	v_exp_f32_e32 v102, v102
	s_nop 0
	v_add_f32_e32 v102, 1.0, v102
	v_rcp_f32_e32 v102, v102
	s_nop 0
	v_mul_f32_e32 v71, v102, v71
	v_mul_f32_e32 v71, v72, v71
	v_and_b32_e32 v72, 0xffff0000, v103
	v_mul_f32_e32 v102, 0xbfb8aa3b, v72
	v_exp_f32_e32 v102, v102
	s_nop 0
	v_add_f32_e32 v102, 1.0, v102
	v_rcp_f32_e32 v102, v102
	s_nop 0
	v_mul_f32_e32 v72, v102, v72
	v_mul_f32_e32 v72, v73, v72
	v_cvt_pk_bf16_f32 v71, v71, v72
	v_lshlrev_b32_e32 v72, 16, v104
	v_mul_f32_e32 v73, 0xbfb8aa3b, v72
	v_exp_f32_e32 v73, v73
	s_nop 0
	v_add_f32_e32 v73, 1.0, v73
	v_rcp_f32_e32 v73, v73
	s_nop 0
	v_mul_f32_e32 v72, v73, v72
	v_mul_f32_e32 v66, v66, v72
	v_and_b32_e32 v72, 0xffff0000, v104
	v_mul_f32_e32 v73, 0xbfb8aa3b, v72
	v_exp_f32_e32 v73, v73
	s_nop 0
	v_add_f32_e32 v73, 1.0, v73
	v_rcp_f32_e32 v73, v73
	s_nop 0
	v_mul_f32_e32 v72, v73, v72
	v_mul_f32_e32 v67, v67, v72
	v_cvt_pk_bf16_f32 v72, v66, v67
	v_lshlrev_b32_e32 v66, 16, v105
	v_mul_f32_e32 v67, 0xbfb8aa3b, v66
	v_exp_f32_e32 v67, v67
	s_nop 0
	v_add_f32_e32 v67, 1.0, v67
	v_rcp_f32_e32 v67, v67
	s_nop 0
	v_mul_f32_e32 v66, v67, v66
	v_and_b32_e32 v67, 0xffff0000, v105
	v_mul_f32_e32 v66, v68, v66
	v_mul_f32_e32 v68, 0xbfb8aa3b, v67
	v_exp_f32_e32 v68, v68
	s_nop 0
	v_add_f32_e32 v68, 1.0, v68
	v_rcp_f32_e32 v68, v68
	s_nop 0
	v_mul_f32_e32 v67, v68, v67
	v_mul_f32_e32 v67, v69, v67
	v_cvt_pk_bf16_f32 v73, v66, v67
	v_lshlrev_b32_e32 v66, 16, v98
	v_mul_f32_e32 v67, 0xbfb8aa3b, v66
	v_exp_f32_e32 v67, v67
	global_store_dwordx4 v[166:167], v[70:73], off offset:256
	v_add_f32_e32 v67, 1.0, v67
	v_rcp_f32_e32 v67, v67
	s_nop 0
	v_mul_f32_e32 v66, v67, v66
	v_mul_f32_e32 v62, v62, v66
	v_and_b32_e32 v66, 0xffff0000, v98
	v_mul_f32_e32 v67, 0xbfb8aa3b, v66
	v_exp_f32_e32 v67, v67
	s_nop 0
	v_add_f32_e32 v67, 1.0, v67
	v_rcp_f32_e32 v67, v67
	s_nop 0
	v_mul_f32_e32 v66, v67, v66
	v_mul_f32_e32 v63, v63, v66
	v_cvt_pk_bf16_f32 v62, v62, v63
	v_lshlrev_b32_e32 v63, 16, v99
	v_mul_f32_e32 v66, 0xbfb8aa3b, v63
	v_exp_f32_e32 v66, v66
	s_nop 0
	v_add_f32_e32 v66, 1.0, v66
	v_rcp_f32_e32 v66, v66
	s_nop 0
	v_mul_f32_e32 v63, v66, v63
	v_mul_f32_e32 v63, v64, v63
	v_and_b32_e32 v64, 0xffff0000, v99
	v_mul_f32_e32 v66, 0xbfb8aa3b, v64
	v_exp_f32_e32 v66, v66
	s_nop 0
	v_add_f32_e32 v66, 1.0, v66
	v_rcp_f32_e32 v66, v66
	s_nop 0
	v_mul_f32_e32 v64, v66, v64
	v_mul_f32_e32 v64, v65, v64
	v_cvt_pk_bf16_f32 v63, v63, v64
	v_lshlrev_b32_e32 v64, 16, v100
	v_mul_f32_e32 v65, 0xbfb8aa3b, v64
	v_exp_f32_e32 v65, v65
	s_nop 0
	v_add_f32_e32 v65, 1.0, v65
	v_rcp_f32_e32 v65, v65
	s_nop 0
	v_mul_f32_e32 v64, v65, v64
	v_mul_f32_e32 v58, v58, v64
	v_and_b32_e32 v64, 0xffff0000, v100
	v_mul_f32_e32 v65, 0xbfb8aa3b, v64
	v_exp_f32_e32 v65, v65
	s_nop 0
	v_add_f32_e32 v65, 1.0, v65
	v_rcp_f32_e32 v65, v65
	s_nop 0
	v_mul_f32_e32 v64, v65, v64
	v_mul_f32_e32 v59, v59, v64
	v_cvt_pk_bf16_f32 v64, v58, v59
	v_lshlrev_b32_e32 v58, 16, v101
	v_mul_f32_e32 v59, 0xbfb8aa3b, v58
	v_exp_f32_e32 v59, v59
	s_nop 0
	v_add_f32_e32 v59, 1.0, v59
	v_rcp_f32_e32 v59, v59
	s_nop 0
	v_mul_f32_e32 v58, v59, v58
	v_and_b32_e32 v59, 0xffff0000, v101
	v_mul_f32_e32 v58, v60, v58
	v_mul_f32_e32 v60, 0xbfb8aa3b, v59
	v_exp_f32_e32 v60, v60
	s_nop 0
	v_add_f32_e32 v60, 1.0, v60
	v_rcp_f32_e32 v60, v60
	s_nop 0
	v_mul_f32_e32 v59, v60, v59
	v_mul_f32_e32 v59, v61, v59
	v_cvt_pk_bf16_f32 v65, v58, v59
	v_lshlrev_b32_e32 v58, 16, v94
	v_mul_f32_e32 v59, 0xbfb8aa3b, v58
	v_exp_f32_e32 v59, v59
	global_store_dwordx4 v[146:147], v[62:65], off offset:256
	v_add_f32_e32 v59, 1.0, v59
	v_rcp_f32_e32 v59, v59
	s_nop 0
	v_mul_f32_e32 v58, v59, v58
	v_mul_f32_e32 v54, v54, v58
	v_and_b32_e32 v58, 0xffff0000, v94
	v_mul_f32_e32 v59, 0xbfb8aa3b, v58
	v_exp_f32_e32 v59, v59
	s_nop 0
	v_add_f32_e32 v59, 1.0, v59
	v_rcp_f32_e32 v59, v59
	s_nop 0
	v_mul_f32_e32 v58, v59, v58
	v_mul_f32_e32 v55, v55, v58
	v_cvt_pk_bf16_f32 v54, v54, v55
	v_lshlrev_b32_e32 v55, 16, v95
	v_mul_f32_e32 v58, 0xbfb8aa3b, v55
	v_exp_f32_e32 v58, v58
	s_nop 0
	v_add_f32_e32 v58, 1.0, v58
	v_rcp_f32_e32 v58, v58
	s_nop 0
	v_mul_f32_e32 v55, v58, v55
	v_mul_f32_e32 v55, v56, v55
	v_and_b32_e32 v56, 0xffff0000, v95
	v_mul_f32_e32 v58, 0xbfb8aa3b, v56
	v_exp_f32_e32 v58, v58
	s_nop 0
	v_add_f32_e32 v58, 1.0, v58
	v_rcp_f32_e32 v58, v58
	s_nop 0
	v_mul_f32_e32 v56, v58, v56
	v_mul_f32_e32 v56, v57, v56
	v_cvt_pk_bf16_f32 v55, v55, v56
	v_lshlrev_b32_e32 v56, 16, v96
	v_mul_f32_e32 v57, 0xbfb8aa3b, v56
	v_exp_f32_e32 v57, v57
	s_nop 0
	v_add_f32_e32 v57, 1.0, v57
	v_rcp_f32_e32 v57, v57
	s_nop 0
	v_mul_f32_e32 v56, v57, v56
	v_mul_f32_e32 v50, v50, v56
	v_and_b32_e32 v56, 0xffff0000, v96
	v_mul_f32_e32 v57, 0xbfb8aa3b, v56
	v_exp_f32_e32 v57, v57
	s_nop 0
	v_add_f32_e32 v57, 1.0, v57
	v_rcp_f32_e32 v57, v57
	s_nop 0
	v_mul_f32_e32 v56, v57, v56
	v_mul_f32_e32 v51, v51, v56
	v_cvt_pk_bf16_f32 v56, v50, v51
	v_lshlrev_b32_e32 v50, 16, v97
	v_mul_f32_e32 v51, 0xbfb8aa3b, v50
	v_exp_f32_e32 v51, v51
	s_nop 0
	v_add_f32_e32 v51, 1.0, v51
	v_rcp_f32_e32 v51, v51
	s_nop 0
	v_mul_f32_e32 v50, v51, v50
	v_and_b32_e32 v51, 0xffff0000, v97
; __device__ __forceinline__ unsigned cvt_pk_bf16(float lo, float hi) { unsigned r; asm volatile("v_cvt_pk_bf16_f32 %0, %1, %2" : "=v"(r) : "v"(lo), "v"(hi)); return r; }
; __device__ __forceinline__ float bf_lo(unsigned w) { return __uint_as_float(w << 16); }
; __device__ __forceinline__ float bf_hi(unsigned w) { return __uint_as_float(w & 0xffff0000u); }
; __device__ __forceinline__ float silu_f(float z) { return z * fast_rcp(1.0f + __builtin_amdgcn_exp2f(z * -1.44269504f)); }
;     __device__ __forceinline__ void operator()(const f32x4 (&acc)[2][2][4][2], const Unit& u, int wr, int wc, int fr, int fq, const Pre&) const {
;     ...
;             for (int g8 = 0; g8 < 8; ++g8) zv[g8] = *(const u32x4*)(Z + (size_t)(row0 + (g8 >> 2) * HALF + (g8 & 3) * 16) * DE2 + c);
; #pragma unroll
;             for (int ai = 0; ai < 2; ++ai)
; #pragma unroll
;                 for (int m = 0; m < 4; ++m) { const int r = row0 + ai * HALF + m * 16;
;                     const u32x4 zw = zv[ai * 4 + m];
;                     const f32x4 a0 = acc[ai][bj][m][0] * sc[bj][0], a1 = acc[ai][bj][m][1] * sc[bj][1];
;                     u32x4 w;
;                     w.x = cvt_pk_bf16(a0[0] * silu_f(bf_lo(zw.x)), a0[1] * silu_f(bf_hi(zw.x)));
;                     w.y = cvt_pk_bf16(a0[2] * silu_f(bf_lo(zw.y)), a0[3] * silu_f(bf_hi(zw.y)));
;                     w.z = cvt_pk_bf16(a1[0] * silu_f(bf_lo(zw.z)), a1[1] * silu_f(bf_hi(zw.z)));
;                     w.w = cvt_pk_bf16(a1[2] * silu_f(bf_lo(zw.w)), a1[3] * silu_f(bf_hi(zw.w)));
;                     *(u32x4*)(O + (size_t)r * DE + c) = w; } }
	v_mul_f32_e32 v50, v52, v50
	v_mul_f32_e32 v52, 0xbfb8aa3b, v51
	v_exp_f32_e32 v52, v52
	s_nop 0
	v_add_f32_e32 v52, 1.0, v52
	v_rcp_f32_e32 v52, v52
	s_nop 0
	v_mul_f32_e32 v51, v52, v51
	v_mul_f32_e32 v51, v53, v51
	v_cvt_pk_bf16_f32 v57, v50, v51
	v_lshlrev_b32_e32 v50, 16, v90
	v_mul_f32_e32 v51, 0xbfb8aa3b, v50
	v_exp_f32_e32 v51, v51
	global_store_dwordx4 v[134:135], v[54:57], off offset:256
	v_add_f32_e32 v51, 1.0, v51
	v_rcp_f32_e32 v51, v51
	s_nop 0
	v_mul_f32_e32 v50, v51, v50
	v_mul_f32_e32 v46, v46, v50
	v_and_b32_e32 v50, 0xffff0000, v90
	v_mul_f32_e32 v51, 0xbfb8aa3b, v50
	v_exp_f32_e32 v51, v51
	s_nop 0
	v_add_f32_e32 v51, 1.0, v51
	v_rcp_f32_e32 v51, v51
	s_nop 0
	v_mul_f32_e32 v50, v51, v50
	v_mul_f32_e32 v47, v47, v50
	v_cvt_pk_bf16_f32 v46, v46, v47
	v_lshlrev_b32_e32 v47, 16, v91
	v_mul_f32_e32 v50, 0xbfb8aa3b, v47
	v_exp_f32_e32 v50, v50
	s_nop 0
	v_add_f32_e32 v50, 1.0, v50
	v_rcp_f32_e32 v50, v50
	s_nop 0
	v_mul_f32_e32 v47, v50, v47
	v_mul_f32_e32 v47, v48, v47
	v_and_b32_e32 v48, 0xffff0000, v91
	v_mul_f32_e32 v50, 0xbfb8aa3b, v48
	v_exp_f32_e32 v50, v50
	s_nop 0
	v_add_f32_e32 v50, 1.0, v50
	v_rcp_f32_e32 v50, v50
	s_nop 0
	v_mul_f32_e32 v48, v50, v48
	v_mul_f32_e32 v48, v49, v48
	v_cvt_pk_bf16_f32 v47, v47, v48
	v_lshlrev_b32_e32 v48, 16, v92
	v_mul_f32_e32 v49, 0xbfb8aa3b, v48
	v_exp_f32_e32 v49, v49
	s_nop 0
	v_add_f32_e32 v49, 1.0, v49
	v_rcp_f32_e32 v49, v49
	s_nop 0
	v_mul_f32_e32 v48, v49, v48
	v_mul_f32_e32 v42, v42, v48
	v_and_b32_e32 v48, 0xffff0000, v92
	v_mul_f32_e32 v49, 0xbfb8aa3b, v48
	v_exp_f32_e32 v49, v49
	s_nop 0
	v_add_f32_e32 v49, 1.0, v49
	v_rcp_f32_e32 v49, v49
	s_nop 0
	v_mul_f32_e32 v48, v49, v48
	v_mul_f32_e32 v43, v43, v48
	v_cvt_pk_bf16_f32 v48, v42, v43
	v_lshlrev_b32_e32 v42, 16, v93
	v_mul_f32_e32 v43, 0xbfb8aa3b, v42
	v_exp_f32_e32 v43, v43
	s_nop 0
	v_add_f32_e32 v43, 1.0, v43
	v_rcp_f32_e32 v43, v43
	s_nop 0
	v_mul_f32_e32 v42, v43, v42
	v_and_b32_e32 v43, 0xffff0000, v93
	v_mul_f32_e32 v42, v44, v42
	v_mul_f32_e32 v44, 0xbfb8aa3b, v43
	v_exp_f32_e32 v44, v44
	s_nop 0
	v_add_f32_e32 v44, 1.0, v44
	v_rcp_f32_e32 v44, v44
	s_nop 0
	v_mul_f32_e32 v43, v44, v43
	v_mul_f32_e32 v43, v45, v43
	v_cvt_pk_bf16_f32 v49, v42, v43
	v_lshlrev_b32_e32 v42, 16, v86
	v_mul_f32_e32 v43, 0xbfb8aa3b, v42
	v_exp_f32_e32 v43, v43
	global_store_dwordx4 v[122:123], v[46:49], off offset:256
	v_add_f32_e32 v43, 1.0, v43
	v_rcp_f32_e32 v43, v43
	s_nop 0
	v_mul_f32_e32 v42, v43, v42
	v_mul_f32_e32 v30, v30, v42
	v_and_b32_e32 v42, 0xffff0000, v86
	v_mul_f32_e32 v43, 0xbfb8aa3b, v42
	v_exp_f32_e32 v43, v43
	s_nop 0
	v_add_f32_e32 v43, 1.0, v43
	v_rcp_f32_e32 v43, v43
	s_nop 0
	v_mul_f32_e32 v42, v43, v42
	v_mul_f32_e32 v31, v31, v42
	v_cvt_pk_bf16_f32 v30, v30, v31
	v_lshlrev_b32_e32 v31, 16, v87
	v_mul_f32_e32 v42, 0xbfb8aa3b, v31
	v_exp_f32_e32 v42, v42
	s_nop 0
	v_add_f32_e32 v42, 1.0, v42
	v_rcp_f32_e32 v42, v42
	s_nop 0
	v_mul_f32_e32 v31, v42, v31
	v_mul_f32_e32 v31, v32, v31
	v_and_b32_e32 v32, 0xffff0000, v87
	v_mul_f32_e32 v42, 0xbfb8aa3b, v32
	v_exp_f32_e32 v42, v42
	s_nop 0
	v_add_f32_e32 v42, 1.0, v42
	v_rcp_f32_e32 v42, v42
	s_nop 0
	v_mul_f32_e32 v32, v42, v32
	v_mul_f32_e32 v32, v33, v32
	v_cvt_pk_bf16_f32 v31, v31, v32
	v_lshlrev_b32_e32 v32, 16, v88
	v_mul_f32_e32 v33, 0xbfb8aa3b, v32
	v_exp_f32_e32 v33, v33
	s_nop 0
	v_add_f32_e32 v33, 1.0, v33
	v_rcp_f32_e32 v33, v33
	s_nop 0
	v_mul_f32_e32 v32, v33, v32
	v_mul_f32_e32 v26, v26, v32
	v_and_b32_e32 v32, 0xffff0000, v88
	v_mul_f32_e32 v33, 0xbfb8aa3b, v32
	v_exp_f32_e32 v33, v33
	s_nop 0
	v_add_f32_e32 v33, 1.0, v33
	v_rcp_f32_e32 v33, v33
	s_nop 0
	v_mul_f32_e32 v32, v33, v32
	v_mul_f32_e32 v27, v27, v32
	v_cvt_pk_bf16_f32 v32, v26, v27
	v_lshlrev_b32_e32 v26, 16, v89
	v_mul_f32_e32 v27, 0xbfb8aa3b, v26
	v_exp_f32_e32 v27, v27
	s_nop 0
	v_add_f32_e32 v27, 1.0, v27
	v_rcp_f32_e32 v27, v27
	s_nop 0
	v_mul_f32_e32 v26, v27, v26
	v_and_b32_e32 v27, 0xffff0000, v89
	v_mul_f32_e32 v26, v28, v26
	v_mul_f32_e32 v28, 0xbfb8aa3b, v27
	v_exp_f32_e32 v28, v28
	s_nop 0
	v_add_f32_e32 v28, 1.0, v28
	v_rcp_f32_e32 v28, v28
	s_nop 0
	v_mul_f32_e32 v27, v28, v27
	v_mul_f32_e32 v27, v29, v27
	v_cvt_pk_bf16_f32 v33, v26, v27
	v_lshlrev_b32_e32 v26, 16, v82
	v_mul_f32_e32 v27, 0xbfb8aa3b, v26
	v_exp_f32_e32 v27, v27
	global_store_dwordx4 v[112:113], v[30:33], off offset:256
	v_add_f32_e32 v27, 1.0, v27
	v_rcp_f32_e32 v27, v27
	s_nop 0
	v_mul_f32_e32 v26, v27, v26
	v_mul_f32_e32 v22, v22, v26
	v_and_b32_e32 v26, 0xffff0000, v82
	v_mul_f32_e32 v27, 0xbfb8aa3b, v26
	v_exp_f32_e32 v27, v27
	s_nop 0
	v_add_f32_e32 v27, 1.0, v27
	v_rcp_f32_e32 v27, v27
	s_nop 0
	v_mul_f32_e32 v26, v27, v26
	v_mul_f32_e32 v23, v23, v26
	v_cvt_pk_bf16_f32 v22, v22, v23
	v_lshlrev_b32_e32 v23, 16, v83
	v_mul_f32_e32 v26, 0xbfb8aa3b, v23
	v_exp_f32_e32 v26, v26
	s_nop 0
	v_add_f32_e32 v26, 1.0, v26
	v_rcp_f32_e32 v26, v26
	s_nop 0
	v_mul_f32_e32 v23, v26, v23
	v_mul_f32_e32 v23, v24, v23
	v_and_b32_e32 v24, 0xffff0000, v83
	v_mul_f32_e32 v26, 0xbfb8aa3b, v24
	v_exp_f32_e32 v26, v26
	s_nop 0
	v_add_f32_e32 v26, 1.0, v26
	v_rcp_f32_e32 v26, v26
; __device__ __forceinline__ unsigned cvt_pk_bf16(float lo, float hi) { unsigned r; asm volatile("v_cvt_pk_bf16_f32 %0, %1, %2" : "=v"(r) : "v"(lo), "v"(hi)); return r; }
; __device__ __forceinline__ float bf_lo(unsigned w) { return __uint_as_float(w << 16); }
; __device__ __forceinline__ float bf_hi(unsigned w) { return __uint_as_float(w & 0xffff0000u); }
; __device__ __forceinline__ float silu_f(float z) { return z * fast_rcp(1.0f + __builtin_amdgcn_exp2f(z * -1.44269504f)); }
; #define PG8_WAIT_V(n) asm volatile("s_waitcnt vmcnt(" #n ")" ::: "memory")
; #define PG8_BAR __builtin_amdgcn_s_barrier()
; template <class Epi>
; __device__ __forceinline__ void gemm_phase(LAS unsigned char* lds, const Gemm g, const StaticOrder& S, const Epi& E) {
;     ...
;         if (!has_next) break;
; #pragma unroll
;         for (int a = 0; a < 2; ++a)
; #pragma unroll
;             for (int b = 0; b < 2; ++b)
; #pragma unroll
;                 for (int m = 0; m < 4; ++m)
; #pragma unroll
;                     for (int n = 0; n < 2; ++n) acc[a][b][m][n] = (f32x4){0.f, 0.f, 0.f, 0.f};
;         cur = nxt; cA = nA; cB = nB; ++ui;
;         pre = E.pre(cur, wr, fr);
;     }
;     PG8_WAIT_V(0);
;     if (wr == 0) PG8_BAR;
;     PG8_BAR;
;     __device__ __forceinline__ void operator()(const f32x4 (&acc)[2][2][4][2], const Unit& u, int wr, int wc, int fr, int fq, const Pre&) const {
;     ...
;                 for (int m = 0; m < 4; ++m) { const int r = row0 + ai * HALF + m * 16;
;                     const u32x4 zw = zv[ai * 4 + m];
;                     const f32x4 a0 = acc[ai][bj][m][0] * sc[bj][0], a1 = acc[ai][bj][m][1] * sc[bj][1];
;                     u32x4 w;
;                     w.x = cvt_pk_bf16(a0[0] * silu_f(bf_lo(zw.x)), a0[1] * silu_f(bf_hi(zw.x)));
;                     w.y = cvt_pk_bf16(a0[2] * silu_f(bf_lo(zw.y)), a0[3] * silu_f(bf_hi(zw.y)));
;                     w.z = cvt_pk_bf16(a1[0] * silu_f(bf_lo(zw.z)), a1[1] * silu_f(bf_hi(zw.z)));
;                     w.w = cvt_pk_bf16(a1[2] * silu_f(bf_lo(zw.w)), a1[3] * silu_f(bf_hi(zw.w)));
;                     *(u32x4*)(O + (size_t)r * DE + c) = w; } }
	s_nop 0
	v_mul_f32_e32 v24, v26, v24
	v_mul_f32_e32 v24, v25, v24
	v_cvt_pk_bf16_f32 v23, v23, v24
	v_lshlrev_b32_e32 v24, 16, v84
	v_mul_f32_e32 v25, 0xbfb8aa3b, v24
	v_exp_f32_e32 v25, v25
	s_nop 0
	v_add_f32_e32 v25, 1.0, v25
	v_rcp_f32_e32 v25, v25
	s_nop 0
	v_mul_f32_e32 v24, v25, v24
	v_mul_f32_e32 v18, v18, v24
	v_and_b32_e32 v24, 0xffff0000, v84
	v_mul_f32_e32 v25, 0xbfb8aa3b, v24
	v_exp_f32_e32 v25, v25
	s_nop 0
	v_add_f32_e32 v25, 1.0, v25
	v_rcp_f32_e32 v25, v25
	s_nop 0
	v_mul_f32_e32 v24, v25, v24
	v_mul_f32_e32 v19, v19, v24
	v_cvt_pk_bf16_f32 v24, v18, v19
	v_lshlrev_b32_e32 v18, 16, v85
	v_mul_f32_e32 v19, 0xbfb8aa3b, v18
	v_exp_f32_e32 v19, v19
	s_nop 0
	v_add_f32_e32 v19, 1.0, v19
	v_rcp_f32_e32 v19, v19
	s_nop 0
	v_mul_f32_e32 v18, v19, v18
	v_and_b32_e32 v19, 0xffff0000, v85
	v_mul_f32_e32 v18, v20, v18
	v_mul_f32_e32 v20, 0xbfb8aa3b, v19
	v_exp_f32_e32 v20, v20
	s_nop 0
	v_add_f32_e32 v20, 1.0, v20
	v_rcp_f32_e32 v20, v20
	s_nop 0
	v_mul_f32_e32 v19, v20, v19
	v_mul_f32_e32 v19, v21, v19
	v_cvt_pk_bf16_f32 v25, v18, v19
	v_lshlrev_b32_e32 v18, 16, v78
	v_mul_f32_e32 v19, 0xbfb8aa3b, v18
	v_exp_f32_e32 v19, v19
	global_store_dwordx4 v[110:111], v[22:25], off offset:256
	v_add_f32_e32 v19, 1.0, v19
	v_rcp_f32_e32 v19, v19
	s_nop 0
	v_mul_f32_e32 v18, v19, v18
	v_mul_f32_e32 v14, v14, v18
	v_and_b32_e32 v18, 0xffff0000, v78
	v_mul_f32_e32 v19, 0xbfb8aa3b, v18
	v_exp_f32_e32 v19, v19
	s_nop 0
	v_add_f32_e32 v19, 1.0, v19
	v_rcp_f32_e32 v19, v19
	s_nop 0
	v_mul_f32_e32 v18, v19, v18
	v_mul_f32_e32 v15, v15, v18
	v_cvt_pk_bf16_f32 v14, v14, v15
	v_lshlrev_b32_e32 v15, 16, v79
	v_mul_f32_e32 v18, 0xbfb8aa3b, v15
	v_exp_f32_e32 v18, v18
	s_nop 0
	v_add_f32_e32 v18, 1.0, v18
	v_rcp_f32_e32 v18, v18
	s_nop 0
	v_mul_f32_e32 v15, v18, v15
	v_mul_f32_e32 v15, v16, v15
	v_and_b32_e32 v16, 0xffff0000, v79
	v_mul_f32_e32 v18, 0xbfb8aa3b, v16
	v_exp_f32_e32 v18, v18
	s_nop 0
	v_add_f32_e32 v18, 1.0, v18
	v_rcp_f32_e32 v18, v18
	s_nop 0
	v_mul_f32_e32 v16, v18, v16
	v_mul_f32_e32 v16, v17, v16
	v_cvt_pk_bf16_f32 v15, v15, v16
	v_lshlrev_b32_e32 v16, 16, v80
	v_mul_f32_e32 v17, 0xbfb8aa3b, v16
	v_exp_f32_e32 v17, v17
	s_nop 0
	v_add_f32_e32 v17, 1.0, v17
	v_rcp_f32_e32 v17, v17
	s_nop 0
	v_mul_f32_e32 v16, v17, v16
	v_mul_f32_e32 v10, v10, v16
	v_and_b32_e32 v16, 0xffff0000, v80
	v_mul_f32_e32 v17, 0xbfb8aa3b, v16
	v_exp_f32_e32 v17, v17
	s_nop 0
	v_add_f32_e32 v17, 1.0, v17
	v_rcp_f32_e32 v17, v17
	s_nop 0
	v_mul_f32_e32 v16, v17, v16
	v_mul_f32_e32 v11, v11, v16
	v_cvt_pk_bf16_f32 v16, v10, v11
	v_lshlrev_b32_e32 v10, 16, v81
	v_mul_f32_e32 v11, 0xbfb8aa3b, v10
	v_exp_f32_e32 v11, v11
	s_nop 0
	v_add_f32_e32 v11, 1.0, v11
	v_rcp_f32_e32 v11, v11
	s_nop 0
	v_mul_f32_e32 v10, v11, v10
	v_and_b32_e32 v11, 0xffff0000, v81
	v_mul_f32_e32 v10, v12, v10
	v_mul_f32_e32 v12, 0xbfb8aa3b, v11
	v_exp_f32_e32 v12, v12
	s_nop 0
	v_add_f32_e32 v12, 1.0, v12
	v_rcp_f32_e32 v12, v12
	s_nop 0
	v_mul_f32_e32 v11, v12, v11
	v_mul_f32_e32 v11, v13, v11
	v_cvt_pk_bf16_f32 v17, v10, v11
	v_lshlrev_b32_e32 v10, 16, v74
	v_mul_f32_e32 v11, 0xbfb8aa3b, v10
	v_exp_f32_e32 v11, v11
	global_store_dwordx4 v[114:115], v[14:17], off offset:256
	v_add_f32_e32 v11, 1.0, v11
	v_rcp_f32_e32 v11, v11
	s_nop 0
	v_mul_f32_e32 v10, v11, v10
	v_mul_f32_e32 v6, v6, v10
	v_and_b32_e32 v10, 0xffff0000, v74
	v_mul_f32_e32 v11, 0xbfb8aa3b, v10
	v_exp_f32_e32 v11, v11
	s_nop 0
	v_add_f32_e32 v11, 1.0, v11
	v_rcp_f32_e32 v11, v11
	s_nop 0
	v_mul_f32_e32 v10, v11, v10
	v_mul_f32_e32 v7, v7, v10
	v_cvt_pk_bf16_f32 v6, v6, v7
	v_lshlrev_b32_e32 v7, 16, v75
	v_mul_f32_e32 v10, 0xbfb8aa3b, v7
	v_exp_f32_e32 v10, v10
	s_nop 0
	v_add_f32_e32 v10, 1.0, v10
	v_rcp_f32_e32 v10, v10
	s_nop 0
	v_mul_f32_e32 v7, v10, v7
	v_mul_f32_e32 v7, v8, v7
	v_and_b32_e32 v8, 0xffff0000, v75
	v_mul_f32_e32 v10, 0xbfb8aa3b, v8
	v_exp_f32_e32 v10, v10
	s_nop 0
	v_add_f32_e32 v10, 1.0, v10
	v_rcp_f32_e32 v10, v10
	s_nop 0
	v_mul_f32_e32 v8, v10, v8
	v_mul_f32_e32 v8, v9, v8
	v_cvt_pk_bf16_f32 v7, v7, v8
	v_lshlrev_b32_e32 v8, 16, v76
	v_mul_f32_e32 v9, 0xbfb8aa3b, v8
	v_exp_f32_e32 v9, v9
	s_nop 0
	v_add_f32_e32 v9, 1.0, v9
	v_rcp_f32_e32 v9, v9
	s_nop 0
	v_mul_f32_e32 v8, v9, v8
	v_mul_f32_e32 v2, v2, v8
	v_and_b32_e32 v8, 0xffff0000, v76
	v_mul_f32_e32 v9, 0xbfb8aa3b, v8
	v_exp_f32_e32 v9, v9
	s_nop 0
	v_add_f32_e32 v9, 1.0, v9
	v_rcp_f32_e32 v9, v9
	s_nop 0
	v_mul_f32_e32 v8, v9, v8
	v_mul_f32_e32 v3, v3, v8
	v_cvt_pk_bf16_f32 v8, v2, v3
	v_lshlrev_b32_e32 v2, 16, v77
	v_mul_f32_e32 v3, 0xbfb8aa3b, v2
	v_exp_f32_e32 v3, v3
	s_nop 0
	v_add_f32_e32 v3, 1.0, v3
	v_rcp_f32_e32 v3, v3
	s_nop 0
	v_mul_f32_e32 v2, v3, v2
	v_and_b32_e32 v3, 0xffff0000, v77
	v_mul_f32_e32 v2, v4, v2
	v_mul_f32_e32 v4, 0xbfb8aa3b, v3
	v_exp_f32_e32 v4, v4
	s_nop 0
	v_add_f32_e32 v4, 1.0, v4
	v_rcp_f32_e32 v4, v4
	s_nop 0
	v_mul_f32_e32 v3, v4, v3
	v_mul_f32_e32 v3, v5, v3
	v_cvt_pk_bf16_f32 v9, v2, v3
	global_store_dwordx4 v[106:107], v[6:9], off offset:256
	s_cbranch_vccz .LBB0_596
	s_waitcnt vmcnt(0)
	s_cmpk_gt_u32 s14, 0xff
	s_mov_b64 s[36:37], s[96:97]
	s_cbranch_scc1 .LBB0_607
	s_barrier

; #define PG8_STAGE(bufoff, gbase, voff) do { _Pragma("unroll") for (int _i = 0; _i < 2; ++_i) \
;         __builtin_amdgcn_global_load_lds((const unsigned*)((const char*)(gbase) + (voff)[_i]), (LAS unsigned*)(lds + (bufoff) + ldsw + _i * 8192), 16, 0, 0); } while (0)
; #define PG8_LDA(dst, b, h) do { _Pragma("unroll") for (int m = 0; m < 4; ++m) _Pragma("unroll") for (int k = 0; k < 2; ++k) dst[m][k] = *(const LAS bf16x8*)(lds + PG8_SA(b, h) + aoff + m * 2048 + k * 1024); } while (0)
; #define PG8_LDB(dst, b, h) do { _Pragma("unroll") for (int n = 0; n < 2; ++n) _Pragma("unroll") for (int k = 0; k < 2; ++k) dst[n][k] = *(const LAS bf16x8*)(lds + PG8_SB(b, h) + boff + n * 2048 + k * 1024); } while (0)
; #define PG8_MMA(ai, bj, At, Bt) do { __builtin_amdgcn_s_setprio(1); _Pragma("unroll") for (int m = 0; m < 4; ++m) _Pragma("unroll") for (int n = 0; n < 2; ++n) _Pragma("unroll") for (int k = 0; k < 2; ++k) \
;         acc[ai][bj][m][n] = __builtin_amdgcn_mfma_f32_16x16x32_bf16(Bt[n][k], At[m][k], acc[ai][bj][m][n], 0, 0, 0); __builtin_amdgcn_s_setprio(0); } while (0)
; #define PG8_WAIT_L(n) asm volatile("s_waitcnt lgkmcnt(" #n ")" ::: "memory")
; #define PG8_BAR __builtin_amdgcn_s_barrier()
; #define PG8_SCHED __builtin_amdgcn_sched_barrier(0)
; template <class Epi>
; __device__ __forceinline__ void gemm_phase(LAS unsigned char* lds, const Gemm g, const StaticOrder& S, const Epi& E) {
;     ...
;         const bool has_next = S.next(ui + 1, nxt);
;         const char* nA = has_next ? (const char*)g.A + (size_t)nxt.pm * tstepA + (size_t)(nxt.pn >> 2) * gstepA : cA; const char* nB = has_next ? (const char*)g.Bt + (size_t)nxt.pn * tstepB : cB;
;         for (int t = 0; t < nt; t += 2) {
;             const bool last = (t == nt - 2);
;             const char* a1 = cA + (size_t)(t + 1) * kstepA;
;             const char* a2 = last ? nA : cA + (size_t)(t + 2) * kstepA; const char* b2 = last ? nB : cB + (size_t)(t + 2) * kstep;
;             const char* a3 = a2 + kstepA; const char* b3 = b2 + kstep;
;             PG8_LDB(B0, 0, 0); PG8_SCHED; PG8_LDA(At, 0, 0); PG8_STAGE(PG8_SA(1, 1), a1 + hstepA, voffA);
;             PG8_WAIT_L(8); PG8_BAR; PG8_WAIT_L(0); PG8_MMA(0, 0, At, B0); PG8_BAR; PG8_SCHED;
.LBB0_795:
	s_ashr_i32 s51, s50, 31
	v_cmp_lt_i64_e32 vcc, s[4:5], v[182:183]
	s_lshl_b64 s[4:5], s[50:51], 13
	s_add_u32 s52, s42, s4
	s_addc_u32 s53, s43, s5
	s_and_b64 s[4:5], vcc, exec
	s_cselect_b32 s37, s53, s15
	s_cselect_b32 s38, s52, s14
	s_ashr_i32 s49, s48, 31
	s_lshl_b64 s[4:5], s[48:49], 21
	s_add_u32 s54, s19, s4
	s_addc_u32 s55, s20, s5
	s_and_b64 s[4:5], vcc, exec
	s_cselect_b32 s39, s55, s9
	s_cselect_b32 s49, s54, s8
	s_add_u32 s51, s8, 0x100
	s_addc_u32 s56, s9, 0
	s_add_u32 s8, s14, 0x105400
	v_mov_b32_e32 v2, 0
	s_addc_u32 s9, s15, 0
	s_mov_b32 s57, -2
	v_mov_b32_e32 v3, v2
	v_mov_b32_e32 v4, v2
	v_mov_b32_e32 v5, v2
	v_mov_b32_e32 v6, v2
	v_mov_b32_e32 v7, v2
	v_mov_b32_e32 v8, v2
	v_mov_b32_e32 v9, v2
	v_mov_b32_e32 v10, v2
	v_mov_b32_e32 v11, v2
	v_mov_b32_e32 v12, v2
	v_mov_b32_e32 v13, v2
	v_mov_b32_e32 v14, v2
	v_mov_b32_e32 v15, v2
	v_mov_b32_e32 v16, v2
	v_mov_b32_e32 v17, v2
	v_mov_b32_e32 v18, v2
	v_mov_b32_e32 v19, v2
	v_mov_b32_e32 v20, v2
	v_mov_b32_e32 v21, v2
	v_mov_b32_e32 v22, v2
	v_mov_b32_e32 v23, v2
	v_mov_b32_e32 v24, v2
	v_mov_b32_e32 v25, v2
	v_mov_b32_e32 v34, v2
	v_mov_b32_e32 v35, v2
	v_mov_b32_e32 v36, v2
	v_mov_b32_e32 v37, v2
	v_mov_b32_e32 v38, v2
	v_mov_b32_e32 v39, v2
	v_mov_b32_e32 v40, v2
	v_mov_b32_e32 v41, v2
	v_mov_b32_e32 v74, v2
	v_mov_b32_e32 v75, v2
	v_mov_b32_e32 v76, v2
	v_mov_b32_e32 v77, v2
	v_mov_b32_e32 v78, v2
	v_mov_b32_e32 v79, v2
	v_mov_b32_e32 v80, v2
	v_mov_b32_e32 v81, v2
	v_mov_b32_e32 v82, v2
	v_mov_b32_e32 v83, v2
	v_mov_b32_e32 v84, v2
	v_mov_b32_e32 v85, v2
	v_mov_b32_e32 v86, v2
	v_mov_b32_e32 v87, v2
	v_mov_b32_e32 v88, v2
	v_mov_b32_e32 v89, v2
	v_mov_b32_e32 v90, v2
	v_mov_b32_e32 v91, v2
	v_mov_b32_e32 v92, v2
	v_mov_b32_e32 v93, v2
	v_mov_b32_e32 v94, v2
	v_mov_b32_e32 v95, v2
	v_mov_b32_e32 v96, v2
	v_mov_b32_e32 v97, v2
	v_mov_b32_e32 v106, v2
	v_mov_b32_e32 v107, v2
	v_mov_b32_e32 v108, v2
	v_mov_b32_e32 v109, v2
	v_mov_b32_e32 v110, v2
	v_mov_b32_e32 v111, v2
	v_mov_b32_e32 v112, v2
	v_mov_b32_e32 v113, v2
	v_mov_b32_e32 v42, v2
	v_mov_b32_e32 v43, v2
	v_mov_b32_e32 v44, v2
	v_mov_b32_e32 v45, v2
	v_mov_b32_e32 v46, v2
	v_mov_b32_e32 v47, v2
	v_mov_b32_e32 v48, v2
	v_mov_b32_e32 v49, v2
	v_mov_b32_e32 v50, v2
	v_mov_b32_e32 v51, v2
	v_mov_b32_e32 v52, v2
	v_mov_b32_e32 v53, v2
	v_mov_b32_e32 v54, v2
	v_mov_b32_e32 v55, v2
	v_mov_b32_e32 v56, v2
	v_mov_b32_e32 v57, v2
	v_mov_b32_e32 v58, v2
	v_mov_b32_e32 v59, v2
	v_mov_b32_e32 v60, v2
	v_mov_b32_e32 v61, v2
	v_mov_b32_e32 v62, v2
	v_mov_b32_e32 v63, v2
	v_mov_b32_e32 v64, v2
	v_mov_b32_e32 v65, v2
	v_mov_b32_e32 v66, v2
	v_mov_b32_e32 v67, v2
	v_mov_b32_e32 v68, v2
	v_mov_b32_e32 v69, v2
	v_mov_b32_e32 v70, v2
	v_mov_b32_e32 v71, v2
	v_mov_b32_e32 v72, v2
	v_mov_b32_e32 v73, v2
	v_mov_b32_e32 v114, v2
	v_mov_b32_e32 v115, v2
	v_mov_b32_e32 v116, v2
	v_mov_b32_e32 v117, v2
	v_mov_b32_e32 v118, v2
	v_mov_b32_e32 v119, v2
	v_mov_b32_e32 v120, v2
	v_mov_b32_e32 v121, v2
	v_mov_b32_e32 v122, v2
	v_mov_b32_e32 v123, v2
	v_mov_b32_e32 v124, v2
	v_mov_b32_e32 v125, v2
	v_mov_b32_e32 v126, v2
	v_mov_b32_e32 v127, v2
	v_mov_b32_e32 v128, v2
	v_mov_b32_e32 v129, v2
	v_mov_b32_e32 v134, v2
	v_mov_b32_e32 v135, v2
	v_mov_b32_e32 v136, v2
	v_mov_b32_e32 v137, v2
	v_mov_b32_e32 v138, v2
	v_mov_b32_e32 v139, v2
	v_mov_b32_e32 v140, v2
	v_mov_b32_e32 v141, v2
	v_mov_b32_e32 v158, v2
	v_mov_b32_e32 v159, v2
	v_mov_b32_e32 v160, v2
	v_mov_b32_e32 v161, v2
	v_mov_b32_e32 v162, v2
	v_mov_b32_e32 v163, v2
	v_mov_b32_e32 v164, v2
	v_mov_b32_e32 v165, v2
	v_add_u32_e32 v250, 0x10000, v245
	v_readfirstlane_b32 s100, v232
	s_nop 3
	s_cmp_ge_u32 s100, 0x100
	s_cbranch_scc1 .Lprio_lo_4
	s_setprio 1
.Lprio_lo_4:
.LBB0_796:
	s_add_u32 s4, s8, 0x103400
	s_addc_u32 s5, s9, 0
	s_cmp_eq_u32 s57, 60
	s_cselect_b32 s16, s38, s4
	s_cselect_b32 s17, s37, s5
	s_cselect_b32 s4, s49, s51
	s_cselect_b32 s5, s39, s56
	s_add_u32 s14, s16, 0x104400
	s_addc_u32 s15, s17, 0
	s_add_i32 s58, 0, 0x10000
	ds_read_b128 v[26:29], v250
	ds_read_b128 v[30:33], v250 offset:1024
	ds_read_b128 v[98:101], v250 offset:2048
	ds_read_b128 v[102:105], v250 offset:3072
	s_add_i32 m0, s22, 0xc000
	ds_read_b128 v[130:133], v247
	ds_read_b128 v[142:145], v247 offset:1024
	ds_read_b128 v[146:149], v247 offset:2048
	ds_read_b128 v[150:153], v247 offset:3072
	ds_read_b128 v[154:157], v247 offset:4096
	ds_read_b128 v[166:169], v247 offset:5120
	ds_read_b128 v[170:173], v247 offset:6144
	ds_read_b128 v[174:177], v247 offset:7168
	global_load_lds_dwordx4 v196, s[8:9]
	s_add_i32 m0, s22, 0xe000
	s_nop 0
	global_load_lds_dwordx4 v198, s[8:9]
	s_waitcnt lgkmcnt(8)
	s_barrier
	s_waitcnt lgkmcnt(0)
	v_mfma_f32_16x16x32_bf16 v[162:165], v[26:29], v[130:133], v[162:165]
	v_mfma_f32_16x16x32_bf16 v[158:161], v[98:101], v[130:133], v[158:161]
	v_mfma_f32_16x16x32_bf16 v[138:141], v[26:29], v[146:149], v[138:141]
	v_mfma_f32_16x16x32_bf16 v[134:137], v[98:101], v[146:149], v[134:137]
	v_mfma_f32_16x16x32_bf16 v[126:129], v[26:29], v[154:157], v[126:129]
	v_mfma_f32_16x16x32_bf16 v[122:125], v[98:101], v[154:157], v[122:125]
	v_mfma_f32_16x16x32_bf16 v[118:121], v[26:29], v[170:173], v[118:121]
	v_mfma_f32_16x16x32_bf16 v[114:117], v[98:101], v[170:173], v[114:117]
	v_mfma_f32_16x16x32_bf16 v[162:165], v[30:33], v[142:145], v[162:165]
	v_mfma_f32_16x16x32_bf16 v[158:161], v[102:105], v[142:145], v[158:161]
	v_mfma_f32_16x16x32_bf16 v[138:141], v[30:33], v[150:153], v[138:141]
	v_mfma_f32_16x16x32_bf16 v[134:137], v[102:105], v[150:153], v[134:137]
	v_mfma_f32_16x16x32_bf16 v[126:129], v[30:33], v[166:169], v[126:129]
	v_mfma_f32_16x16x32_bf16 v[122:125], v[102:105], v[166:169], v[122:125]
	v_mfma_f32_16x16x32_bf16 v[118:121], v[30:33], v[174:177], v[118:121]
	v_mfma_f32_16x16x32_bf16 v[114:117], v[102:105], v[174:177], v[114:117]
	s_barrier
; #define PG8_STAGE(bufoff, gbase, voff) do { _Pragma("unroll") for (int _i = 0; _i < 2; ++_i) \
;         __builtin_amdgcn_global_load_lds((const unsigned*)((const char*)(gbase) + (voff)[_i]), (LAS unsigned*)(lds + (bufoff) + ldsw + _i * 8192), 16, 0, 0); } while (0)
; #define PG8_LDA(dst, b, h) do { _Pragma("unroll") for (int m = 0; m < 4; ++m) _Pragma("unroll") for (int k = 0; k < 2; ++k) dst[m][k] = *(const LAS bf16x8*)(lds + PG8_SA(b, h) + aoff + m * 2048 + k * 1024); } while (0)
; #define PG8_LDB(dst, b, h) do { _Pragma("unroll") for (int n = 0; n < 2; ++n) _Pragma("unroll") for (int k = 0; k < 2; ++k) dst[n][k] = *(const LAS bf16x8*)(lds + PG8_SB(b, h) + boff + n * 2048 + k * 1024); } while (0)
; #define PG8_MMA(ai, bj, At, Bt) do { __builtin_amdgcn_s_setprio(1); _Pragma("unroll") for (int m = 0; m < 4; ++m) _Pragma("unroll") for (int n = 0; n < 2; ++n) _Pragma("unroll") for (int k = 0; k < 2; ++k) \
;         acc[ai][bj][m][n] = __builtin_amdgcn_mfma_f32_16x16x32_bf16(Bt[n][k], At[m][k], acc[ai][bj][m][n], 0, 0, 0); __builtin_amdgcn_s_setprio(0); } while (0)
; #define PG8_WAIT_V(n) asm volatile("s_waitcnt vmcnt(" #n ")" ::: "memory")
; #define PG8_WAIT_L(n) asm volatile("s_waitcnt lgkmcnt(" #n ")" ::: "memory")
; #define PG8_BAR __builtin_amdgcn_s_barrier()
; #define PG8_SCHED __builtin_amdgcn_sched_barrier(0)
; template <class Epi>
; __device__ __forceinline__ void gemm_phase(LAS unsigned char* lds, const Gemm g, const StaticOrder& S, const Epi& E) {
;     ...
;             PG8_LDB(B1, 0, 1); PG8_STAGE(PG8_SB(0, 0), b2, voffB);
;             PG8_BAR; PG8_WAIT_L(0); PG8_MMA(0, 1, At, B1); PG8_BAR;
;             PG8_LDA(At, 0, 1); PG8_STAGE(PG8_SA(0, 0), a2, voffA);
;             PG8_BAR; PG8_WAIT_L(0); PG8_MMA(1, 0, At, B0); PG8_BAR; PG8_SCHED;
;             PG8_STAGE(PG8_SB(0, 1), b2 + hstepB, voffB);
;             PG8_WAIT_V(6); PG8_BAR; PG8_MMA(1, 1, At, B1); PG8_BAR;
;             PG8_LDB(B0, 1, 0); PG8_SCHED; PG8_LDA(At, 1, 0); PG8_STAGE(PG8_SA(0, 1), a2 + hstepA, voffA);
;             PG8_WAIT_L(8); PG8_BAR; PG8_WAIT_L(0); PG8_MMA(0, 0, At, B0); PG8_BAR; PG8_SCHED;
;             PG8_LDB(B1, 1, 1); PG8_STAGE(PG8_SB(1, 0), b3, voffB);
	s_add_i32 s60, 0, 0x14000
	s_add_i32 s58, s58, s21
	s_add_u32 s100, s4, s6
	s_addc_u32 s101, s5, s7
	s_mov_b32 m0, s58
	ds_read_b128 v[184:187], v250 offset:16384
	ds_read_b128 v[200:203], v250 offset:17408
	ds_read_b128 v[204:207], v250 offset:18432
	ds_read_b128 v[208:211], v250 offset:19456
	global_load_lds_dwordx4 v0, s[4:5]
	s_add_i32 m0, s58, 0x2000
	s_nop 0
	global_load_lds_dwordx4 v188, s[4:5]
	s_barrier
	s_waitcnt lgkmcnt(0)
	v_mfma_f32_16x16x32_bf16 v[70:73], v[184:187], v[130:133], v[70:73]
	v_mfma_f32_16x16x32_bf16 v[66:69], v[204:207], v[130:133], v[66:69]
	v_mfma_f32_16x16x32_bf16 v[62:65], v[184:187], v[146:149], v[62:65]
	v_mfma_f32_16x16x32_bf16 v[58:61], v[204:207], v[146:149], v[58:61]
	v_mfma_f32_16x16x32_bf16 v[54:57], v[184:187], v[154:157], v[54:57]
	v_mfma_f32_16x16x32_bf16 v[50:53], v[204:207], v[154:157], v[50:53]
	v_mfma_f32_16x16x32_bf16 v[46:49], v[184:187], v[170:173], v[46:49]
	v_mfma_f32_16x16x32_bf16 v[42:45], v[204:207], v[170:173], v[42:45]
	v_mfma_f32_16x16x32_bf16 v[70:73], v[200:203], v[142:145], v[70:73]
	v_mfma_f32_16x16x32_bf16 v[66:69], v[208:211], v[142:145], v[66:69]
	v_mfma_f32_16x16x32_bf16 v[62:65], v[200:203], v[150:153], v[62:65]
	v_mfma_f32_16x16x32_bf16 v[58:61], v[208:211], v[150:153], v[58:61]
	v_mfma_f32_16x16x32_bf16 v[54:57], v[200:203], v[166:169], v[54:57]
	v_mfma_f32_16x16x32_bf16 v[50:53], v[208:211], v[166:169], v[50:53]
	v_mfma_f32_16x16x32_bf16 v[46:49], v[200:203], v[174:177], v[46:49]
	v_mfma_f32_16x16x32_bf16 v[42:45], v[208:211], v[174:177], v[42:45]
	s_mov_b32 m0, s22
	s_barrier
	ds_read_b128 v[130:133], v247 offset:16384
	ds_read_b128 v[142:145], v247 offset:17408
	ds_read_b128 v[146:149], v247 offset:18432
	ds_read_b128 v[150:153], v247 offset:19456
	ds_read_b128 v[154:157], v247 offset:20480
	ds_read_b128 v[166:169], v247 offset:21504
	ds_read_b128 v[170:173], v247 offset:22528
	ds_read_b128 v[174:177], v247 offset:23552
	global_load_lds_dwordx4 v192, s[16:17]
	s_mov_b32 m0, s23
	s_nop 0
	global_load_lds_dwordx4 v190, s[16:17]
	s_barrier
	s_waitcnt lgkmcnt(0)
	v_mfma_f32_16x16x32_bf16 v[110:113], v[26:29], v[130:133], v[110:113]
	v_mfma_f32_16x16x32_bf16 v[106:109], v[98:101], v[130:133], v[106:109]
	v_mfma_f32_16x16x32_bf16 v[94:97], v[26:29], v[146:149], v[94:97]
	v_mfma_f32_16x16x32_bf16 v[90:93], v[98:101], v[146:149], v[90:93]
	v_mfma_f32_16x16x32_bf16 v[86:89], v[26:29], v[154:157], v[86:89]
	v_mfma_f32_16x16x32_bf16 v[82:85], v[98:101], v[154:157], v[82:85]
	v_mfma_f32_16x16x32_bf16 v[26:29], v[26:29], v[170:173], v[78:81]
	v_mfma_f32_16x16x32_bf16 v[110:113], v[30:33], v[142:145], v[110:113]
	v_mfma_f32_16x16x32_bf16 v[106:109], v[102:105], v[142:145], v[106:109]
	v_mfma_f32_16x16x32_bf16 v[94:97], v[30:33], v[150:153], v[94:97]
	v_mfma_f32_16x16x32_bf16 v[90:93], v[102:105], v[150:153], v[90:93]
	v_mfma_f32_16x16x32_bf16 v[86:89], v[30:33], v[166:169], v[86:89]
	v_mfma_f32_16x16x32_bf16 v[82:85], v[102:105], v[166:169], v[82:85]
	v_mfma_f32_16x16x32_bf16 v[26:29], v[30:33], v[174:177], v[26:29]
	v_mfma_f32_16x16x32_bf16 v[30:33], v[98:101], v[170:173], v[74:77]
	v_mfma_f32_16x16x32_bf16 v[30:33], v[102:105], v[174:177], v[30:33]
	s_barrier
	s_add_u32 s58, s4, 0x100000
	s_addc_u32 s59, s5, 0
	s_add_i32 s60, s60, s21
	s_mov_b32 m0, s60
	s_nop 0
	global_load_lds_dwordx4 v0, s[58:59]
	s_add_i32 m0, s60, 0x2000
	s_nop 0
	global_load_lds_dwordx4 v188, s[58:59]
	s_waitcnt vmcnt(6)
	s_barrier
	v_mfma_f32_16x16x32_bf16 v[38:41], v[184:187], v[130:133], v[38:41]
	v_mfma_f32_16x16x32_bf16 v[34:37], v[204:207], v[130:133], v[34:37]
	v_mfma_f32_16x16x32_bf16 v[22:25], v[184:187], v[146:149], v[22:25]
	v_mfma_f32_16x16x32_bf16 v[18:21], v[204:207], v[146:149], v[18:21]
	v_mfma_f32_16x16x32_bf16 v[14:17], v[184:187], v[154:157], v[14:17]
	v_mfma_f32_16x16x32_bf16 v[10:13], v[204:207], v[154:157], v[10:13]
	v_mfma_f32_16x16x32_bf16 v[6:9], v[184:187], v[170:173], v[6:9]
	v_mfma_f32_16x16x32_bf16 v[2:5], v[204:207], v[170:173], v[2:5]
	v_mfma_f32_16x16x32_bf16 v[38:41], v[200:203], v[142:145], v[38:41]
	v_mfma_f32_16x16x32_bf16 v[34:37], v[208:211], v[142:145], v[34:37]
	v_mfma_f32_16x16x32_bf16 v[22:25], v[200:203], v[150:153], v[22:25]
	v_mfma_f32_16x16x32_bf16 v[18:21], v[208:211], v[150:153], v[18:21]
	v_mfma_f32_16x16x32_bf16 v[14:17], v[200:203], v[166:169], v[14:17]
	v_mfma_f32_16x16x32_bf16 v[10:13], v[208:211], v[166:169], v[10:13]
	v_mfma_f32_16x16x32_bf16 v[6:9], v[200:203], v[174:177], v[6:9]
	v_mfma_f32_16x16x32_bf16 v[2:5], v[208:211], v[174:177], v[2:5]
	s_add_i32 s58, 0, 0x18000
	s_barrier
	ds_read_b128 v[74:77], v250 offset:32768
	ds_read_b128 v[78:81], v250 offset:33792
	ds_read_b128 v[98:101], v250 offset:34816
	ds_read_b128 v[102:105], v250 offset:35840
	s_add_u32 s16, s16, 0x1000
	s_addc_u32 s17, s17, 0
	s_mov_b32 m0, s24
	ds_read_b128 v[130:133], v247 offset:32768
	ds_read_b128 v[142:145], v247 offset:33792
	ds_read_b128 v[146:149], v247 offset:34816
	ds_read_b128 v[150:153], v247 offset:35840
	ds_read_b128 v[154:157], v247 offset:36864
	ds_read_b128 v[166:169], v247 offset:37888
	ds_read_b128 v[170:173], v247 offset:38912
	ds_read_b128 v[174:177], v247 offset:39936
	global_load_lds_dwordx4 v192, s[16:17]
	s_mov_b32 m0, s25
	s_nop 0
	global_load_lds_dwordx4 v190, s[16:17]
	s_waitcnt lgkmcnt(8)
	s_barrier
; #define PG8_STAGE(bufoff, gbase, voff) do { _Pragma("unroll") for (int _i = 0; _i < 2; ++_i) \
;         __builtin_amdgcn_global_load_lds((const unsigned*)((const char*)(gbase) + (voff)[_i]), (LAS unsigned*)(lds + (bufoff) + ldsw + _i * 8192), 16, 0, 0); } while (0)
; #define PG8_LDA(dst, b, h) do { _Pragma("unroll") for (int m = 0; m < 4; ++m) _Pragma("unroll") for (int k = 0; k < 2; ++k) dst[m][k] = *(const LAS bf16x8*)(lds + PG8_SA(b, h) + aoff + m * 2048 + k * 1024); } while (0)
; #define PG8_MMA(ai, bj, At, Bt) do { __builtin_amdgcn_s_setprio(1); _Pragma("unroll") for (int m = 0; m < 4; ++m) _Pragma("unroll") for (int n = 0; n < 2; ++n) _Pragma("unroll") for (int k = 0; k < 2; ++k) \
;         acc[ai][bj][m][n] = __builtin_amdgcn_mfma_f32_16x16x32_bf16(Bt[n][k], At[m][k], acc[ai][bj][m][n], 0, 0, 0); __builtin_amdgcn_s_setprio(0); } while (0)
; #define PG8_WAIT_V(n) asm volatile("s_waitcnt vmcnt(" #n ")" ::: "memory")
; #define PG8_WAIT_L(n) asm volatile("s_waitcnt lgkmcnt(" #n ")" ::: "memory")
; #define PG8_BAR __builtin_amdgcn_s_barrier()
; #define PG8_SCHED __builtin_amdgcn_sched_barrier(0)
; template <class Epi>
; __device__ __forceinline__ void gemm_phase(LAS unsigned char* lds, const Gemm g, const StaticOrder& S, const Epi& E) {
;     ...
;             PG8_BAR; PG8_WAIT_L(0); PG8_MMA(0, 1, At, B1); PG8_BAR;
;             PG8_LDA(At, 1, 1); PG8_STAGE(PG8_SA(1, 0), a3, voffA);
;             PG8_BAR; PG8_WAIT_L(0); PG8_MMA(1, 0, At, B0); PG8_BAR; PG8_SCHED;
;             PG8_STAGE(PG8_SB(1, 1), b3 + hstepB, voffB);
;             PG8_WAIT_V(6); PG8_BAR; PG8_MMA(1, 1, At, B1); PG8_BAR;
	s_waitcnt lgkmcnt(0)
	v_mfma_f32_16x16x32_bf16 v[162:165], v[74:77], v[130:133], v[162:165]
	v_mfma_f32_16x16x32_bf16 v[158:161], v[98:101], v[130:133], v[158:161]
	v_mfma_f32_16x16x32_bf16 v[138:141], v[74:77], v[146:149], v[138:141]
	v_mfma_f32_16x16x32_bf16 v[134:137], v[98:101], v[146:149], v[134:137]
	v_mfma_f32_16x16x32_bf16 v[126:129], v[74:77], v[154:157], v[126:129]
	v_mfma_f32_16x16x32_bf16 v[122:125], v[98:101], v[154:157], v[122:125]
	v_mfma_f32_16x16x32_bf16 v[118:121], v[74:77], v[170:173], v[118:121]
	v_mfma_f32_16x16x32_bf16 v[114:117], v[98:101], v[170:173], v[114:117]
	v_mfma_f32_16x16x32_bf16 v[162:165], v[78:81], v[142:145], v[162:165]
	v_mfma_f32_16x16x32_bf16 v[158:161], v[102:105], v[142:145], v[158:161]
	v_mfma_f32_16x16x32_bf16 v[138:141], v[78:81], v[150:153], v[138:141]
	v_mfma_f32_16x16x32_bf16 v[134:137], v[102:105], v[150:153], v[134:137]
	v_mfma_f32_16x16x32_bf16 v[126:129], v[78:81], v[166:169], v[126:129]
	v_mfma_f32_16x16x32_bf16 v[122:125], v[102:105], v[166:169], v[122:125]
	v_mfma_f32_16x16x32_bf16 v[118:121], v[78:81], v[174:177], v[118:121]
	v_mfma_f32_16x16x32_bf16 v[114:117], v[102:105], v[174:177], v[114:117]
	s_barrier
	s_add_i32 s16, 0, 0x1c000
	s_add_i32 s17, s58, s21
	s_mov_b32 m0, s17
	ds_read_b128 v[184:187], v250 offset:49152
	ds_read_b128 v[200:203], v250 offset:50176
	ds_read_b128 v[204:207], v250 offset:51200
	ds_read_b128 v[208:211], v250 offset:52224
	global_load_lds_dwordx4 v0, s[100:101]
	s_add_i32 m0, s17, 0x2000
	s_nop 0
	global_load_lds_dwordx4 v188, s[100:101]
	s_barrier
	s_waitcnt lgkmcnt(0)
	v_mfma_f32_16x16x32_bf16 v[70:73], v[184:187], v[130:133], v[70:73]
	v_mfma_f32_16x16x32_bf16 v[66:69], v[204:207], v[130:133], v[66:69]
	v_mfma_f32_16x16x32_bf16 v[62:65], v[184:187], v[146:149], v[62:65]
	v_mfma_f32_16x16x32_bf16 v[58:61], v[204:207], v[146:149], v[58:61]
	v_mfma_f32_16x16x32_bf16 v[54:57], v[184:187], v[154:157], v[54:57]
	v_mfma_f32_16x16x32_bf16 v[50:53], v[204:207], v[154:157], v[50:53]
	v_mfma_f32_16x16x32_bf16 v[46:49], v[184:187], v[170:173], v[46:49]
	v_mfma_f32_16x16x32_bf16 v[42:45], v[204:207], v[170:173], v[42:45]
	v_mfma_f32_16x16x32_bf16 v[70:73], v[200:203], v[142:145], v[70:73]
	v_mfma_f32_16x16x32_bf16 v[66:69], v[208:211], v[142:145], v[66:69]
	v_mfma_f32_16x16x32_bf16 v[62:65], v[200:203], v[150:153], v[62:65]
	v_mfma_f32_16x16x32_bf16 v[58:61], v[208:211], v[150:153], v[58:61]
	v_mfma_f32_16x16x32_bf16 v[54:57], v[200:203], v[166:169], v[54:57]
	v_mfma_f32_16x16x32_bf16 v[50:53], v[208:211], v[166:169], v[50:53]
	v_mfma_f32_16x16x32_bf16 v[46:49], v[200:203], v[174:177], v[46:49]
	v_mfma_f32_16x16x32_bf16 v[42:45], v[208:211], v[174:177], v[42:45]
	s_mov_b32 m0, s26
	s_barrier
	ds_read_b128 v[130:133], v247 offset:49152
	ds_read_b128 v[142:145], v247 offset:50176
	ds_read_b128 v[146:149], v247 offset:51200
	ds_read_b128 v[150:153], v247 offset:52224
	ds_read_b128 v[154:157], v247 offset:53248
	ds_read_b128 v[166:169], v247 offset:54272
	ds_read_b128 v[170:173], v247 offset:55296
	ds_read_b128 v[174:177], v247 offset:56320
	global_load_lds_dwordx4 v192, s[14:15]
	s_mov_b32 m0, s27
	s_nop 0
	global_load_lds_dwordx4 v190, s[14:15]
	s_barrier
	s_waitcnt lgkmcnt(0)
	v_mfma_f32_16x16x32_bf16 v[110:113], v[74:77], v[130:133], v[110:113]
	v_mfma_f32_16x16x32_bf16 v[94:97], v[74:77], v[146:149], v[94:97]
	v_mfma_f32_16x16x32_bf16 v[86:89], v[74:77], v[154:157], v[86:89]
	v_mfma_f32_16x16x32_bf16 v[26:29], v[74:77], v[170:173], v[26:29]
	v_mfma_f32_16x16x32_bf16 v[110:113], v[78:81], v[142:145], v[110:113]
	v_mfma_f32_16x16x32_bf16 v[106:109], v[98:101], v[130:133], v[106:109]
	v_mfma_f32_16x16x32_bf16 v[94:97], v[78:81], v[150:153], v[94:97]
	v_mfma_f32_16x16x32_bf16 v[90:93], v[98:101], v[146:149], v[90:93]
	v_mfma_f32_16x16x32_bf16 v[86:89], v[78:81], v[166:169], v[86:89]
	v_mfma_f32_16x16x32_bf16 v[82:85], v[98:101], v[154:157], v[82:85]
	v_mfma_f32_16x16x32_bf16 v[78:81], v[78:81], v[174:177], v[26:29]
	v_mfma_f32_16x16x32_bf16 v[26:29], v[98:101], v[170:173], v[30:33]
	v_mfma_f32_16x16x32_bf16 v[106:109], v[102:105], v[142:145], v[106:109]
	v_mfma_f32_16x16x32_bf16 v[90:93], v[102:105], v[150:153], v[90:93]
	v_mfma_f32_16x16x32_bf16 v[82:85], v[102:105], v[166:169], v[82:85]
	v_mfma_f32_16x16x32_bf16 v[74:77], v[102:105], v[174:177], v[26:29]
	s_barrier
	s_add_u32 s4, s4, 0x100080
	s_addc_u32 s5, s5, 0
	s_add_i32 s14, s16, s21
	s_mov_b32 m0, s14
	s_nop 0
	global_load_lds_dwordx4 v0, s[4:5]
	s_add_i32 m0, s14, 0x2000
	s_nop 0
	global_load_lds_dwordx4 v188, s[4:5]
	s_waitcnt vmcnt(6)
	s_barrier
	v_mfma_f32_16x16x32_bf16 v[26:29], v[184:187], v[130:133], v[38:41]
	v_mfma_f32_16x16x32_bf16 v[38:41], v[200:203], v[142:145], v[26:29]
	v_mfma_f32_16x16x32_bf16 v[26:29], v[204:207], v[130:133], v[34:37]
	v_mfma_f32_16x16x32_bf16 v[22:25], v[184:187], v[146:149], v[22:25]
	v_mfma_f32_16x16x32_bf16 v[18:21], v[204:207], v[146:149], v[18:21]
	v_mfma_f32_16x16x32_bf16 v[14:17], v[184:187], v[154:157], v[14:17]
	v_mfma_f32_16x16x32_bf16 v[10:13], v[204:207], v[154:157], v[10:13]
	v_mfma_f32_16x16x32_bf16 v[6:9], v[184:187], v[170:173], v[6:9]
	v_mfma_f32_16x16x32_bf16 v[2:5], v[204:207], v[170:173], v[2:5]
	v_mfma_f32_16x16x32_bf16 v[34:37], v[208:211], v[142:145], v[26:29]
	v_mfma_f32_16x16x32_bf16 v[22:25], v[200:203], v[150:153], v[22:25]
	v_mfma_f32_16x16x32_bf16 v[18:21], v[208:211], v[150:153], v[18:21]
	v_mfma_f32_16x16x32_bf16 v[14:17], v[200:203], v[166:169], v[14:17]
	v_mfma_f32_16x16x32_bf16 v[10:13], v[208:211], v[166:169], v[10:13]
	v_mfma_f32_16x16x32_bf16 v[6:9], v[200:203], v[174:177], v[6:9]
	v_mfma_f32_16x16x32_bf16 v[2:5], v[208:211], v[174:177], v[2:5]
	s_add_i32 s57, s57, 2
	s_add_u32 s51, s51, 0x100
	s_addc_u32 s56, s56, 0
	s_add_u32 s8, s8, 0x208800
	s_addc_u32 s9, s9, 0
	s_cmp_gt_u32 s57, 61
	s_barrier
; __device__ __forceinline__ unsigned cvt_pk_bf16(float lo, float hi) { unsigned r; asm volatile("v_cvt_pk_bf16_f32 %0, %1, %2" : "=v"(r) : "v"(lo), "v"(hi)); return r; }
; __device__ __forceinline__ float bf_lo(unsigned w) { return __uint_as_float(w << 16); }
; __device__ __forceinline__ float bf_hi(unsigned w) { return __uint_as_float(w & 0xffff0000u); }
; template <class Epi>
; __device__ __forceinline__ void gemm_phase(LAS unsigned char* lds, const Gemm g, const StaticOrder& S, const Epi& E) {
;     ...
;         }
;         if constexpr (!Epi::AFTER_DRAIN) E(acc, cur, wr, wc, fr, fq, pre);
;     __device__ __forceinline__ void operator()(const f32x4 (&acc)[2][2][4][2], const Unit& u, int wr, int wc, int fr, int fq, const Pre&) const {
;         const int row0 = u.pm * BM + wr * 64 + fr, col0 = u.pn * BM + wc * 32 + 8 * fq;
;         f32x4 bs[2][2];
; #pragma unroll
;         for (int bj = 0; bj < 2; ++bj) { bs[bj][0] = *(const f32x4*)(bias + col0 + bj * HALF); bs[bj][1] = *(const f32x4*)(bias + col0 + bj * HALF + 4); }
; #pragma unroll
;         for (int bj = 0; bj < 2; ++bj) { const int c = col0 + bj * HALF;
; #pragma unroll
;             for (int ai = 0; ai < 2; ++ai) { u32x4 zv[4], gv[4];
; #pragma unroll
;                 for (int m = 0; m < 4; ++m) { const int r = row0 + ai * HALF + m * 16; zv[m] = *(const u32x4*)(Z + (size_t)r * DE2 + c); gv[m] = *(const u32x4*)(Gm + (size_t)(c >> 4) * GSTR + r * 16 + (c & 15)); }
; #pragma unroll
;                 for (int m = 0; m < 4; ++m) { const int r = row0 + ai * HALF + m * 16;
;                     const u32x4 zw = zv[m], gw = gv[m];
;                     const f32x4 a0 = acc[ai][bj][m][0] + bs[bj][0], a1 = acc[ai][bj][m][1] + bs[bj][1];
;                     u32x4 w;
;                     w.x = cvt_pk_bf16(glu_gate_f(bf_lo(gw.x), a0[0], bf_lo(zw.x)), glu_gate_f(bf_hi(gw.x), a0[1], bf_hi(zw.x)));
;                     w.y = cvt_pk_bf16(glu_gate_f(bf_lo(gw.y), a0[2], bf_lo(zw.y)), glu_gate_f(bf_hi(gw.y), a0[3], bf_hi(zw.y)));
;                     w.z = cvt_pk_bf16(glu_gate_f(bf_lo(gw.z), a1[0], bf_lo(zw.z)), glu_gate_f(bf_hi(gw.z), a1[1], bf_hi(zw.z)));
;                     w.w = cvt_pk_bf16(glu_gate_f(bf_lo(gw.w), a1[2], bf_lo(zw.w)), glu_gate_f(bf_hi(gw.w), a1[3], bf_hi(zw.w)));
	s_cbranch_scc0 .LBB0_796
	s_setprio 0
	v_lshl_or_b32 v200, s36, 8, v246
	v_ashrrev_i32_e32 v201, 31, v200
	v_lshl_add_u32 v224, s35, 8, v244
	v_lshlrev_b64 v[204:205], 1, v[200:201]
	v_ashrrev_i32_e32 v225, 31, v224
	v_ashrrev_i32_e32 v130, 4, v200
	v_lshl_add_u64 v[222:223], s[46:47], 0, v[204:205]
	v_lshlrev_b64 v[202:203], 14, v[224:225]
	v_lshl_add_u64 v[30:31], v[200:201], 2, s[10:11]
	v_mad_i64_i32 v[220:221], s[4:5], v130, s94, v[194:195]
	v_lshl_add_u64 v[130:131], v[222:223], 0, v[202:203]
	global_load_dwordx4 v[98:101], v[30:31], off offset:16
	global_load_dwordx4 v[102:105], v[30:31], off
	global_load_dwordx4 v[26:29], v[30:31], off offset:528
	s_nop 0
	global_load_dwordx4 v[30:33], v[30:31], off offset:512
	v_or_b32_e32 v226, 48, v224
	global_load_dwordx4 v[170:173], v[130:131], off
	v_lshlrev_b32_e32 v142, 4, v226
	v_ashrrev_i32_e32 v143, 31, v142
	v_lshlrev_b64 v[218:219], 1, v[142:143]
	v_lshl_add_u64 v[142:143], v[220:221], 0, v[218:219]
	global_load_dwordx4 v[142:145], v[142:143], off
	v_lshlrev_b32_e32 v130, 4, v224
	v_ashrrev_i32_e32 v131, 31, v130
	v_lshlrev_b64 v[206:207], 1, v[130:131]
	v_lshl_add_u64 v[130:131], v[220:221], 0, v[206:207]
	global_load_dwordx4 v[174:177], v[130:131], off
	v_or_b32_e32 v230, 16, v224
	v_ashrrev_i32_e32 v231, 31, v230
	v_lshlrev_b64 v[210:211], 14, v[230:231]
	v_lshl_add_u64 v[130:131], v[222:223], 0, v[210:211]
	global_load_dwordx4 v[154:157], v[130:131], off
	v_lshlrev_b32_e32 v130, 4, v230
	v_ashrrev_i32_e32 v131, 31, v130
	v_or_b32_e32 v228, 32, v224
	v_lshlrev_b64 v[208:209], 1, v[130:131]
	v_ashrrev_i32_e32 v229, 31, v228
	v_lshl_add_u64 v[130:131], v[220:221], 0, v[208:209]
	v_lshlrev_b64 v[214:215], 14, v[228:229]
	global_load_dwordx4 v[166:169], v[130:131], off
	v_lshl_add_u64 v[130:131], v[222:223], 0, v[214:215]
	global_load_dwordx4 v[146:149], v[130:131], off
	v_lshlrev_b32_e32 v130, 4, v228
	v_ashrrev_i32_e32 v131, 31, v130
	v_lshlrev_b64 v[212:213], 1, v[130:131]
	v_ashrrev_i32_e32 v227, 31, v226
	v_lshl_add_u64 v[130:131], v[220:221], 0, v[212:213]
	v_lshlrev_b64 v[216:217], 14, v[226:227]
	global_load_dwordx4 v[150:153], v[130:131], off
	v_lshl_add_u64 v[130:131], v[222:223], 0, v[216:217]
	global_load_dwordx4 v[130:133], v[130:131], off
	s_and_b64 vcc, exec, s[40:41]
	s_mov_b32 s35, s50
	s_mov_b32 s36, s48
	s_mov_b64 s[8:9], s[54:55]
	s_mov_b64 s[14:15], s[52:53]
	s_waitcnt vmcnt(0)
	v_pk_add_f32 v[134:135], v[134:135], v[98:99]
	v_pk_add_f32 v[184:185], v[162:163], v[102:103]
	v_pk_add_f32 v[162:163], v[160:161], v[100:101]
	v_pk_add_f32 v[160:161], v[158:159], v[98:99]
	v_mul_f32_e32 v158, 0xbfb8aa3b, v184
	v_lshlrev_b32_e32 v186, 16, v170
	v_mul_f32_e32 v159, 0xbfb8aa3b, v186
	v_exp_f32_e32 v158, v158
	v_exp_f32_e32 v159, v159
	v_and_b32_e32 v170, 0xffff0000, v170
	v_pk_add_f32 v[164:165], v[164:165], v[104:105]
	v_mul_f32_e32 v160, 0xbfb8aa3b, v160
	v_pk_add_f32 v[158:159], v[158:159], 1.0 op_sel_hi:[1,0]
	v_mul_f32_e32 v164, 0xbfb8aa3b, v164
	v_mul_f32_e32 v158, v158, v159
	v_rcp_f32_e32 v158, v158
	v_lshlrev_b32_e32 v187, 16, v174
	v_mul_f32_e32 v184, v187, v186
	v_mul_f32_e32 v159, 0xbfb8aa3b, v170
	v_mul_f32_e32 v184, v184, v158
	v_mul_f32_e32 v158, 0xbfb8aa3b, v185
	v_exp_f32_e32 v158, v158
	v_exp_f32_e32 v159, v159
	v_and_b32_e32 v174, 0xffff0000, v174
	v_mul_f32_e32 v170, v174, v170
	v_mul_f32_e32 v162, 0xbfb8aa3b, v162
	v_pk_add_f32 v[158:159], v[158:159], 1.0 op_sel_hi:[1,0]
	v_pk_add_f32 v[138:139], v[138:139], v[102:103]
	v_mul_f32_e32 v158, v158, v159
	v_rcp_f32_e32 v158, v158
	v_lshlrev_b32_e32 v159, 16, v171
	v_and_b32_e32 v171, 0xffff0000, v171
	v_mul_f32_e32 v138, 0xbfb8aa3b, v138
	v_mul_f32_e32 v158, v170, v158
	v_cvt_pk_bf16_f32 v158, v184, v158
	v_exp_f32_e32 v184, v164
	v_mul_f32_e32 v164, 0xbfb8aa3b, v159
	v_exp_f32_e32 v185, v164
	v_lshlrev_b32_e32 v170, 16, v175
	v_mul_f32_e32 v159, v170, v159
	v_and_b32_e32 v170, 0xffff0000, v175
	v_pk_add_f32 v[184:185], v[184:185], 1.0 op_sel_hi:[1,0]
	v_mul_f32_e32 v170, v170, v171
	v_mul_f32_e32 v164, v184, v185
	v_rcp_f32_e32 v164, v164
	v_pk_add_f32 v[140:141], v[140:141], v[104:105]
	v_mul_f32_e32 v134, 0xbfb8aa3b, v134
	v_mul_f32_e32 v140, 0xbfb8aa3b, v140
	v_mul_f32_e32 v159, v159, v164
	v_mul_f32_e32 v164, 0xbfb8aa3b, v165
	v_mul_f32_e32 v165, 0xbfb8aa3b, v171
	v_exp_f32_e32 v164, v164
	v_exp_f32_e32 v165, v165
	v_lshlrev_b32_e32 v171, 16, v176
	v_pk_add_f32 v[136:137], v[136:137], v[100:101]
	v_pk_add_f32 v[126:127], v[126:127], v[102:103]
	v_pk_add_f32 v[164:165], v[164:165], 1.0 op_sel_hi:[1,0]
	v_mul_f32_e32 v126, 0xbfb8aa3b, v126
	v_mul_f32_e32 v164, v164, v165
	v_rcp_f32_e32 v164, v164
	v_pk_add_f32 v[128:129], v[128:129], v[104:105]
	v_pk_add_f32 v[122:123], v[122:123], v[98:99]
	v_mul_f32_e32 v128, 0xbfb8aa3b, v128
	v_mul_f32_e32 v164, v170, v164
	v_lshlrev_b32_e32 v170, 16, v172
	v_cvt_pk_bf16_f32 v159, v159, v164
	v_exp_f32_e32 v164, v160
	v_mul_f32_e32 v160, 0xbfb8aa3b, v170
	v_exp_f32_e32 v165, v160
	v_mul_f32_e32 v160, v171, v170
	v_and_b32_e32 v170, 0xffff0000, v172
	v_mul_f32_e32 v122, 0xbfb8aa3b, v122
	v_pk_add_f32 v[164:165], v[164:165], 1.0 op_sel_hi:[1,0]
	v_pk_add_f32 v[124:125], v[124:125], v[100:101]
	v_mul_f32_e32 v164, v164, v165
	v_rcp_f32_e32 v164, v164
	v_and_b32_e32 v165, 0xffff0000, v176
	v_mul_f32_e32 v165, v165, v170
	v_pk_add_f32 v[118:119], v[118:119], v[102:103]
	v_mul_f32_e32 v164, v160, v164
	v_mul_f32_e32 v160, 0xbfb8aa3b, v161
	v_mul_f32_e32 v161, 0xbfb8aa3b, v170
	v_exp_f32_e32 v160, v160
	v_exp_f32_e32 v161, v161
	v_lshlrev_b32_e32 v170, 16, v177
	v_mul_f32_e32 v118, 0xbfb8aa3b, v118
	v_pk_add_f32 v[120:121], v[120:121], v[104:105]
; __device__ __forceinline__ unsigned cvt_pk_bf16(float lo, float hi) { unsigned r; asm volatile("v_cvt_pk_bf16_f32 %0, %1, %2" : "=v"(r) : "v"(lo), "v"(hi)); return r; }
; __device__ __forceinline__ float bf_lo(unsigned w) { return __uint_as_float(w << 16); }
; __device__ __forceinline__ float bf_hi(unsigned w) { return __uint_as_float(w & 0xffff0000u); }
;     __device__ __forceinline__ void operator()(const f32x4 (&acc)[2][2][4][2], const Unit& u, int wr, int wc, int fr, int fq, const Pre&) const {
;     ...
;                 for (int m = 0; m < 4; ++m) { const int r = row0 + ai * HALF + m * 16; zv[m] = *(const u32x4*)(Z + (size_t)r * DE2 + c); gv[m] = *(const u32x4*)(Gm + (size_t)(c >> 4) * GSTR + r * 16 + (c & 15)); }
; #pragma unroll
;                 for (int m = 0; m < 4; ++m) { const int r = row0 + ai * HALF + m * 16;
;                     const u32x4 zw = zv[m], gw = gv[m];
;                     const f32x4 a0 = acc[ai][bj][m][0] + bs[bj][0], a1 = acc[ai][bj][m][1] + bs[bj][1];
;                     u32x4 w;
;                     w.x = cvt_pk_bf16(glu_gate_f(bf_lo(gw.x), a0[0], bf_lo(zw.x)), glu_gate_f(bf_hi(gw.x), a0[1], bf_hi(zw.x)));
;                     w.y = cvt_pk_bf16(glu_gate_f(bf_lo(gw.y), a0[2], bf_lo(zw.y)), glu_gate_f(bf_hi(gw.y), a0[3], bf_hi(zw.y)));
;                     w.z = cvt_pk_bf16(glu_gate_f(bf_lo(gw.z), a1[0], bf_lo(zw.z)), glu_gate_f(bf_hi(gw.z), a1[1], bf_hi(zw.z)));
;                     w.w = cvt_pk_bf16(glu_gate_f(bf_lo(gw.w), a1[2], bf_lo(zw.w)), glu_gate_f(bf_hi(gw.w), a1[3], bf_hi(zw.w)));
;                     *(u32x4*)(O + (size_t)r * DE + c) = w; } } }
	v_pk_add_f32 v[160:161], v[160:161], 1.0 op_sel_hi:[1,0]
	v_mul_f32_e32 v120, 0xbfb8aa3b, v120
	v_mul_f32_e32 v160, v160, v161
	v_rcp_f32_e32 v160, v160
	v_lshlrev_b32_e32 v161, 16, v173
	v_pk_add_f32 v[114:115], v[114:115], v[98:99]
	v_pk_add_f32 v[116:117], v[116:117], v[100:101]
	v_mul_f32_e32 v160, v165, v160
	v_cvt_pk_bf16_f32 v160, v164, v160
	v_exp_f32_e32 v164, v162
	v_mul_f32_e32 v162, 0xbfb8aa3b, v161
	v_exp_f32_e32 v165, v162
	v_mul_f32_e32 v161, v170, v161
	v_mul_f32_e32 v114, 0xbfb8aa3b, v114
	v_add_u32_e32 v176, 0x80, v224
	v_pk_add_f32 v[164:165], v[164:165], 1.0 op_sel_hi:[1,0]
	v_add_u32_e32 v170, 0xb0, v224
	v_mul_f32_e32 v162, v164, v165
	v_rcp_f32_e32 v162, v162
	v_and_b32_e32 v165, 0xffff0000, v173
	v_and_b32_e32 v164, 0xffff0000, v177
	v_mul_f32_e32 v164, v164, v165
	v_mul_f32_e32 v161, v161, v162
	v_mul_f32_e32 v162, 0xbfb8aa3b, v163
	v_mul_f32_e32 v163, 0xbfb8aa3b, v165
	v_exp_f32_e32 v162, v162
	v_exp_f32_e32 v163, v163
	v_ashrrev_i32_e32 v177, 31, v176
	v_pk_add_f32 v[110:111], v[110:111], v[102:103]
	v_add_u32_e32 v174, 0x90, v224
	v_pk_add_f32 v[162:163], v[162:163], 1.0 op_sel_hi:[1,0]
	v_mul_f32_e32 v110, 0xbfb8aa3b, v110
	v_mul_f32_e32 v162, v162, v163
	v_rcp_f32_e32 v162, v162
	v_exp_f32_e32 v184, v110
	v_ashrrev_i32_e32 v175, 31, v174
	v_add_u32_e32 v172, 0xa0, v224
	v_mul_f32_e32 v162, v164, v162
	v_cvt_pk_bf16_f32 v161, v161, v162
	v_lshlrev_b64 v[162:163], 13, v[224:225]
	v_lshl_add_u64 v[162:163], s[44:45], 0, v[162:163]
	v_lshl_add_u64 v[162:163], v[162:163], 0, v[204:205]
	global_store_dwordx4 v[162:163], v[158:161], off
	v_ashrrev_i32_e32 v173, 31, v172
	v_ashrrev_i32_e32 v171, 31, v170
	v_lshlrev_b32_e32 v160, 16, v154
	v_exp_f32_e32 v158, v138
	v_mul_f32_e32 v138, 0xbfb8aa3b, v160
	v_exp_f32_e32 v159, v138
	v_lshlrev_b32_e32 v161, 16, v166
	v_mul_f32_e32 v138, v161, v160
	v_and_b32_e32 v154, 0xffff0000, v154
	v_pk_add_f32 v[158:159], v[158:159], 1.0 op_sel_hi:[1,0]
	v_lshlrev_b64 v[160:161], 14, v[172:173]
	v_mul_f32_e32 v158, v158, v159
	v_rcp_f32_e32 v158, v158
	v_and_b32_e32 v159, 0xffff0000, v166
	v_pk_add_f32 v[112:113], v[112:113], v[104:105]
	v_pk_add_f32 v[106:107], v[106:107], v[98:99]
	v_mul_f32_e32 v158, v138, v158
	v_mul_f32_e32 v138, 0xbfb8aa3b, v139
	v_mul_f32_e32 v139, 0xbfb8aa3b, v154
	v_exp_f32_e32 v138, v138
	v_exp_f32_e32 v139, v139
	v_mul_f32_e32 v154, v159, v154
	v_mul_f32_e32 v112, 0xbfb8aa3b, v112
	v_mul_f32_e32 v106, 0xbfb8aa3b, v106
	v_pk_add_f32 v[138:139], v[138:139], 1.0 op_sel_hi:[1,0]
	v_pk_add_f32 v[108:109], v[108:109], v[100:101]
	v_mul_f32_e32 v138, v138, v139
	v_rcp_f32_e32 v138, v138
	v_lshlrev_b32_e32 v139, 16, v155
	v_and_b32_e32 v155, 0xffff0000, v155
	v_pk_add_f32 v[94:95], v[94:95], v[102:103]
	v_mul_f32_e32 v138, v154, v138
	v_cvt_pk_bf16_f32 v138, v158, v138
	v_exp_f32_e32 v158, v140
	v_mul_f32_e32 v140, 0xbfb8aa3b, v139
	v_exp_f32_e32 v159, v140
	v_lshlrev_b32_e32 v154, 16, v167
	v_mul_f32_e32 v139, v154, v139
	v_and_b32_e32 v154, 0xffff0000, v167
	v_pk_add_f32 v[158:159], v[158:159], 1.0 op_sel_hi:[1,0]
	v_mul_f32_e32 v154, v154, v155
	v_mul_f32_e32 v140, v158, v159
	v_rcp_f32_e32 v140, v140
	v_lshlrev_b64 v[166:167], 14, v[170:171]
	v_mul_f32_e32 v94, 0xbfb8aa3b, v94
	v_pk_add_f32 v[96:97], v[96:97], v[104:105]
	v_mul_f32_e32 v139, v139, v140
	v_mul_f32_e32 v140, 0xbfb8aa3b, v141
	v_mul_f32_e32 v141, 0xbfb8aa3b, v155
	v_exp_f32_e32 v140, v140
	v_exp_f32_e32 v141, v141
	v_lshlrev_b32_e32 v155, 16, v168
	v_mul_f32_e32 v96, 0xbfb8aa3b, v96
	v_pk_add_f32 v[90:91], v[90:91], v[98:99]
	v_pk_add_f32 v[140:141], v[140:141], 1.0 op_sel_hi:[1,0]
	v_mul_f32_e32 v90, 0xbfb8aa3b, v90
	v_mul_f32_e32 v140, v140, v141
	v_rcp_f32_e32 v140, v140
	v_pk_add_f32 v[92:93], v[92:93], v[100:101]
	v_pk_add_f32 v[86:87], v[86:87], v[102:103]
	v_pk_add_f32 v[88:89], v[88:89], v[104:105]
	v_mul_f32_e32 v140, v154, v140
	v_lshlrev_b32_e32 v154, 16, v156
	v_cvt_pk_bf16_f32 v139, v139, v140
	v_exp_f32_e32 v140, v134
	v_mul_f32_e32 v134, 0xbfb8aa3b, v154
	v_exp_f32_e32 v141, v134
	v_mul_f32_e32 v134, v155, v154
	v_and_b32_e32 v154, 0xffff0000, v156
	v_mul_f32_e32 v86, 0xbfb8aa3b, v86
	v_pk_add_f32 v[140:141], v[140:141], 1.0 op_sel_hi:[1,0]
	v_mul_f32_e32 v88, 0xbfb8aa3b, v88
	v_mul_f32_e32 v140, v140, v141
	v_rcp_f32_e32 v140, v140
	v_and_b32_e32 v141, 0xffff0000, v168
	v_mul_f32_e32 v141, v141, v154
	v_pk_add_f32 v[82:83], v[82:83], v[98:99]
	v_mul_f32_e32 v140, v134, v140
	v_mul_f32_e32 v134, 0xbfb8aa3b, v135
	v_mul_f32_e32 v135, 0xbfb8aa3b, v154
	v_exp_f32_e32 v134, v134
	v_exp_f32_e32 v135, v135
	v_lshlrev_b32_e32 v154, 16, v169
	v_mul_f32_e32 v82, 0xbfb8aa3b, v82
	v_pk_add_f32 v[84:85], v[84:85], v[100:101]
	v_pk_add_f32 v[134:135], v[134:135], 1.0 op_sel_hi:[1,0]
	v_pk_add_f32 v[78:79], v[78:79], v[102:103]
	v_mul_f32_e32 v134, v134, v135
	v_rcp_f32_e32 v134, v134
	v_mul_f32_e32 v78, 0xbfb8aa3b, v78
	v_pk_add_f32 v[80:81], v[80:81], v[104:105]
	v_pk_add_f32 v[74:75], v[74:75], v[98:99]
	v_mul_f32_e32 v134, v141, v134
	v_lshlrev_b32_e32 v141, 16, v157
	v_cvt_pk_bf16_f32 v140, v140, v134
	v_mul_f32_e32 v134, 0xbfb8aa3b, v136
	v_mul_f32_e32 v135, 0xbfb8aa3b, v141
	v_exp_f32_e32 v134, v134
	v_exp_f32_e32 v135, v135
	v_mul_f32_e32 v136, v154, v141
	v_and_b32_e32 v154, 0xffff0000, v157
	v_and_b32_e32 v141, 0xffff0000, v169
	v_pk_add_f32 v[134:135], v[134:135], 1.0 op_sel_hi:[1,0]
	v_lshlrev_b64 v[156:157], 14, v[174:175]
	v_mul_f32_e32 v134, v134, v135
	v_rcp_f32_e32 v134, v134
	v_mul_f32_e32 v135, 0xbfb8aa3b, v154
	v_exp_f32_e32 v135, v135
	v_mul_f32_e32 v80, 0xbfb8aa3b, v80
	v_mul_f32_e32 v136, v136, v134
	v_mul_f32_e32 v134, 0xbfb8aa3b, v137
	v_exp_f32_e32 v134, v134
; __device__ __forceinline__ unsigned cvt_pk_bf16(float lo, float hi) { unsigned r; asm volatile("v_cvt_pk_bf16_f32 %0, %1, %2" : "=v"(r) : "v"(lo), "v"(hi)); return r; }
; __device__ __forceinline__ float bf_lo(unsigned w) { return __uint_as_float(w << 16); }
; __device__ __forceinline__ float bf_hi(unsigned w) { return __uint_as_float(w & 0xffff0000u); }
;     __device__ __forceinline__ void operator()(const f32x4 (&acc)[2][2][4][2], const Unit& u, int wr, int wc, int fr, int fq, const Pre&) const {
;     ...
;                 for (int m = 0; m < 4; ++m) { const int r = row0 + ai * HALF + m * 16; zv[m] = *(const u32x4*)(Z + (size_t)r * DE2 + c); gv[m] = *(const u32x4*)(Gm + (size_t)(c >> 4) * GSTR + r * 16 + (c & 15)); }
; #pragma unroll
;                 for (int m = 0; m < 4; ++m) { const int r = row0 + ai * HALF + m * 16;
;                     const u32x4 zw = zv[m], gw = gv[m];
;                     const f32x4 a0 = acc[ai][bj][m][0] + bs[bj][0], a1 = acc[ai][bj][m][1] + bs[bj][1];
;                     u32x4 w;
;                     w.x = cvt_pk_bf16(glu_gate_f(bf_lo(gw.x), a0[0], bf_lo(zw.x)), glu_gate_f(bf_hi(gw.x), a0[1], bf_hi(zw.x)));
;                     w.y = cvt_pk_bf16(glu_gate_f(bf_lo(gw.y), a0[2], bf_lo(zw.y)), glu_gate_f(bf_hi(gw.y), a0[3], bf_hi(zw.y)));
;                     w.z = cvt_pk_bf16(glu_gate_f(bf_lo(gw.z), a1[0], bf_lo(zw.z)), glu_gate_f(bf_hi(gw.z), a1[1], bf_hi(zw.z)));
;                     w.w = cvt_pk_bf16(glu_gate_f(bf_lo(gw.w), a1[2], bf_lo(zw.w)), glu_gate_f(bf_hi(gw.w), a1[3], bf_hi(zw.w)));
;                     *(u32x4*)(O + (size_t)r * DE + c) = w; } } }
	v_mul_f32_e32 v137, v141, v154
	v_mul_f32_e32 v74, 0xbfb8aa3b, v74
	v_pk_add_f32 v[76:77], v[76:77], v[100:101]
	v_pk_add_f32 v[134:135], v[134:135], 1.0 op_sel_hi:[1,0]
	v_pk_add_f32 v[70:71], v[70:71], v[30:31]
	v_mul_f32_e32 v134, v134, v135
	v_rcp_f32_e32 v134, v134
	v_mul_f32_e32 v70, 0xbfb8aa3b, v70
	v_pk_add_f32 v[72:73], v[72:73], v[32:33]
	v_pk_add_f32 v[66:67], v[66:67], v[26:27]
	v_mul_f32_e32 v134, v137, v134
	v_cvt_pk_bf16_f32 v141, v136, v134
	v_lshlrev_b64 v[134:135], 13, v[230:231]
	v_lshl_add_u64 v[134:135], s[44:45], 0, v[134:135]
	v_lshlrev_b32_e32 v136, 16, v146
	v_lshl_add_u64 v[154:155], v[134:135], 0, v[204:205]
	v_exp_f32_e32 v134, v126
	v_mul_f32_e32 v126, 0xbfb8aa3b, v136
	v_exp_f32_e32 v135, v126
	v_lshlrev_b32_e32 v137, 16, v150
	v_mul_f32_e32 v126, v137, v136
	v_and_b32_e32 v136, 0xffff0000, v146
	v_pk_add_f32 v[134:135], v[134:135], 1.0 op_sel_hi:[1,0]
	global_store_dwordx4 v[154:155], v[138:141], off
	v_mul_f32_e32 v134, v134, v135
	v_rcp_f32_e32 v134, v134
	v_and_b32_e32 v135, 0xffff0000, v150
	v_mul_f32_e32 v135, v135, v136
	v_mul_f32_e32 v72, 0xbfb8aa3b, v72
	v_mul_f32_e32 v134, v126, v134
	v_mul_f32_e32 v126, 0xbfb8aa3b, v127
	v_mul_f32_e32 v127, 0xbfb8aa3b, v136
	v_exp_f32_e32 v126, v126
	v_exp_f32_e32 v127, v127
	v_lshlrev_b32_e32 v136, 16, v151
	v_mul_f32_e32 v66, 0xbfb8aa3b, v66
	v_pk_add_f32 v[68:69], v[68:69], v[28:29]
	v_pk_add_f32 v[126:127], v[126:127], 1.0 op_sel_hi:[1,0]
	v_pk_add_f32 v[62:63], v[62:63], v[30:31]
	v_mul_f32_e32 v126, v126, v127
	v_rcp_f32_e32 v126, v126
	v_lshlrev_b32_e32 v127, 16, v147
	v_mul_f32_e32 v62, 0xbfb8aa3b, v62
	v_pk_add_f32 v[64:65], v[64:65], v[32:33]
	v_mul_f32_e32 v126, v135, v126
	v_cvt_pk_bf16_f32 v126, v134, v126
	v_exp_f32_e32 v134, v128
	v_mul_f32_e32 v128, 0xbfb8aa3b, v127
	v_exp_f32_e32 v135, v128
	v_mul_f32_e32 v127, v136, v127
	v_mul_f32_e32 v64, 0xbfb8aa3b, v64
	v_pk_add_f32 v[58:59], v[58:59], v[26:27]
	v_pk_add_f32 v[134:135], v[134:135], 1.0 op_sel_hi:[1,0]
	v_mul_f32_e32 v58, 0xbfb8aa3b, v58
	v_mul_f32_e32 v128, v134, v135
	v_rcp_f32_e32 v128, v128
	v_and_b32_e32 v135, 0xffff0000, v147
	v_and_b32_e32 v134, 0xffff0000, v151
	v_mul_f32_e32 v134, v134, v135
	v_mul_f32_e32 v127, v127, v128
	v_mul_f32_e32 v128, 0xbfb8aa3b, v129
	v_mul_f32_e32 v129, 0xbfb8aa3b, v135
	v_exp_f32_e32 v128, v128
	v_exp_f32_e32 v129, v129
	v_lshlrev_b32_e32 v135, 16, v152
	v_lshlrev_b64 v[150:151], 14, v[176:177]
	v_pk_add_f32 v[60:61], v[60:61], v[28:29]
	v_pk_add_f32 v[128:129], v[128:129], 1.0 op_sel_hi:[1,0]
	v_pk_add_f32 v[54:55], v[54:55], v[30:31]
	v_mul_f32_e32 v128, v128, v129
	v_rcp_f32_e32 v128, v128
	v_mul_f32_e32 v54, 0xbfb8aa3b, v54
	v_pk_add_f32 v[56:57], v[56:57], v[32:33]
	v_pk_add_f32 v[50:51], v[50:51], v[26:27]
	v_mul_f32_e32 v128, v134, v128
	v_lshlrev_b32_e32 v134, 16, v148
	v_cvt_pk_bf16_f32 v127, v127, v128
	v_exp_f32_e32 v128, v122
	v_mul_f32_e32 v122, 0xbfb8aa3b, v134
	v_exp_f32_e32 v129, v122
	v_mul_f32_e32 v122, v135, v134
	v_and_b32_e32 v134, 0xffff0000, v148
	v_mul_f32_e32 v56, 0xbfb8aa3b, v56
	v_pk_add_f32 v[128:129], v[128:129], 1.0 op_sel_hi:[1,0]
	v_mul_f32_e32 v50, 0xbfb8aa3b, v50
	v_mul_f32_e32 v128, v128, v129
	v_rcp_f32_e32 v128, v128
	v_and_b32_e32 v129, 0xffff0000, v152
	v_mul_f32_e32 v129, v129, v134
	v_pk_add_f32 v[52:53], v[52:53], v[28:29]
	v_mul_f32_e32 v128, v122, v128
	v_mul_f32_e32 v122, 0xbfb8aa3b, v123
	v_mul_f32_e32 v123, 0xbfb8aa3b, v134
	v_exp_f32_e32 v122, v122
	v_exp_f32_e32 v123, v123
	v_lshlrev_b32_e32 v134, 16, v153
	v_pk_add_f32 v[46:47], v[46:47], v[30:31]
	v_pk_add_f32 v[48:49], v[48:49], v[32:33]
	v_pk_add_f32 v[122:123], v[122:123], 1.0 op_sel_hi:[1,0]
	v_mul_f32_e32 v46, 0xbfb8aa3b, v46
	v_mul_f32_e32 v122, v122, v123
	v_rcp_f32_e32 v122, v122
	v_mul_f32_e32 v48, 0xbfb8aa3b, v48
	v_pk_add_f32 v[42:43], v[42:43], v[26:27]
	v_pk_add_f32 v[44:45], v[44:45], v[28:29]
	v_mul_f32_e32 v122, v129, v122
	v_lshlrev_b32_e32 v129, 16, v149
	v_cvt_pk_bf16_f32 v128, v128, v122
	v_mul_f32_e32 v122, 0xbfb8aa3b, v124
	v_mul_f32_e32 v123, 0xbfb8aa3b, v129
	v_exp_f32_e32 v122, v122
	v_exp_f32_e32 v123, v123
	v_mul_f32_e32 v124, v134, v129
	v_and_b32_e32 v134, 0xffff0000, v149
	v_and_b32_e32 v129, 0xffff0000, v153
	v_pk_add_f32 v[122:123], v[122:123], 1.0 op_sel_hi:[1,0]
	v_mul_f32_e32 v42, 0xbfb8aa3b, v42
	v_mul_f32_e32 v122, v122, v123
	v_rcp_f32_e32 v122, v122
	v_mul_f32_e32 v123, 0xbfb8aa3b, v134
	v_exp_f32_e32 v123, v123
	v_pk_add_f32 v[38:39], v[38:39], v[30:31]
	v_mul_f32_e32 v124, v124, v122
	v_mul_f32_e32 v122, 0xbfb8aa3b, v125
	v_exp_f32_e32 v122, v122
	v_mul_f32_e32 v125, v129, v134
	v_mul_f32_e32 v38, 0xbfb8aa3b, v38
	v_pk_add_f32 v[40:41], v[40:41], v[32:33]
	v_pk_add_f32 v[122:123], v[122:123], 1.0 op_sel_hi:[1,0]
	v_mul_f32_e32 v40, 0xbfb8aa3b, v40
	v_mul_f32_e32 v122, v122, v123
	v_rcp_f32_e32 v122, v122
	v_pk_add_f32 v[34:35], v[34:35], v[26:27]
	v_pk_add_f32 v[36:37], v[36:37], v[28:29]
	v_mul_f32_e32 v34, 0xbfb8aa3b, v34
	v_mul_f32_e32 v122, v125, v122
	v_cvt_pk_bf16_f32 v129, v124, v122
	v_lshlrev_b64 v[122:123], 13, v[228:229]
	v_lshl_add_u64 v[122:123], s[44:45], 0, v[122:123]
	v_lshlrev_b32_e32 v124, 16, v130
	v_lshl_add_u64 v[146:147], v[122:123], 0, v[204:205]
	v_exp_f32_e32 v122, v118
	v_mul_f32_e32 v118, 0xbfb8aa3b, v124
	v_exp_f32_e32 v123, v118
	v_lshlrev_b32_e32 v125, 16, v142
	v_mul_f32_e32 v118, v125, v124
	v_and_b32_e32 v124, 0xffff0000, v130
	v_pk_add_f32 v[122:123], v[122:123], 1.0 op_sel_hi:[1,0]
	global_store_dwordx4 v[146:147], v[126:129], off
	v_mul_f32_e32 v122, v122, v123
	v_rcp_f32_e32 v122, v122
	v_and_b32_e32 v123, 0xffff0000, v142
	v_mul_f32_e32 v123, v123, v124
; __device__ __forceinline__ unsigned cvt_pk_bf16(float lo, float hi) { unsigned r; asm volatile("v_cvt_pk_bf16_f32 %0, %1, %2" : "=v"(r) : "v"(lo), "v"(hi)); return r; }
; __device__ __forceinline__ float bf_lo(unsigned w) { return __uint_as_float(w << 16); }
; __device__ __forceinline__ float bf_hi(unsigned w) { return __uint_as_float(w & 0xffff0000u); }
;     __device__ __forceinline__ void operator()(const f32x4 (&acc)[2][2][4][2], const Unit& u, int wr, int wc, int fr, int fq, const Pre&) const {
;     ...
;             for (int ai = 0; ai < 2; ++ai) { u32x4 zv[4], gv[4];
; #pragma unroll
;                 for (int m = 0; m < 4; ++m) { const int r = row0 + ai * HALF + m * 16; zv[m] = *(const u32x4*)(Z + (size_t)r * DE2 + c); gv[m] = *(const u32x4*)(Gm + (size_t)(c >> 4) * GSTR + r * 16 + (c & 15)); }
; #pragma unroll
;                 for (int m = 0; m < 4; ++m) { const int r = row0 + ai * HALF + m * 16;
;                     const u32x4 zw = zv[m], gw = gv[m];
;                     const f32x4 a0 = acc[ai][bj][m][0] + bs[bj][0], a1 = acc[ai][bj][m][1] + bs[bj][1];
;                     u32x4 w;
;                     w.x = cvt_pk_bf16(glu_gate_f(bf_lo(gw.x), a0[0], bf_lo(zw.x)), glu_gate_f(bf_hi(gw.x), a0[1], bf_hi(zw.x)));
;                     w.y = cvt_pk_bf16(glu_gate_f(bf_lo(gw.y), a0[2], bf_lo(zw.y)), glu_gate_f(bf_hi(gw.y), a0[3], bf_hi(zw.y)));
;                     w.z = cvt_pk_bf16(glu_gate_f(bf_lo(gw.z), a1[0], bf_lo(zw.z)), glu_gate_f(bf_hi(gw.z), a1[1], bf_hi(zw.z)));
;                     w.w = cvt_pk_bf16(glu_gate_f(bf_lo(gw.w), a1[2], bf_lo(zw.w)), glu_gate_f(bf_hi(gw.w), a1[3], bf_hi(zw.w)));
;                     *(u32x4*)(O + (size_t)r * DE + c) = w; } } }
	v_pk_add_f32 v[22:23], v[22:23], v[30:31]
	v_mul_f32_e32 v122, v118, v122
	v_mul_f32_e32 v118, 0xbfb8aa3b, v119
	v_mul_f32_e32 v119, 0xbfb8aa3b, v124
	v_exp_f32_e32 v118, v118
	v_exp_f32_e32 v119, v119
	v_lshlrev_b32_e32 v124, 16, v143
	v_mul_f32_e32 v22, 0xbfb8aa3b, v22
	v_pk_add_f32 v[24:25], v[24:25], v[32:33]
	v_pk_add_f32 v[118:119], v[118:119], 1.0 op_sel_hi:[1,0]
	v_mul_f32_e32 v24, 0xbfb8aa3b, v24
	v_mul_f32_e32 v118, v118, v119
	v_rcp_f32_e32 v118, v118
	v_lshlrev_b32_e32 v119, 16, v131
	v_pk_add_f32 v[18:19], v[18:19], v[26:27]
	v_pk_add_f32 v[20:21], v[20:21], v[28:29]
	v_mul_f32_e32 v118, v123, v118
	v_cvt_pk_bf16_f32 v118, v122, v118
	v_exp_f32_e32 v122, v120
	v_mul_f32_e32 v120, 0xbfb8aa3b, v119
	v_exp_f32_e32 v123, v120
	v_mul_f32_e32 v119, v124, v119
	v_mul_f32_e32 v18, 0xbfb8aa3b, v18
	v_pk_add_f32 v[14:15], v[14:15], v[30:31]
	v_pk_add_f32 v[122:123], v[122:123], 1.0 op_sel_hi:[1,0]
	v_mul_f32_e32 v14, 0xbfb8aa3b, v14
	v_mul_f32_e32 v120, v122, v123
	v_rcp_f32_e32 v120, v120
	v_and_b32_e32 v123, 0xffff0000, v131
	v_and_b32_e32 v122, 0xffff0000, v143
	v_mul_f32_e32 v122, v122, v123
	v_mul_f32_e32 v119, v119, v120
	v_mul_f32_e32 v120, 0xbfb8aa3b, v121
	v_mul_f32_e32 v121, 0xbfb8aa3b, v123
	v_exp_f32_e32 v120, v120
	v_exp_f32_e32 v121, v121
	v_lshlrev_b32_e32 v123, 16, v144
	v_pk_add_f32 v[16:17], v[16:17], v[32:33]
	v_pk_add_f32 v[10:11], v[10:11], v[26:27]
	v_pk_add_f32 v[120:121], v[120:121], 1.0 op_sel_hi:[1,0]
	v_mul_f32_e32 v16, 0xbfb8aa3b, v16
	v_mul_f32_e32 v120, v120, v121
	v_rcp_f32_e32 v120, v120
	v_mul_f32_e32 v10, 0xbfb8aa3b, v10
	v_pk_add_f32 v[12:13], v[12:13], v[28:29]
	v_pk_add_f32 v[6:7], v[6:7], v[30:31]
	v_mul_f32_e32 v120, v122, v120
	v_lshlrev_b32_e32 v122, 16, v132
	v_cvt_pk_bf16_f32 v119, v119, v120
	v_exp_f32_e32 v120, v114
	v_mul_f32_e32 v114, 0xbfb8aa3b, v122
	v_exp_f32_e32 v121, v114
	v_mul_f32_e32 v114, v123, v122
	v_and_b32_e32 v122, 0xffff0000, v132
	v_mul_f32_e32 v6, 0xbfb8aa3b, v6
	v_pk_add_f32 v[120:121], v[120:121], 1.0 op_sel_hi:[1,0]
	v_pk_add_f32 v[8:9], v[8:9], v[32:33]
	v_mul_f32_e32 v120, v120, v121
	v_rcp_f32_e32 v120, v120
	v_and_b32_e32 v121, 0xffff0000, v144
	v_mul_f32_e32 v121, v121, v122
	v_mul_f32_e32 v8, 0xbfb8aa3b, v8
	v_mul_f32_e32 v120, v114, v120
	v_mul_f32_e32 v114, 0xbfb8aa3b, v115
	v_mul_f32_e32 v115, 0xbfb8aa3b, v122
	v_exp_f32_e32 v114, v114
	v_exp_f32_e32 v115, v115
	v_lshlrev_b32_e32 v122, 16, v145
	v_pk_add_f32 v[2:3], v[2:3], v[26:27]
	v_pk_add_f32 v[4:5], v[4:5], v[28:29]
	v_pk_add_f32 v[114:115], v[114:115], 1.0 op_sel_hi:[1,0]
	v_mul_f32_e32 v2, 0xbfb8aa3b, v2
	v_mul_f32_e32 v114, v114, v115
	v_rcp_f32_e32 v114, v114
	s_nop 0
	v_mul_f32_e32 v114, v121, v114
	v_lshlrev_b32_e32 v121, 16, v133
	v_cvt_pk_bf16_f32 v120, v120, v114
	v_mul_f32_e32 v114, 0xbfb8aa3b, v116
	v_mul_f32_e32 v115, 0xbfb8aa3b, v121
	v_exp_f32_e32 v114, v114
	v_exp_f32_e32 v115, v115
	v_mul_f32_e32 v116, v122, v121
	v_and_b32_e32 v122, 0xffff0000, v133
	v_and_b32_e32 v121, 0xffff0000, v145
	v_pk_add_f32 v[114:115], v[114:115], 1.0 op_sel_hi:[1,0]
	s_nop 0
	v_mul_f32_e32 v114, v114, v115
	v_rcp_f32_e32 v114, v114
	v_mul_f32_e32 v115, 0xbfb8aa3b, v122
	v_exp_f32_e32 v115, v115
	v_mul_f32_e32 v116, v116, v114
	v_mul_f32_e32 v114, 0xbfb8aa3b, v117
	v_exp_f32_e32 v114, v114
	v_mul_f32_e32 v117, v121, v122
	v_pk_add_f32 v[114:115], v[114:115], 1.0 op_sel_hi:[1,0]
	s_nop 0
	v_mul_f32_e32 v114, v114, v115
	v_rcp_f32_e32 v114, v114
	s_nop 0
	v_mul_f32_e32 v114, v117, v114
	v_cvt_pk_bf16_f32 v121, v116, v114
	v_lshlrev_b64 v[114:115], 13, v[226:227]
	v_lshl_add_u64 v[114:115], s[44:45], 0, v[114:115]
	v_lshl_add_u64 v[148:149], v[114:115], 0, v[204:205]
	global_store_dwordx4 v[148:149], v[118:121], off
	v_lshl_add_u64 v[114:115], v[222:223], 0, v[150:151]
	global_load_dwordx4 v[138:141], v[114:115], off
	v_lshlrev_b32_e32 v118, 4, v170
	v_ashrrev_i32_e32 v119, 31, v118
	v_lshlrev_b64 v[168:169], 1, v[118:119]
	v_lshl_add_u64 v[118:119], v[220:221], 0, v[168:169]
	global_load_dwordx4 v[118:121], v[118:119], off
	v_lshlrev_b32_e32 v114, 4, v176
	v_ashrrev_i32_e32 v115, 31, v114
	v_lshlrev_b64 v[152:153], 1, v[114:115]
	v_lshl_add_u64 v[114:115], v[220:221], 0, v[152:153]
	global_load_dwordx4 v[142:145], v[114:115], off
	v_lshl_add_u64 v[114:115], v[222:223], 0, v[156:157]
	global_load_dwordx4 v[130:133], v[114:115], off
	v_lshlrev_b32_e32 v114, 4, v174
	v_ashrrev_i32_e32 v115, 31, v114
	v_lshlrev_b64 v[158:159], 1, v[114:115]
	v_lshl_add_u64 v[114:115], v[220:221], 0, v[158:159]
	global_load_dwordx4 v[134:137], v[114:115], off
	v_lshl_add_u64 v[114:115], v[222:223], 0, v[160:161]
	global_load_dwordx4 v[122:125], v[114:115], off
	v_lshlrev_b32_e32 v114, 4, v172
	v_ashrrev_i32_e32 v115, 31, v114
	v_lshlrev_b64 v[164:165], 1, v[114:115]
	v_lshl_add_u64 v[114:115], v[220:221], 0, v[164:165]
	global_load_dwordx4 v[126:129], v[114:115], off
	v_lshl_add_u64 v[114:115], v[222:223], 0, v[166:167]
	global_load_dwordx4 v[114:117], v[114:115], off
	s_waitcnt vmcnt(0)
; __device__ __forceinline__ unsigned cvt_pk_bf16(float lo, float hi) { unsigned r; asm volatile("v_cvt_pk_bf16_f32 %0, %1, %2" : "=v"(r) : "v"(lo), "v"(hi)); return r; }
; __device__ __forceinline__ float bf_lo(unsigned w) { return __uint_as_float(w << 16); }
; __device__ __forceinline__ float bf_hi(unsigned w) { return __uint_as_float(w & 0xffff0000u); }
;     __device__ __forceinline__ void operator()(const f32x4 (&acc)[2][2][4][2], const Unit& u, int wr, int wc, int fr, int fq, const Pre&) const {
;     ...
;                 for (int m = 0; m < 4; ++m) { const int r = row0 + ai * HALF + m * 16;
;                     const u32x4 zw = zv[m], gw = gv[m];
;                     const f32x4 a0 = acc[ai][bj][m][0] + bs[bj][0], a1 = acc[ai][bj][m][1] + bs[bj][1];
;                     u32x4 w;
;                     w.x = cvt_pk_bf16(glu_gate_f(bf_lo(gw.x), a0[0], bf_lo(zw.x)), glu_gate_f(bf_hi(gw.x), a0[1], bf_hi(zw.x)));
;                     w.y = cvt_pk_bf16(glu_gate_f(bf_lo(gw.y), a0[2], bf_lo(zw.y)), glu_gate_f(bf_hi(gw.y), a0[3], bf_hi(zw.y)));
;                     w.z = cvt_pk_bf16(glu_gate_f(bf_lo(gw.z), a1[0], bf_lo(zw.z)), glu_gate_f(bf_hi(gw.z), a1[1], bf_hi(zw.z)));
;                     w.w = cvt_pk_bf16(glu_gate_f(bf_lo(gw.w), a1[2], bf_lo(zw.w)), glu_gate_f(bf_hi(gw.w), a1[3], bf_hi(zw.w)));
;                     *(u32x4*)(O + (size_t)r * DE + c) = w; } } }
	v_lshlrev_b32_e32 v186, 16, v138
	v_mul_f32_e32 v110, 0xbfb8aa3b, v186
	v_exp_f32_e32 v185, v110
	v_and_b32_e32 v138, 0xffff0000, v138
	v_pk_add_f32 v[184:185], v[184:185], 1.0 op_sel_hi:[1,0]
	s_nop 0
	v_mul_f32_e32 v184, v184, v185
	v_rcp_f32_e32 v184, v184
	v_lshlrev_b32_e32 v187, 16, v142
	v_mul_f32_e32 v110, v187, v186
	v_mul_f32_e32 v184, v110, v184
	v_mul_f32_e32 v110, 0xbfb8aa3b, v111
	v_mul_f32_e32 v111, 0xbfb8aa3b, v138
	v_exp_f32_e32 v110, v110
	v_exp_f32_e32 v111, v111
	v_and_b32_e32 v142, 0xffff0000, v142
	v_mul_f32_e32 v138, v142, v138
	v_pk_add_f32 v[110:111], v[110:111], 1.0 op_sel_hi:[1,0]
	s_nop 0
	v_mul_f32_e32 v110, v110, v111
	v_rcp_f32_e32 v110, v110
	v_lshlrev_b32_e32 v111, 16, v139
	v_and_b32_e32 v139, 0xffff0000, v139
	v_mul_f32_e32 v110, v138, v110
	v_cvt_pk_bf16_f32 v110, v184, v110
	v_exp_f32_e32 v184, v112
	v_mul_f32_e32 v112, 0xbfb8aa3b, v111
	v_exp_f32_e32 v185, v112
	v_lshlrev_b32_e32 v138, 16, v143
	v_mul_f32_e32 v111, v138, v111
	v_and_b32_e32 v138, 0xffff0000, v143
	v_pk_add_f32 v[184:185], v[184:185], 1.0 op_sel_hi:[1,0]
	v_mul_f32_e32 v138, v138, v139
	v_mul_f32_e32 v112, v184, v185
	v_rcp_f32_e32 v112, v112
	s_nop 0
	v_mul_f32_e32 v111, v111, v112
	v_mul_f32_e32 v112, 0xbfb8aa3b, v113
	v_mul_f32_e32 v113, 0xbfb8aa3b, v139
	v_exp_f32_e32 v112, v112
	v_exp_f32_e32 v113, v113
	v_lshlrev_b32_e32 v139, 16, v144
	v_pk_add_f32 v[112:113], v[112:113], 1.0 op_sel_hi:[1,0]
	s_nop 0
	v_mul_f32_e32 v112, v112, v113
	v_rcp_f32_e32 v112, v112
	s_nop 0
	v_mul_f32_e32 v112, v138, v112
	v_lshlrev_b32_e32 v138, 16, v140
	v_cvt_pk_bf16_f32 v111, v111, v112
	v_exp_f32_e32 v112, v106
	v_mul_f32_e32 v106, 0xbfb8aa3b, v138
	v_exp_f32_e32 v113, v106
	v_mul_f32_e32 v106, v139, v138
	v_and_b32_e32 v138, 0xffff0000, v140
	v_pk_add_f32 v[112:113], v[112:113], 1.0 op_sel_hi:[1,0]
	s_nop 0
	v_mul_f32_e32 v112, v112, v113
	v_rcp_f32_e32 v112, v112
	v_and_b32_e32 v113, 0xffff0000, v144
	v_mul_f32_e32 v113, v113, v138
	v_mul_f32_e32 v112, v106, v112
	v_mul_f32_e32 v106, 0xbfb8aa3b, v107
	v_mul_f32_e32 v107, 0xbfb8aa3b, v138
	v_exp_f32_e32 v106, v106
	v_exp_f32_e32 v107, v107
	v_lshlrev_b32_e32 v138, 16, v145
	v_pk_add_f32 v[106:107], v[106:107], 1.0 op_sel_hi:[1,0]
	s_nop 0
	v_mul_f32_e32 v106, v106, v107
	v_rcp_f32_e32 v106, v106
	s_nop 0
	v_mul_f32_e32 v106, v113, v106
	v_lshlrev_b32_e32 v113, 16, v141
	v_cvt_pk_bf16_f32 v112, v112, v106
	v_mul_f32_e32 v106, 0xbfb8aa3b, v108
	v_mul_f32_e32 v107, 0xbfb8aa3b, v113
	v_exp_f32_e32 v106, v106
	v_exp_f32_e32 v107, v107
	v_mul_f32_e32 v108, v138, v113
	v_and_b32_e32 v138, 0xffff0000, v141
	v_and_b32_e32 v113, 0xffff0000, v145
	v_pk_add_f32 v[106:107], v[106:107], 1.0 op_sel_hi:[1,0]
	s_nop 0
	v_mul_f32_e32 v106, v106, v107
	v_rcp_f32_e32 v106, v106
	v_mul_f32_e32 v107, 0xbfb8aa3b, v138
	v_exp_f32_e32 v107, v107
	v_mul_f32_e32 v108, v108, v106
	v_mul_f32_e32 v106, 0xbfb8aa3b, v109
	v_exp_f32_e32 v106, v106
	v_mul_f32_e32 v109, v113, v138
	v_pk_add_f32 v[106:107], v[106:107], 1.0 op_sel_hi:[1,0]
	s_nop 0
	v_mul_f32_e32 v106, v106, v107
	v_rcp_f32_e32 v106, v106
	s_nop 0
	v_mul_f32_e32 v106, v109, v106
	v_cvt_pk_bf16_f32 v113, v108, v106
	v_lshlrev_b64 v[106:107], 13, v[176:177]
	v_lshl_add_u64 v[106:107], s[44:45], 0, v[106:107]
	v_lshl_add_u64 v[106:107], v[106:107], 0, v[204:205]
	global_store_dwordx4 v[106:107], v[110:113], off
	v_exp_f32_e32 v108, v94
	s_nop 0
	v_lshlrev_b32_e32 v110, 16, v130
	v_mul_f32_e32 v94, 0xbfb8aa3b, v110
	v_exp_f32_e32 v109, v94
	v_lshlrev_b32_e32 v111, 16, v134
	v_mul_f32_e32 v94, v111, v110
	v_and_b32_e32 v110, 0xffff0000, v130
	v_pk_add_f32 v[108:109], v[108:109], 1.0 op_sel_hi:[1,0]
	s_nop 0
	v_mul_f32_e32 v108, v108, v109
	v_rcp_f32_e32 v108, v108
	v_and_b32_e32 v109, 0xffff0000, v134
	v_mul_f32_e32 v109, v109, v110
	v_mul_f32_e32 v108, v94, v108
	v_mul_f32_e32 v94, 0xbfb8aa3b, v95
	v_mul_f32_e32 v95, 0xbfb8aa3b, v110
	v_exp_f32_e32 v94, v94
	v_exp_f32_e32 v95, v95
	v_lshlrev_b32_e32 v110, 16, v135
	v_pk_add_f32 v[94:95], v[94:95], 1.0 op_sel_hi:[1,0]
	s_nop 0
	v_mul_f32_e32 v94, v94, v95
	v_rcp_f32_e32 v94, v94
	v_lshlrev_b32_e32 v95, 16, v131
	v_mul_f32_e32 v94, v109, v94
	v_cvt_pk_bf16_f32 v94, v108, v94
	v_exp_f32_e32 v108, v96
	v_mul_f32_e32 v96, 0xbfb8aa3b, v95
	v_exp_f32_e32 v109, v96
	v_mul_f32_e32 v95, v110, v95
	v_pk_add_f32 v[108:109], v[108:109], 1.0 op_sel_hi:[1,0]
	s_nop 0
	v_mul_f32_e32 v96, v108, v109
	v_rcp_f32_e32 v96, v96
	v_and_b32_e32 v109, 0xffff0000, v131
	v_and_b32_e32 v108, 0xffff0000, v135
	v_mul_f32_e32 v108, v108, v109
	v_mul_f32_e32 v95, v95, v96
	v_mul_f32_e32 v96, 0xbfb8aa3b, v97
	v_mul_f32_e32 v97, 0xbfb8aa3b, v109
	v_exp_f32_e32 v96, v96
	v_exp_f32_e32 v97, v97
	v_lshlrev_b32_e32 v109, 16, v136
	v_pk_add_f32 v[96:97], v[96:97], 1.0 op_sel_hi:[1,0]
	s_nop 0
	v_mul_f32_e32 v96, v96, v97
	v_rcp_f32_e32 v96, v96
	s_nop 0
	v_mul_f32_e32 v96, v108, v96
	v_lshlrev_b32_e32 v108, 16, v132
	v_cvt_pk_bf16_f32 v95, v95, v96
	v_exp_f32_e32 v96, v90
	v_mul_f32_e32 v90, 0xbfb8aa3b, v108
	v_exp_f32_e32 v97, v90
	v_mul_f32_e32 v90, v109, v108
	v_and_b32_e32 v108, 0xffff0000, v132
	v_pk_add_f32 v[96:97], v[96:97], 1.0 op_sel_hi:[1,0]
	s_nop 0
	v_mul_f32_e32 v96, v96, v97
	v_rcp_f32_e32 v96, v96
	v_and_b32_e32 v97, 0xffff0000, v136
	v_mul_f32_e32 v97, v97, v108
	v_mul_f32_e32 v96, v90, v96
	v_mul_f32_e32 v90, 0xbfb8aa3b, v91
	v_mul_f32_e32 v91, 0xbfb8aa3b, v108
	v_exp_f32_e32 v90, v90
	v_exp_f32_e32 v91, v91
	v_lshlrev_b32_e32 v108, 16, v137
	v_pk_add_f32 v[90:91], v[90:91], 1.0 op_sel_hi:[1,0]
	s_nop 0
	v_mul_f32_e32 v90, v90, v91
	v_rcp_f32_e32 v90, v90
	s_nop 0
	v_mul_f32_e32 v90, v97, v90
	v_lshlrev_b32_e32 v97, 16, v133
; __device__ __forceinline__ unsigned cvt_pk_bf16(float lo, float hi) { unsigned r; asm volatile("v_cvt_pk_bf16_f32 %0, %1, %2" : "=v"(r) : "v"(lo), "v"(hi)); return r; }
; __device__ __forceinline__ float bf_lo(unsigned w) { return __uint_as_float(w << 16); }
; __device__ __forceinline__ float bf_hi(unsigned w) { return __uint_as_float(w & 0xffff0000u); }
;     __device__ __forceinline__ void operator()(const f32x4 (&acc)[2][2][4][2], const Unit& u, int wr, int wc, int fr, int fq, const Pre&) const {
;     ...
;                 for (int m = 0; m < 4; ++m) { const int r = row0 + ai * HALF + m * 16;
;                     const u32x4 zw = zv[m], gw = gv[m];
;                     const f32x4 a0 = acc[ai][bj][m][0] + bs[bj][0], a1 = acc[ai][bj][m][1] + bs[bj][1];
;                     u32x4 w;
;                     w.x = cvt_pk_bf16(glu_gate_f(bf_lo(gw.x), a0[0], bf_lo(zw.x)), glu_gate_f(bf_hi(gw.x), a0[1], bf_hi(zw.x)));
;                     w.y = cvt_pk_bf16(glu_gate_f(bf_lo(gw.y), a0[2], bf_lo(zw.y)), glu_gate_f(bf_hi(gw.y), a0[3], bf_hi(zw.y)));
;                     w.z = cvt_pk_bf16(glu_gate_f(bf_lo(gw.z), a1[0], bf_lo(zw.z)), glu_gate_f(bf_hi(gw.z), a1[1], bf_hi(zw.z)));
;                     w.w = cvt_pk_bf16(glu_gate_f(bf_lo(gw.w), a1[2], bf_lo(zw.w)), glu_gate_f(bf_hi(gw.w), a1[3], bf_hi(zw.w)));
;                     *(u32x4*)(O + (size_t)r * DE + c) = w; } } }
	v_cvt_pk_bf16_f32 v96, v96, v90
	v_mul_f32_e32 v90, 0xbfb8aa3b, v92
	v_mul_f32_e32 v91, 0xbfb8aa3b, v97
	v_exp_f32_e32 v90, v90
	v_exp_f32_e32 v91, v91
	v_mul_f32_e32 v92, v108, v97
	v_and_b32_e32 v108, 0xffff0000, v133
	v_and_b32_e32 v97, 0xffff0000, v137
	v_pk_add_f32 v[90:91], v[90:91], 1.0 op_sel_hi:[1,0]
	s_nop 0
	v_mul_f32_e32 v90, v90, v91
	v_rcp_f32_e32 v90, v90
	v_mul_f32_e32 v91, 0xbfb8aa3b, v108
	v_exp_f32_e32 v91, v91
	v_mul_f32_e32 v92, v92, v90
	v_mul_f32_e32 v90, 0xbfb8aa3b, v93
	v_exp_f32_e32 v90, v90
	v_mul_f32_e32 v93, v97, v108
	v_pk_add_f32 v[90:91], v[90:91], 1.0 op_sel_hi:[1,0]
	s_nop 0
	v_mul_f32_e32 v90, v90, v91
	v_rcp_f32_e32 v90, v90
	s_nop 0
	v_mul_f32_e32 v90, v93, v90
	v_cvt_pk_bf16_f32 v97, v92, v90
	v_lshlrev_b64 v[90:91], 13, v[174:175]
	v_lshl_add_u64 v[90:91], s[44:45], 0, v[90:91]
	v_lshlrev_b32_e32 v92, 16, v122
	v_lshl_add_u64 v[108:109], v[90:91], 0, v[204:205]
	v_exp_f32_e32 v90, v86
	v_mul_f32_e32 v86, 0xbfb8aa3b, v92
	v_exp_f32_e32 v91, v86
	v_lshlrev_b32_e32 v93, 16, v126
	v_mul_f32_e32 v86, v93, v92
	v_and_b32_e32 v92, 0xffff0000, v122
	v_pk_add_f32 v[90:91], v[90:91], 1.0 op_sel_hi:[1,0]
	global_store_dwordx4 v[108:109], v[94:97], off
	v_mul_f32_e32 v90, v90, v91
	v_rcp_f32_e32 v90, v90
	v_and_b32_e32 v91, 0xffff0000, v126
	v_mul_f32_e32 v91, v91, v92
	v_mul_f32_e32 v90, v86, v90
	v_mul_f32_e32 v86, 0xbfb8aa3b, v87
	v_mul_f32_e32 v87, 0xbfb8aa3b, v92
	v_exp_f32_e32 v86, v86
	v_exp_f32_e32 v87, v87
	v_lshlrev_b32_e32 v92, 16, v127
	v_pk_add_f32 v[86:87], v[86:87], 1.0 op_sel_hi:[1,0]
	s_nop 0
	v_mul_f32_e32 v86, v86, v87
	v_rcp_f32_e32 v86, v86
	v_lshlrev_b32_e32 v87, 16, v123
	v_mul_f32_e32 v86, v91, v86
	v_cvt_pk_bf16_f32 v86, v90, v86
	v_exp_f32_e32 v90, v88
	v_mul_f32_e32 v88, 0xbfb8aa3b, v87
	v_exp_f32_e32 v91, v88
	v_mul_f32_e32 v87, v92, v87
	v_pk_add_f32 v[90:91], v[90:91], 1.0 op_sel_hi:[1,0]
	s_nop 0
	v_mul_f32_e32 v88, v90, v91
	v_rcp_f32_e32 v88, v88
	v_and_b32_e32 v91, 0xffff0000, v123
	v_and_b32_e32 v90, 0xffff0000, v127
	v_mul_f32_e32 v90, v90, v91
	v_mul_f32_e32 v87, v87, v88
	v_mul_f32_e32 v88, 0xbfb8aa3b, v89
	v_mul_f32_e32 v89, 0xbfb8aa3b, v91
	v_exp_f32_e32 v88, v88
	v_exp_f32_e32 v89, v89
	v_lshlrev_b32_e32 v91, 16, v128
	v_pk_add_f32 v[88:89], v[88:89], 1.0 op_sel_hi:[1,0]
	s_nop 0
	v_mul_f32_e32 v88, v88, v89
	v_rcp_f32_e32 v88, v88
	s_nop 0
	v_mul_f32_e32 v88, v90, v88
	v_lshlrev_b32_e32 v90, 16, v124
	v_cvt_pk_bf16_f32 v87, v87, v88
	v_exp_f32_e32 v88, v82
	v_mul_f32_e32 v82, 0xbfb8aa3b, v90
	v_exp_f32_e32 v89, v82
	v_mul_f32_e32 v82, v91, v90
	v_and_b32_e32 v90, 0xffff0000, v124
	v_pk_add_f32 v[88:89], v[88:89], 1.0 op_sel_hi:[1,0]
	s_nop 0
	v_mul_f32_e32 v88, v88, v89
	v_rcp_f32_e32 v88, v88
	v_and_b32_e32 v89, 0xffff0000, v128
	v_mul_f32_e32 v89, v89, v90
	v_mul_f32_e32 v88, v82, v88
	v_mul_f32_e32 v82, 0xbfb8aa3b, v83
	v_mul_f32_e32 v83, 0xbfb8aa3b, v90
	v_exp_f32_e32 v82, v82
	v_exp_f32_e32 v83, v83
	v_lshlrev_b32_e32 v90, 16, v129
	v_pk_add_f32 v[82:83], v[82:83], 1.0 op_sel_hi:[1,0]
	s_nop 0
	v_mul_f32_e32 v82, v82, v83
	v_rcp_f32_e32 v82, v82
	s_nop 0
	v_mul_f32_e32 v82, v89, v82
	v_lshlrev_b32_e32 v89, 16, v125
	v_cvt_pk_bf16_f32 v88, v88, v82
	v_mul_f32_e32 v82, 0xbfb8aa3b, v84
	v_mul_f32_e32 v83, 0xbfb8aa3b, v89
	v_exp_f32_e32 v82, v82
	v_exp_f32_e32 v83, v83
	v_mul_f32_e32 v84, v90, v89
	v_and_b32_e32 v90, 0xffff0000, v125
	v_and_b32_e32 v89, 0xffff0000, v129
	v_pk_add_f32 v[82:83], v[82:83], 1.0 op_sel_hi:[1,0]
	s_nop 0
	v_mul_f32_e32 v82, v82, v83
	v_rcp_f32_e32 v82, v82
	v_mul_f32_e32 v83, 0xbfb8aa3b, v90
	v_exp_f32_e32 v83, v83
	v_mul_f32_e32 v84, v84, v82
	v_mul_f32_e32 v82, 0xbfb8aa3b, v85
	v_exp_f32_e32 v82, v82
	v_mul_f32_e32 v85, v89, v90
	v_pk_add_f32 v[82:83], v[82:83], 1.0 op_sel_hi:[1,0]
	s_nop 0
	v_mul_f32_e32 v82, v82, v83
	v_rcp_f32_e32 v82, v82
	s_nop 0
	v_mul_f32_e32 v82, v85, v82
	v_cvt_pk_bf16_f32 v89, v84, v82
	v_lshlrev_b64 v[82:83], 13, v[172:173]
	v_lshl_add_u64 v[82:83], s[44:45], 0, v[82:83]
	v_lshlrev_b32_e32 v84, 16, v114
	v_lshl_add_u64 v[110:111], v[82:83], 0, v[204:205]
	v_exp_f32_e32 v82, v78
	v_mul_f32_e32 v78, 0xbfb8aa3b, v84
	v_exp_f32_e32 v83, v78
	v_lshlrev_b32_e32 v85, 16, v118
	v_mul_f32_e32 v78, v85, v84
	v_and_b32_e32 v84, 0xffff0000, v114
	v_pk_add_f32 v[82:83], v[82:83], 1.0 op_sel_hi:[1,0]
	global_store_dwordx4 v[110:111], v[86:89], off
	v_mul_f32_e32 v82, v82, v83
	v_rcp_f32_e32 v82, v82
	v_and_b32_e32 v83, 0xffff0000, v118
	v_mul_f32_e32 v83, v83, v84
	v_exp_f32_e32 v118, v70
	v_mul_f32_e32 v82, v78, v82
	v_mul_f32_e32 v78, 0xbfb8aa3b, v79
	v_mul_f32_e32 v79, 0xbfb8aa3b, v84
	v_exp_f32_e32 v78, v78
	v_exp_f32_e32 v79, v79
	v_lshlrev_b32_e32 v84, 16, v119
	v_pk_add_f32 v[78:79], v[78:79], 1.0 op_sel_hi:[1,0]
	s_nop 0
	v_mul_f32_e32 v78, v78, v79
	v_rcp_f32_e32 v78, v78
	v_lshlrev_b32_e32 v79, 16, v115
	v_mul_f32_e32 v78, v83, v78
	v_cvt_pk_bf16_f32 v78, v82, v78
	v_exp_f32_e32 v82, v80
	v_mul_f32_e32 v80, 0xbfb8aa3b, v79
	v_exp_f32_e32 v83, v80
	v_mul_f32_e32 v79, v84, v79
	v_pk_add_f32 v[82:83], v[82:83], 1.0 op_sel_hi:[1,0]
	s_nop 0
	v_mul_f32_e32 v80, v82, v83
	v_rcp_f32_e32 v80, v80
	v_and_b32_e32 v83, 0xffff0000, v115
	v_and_b32_e32 v82, 0xffff0000, v119
	v_mul_f32_e32 v82, v82, v83
	v_mul_f32_e32 v79, v79, v80
	v_mul_f32_e32 v80, 0xbfb8aa3b, v81
	v_mul_f32_e32 v81, 0xbfb8aa3b, v83
	v_exp_f32_e32 v80, v80
	v_exp_f32_e32 v81, v81
	v_lshlrev_b32_e32 v83, 16, v120
	v_pk_add_f32 v[80:81], v[80:81], 1.0 op_sel_hi:[1,0]
	s_nop 0
	v_mul_f32_e32 v80, v80, v81
	v_rcp_f32_e32 v80, v80
	s_nop 0
	v_mul_f32_e32 v80, v82, v80
	v_lshlrev_b32_e32 v82, 16, v116
	v_cvt_pk_bf16_f32 v79, v79, v80
	v_exp_f32_e32 v80, v74
; __device__ __forceinline__ unsigned cvt_pk_bf16(float lo, float hi) { unsigned r; asm volatile("v_cvt_pk_bf16_f32 %0, %1, %2" : "=v"(r) : "v"(lo), "v"(hi)); return r; }
; __device__ __forceinline__ float bf_lo(unsigned w) { return __uint_as_float(w << 16); }
; __device__ __forceinline__ float bf_hi(unsigned w) { return __uint_as_float(w & 0xffff0000u); }
;     __device__ __forceinline__ void operator()(const f32x4 (&acc)[2][2][4][2], const Unit& u, int wr, int wc, int fr, int fq, const Pre&) const {
;     ...
;             for (int ai = 0; ai < 2; ++ai) { u32x4 zv[4], gv[4];
; #pragma unroll
;                 for (int m = 0; m < 4; ++m) { const int r = row0 + ai * HALF + m * 16; zv[m] = *(const u32x4*)(Z + (size_t)r * DE2 + c); gv[m] = *(const u32x4*)(Gm + (size_t)(c >> 4) * GSTR + r * 16 + (c & 15)); }
; #pragma unroll
;                 for (int m = 0; m < 4; ++m) { const int r = row0 + ai * HALF + m * 16;
;                     const u32x4 zw = zv[m], gw = gv[m];
;                     const f32x4 a0 = acc[ai][bj][m][0] + bs[bj][0], a1 = acc[ai][bj][m][1] + bs[bj][1];
;                     u32x4 w;
;                     w.x = cvt_pk_bf16(glu_gate_f(bf_lo(gw.x), a0[0], bf_lo(zw.x)), glu_gate_f(bf_hi(gw.x), a0[1], bf_hi(zw.x)));
;                     w.y = cvt_pk_bf16(glu_gate_f(bf_lo(gw.y), a0[2], bf_lo(zw.y)), glu_gate_f(bf_hi(gw.y), a0[3], bf_hi(zw.y)));
;                     w.z = cvt_pk_bf16(glu_gate_f(bf_lo(gw.z), a1[0], bf_lo(zw.z)), glu_gate_f(bf_hi(gw.z), a1[1], bf_hi(zw.z)));
;                     w.w = cvt_pk_bf16(glu_gate_f(bf_lo(gw.w), a1[2], bf_lo(zw.w)), glu_gate_f(bf_hi(gw.w), a1[3], bf_hi(zw.w)));
;                     *(u32x4*)(O + (size_t)r * DE + c) = w; } } }
	v_mul_f32_e32 v74, 0xbfb8aa3b, v82
	v_exp_f32_e32 v81, v74
	v_mul_f32_e32 v74, v83, v82
	v_and_b32_e32 v82, 0xffff0000, v116
	v_pk_add_f32 v[80:81], v[80:81], 1.0 op_sel_hi:[1,0]
	s_nop 0
	v_mul_f32_e32 v80, v80, v81
	v_rcp_f32_e32 v80, v80
	v_and_b32_e32 v81, 0xffff0000, v120
	v_mul_f32_e32 v81, v81, v82
	v_mul_f32_e32 v80, v74, v80
	v_mul_f32_e32 v74, 0xbfb8aa3b, v75
	v_mul_f32_e32 v75, 0xbfb8aa3b, v82
	v_exp_f32_e32 v74, v74
	v_exp_f32_e32 v75, v75
	v_lshlrev_b32_e32 v82, 16, v121
	v_pk_add_f32 v[74:75], v[74:75], 1.0 op_sel_hi:[1,0]
	s_nop 0
	v_mul_f32_e32 v74, v74, v75
	v_rcp_f32_e32 v74, v74
	s_nop 0
	v_mul_f32_e32 v74, v81, v74
	v_lshlrev_b32_e32 v81, 16, v117
	v_cvt_pk_bf16_f32 v80, v80, v74
	v_mul_f32_e32 v74, 0xbfb8aa3b, v76
	v_mul_f32_e32 v75, 0xbfb8aa3b, v81
	v_exp_f32_e32 v74, v74
	v_exp_f32_e32 v75, v75
	v_mul_f32_e32 v76, v82, v81
	v_and_b32_e32 v82, 0xffff0000, v117
	v_and_b32_e32 v81, 0xffff0000, v121
	v_pk_add_f32 v[74:75], v[74:75], 1.0 op_sel_hi:[1,0]
	s_nop 0
	v_mul_f32_e32 v74, v74, v75
	v_rcp_f32_e32 v74, v74
	v_mul_f32_e32 v75, 0xbfb8aa3b, v82
	v_exp_f32_e32 v75, v75
	v_mul_f32_e32 v76, v76, v74
	v_mul_f32_e32 v74, 0xbfb8aa3b, v77
	v_exp_f32_e32 v74, v74
	v_mul_f32_e32 v77, v81, v82
	v_pk_add_f32 v[74:75], v[74:75], 1.0 op_sel_hi:[1,0]
	s_nop 0
	v_mul_f32_e32 v74, v74, v75
	v_rcp_f32_e32 v74, v74
	s_nop 0
	v_mul_f32_e32 v74, v77, v74
	v_cvt_pk_bf16_f32 v81, v76, v74
	v_lshlrev_b64 v[74:75], 13, v[170:171]
	v_lshl_add_u64 v[74:75], s[44:45], 0, v[74:75]
	v_lshl_add_u64 v[112:113], v[74:75], 0, v[204:205]
	v_or_b32_e32 v74, 0x80, v200
	v_ashrrev_i32_e32 v75, 31, v74
	v_ashrrev_i32_e32 v76, 4, v74
	v_mad_i64_i32 v[114:115], s[4:5], v76, s94, v[194:195]
	v_lshl_add_u64 v[76:77], s[46:47], 0, v[202:203]
	v_lshlrev_b64 v[116:117], 1, v[74:75]
	v_lshl_add_u64 v[74:75], v[76:77], 0, v[116:117]
	global_load_dwordx4 v[98:101], v[74:75], off
	s_nop 0
	global_store_dwordx4 v[112:113], v[78:81], off
	s_nop 1
	v_lshl_add_u64 v[78:79], v[114:115], 0, v[218:219]
	global_load_dwordx4 v[78:81], v[78:79], off
	v_lshl_add_u64 v[74:75], v[114:115], 0, v[206:207]
	global_load_dwordx4 v[102:105], v[74:75], off
	v_lshl_add_u64 v[74:75], s[46:47], 0, v[210:211]
	v_lshl_add_u64 v[74:75], v[74:75], 0, v[116:117]
	global_load_dwordx4 v[90:93], v[74:75], off
	v_lshl_add_u64 v[74:75], v[114:115], 0, v[208:209]
	global_load_dwordx4 v[94:97], v[74:75], off
	v_lshl_add_u64 v[74:75], s[46:47], 0, v[214:215]
	v_lshl_add_u64 v[74:75], v[74:75], 0, v[116:117]
	global_load_dwordx4 v[82:85], v[74:75], off
	v_lshl_add_u64 v[74:75], v[114:115], 0, v[212:213]
	global_load_dwordx4 v[86:89], v[74:75], off
	v_lshl_add_u64 v[74:75], s[46:47], 0, v[216:217]
	v_lshl_add_u64 v[74:75], v[74:75], 0, v[116:117]
	global_load_dwordx4 v[74:77], v[74:75], off
	s_waitcnt vmcnt(0)
	v_lshlrev_b32_e32 v120, 16, v98
	v_mul_f32_e32 v70, 0xbfb8aa3b, v120
	v_exp_f32_e32 v119, v70
	v_and_b32_e32 v98, 0xffff0000, v98
	v_pk_add_f32 v[118:119], v[118:119], 1.0 op_sel_hi:[1,0]
	s_nop 0
	v_mul_f32_e32 v118, v118, v119
	v_rcp_f32_e32 v118, v118
	v_lshlrev_b32_e32 v121, 16, v102
	v_mul_f32_e32 v70, v121, v120
	v_and_b32_e32 v102, 0xffff0000, v102
	v_mul_f32_e32 v118, v70, v118
	v_mul_f32_e32 v70, 0xbfb8aa3b, v71
	v_mul_f32_e32 v71, 0xbfb8aa3b, v98
	v_exp_f32_e32 v70, v70
	v_exp_f32_e32 v71, v71
	v_mul_f32_e32 v98, v102, v98
	v_pk_add_f32 v[70:71], v[70:71], 1.0 op_sel_hi:[1,0]
	s_nop 0
	v_mul_f32_e32 v70, v70, v71
	v_rcp_f32_e32 v70, v70
	v_lshlrev_b32_e32 v71, 16, v99
	v_and_b32_e32 v99, 0xffff0000, v99
	v_mul_f32_e32 v70, v98, v70
	v_cvt_pk_bf16_f32 v70, v118, v70
	v_exp_f32_e32 v118, v72
	v_mul_f32_e32 v72, 0xbfb8aa3b, v71
	v_exp_f32_e32 v119, v72
	v_lshlrev_b32_e32 v98, 16, v103
	v_mul_f32_e32 v71, v98, v71
	v_and_b32_e32 v98, 0xffff0000, v103
	v_pk_add_f32 v[118:119], v[118:119], 1.0 op_sel_hi:[1,0]
	v_mul_f32_e32 v98, v98, v99
	v_mul_f32_e32 v72, v118, v119
	v_rcp_f32_e32 v72, v72
	s_nop 0
	v_mul_f32_e32 v71, v71, v72
	v_mul_f32_e32 v72, 0xbfb8aa3b, v73
	v_mul_f32_e32 v73, 0xbfb8aa3b, v99
	v_exp_f32_e32 v72, v72
	v_exp_f32_e32 v73, v73
	v_lshlrev_b32_e32 v99, 16, v104
	v_pk_add_f32 v[72:73], v[72:73], 1.0 op_sel_hi:[1,0]
	s_nop 0
	v_mul_f32_e32 v72, v72, v73
	v_rcp_f32_e32 v72, v72
	s_nop 0
	v_mul_f32_e32 v72, v98, v72
	v_lshlrev_b32_e32 v98, 16, v100
	v_cvt_pk_bf16_f32 v71, v71, v72
	v_exp_f32_e32 v72, v66
	v_mul_f32_e32 v66, 0xbfb8aa3b, v98
	v_exp_f32_e32 v73, v66
	v_mul_f32_e32 v66, v99, v98
	v_and_b32_e32 v98, 0xffff0000, v100
	v_pk_add_f32 v[72:73], v[72:73], 1.0 op_sel_hi:[1,0]
	s_nop 0
	v_mul_f32_e32 v72, v72, v73
	v_rcp_f32_e32 v72, v72
	v_and_b32_e32 v73, 0xffff0000, v104
	v_mul_f32_e32 v73, v73, v98
	v_mul_f32_e32 v72, v66, v72
	v_mul_f32_e32 v66, 0xbfb8aa3b, v67
	v_mul_f32_e32 v67, 0xbfb8aa3b, v98
	v_exp_f32_e32 v66, v66
	v_exp_f32_e32 v67, v67
	v_lshlrev_b32_e32 v98, 16, v105
	v_pk_add_f32 v[66:67], v[66:67], 1.0 op_sel_hi:[1,0]
	s_nop 0
	v_mul_f32_e32 v66, v66, v67
	v_rcp_f32_e32 v66, v66
	s_nop 0
	v_mul_f32_e32 v66, v73, v66
	v_lshlrev_b32_e32 v73, 16, v101
	v_cvt_pk_bf16_f32 v72, v72, v66
	v_mul_f32_e32 v66, 0xbfb8aa3b, v68
	v_mul_f32_e32 v67, 0xbfb8aa3b, v73
	v_exp_f32_e32 v66, v66
	v_exp_f32_e32 v67, v67
	v_mul_f32_e32 v68, v98, v73
	v_and_b32_e32 v98, 0xffff0000, v101
	v_and_b32_e32 v73, 0xffff0000, v105
	v_pk_add_f32 v[66:67], v[66:67], 1.0 op_sel_hi:[1,0]
	s_nop 0
	v_mul_f32_e32 v66, v66, v67
	v_rcp_f32_e32 v66, v66
	v_mul_f32_e32 v67, 0xbfb8aa3b, v98
	v_exp_f32_e32 v67, v67
	v_mul_f32_e32 v68, v68, v66
	v_mul_f32_e32 v66, 0xbfb8aa3b, v69
	v_exp_f32_e32 v66, v66
	v_mul_f32_e32 v69, v73, v98
	v_pk_add_f32 v[66:67], v[66:67], 1.0 op_sel_hi:[1,0]
	s_nop 0
; __device__ __forceinline__ unsigned cvt_pk_bf16(float lo, float hi) { unsigned r; asm volatile("v_cvt_pk_bf16_f32 %0, %1, %2" : "=v"(r) : "v"(lo), "v"(hi)); return r; }
; __device__ __forceinline__ float bf_lo(unsigned w) { return __uint_as_float(w << 16); }
; __device__ __forceinline__ float bf_hi(unsigned w) { return __uint_as_float(w & 0xffff0000u); }
;     __device__ __forceinline__ void operator()(const f32x4 (&acc)[2][2][4][2], const Unit& u, int wr, int wc, int fr, int fq, const Pre&) const {
;     ...
;                 for (int m = 0; m < 4; ++m) { const int r = row0 + ai * HALF + m * 16;
;                     const u32x4 zw = zv[m], gw = gv[m];
;                     const f32x4 a0 = acc[ai][bj][m][0] + bs[bj][0], a1 = acc[ai][bj][m][1] + bs[bj][1];
;                     u32x4 w;
;                     w.x = cvt_pk_bf16(glu_gate_f(bf_lo(gw.x), a0[0], bf_lo(zw.x)), glu_gate_f(bf_hi(gw.x), a0[1], bf_hi(zw.x)));
;                     w.y = cvt_pk_bf16(glu_gate_f(bf_lo(gw.y), a0[2], bf_lo(zw.y)), glu_gate_f(bf_hi(gw.y), a0[3], bf_hi(zw.y)));
;                     w.z = cvt_pk_bf16(glu_gate_f(bf_lo(gw.z), a1[0], bf_lo(zw.z)), glu_gate_f(bf_hi(gw.z), a1[1], bf_hi(zw.z)));
;                     w.w = cvt_pk_bf16(glu_gate_f(bf_lo(gw.w), a1[2], bf_lo(zw.w)), glu_gate_f(bf_hi(gw.w), a1[3], bf_hi(zw.w)));
;                     *(u32x4*)(O + (size_t)r * DE + c) = w; } } }
	v_mul_f32_e32 v66, v66, v67
	v_rcp_f32_e32 v66, v66
	s_nop 0
	v_mul_f32_e32 v66, v69, v66
	v_cvt_pk_bf16_f32 v73, v68, v66
	v_lshlrev_b32_e32 v68, 16, v90
	v_exp_f32_e32 v66, v62
	v_mul_f32_e32 v62, 0xbfb8aa3b, v68
	v_exp_f32_e32 v67, v62
	v_lshlrev_b32_e32 v69, 16, v94
	v_mul_f32_e32 v62, v69, v68
	v_and_b32_e32 v68, 0xffff0000, v90
	v_pk_add_f32 v[66:67], v[66:67], 1.0 op_sel_hi:[1,0]
	global_store_dwordx4 v[162:163], v[70:73], off offset:256
	v_mul_f32_e32 v66, v66, v67
	v_rcp_f32_e32 v66, v66
	v_and_b32_e32 v67, 0xffff0000, v94
	v_mul_f32_e32 v67, v67, v68
	v_mul_f32_e32 v66, v62, v66
	v_mul_f32_e32 v62, 0xbfb8aa3b, v63
	v_mul_f32_e32 v63, 0xbfb8aa3b, v68
	v_exp_f32_e32 v62, v62
	v_exp_f32_e32 v63, v63
	v_lshlrev_b32_e32 v68, 16, v95
	v_pk_add_f32 v[62:63], v[62:63], 1.0 op_sel_hi:[1,0]
	s_nop 0
	v_mul_f32_e32 v62, v62, v63
	v_rcp_f32_e32 v62, v62
	v_lshlrev_b32_e32 v63, 16, v91
	v_mul_f32_e32 v62, v67, v62
	v_cvt_pk_bf16_f32 v62, v66, v62
	v_exp_f32_e32 v66, v64
	v_mul_f32_e32 v64, 0xbfb8aa3b, v63
	v_exp_f32_e32 v67, v64
	v_mul_f32_e32 v63, v68, v63
	v_pk_add_f32 v[66:67], v[66:67], 1.0 op_sel_hi:[1,0]
	s_nop 0
	v_mul_f32_e32 v64, v66, v67
	v_rcp_f32_e32 v64, v64
	v_and_b32_e32 v67, 0xffff0000, v91
	v_and_b32_e32 v66, 0xffff0000, v95
	v_mul_f32_e32 v66, v66, v67
	v_mul_f32_e32 v63, v63, v64
	v_mul_f32_e32 v64, 0xbfb8aa3b, v65
	v_mul_f32_e32 v65, 0xbfb8aa3b, v67
	v_exp_f32_e32 v64, v64
	v_exp_f32_e32 v65, v65
	v_lshlrev_b32_e32 v67, 16, v96
	v_pk_add_f32 v[64:65], v[64:65], 1.0 op_sel_hi:[1,0]
	s_nop 0
	v_mul_f32_e32 v64, v64, v65
	v_rcp_f32_e32 v64, v64
	s_nop 0
	v_mul_f32_e32 v64, v66, v64
	v_lshlrev_b32_e32 v66, 16, v92
	v_cvt_pk_bf16_f32 v63, v63, v64
	v_exp_f32_e32 v64, v58
	v_mul_f32_e32 v58, 0xbfb8aa3b, v66
	v_exp_f32_e32 v65, v58
	v_mul_f32_e32 v58, v67, v66
	v_and_b32_e32 v66, 0xffff0000, v92
	v_pk_add_f32 v[64:65], v[64:65], 1.0 op_sel_hi:[1,0]
	s_nop 0
	v_mul_f32_e32 v64, v64, v65
	v_rcp_f32_e32 v64, v64
	v_and_b32_e32 v65, 0xffff0000, v96
	v_mul_f32_e32 v65, v65, v66
	v_mul_f32_e32 v64, v58, v64
	v_mul_f32_e32 v58, 0xbfb8aa3b, v59
	v_mul_f32_e32 v59, 0xbfb8aa3b, v66
	v_exp_f32_e32 v58, v58
	v_exp_f32_e32 v59, v59
	v_lshlrev_b32_e32 v66, 16, v97
	v_pk_add_f32 v[58:59], v[58:59], 1.0 op_sel_hi:[1,0]
	s_nop 0
	v_mul_f32_e32 v58, v58, v59
	v_rcp_f32_e32 v58, v58
	s_nop 0
	v_mul_f32_e32 v58, v65, v58
	v_lshlrev_b32_e32 v65, 16, v93
	v_cvt_pk_bf16_f32 v64, v64, v58
	v_mul_f32_e32 v58, 0xbfb8aa3b, v60
	v_mul_f32_e32 v59, 0xbfb8aa3b, v65
	v_exp_f32_e32 v58, v58
	v_exp_f32_e32 v59, v59
	v_mul_f32_e32 v60, v66, v65
	v_and_b32_e32 v66, 0xffff0000, v93
	v_and_b32_e32 v65, 0xffff0000, v97
	v_pk_add_f32 v[58:59], v[58:59], 1.0 op_sel_hi:[1,0]
	s_nop 0
	v_mul_f32_e32 v58, v58, v59
	v_rcp_f32_e32 v58, v58
	v_mul_f32_e32 v59, 0xbfb8aa3b, v66
	v_exp_f32_e32 v59, v59
	v_mul_f32_e32 v60, v60, v58
	v_mul_f32_e32 v58, 0xbfb8aa3b, v61
	v_exp_f32_e32 v58, v58
	v_mul_f32_e32 v61, v65, v66
	v_pk_add_f32 v[58:59], v[58:59], 1.0 op_sel_hi:[1,0]
	s_nop 0
	v_mul_f32_e32 v58, v58, v59
	v_rcp_f32_e32 v58, v58
	s_nop 0
	v_mul_f32_e32 v58, v61, v58
	v_cvt_pk_bf16_f32 v65, v60, v58
	v_lshlrev_b32_e32 v60, 16, v82
	v_exp_f32_e32 v58, v54
	v_mul_f32_e32 v54, 0xbfb8aa3b, v60
	v_exp_f32_e32 v59, v54
	v_lshlrev_b32_e32 v61, 16, v86
	v_mul_f32_e32 v54, v61, v60
	v_and_b32_e32 v60, 0xffff0000, v82
	v_pk_add_f32 v[58:59], v[58:59], 1.0 op_sel_hi:[1,0]
	global_store_dwordx4 v[154:155], v[62:65], off offset:256
	v_mul_f32_e32 v58, v58, v59
	v_rcp_f32_e32 v58, v58
	v_and_b32_e32 v59, 0xffff0000, v86
	v_mul_f32_e32 v59, v59, v60
	v_mul_f32_e32 v58, v54, v58
	v_mul_f32_e32 v54, 0xbfb8aa3b, v55
	v_mul_f32_e32 v55, 0xbfb8aa3b, v60
	v_exp_f32_e32 v54, v54
	v_exp_f32_e32 v55, v55
	v_lshlrev_b32_e32 v60, 16, v87
	v_pk_add_f32 v[54:55], v[54:55], 1.0 op_sel_hi:[1,0]
	s_nop 0
	v_mul_f32_e32 v54, v54, v55
	v_rcp_f32_e32 v54, v54
	v_lshlrev_b32_e32 v55, 16, v83
	v_mul_f32_e32 v54, v59, v54
	v_cvt_pk_bf16_f32 v54, v58, v54
	v_exp_f32_e32 v58, v56
	v_mul_f32_e32 v56, 0xbfb8aa3b, v55
	v_exp_f32_e32 v59, v56
	v_mul_f32_e32 v55, v60, v55
	v_pk_add_f32 v[58:59], v[58:59], 1.0 op_sel_hi:[1,0]
	s_nop 0
	v_mul_f32_e32 v56, v58, v59
	v_rcp_f32_e32 v56, v56
	v_and_b32_e32 v59, 0xffff0000, v83
	v_and_b32_e32 v58, 0xffff0000, v87
	v_mul_f32_e32 v58, v58, v59
	v_mul_f32_e32 v55, v55, v56
	v_mul_f32_e32 v56, 0xbfb8aa3b, v57
	v_mul_f32_e32 v57, 0xbfb8aa3b, v59
	v_exp_f32_e32 v56, v56
	v_exp_f32_e32 v57, v57
	v_lshlrev_b32_e32 v59, 16, v88
	v_pk_add_f32 v[56:57], v[56:57], 1.0 op_sel_hi:[1,0]
	s_nop 0
	v_mul_f32_e32 v56, v56, v57
	v_rcp_f32_e32 v56, v56
	s_nop 0
	v_mul_f32_e32 v56, v58, v56
	v_lshlrev_b32_e32 v58, 16, v84
	v_cvt_pk_bf16_f32 v55, v55, v56
	v_exp_f32_e32 v56, v50
	v_mul_f32_e32 v50, 0xbfb8aa3b, v58
	v_exp_f32_e32 v57, v50
	v_mul_f32_e32 v50, v59, v58
	v_and_b32_e32 v58, 0xffff0000, v84
	v_pk_add_f32 v[56:57], v[56:57], 1.0 op_sel_hi:[1,0]
	s_nop 0
	v_mul_f32_e32 v56, v56, v57
	v_rcp_f32_e32 v56, v56
	v_and_b32_e32 v57, 0xffff0000, v88
	v_mul_f32_e32 v57, v57, v58
	v_mul_f32_e32 v56, v50, v56
	v_mul_f32_e32 v50, 0xbfb8aa3b, v51
	v_mul_f32_e32 v51, 0xbfb8aa3b, v58
	v_exp_f32_e32 v50, v50
	v_exp_f32_e32 v51, v51
	v_lshlrev_b32_e32 v58, 16, v89
	v_pk_add_f32 v[50:51], v[50:51], 1.0 op_sel_hi:[1,0]
	s_nop 0
	v_mul_f32_e32 v50, v50, v51
	v_rcp_f32_e32 v50, v50
	s_nop 0
	v_mul_f32_e32 v50, v57, v50
	v_lshlrev_b32_e32 v57, 16, v85
	v_cvt_pk_bf16_f32 v56, v56, v50
	v_mul_f32_e32 v50, 0xbfb8aa3b, v52
	v_mul_f32_e32 v51, 0xbfb8aa3b, v57
	v_exp_f32_e32 v50, v50
	v_exp_f32_e32 v51, v51
	v_mul_f32_e32 v52, v58, v57
	v_and_b32_e32 v58, 0xffff0000, v85
	v_and_b32_e32 v57, 0xffff0000, v89
; __device__ __forceinline__ unsigned cvt_pk_bf16(float lo, float hi) { unsigned r; asm volatile("v_cvt_pk_bf16_f32 %0, %1, %2" : "=v"(r) : "v"(lo), "v"(hi)); return r; }
; __device__ __forceinline__ float bf_lo(unsigned w) { return __uint_as_float(w << 16); }
; __device__ __forceinline__ float bf_hi(unsigned w) { return __uint_as_float(w & 0xffff0000u); }
;     __device__ __forceinline__ void operator()(const f32x4 (&acc)[2][2][4][2], const Unit& u, int wr, int wc, int fr, int fq, const Pre&) const {
;     ...
;             for (int ai = 0; ai < 2; ++ai) { u32x4 zv[4], gv[4];
; #pragma unroll
;                 for (int m = 0; m < 4; ++m) { const int r = row0 + ai * HALF + m * 16; zv[m] = *(const u32x4*)(Z + (size_t)r * DE2 + c); gv[m] = *(const u32x4*)(Gm + (size_t)(c >> 4) * GSTR + r * 16 + (c & 15)); }
; #pragma unroll
;                 for (int m = 0; m < 4; ++m) { const int r = row0 + ai * HALF + m * 16;
;                     const u32x4 zw = zv[m], gw = gv[m];
;                     const f32x4 a0 = acc[ai][bj][m][0] + bs[bj][0], a1 = acc[ai][bj][m][1] + bs[bj][1];
;                     u32x4 w;
;                     w.x = cvt_pk_bf16(glu_gate_f(bf_lo(gw.x), a0[0], bf_lo(zw.x)), glu_gate_f(bf_hi(gw.x), a0[1], bf_hi(zw.x)));
;                     w.y = cvt_pk_bf16(glu_gate_f(bf_lo(gw.y), a0[2], bf_lo(zw.y)), glu_gate_f(bf_hi(gw.y), a0[3], bf_hi(zw.y)));
;                     w.z = cvt_pk_bf16(glu_gate_f(bf_lo(gw.z), a1[0], bf_lo(zw.z)), glu_gate_f(bf_hi(gw.z), a1[1], bf_hi(zw.z)));
;                     w.w = cvt_pk_bf16(glu_gate_f(bf_lo(gw.w), a1[2], bf_lo(zw.w)), glu_gate_f(bf_hi(gw.w), a1[3], bf_hi(zw.w)));
;                     *(u32x4*)(O + (size_t)r * DE + c) = w; } } }
	v_pk_add_f32 v[50:51], v[50:51], 1.0 op_sel_hi:[1,0]
	s_nop 0
	v_mul_f32_e32 v50, v50, v51
	v_rcp_f32_e32 v50, v50
	v_mul_f32_e32 v51, 0xbfb8aa3b, v58
	v_exp_f32_e32 v51, v51
	v_mul_f32_e32 v52, v52, v50
	v_mul_f32_e32 v50, 0xbfb8aa3b, v53
	v_exp_f32_e32 v50, v50
	v_mul_f32_e32 v53, v57, v58
	v_pk_add_f32 v[50:51], v[50:51], 1.0 op_sel_hi:[1,0]
	s_nop 0
	v_mul_f32_e32 v50, v50, v51
	v_rcp_f32_e32 v50, v50
	s_nop 0
	v_mul_f32_e32 v50, v53, v50
	v_cvt_pk_bf16_f32 v57, v52, v50
	v_lshlrev_b32_e32 v52, 16, v74
	v_exp_f32_e32 v50, v46
	v_mul_f32_e32 v46, 0xbfb8aa3b, v52
	v_exp_f32_e32 v51, v46
	v_lshlrev_b32_e32 v53, 16, v78
	v_mul_f32_e32 v46, v53, v52
	v_and_b32_e32 v52, 0xffff0000, v74
	v_pk_add_f32 v[50:51], v[50:51], 1.0 op_sel_hi:[1,0]
	global_store_dwordx4 v[146:147], v[54:57], off offset:256
	v_mul_f32_e32 v50, v50, v51
	v_rcp_f32_e32 v50, v50
	v_and_b32_e32 v51, 0xffff0000, v78
	v_mul_f32_e32 v51, v51, v52
	v_exp_f32_e32 v74, v38
	v_mul_f32_e32 v50, v46, v50
	v_mul_f32_e32 v46, 0xbfb8aa3b, v47
	v_mul_f32_e32 v47, 0xbfb8aa3b, v52
	v_exp_f32_e32 v46, v46
	v_exp_f32_e32 v47, v47
	v_lshlrev_b32_e32 v52, 16, v79
	v_pk_add_f32 v[46:47], v[46:47], 1.0 op_sel_hi:[1,0]
	s_nop 0
	v_mul_f32_e32 v46, v46, v47
	v_rcp_f32_e32 v46, v46
	v_lshlrev_b32_e32 v47, 16, v75
	v_mul_f32_e32 v46, v51, v46
	v_cvt_pk_bf16_f32 v46, v50, v46
	v_exp_f32_e32 v50, v48
	v_mul_f32_e32 v48, 0xbfb8aa3b, v47
	v_exp_f32_e32 v51, v48
	v_mul_f32_e32 v47, v52, v47
	v_pk_add_f32 v[50:51], v[50:51], 1.0 op_sel_hi:[1,0]
	s_nop 0
	v_mul_f32_e32 v48, v50, v51
	v_rcp_f32_e32 v48, v48
	v_and_b32_e32 v51, 0xffff0000, v75
	v_and_b32_e32 v50, 0xffff0000, v79
	v_mul_f32_e32 v50, v50, v51
	v_mul_f32_e32 v47, v47, v48
	v_mul_f32_e32 v48, 0xbfb8aa3b, v49
	v_mul_f32_e32 v49, 0xbfb8aa3b, v51
	v_exp_f32_e32 v48, v48
	v_exp_f32_e32 v49, v49
	v_lshlrev_b32_e32 v51, 16, v80
	v_pk_add_f32 v[48:49], v[48:49], 1.0 op_sel_hi:[1,0]
	s_nop 0
	v_mul_f32_e32 v48, v48, v49
	v_rcp_f32_e32 v48, v48
	s_nop 0
	v_mul_f32_e32 v48, v50, v48
	v_lshlrev_b32_e32 v50, 16, v76
	v_cvt_pk_bf16_f32 v47, v47, v48
	v_exp_f32_e32 v48, v42
	v_mul_f32_e32 v42, 0xbfb8aa3b, v50
	v_exp_f32_e32 v49, v42
	v_mul_f32_e32 v42, v51, v50
	v_and_b32_e32 v50, 0xffff0000, v76
	v_pk_add_f32 v[48:49], v[48:49], 1.0 op_sel_hi:[1,0]
	s_nop 0
	v_mul_f32_e32 v48, v48, v49
	v_rcp_f32_e32 v48, v48
	v_and_b32_e32 v49, 0xffff0000, v80
	v_mul_f32_e32 v49, v49, v50
	v_mul_f32_e32 v48, v42, v48
	v_mul_f32_e32 v42, 0xbfb8aa3b, v43
	v_mul_f32_e32 v43, 0xbfb8aa3b, v50
	v_exp_f32_e32 v42, v42
	v_exp_f32_e32 v43, v43
	v_lshlrev_b32_e32 v50, 16, v81
	v_pk_add_f32 v[42:43], v[42:43], 1.0 op_sel_hi:[1,0]
	s_nop 0
	v_mul_f32_e32 v42, v42, v43
	v_rcp_f32_e32 v42, v42
	s_nop 0
	v_mul_f32_e32 v42, v49, v42
	v_lshlrev_b32_e32 v49, 16, v77
	v_cvt_pk_bf16_f32 v48, v48, v42
	v_mul_f32_e32 v42, 0xbfb8aa3b, v44
	v_mul_f32_e32 v43, 0xbfb8aa3b, v49
	v_exp_f32_e32 v42, v42
	v_exp_f32_e32 v43, v43
	v_mul_f32_e32 v44, v50, v49
	v_and_b32_e32 v50, 0xffff0000, v77
	v_and_b32_e32 v49, 0xffff0000, v81
	v_pk_add_f32 v[42:43], v[42:43], 1.0 op_sel_hi:[1,0]
	s_nop 0
	v_mul_f32_e32 v42, v42, v43
	v_rcp_f32_e32 v42, v42
	v_mul_f32_e32 v43, 0xbfb8aa3b, v50
	v_exp_f32_e32 v43, v43
	v_mul_f32_e32 v44, v44, v42
	v_mul_f32_e32 v42, 0xbfb8aa3b, v45
	v_exp_f32_e32 v42, v42
	v_mul_f32_e32 v45, v49, v50
	v_pk_add_f32 v[42:43], v[42:43], 1.0 op_sel_hi:[1,0]
	s_nop 0
	v_mul_f32_e32 v42, v42, v43
	v_rcp_f32_e32 v42, v42
	s_nop 0
	v_mul_f32_e32 v42, v45, v42
	v_cvt_pk_bf16_f32 v49, v44, v42
	v_lshl_add_u64 v[42:43], s[46:47], 0, v[150:151]
	global_store_dwordx4 v[148:149], v[46:49], off offset:256
	v_lshl_add_u64 v[42:43], v[42:43], 0, v[116:117]
	global_load_dwordx4 v[66:69], v[42:43], off
	v_lshl_add_u64 v[46:47], v[114:115], 0, v[168:169]
	global_load_dwordx4 v[46:49], v[46:47], off
	v_lshl_add_u64 v[42:43], v[114:115], 0, v[152:153]
	global_load_dwordx4 v[70:73], v[42:43], off
	v_lshl_add_u64 v[42:43], s[46:47], 0, v[156:157]
	v_lshl_add_u64 v[42:43], v[42:43], 0, v[116:117]
	global_load_dwordx4 v[58:61], v[42:43], off
	v_lshl_add_u64 v[42:43], v[114:115], 0, v[158:159]
	global_load_dwordx4 v[62:65], v[42:43], off
	v_lshl_add_u64 v[42:43], s[46:47], 0, v[160:161]
	v_lshl_add_u64 v[42:43], v[42:43], 0, v[116:117]
	global_load_dwordx4 v[50:53], v[42:43], off
	v_lshl_add_u64 v[42:43], v[114:115], 0, v[164:165]
	global_load_dwordx4 v[54:57], v[42:43], off
	v_lshl_add_u64 v[42:43], s[46:47], 0, v[166:167]
	v_lshl_add_u64 v[42:43], v[42:43], 0, v[116:117]
	global_load_dwordx4 v[42:45], v[42:43], off
	s_waitcnt vmcnt(0)
; __device__ __forceinline__ unsigned cvt_pk_bf16(float lo, float hi) { unsigned r; asm volatile("v_cvt_pk_bf16_f32 %0, %1, %2" : "=v"(r) : "v"(lo), "v"(hi)); return r; }
; __device__ __forceinline__ float bf_lo(unsigned w) { return __uint_as_float(w << 16); }
; __device__ __forceinline__ float bf_hi(unsigned w) { return __uint_as_float(w & 0xffff0000u); }
;     __device__ __forceinline__ void operator()(const f32x4 (&acc)[2][2][4][2], const Unit& u, int wr, int wc, int fr, int fq, const Pre&) const {
;     ...
;                 for (int m = 0; m < 4; ++m) { const int r = row0 + ai * HALF + m * 16;
;                     const u32x4 zw = zv[m], gw = gv[m];
;                     const f32x4 a0 = acc[ai][bj][m][0] + bs[bj][0], a1 = acc[ai][bj][m][1] + bs[bj][1];
;                     u32x4 w;
;                     w.x = cvt_pk_bf16(glu_gate_f(bf_lo(gw.x), a0[0], bf_lo(zw.x)), glu_gate_f(bf_hi(gw.x), a0[1], bf_hi(zw.x)));
;                     w.y = cvt_pk_bf16(glu_gate_f(bf_lo(gw.y), a0[2], bf_lo(zw.y)), glu_gate_f(bf_hi(gw.y), a0[3], bf_hi(zw.y)));
;                     w.z = cvt_pk_bf16(glu_gate_f(bf_lo(gw.z), a1[0], bf_lo(zw.z)), glu_gate_f(bf_hi(gw.z), a1[1], bf_hi(zw.z)));
;                     w.w = cvt_pk_bf16(glu_gate_f(bf_lo(gw.w), a1[2], bf_lo(zw.w)), glu_gate_f(bf_hi(gw.w), a1[3], bf_hi(zw.w)));
;                     *(u32x4*)(O + (size_t)r * DE + c) = w; } } }
	v_lshlrev_b32_e32 v76, 16, v66
	v_mul_f32_e32 v38, 0xbfb8aa3b, v76
	v_exp_f32_e32 v75, v38
	v_and_b32_e32 v66, 0xffff0000, v66
	v_lshlrev_b32_e32 v77, 16, v70
	v_mul_f32_e32 v38, v77, v76
	v_pk_add_f32 v[74:75], v[74:75], 1.0 op_sel_hi:[1,0]
	v_and_b32_e32 v70, 0xffff0000, v70
	v_mul_f32_e32 v74, v74, v75
	v_rcp_f32_e32 v74, v74
	s_nop 0
	v_mul_f32_e32 v74, v38, v74
	v_mul_f32_e32 v38, 0xbfb8aa3b, v39
	v_mul_f32_e32 v39, 0xbfb8aa3b, v66
	v_exp_f32_e32 v38, v38
	v_exp_f32_e32 v39, v39
	v_mul_f32_e32 v66, v70, v66
	v_pk_add_f32 v[38:39], v[38:39], 1.0 op_sel_hi:[1,0]
	s_nop 0
	v_mul_f32_e32 v38, v38, v39
	v_rcp_f32_e32 v38, v38
	v_lshlrev_b32_e32 v39, 16, v67
	v_and_b32_e32 v67, 0xffff0000, v67
	v_mul_f32_e32 v38, v66, v38
	v_cvt_pk_bf16_f32 v38, v74, v38
	v_exp_f32_e32 v74, v40
	v_mul_f32_e32 v40, 0xbfb8aa3b, v39
	v_exp_f32_e32 v75, v40
	v_lshlrev_b32_e32 v66, 16, v71
	v_mul_f32_e32 v39, v66, v39
	v_and_b32_e32 v66, 0xffff0000, v71
	v_pk_add_f32 v[74:75], v[74:75], 1.0 op_sel_hi:[1,0]
	v_mul_f32_e32 v66, v66, v67
	v_mul_f32_e32 v40, v74, v75
	v_rcp_f32_e32 v40, v40
	s_nop 0
	v_mul_f32_e32 v39, v39, v40
	v_mul_f32_e32 v40, 0xbfb8aa3b, v41
	v_mul_f32_e32 v41, 0xbfb8aa3b, v67
	v_exp_f32_e32 v40, v40
	v_exp_f32_e32 v41, v41
	v_lshlrev_b32_e32 v67, 16, v72
	v_pk_add_f32 v[40:41], v[40:41], 1.0 op_sel_hi:[1,0]
	s_nop 0
	v_mul_f32_e32 v40, v40, v41
	v_rcp_f32_e32 v40, v40
	s_nop 0
	v_mul_f32_e32 v40, v66, v40
	v_lshlrev_b32_e32 v66, 16, v68
	v_cvt_pk_bf16_f32 v39, v39, v40
	v_exp_f32_e32 v40, v34
	v_mul_f32_e32 v34, 0xbfb8aa3b, v66
	v_exp_f32_e32 v41, v34
	v_mul_f32_e32 v34, v67, v66
	v_and_b32_e32 v66, 0xffff0000, v68
	v_pk_add_f32 v[40:41], v[40:41], 1.0 op_sel_hi:[1,0]
	s_nop 0
	v_mul_f32_e32 v40, v40, v41
	v_rcp_f32_e32 v40, v40
	v_and_b32_e32 v41, 0xffff0000, v72
	v_mul_f32_e32 v41, v41, v66
	v_mul_f32_e32 v40, v34, v40
	v_mul_f32_e32 v34, 0xbfb8aa3b, v35
	v_mul_f32_e32 v35, 0xbfb8aa3b, v66
	v_exp_f32_e32 v34, v34
	v_exp_f32_e32 v35, v35
	v_lshlrev_b32_e32 v66, 16, v73
	v_pk_add_f32 v[34:35], v[34:35], 1.0 op_sel_hi:[1,0]
	s_nop 0
	v_mul_f32_e32 v34, v34, v35
	v_rcp_f32_e32 v34, v34
	s_nop 0
	v_mul_f32_e32 v34, v41, v34
	v_lshlrev_b32_e32 v41, 16, v69
	v_cvt_pk_bf16_f32 v40, v40, v34
	v_mul_f32_e32 v34, 0xbfb8aa3b, v36
	v_mul_f32_e32 v35, 0xbfb8aa3b, v41
	v_exp_f32_e32 v34, v34
	v_exp_f32_e32 v35, v35
	v_mul_f32_e32 v36, v66, v41
	v_and_b32_e32 v66, 0xffff0000, v69
	v_and_b32_e32 v41, 0xffff0000, v73
	v_pk_add_f32 v[34:35], v[34:35], 1.0 op_sel_hi:[1,0]
	s_nop 0
	v_mul_f32_e32 v34, v34, v35
	v_rcp_f32_e32 v34, v34
	v_mul_f32_e32 v35, 0xbfb8aa3b, v66
	v_exp_f32_e32 v35, v35
	v_mul_f32_e32 v36, v36, v34
	v_mul_f32_e32 v34, 0xbfb8aa3b, v37
	v_exp_f32_e32 v34, v34
	v_mul_f32_e32 v37, v41, v66
	v_pk_add_f32 v[34:35], v[34:35], 1.0 op_sel_hi:[1,0]
	s_nop 0
	v_mul_f32_e32 v34, v34, v35
	v_rcp_f32_e32 v34, v34
	s_nop 0
	v_mul_f32_e32 v34, v37, v34
	v_cvt_pk_bf16_f32 v41, v36, v34
	v_lshlrev_b32_e32 v36, 16, v58
	v_exp_f32_e32 v34, v22
	v_mul_f32_e32 v22, 0xbfb8aa3b, v36
	v_exp_f32_e32 v35, v22
	v_lshlrev_b32_e32 v37, 16, v62
	v_mul_f32_e32 v22, v37, v36
	v_and_b32_e32 v36, 0xffff0000, v58
	v_pk_add_f32 v[34:35], v[34:35], 1.0 op_sel_hi:[1,0]
	global_store_dwordx4 v[106:107], v[38:41], off offset:256
	v_mul_f32_e32 v34, v34, v35
	v_rcp_f32_e32 v34, v34
	v_and_b32_e32 v35, 0xffff0000, v62
	v_mul_f32_e32 v35, v35, v36
	v_mul_f32_e32 v34, v22, v34
	v_mul_f32_e32 v22, 0xbfb8aa3b, v23
	v_mul_f32_e32 v23, 0xbfb8aa3b, v36
	v_exp_f32_e32 v22, v22
	v_exp_f32_e32 v23, v23
	v_lshlrev_b32_e32 v36, 16, v63
	v_pk_add_f32 v[22:23], v[22:23], 1.0 op_sel_hi:[1,0]
	s_nop 0
	v_mul_f32_e32 v22, v22, v23
	v_rcp_f32_e32 v22, v22
	v_lshlrev_b32_e32 v23, 16, v59
	v_mul_f32_e32 v22, v35, v22
	v_cvt_pk_bf16_f32 v22, v34, v22
	v_exp_f32_e32 v34, v24
	v_mul_f32_e32 v24, 0xbfb8aa3b, v23
	v_exp_f32_e32 v35, v24
	v_mul_f32_e32 v23, v36, v23
	v_pk_add_f32 v[34:35], v[34:35], 1.0 op_sel_hi:[1,0]
	s_nop 0
	v_mul_f32_e32 v24, v34, v35
	v_rcp_f32_e32 v24, v24
	v_and_b32_e32 v35, 0xffff0000, v59
	v_and_b32_e32 v34, 0xffff0000, v63
	v_mul_f32_e32 v34, v34, v35
	v_mul_f32_e32 v23, v23, v24
	v_mul_f32_e32 v24, 0xbfb8aa3b, v25
	v_mul_f32_e32 v25, 0xbfb8aa3b, v35
	v_exp_f32_e32 v24, v24
	v_exp_f32_e32 v25, v25
	v_lshlrev_b32_e32 v35, 16, v64
	v_pk_add_f32 v[24:25], v[24:25], 1.0 op_sel_hi:[1,0]
	s_nop 0
	v_mul_f32_e32 v24, v24, v25
	v_rcp_f32_e32 v24, v24
	s_nop 0
	v_mul_f32_e32 v24, v34, v24
	v_lshlrev_b32_e32 v34, 16, v60
	v_cvt_pk_bf16_f32 v23, v23, v24
	v_exp_f32_e32 v24, v18
	v_mul_f32_e32 v18, 0xbfb8aa3b, v34
	v_exp_f32_e32 v25, v18
	v_mul_f32_e32 v18, v35, v34
	v_and_b32_e32 v34, 0xffff0000, v60
	v_pk_add_f32 v[24:25], v[24:25], 1.0 op_sel_hi:[1,0]
	s_nop 0
	v_mul_f32_e32 v24, v24, v25
	v_rcp_f32_e32 v24, v24
	v_and_b32_e32 v25, 0xffff0000, v64
	v_mul_f32_e32 v25, v25, v34
	v_mul_f32_e32 v24, v18, v24
	v_mul_f32_e32 v18, 0xbfb8aa3b, v19
	v_mul_f32_e32 v19, 0xbfb8aa3b, v34
	v_exp_f32_e32 v18, v18
	v_exp_f32_e32 v19, v19
	v_lshlrev_b32_e32 v34, 16, v65
	v_pk_add_f32 v[18:19], v[18:19], 1.0 op_sel_hi:[1,0]
	s_nop 0
	v_mul_f32_e32 v18, v18, v19
	v_rcp_f32_e32 v18, v18
	s_nop 0
	v_mul_f32_e32 v18, v25, v18
	v_lshlrev_b32_e32 v25, 16, v61
	v_cvt_pk_bf16_f32 v24, v24, v18
	v_mul_f32_e32 v18, 0xbfb8aa3b, v20
	v_mul_f32_e32 v19, 0xbfb8aa3b, v25
	v_exp_f32_e32 v18, v18
	v_exp_f32_e32 v19, v19
	v_mul_f32_e32 v20, v34, v25
	v_and_b32_e32 v34, 0xffff0000, v61
	v_and_b32_e32 v25, 0xffff0000, v65
	v_pk_add_f32 v[18:19], v[18:19], 1.0 op_sel_hi:[1,0]
	s_nop 0
	v_mul_f32_e32 v18, v18, v19
	v_rcp_f32_e32 v18, v18
	v_mul_f32_e32 v19, 0xbfb8aa3b, v34
	v_exp_f32_e32 v19, v19
	v_mul_f32_e32 v20, v20, v18
; __device__ __forceinline__ unsigned cvt_pk_bf16(float lo, float hi) { unsigned r; asm volatile("v_cvt_pk_bf16_f32 %0, %1, %2" : "=v"(r) : "v"(lo), "v"(hi)); return r; }
; __device__ __forceinline__ float bf_lo(unsigned w) { return __uint_as_float(w << 16); }
; __device__ __forceinline__ float bf_hi(unsigned w) { return __uint_as_float(w & 0xffff0000u); }
; #define PG8_WAIT_V(n) asm volatile("s_waitcnt vmcnt(" #n ")" ::: "memory")
; #define PG8_BAR __builtin_amdgcn_s_barrier()
; template <class Epi>
; __device__ __forceinline__ void gemm_phase(LAS unsigned char* lds, const Gemm g, const StaticOrder& S, const Epi& E) {
;     ...
;         if (!has_next) break;
; #pragma unroll
;         for (int a = 0; a < 2; ++a)
; #pragma unroll
;             for (int b = 0; b < 2; ++b)
; #pragma unroll
;                 for (int m = 0; m < 4; ++m)
; #pragma unroll
;                     for (int n = 0; n < 2; ++n) acc[a][b][m][n] = (f32x4){0.f, 0.f, 0.f, 0.f};
;         cur = nxt; cA = nA; cB = nB; ++ui;
;         pre = E.pre(cur, wr, fr);
;     }
;     PG8_WAIT_V(0);
;     if (wr == 0) PG8_BAR;
;     __device__ __forceinline__ void operator()(const f32x4 (&acc)[2][2][4][2], const Unit& u, int wr, int wc, int fr, int fq, const Pre&) const {
;     ...
;                     w.x = cvt_pk_bf16(glu_gate_f(bf_lo(gw.x), a0[0], bf_lo(zw.x)), glu_gate_f(bf_hi(gw.x), a0[1], bf_hi(zw.x)));
;                     w.y = cvt_pk_bf16(glu_gate_f(bf_lo(gw.y), a0[2], bf_lo(zw.y)), glu_gate_f(bf_hi(gw.y), a0[3], bf_hi(zw.y)));
;                     w.z = cvt_pk_bf16(glu_gate_f(bf_lo(gw.z), a1[0], bf_lo(zw.z)), glu_gate_f(bf_hi(gw.z), a1[1], bf_hi(zw.z)));
;                     w.w = cvt_pk_bf16(glu_gate_f(bf_lo(gw.w), a1[2], bf_lo(zw.w)), glu_gate_f(bf_hi(gw.w), a1[3], bf_hi(zw.w)));
;                     *(u32x4*)(O + (size_t)r * DE + c) = w; } } }
	v_mul_f32_e32 v18, 0xbfb8aa3b, v21
	v_exp_f32_e32 v18, v18
	v_mul_f32_e32 v21, v25, v34
	v_pk_add_f32 v[18:19], v[18:19], 1.0 op_sel_hi:[1,0]
	s_nop 0
	v_mul_f32_e32 v18, v18, v19
	v_rcp_f32_e32 v18, v18
	s_nop 0
	v_mul_f32_e32 v18, v21, v18
	v_cvt_pk_bf16_f32 v25, v20, v18
	v_lshlrev_b32_e32 v20, 16, v50
	v_exp_f32_e32 v18, v14
	v_mul_f32_e32 v14, 0xbfb8aa3b, v20
	v_exp_f32_e32 v19, v14
	v_lshlrev_b32_e32 v21, 16, v54
	v_mul_f32_e32 v14, v21, v20
	v_and_b32_e32 v20, 0xffff0000, v50
	v_pk_add_f32 v[18:19], v[18:19], 1.0 op_sel_hi:[1,0]
	global_store_dwordx4 v[108:109], v[22:25], off offset:256
	v_mul_f32_e32 v18, v18, v19
	v_rcp_f32_e32 v18, v18
	v_and_b32_e32 v19, 0xffff0000, v54
	v_mul_f32_e32 v19, v19, v20
	v_mul_f32_e32 v18, v14, v18
	v_mul_f32_e32 v14, 0xbfb8aa3b, v15
	v_mul_f32_e32 v15, 0xbfb8aa3b, v20
	v_exp_f32_e32 v14, v14
	v_exp_f32_e32 v15, v15
	v_lshlrev_b32_e32 v20, 16, v55
	v_pk_add_f32 v[14:15], v[14:15], 1.0 op_sel_hi:[1,0]
	s_nop 0
	v_mul_f32_e32 v14, v14, v15
	v_rcp_f32_e32 v14, v14
	v_lshlrev_b32_e32 v15, 16, v51
	v_mul_f32_e32 v14, v19, v14
	v_cvt_pk_bf16_f32 v14, v18, v14
	v_exp_f32_e32 v18, v16
	v_mul_f32_e32 v16, 0xbfb8aa3b, v15
	v_exp_f32_e32 v19, v16
	v_mul_f32_e32 v15, v20, v15
	v_pk_add_f32 v[18:19], v[18:19], 1.0 op_sel_hi:[1,0]
	s_nop 0
	v_mul_f32_e32 v16, v18, v19
	v_rcp_f32_e32 v16, v16
	v_and_b32_e32 v19, 0xffff0000, v51
	v_and_b32_e32 v18, 0xffff0000, v55
	v_mul_f32_e32 v18, v18, v19
	v_mul_f32_e32 v15, v15, v16
	v_mul_f32_e32 v16, 0xbfb8aa3b, v17
	v_mul_f32_e32 v17, 0xbfb8aa3b, v19
	v_exp_f32_e32 v16, v16
	v_exp_f32_e32 v17, v17
	v_lshlrev_b32_e32 v19, 16, v56
	v_pk_add_f32 v[16:17], v[16:17], 1.0 op_sel_hi:[1,0]
	s_nop 0
	v_mul_f32_e32 v16, v16, v17
	v_rcp_f32_e32 v16, v16
	s_nop 0
	v_mul_f32_e32 v16, v18, v16
	v_lshlrev_b32_e32 v18, 16, v52
	v_cvt_pk_bf16_f32 v15, v15, v16
	v_exp_f32_e32 v16, v10
	v_mul_f32_e32 v10, 0xbfb8aa3b, v18
	v_exp_f32_e32 v17, v10
	v_mul_f32_e32 v10, v19, v18
	v_and_b32_e32 v18, 0xffff0000, v52
	v_pk_add_f32 v[16:17], v[16:17], 1.0 op_sel_hi:[1,0]
	s_nop 0
	v_mul_f32_e32 v16, v16, v17
	v_rcp_f32_e32 v16, v16
	v_and_b32_e32 v17, 0xffff0000, v56
	v_mul_f32_e32 v17, v17, v18
	v_mul_f32_e32 v16, v10, v16
	v_mul_f32_e32 v10, 0xbfb8aa3b, v11
	v_mul_f32_e32 v11, 0xbfb8aa3b, v18
	v_exp_f32_e32 v10, v10
	v_exp_f32_e32 v11, v11
	v_lshlrev_b32_e32 v18, 16, v57
	v_pk_add_f32 v[10:11], v[10:11], 1.0 op_sel_hi:[1,0]
	s_nop 0
	v_mul_f32_e32 v10, v10, v11
	v_rcp_f32_e32 v10, v10
	s_nop 0
	v_mul_f32_e32 v10, v17, v10
	v_lshlrev_b32_e32 v17, 16, v53
	v_cvt_pk_bf16_f32 v16, v16, v10
	v_mul_f32_e32 v10, 0xbfb8aa3b, v12
	v_mul_f32_e32 v11, 0xbfb8aa3b, v17
	v_exp_f32_e32 v10, v10
	v_exp_f32_e32 v11, v11
	v_mul_f32_e32 v12, v18, v17
	v_and_b32_e32 v18, 0xffff0000, v53
	v_and_b32_e32 v17, 0xffff0000, v57
	v_pk_add_f32 v[10:11], v[10:11], 1.0 op_sel_hi:[1,0]
	s_nop 0
	v_mul_f32_e32 v10, v10, v11
	v_rcp_f32_e32 v10, v10
	v_mul_f32_e32 v11, 0xbfb8aa3b, v18
	v_exp_f32_e32 v11, v11
	v_mul_f32_e32 v12, v12, v10
	v_mul_f32_e32 v10, 0xbfb8aa3b, v13
	v_exp_f32_e32 v10, v10
	v_mul_f32_e32 v13, v17, v18
	v_pk_add_f32 v[10:11], v[10:11], 1.0 op_sel_hi:[1,0]
	s_nop 0
	v_mul_f32_e32 v10, v10, v11
	v_rcp_f32_e32 v10, v10
	s_nop 0
	v_mul_f32_e32 v10, v13, v10
	v_cvt_pk_bf16_f32 v17, v12, v10
	v_lshlrev_b32_e32 v12, 16, v42
	v_exp_f32_e32 v10, v6
	v_mul_f32_e32 v6, 0xbfb8aa3b, v12
	v_exp_f32_e32 v11, v6
	v_lshlrev_b32_e32 v13, 16, v46
	v_mul_f32_e32 v6, v13, v12
	v_and_b32_e32 v12, 0xffff0000, v42
	v_pk_add_f32 v[10:11], v[10:11], 1.0 op_sel_hi:[1,0]
	global_store_dwordx4 v[110:111], v[14:17], off offset:256
	v_mul_f32_e32 v10, v10, v11
	v_rcp_f32_e32 v10, v10
	v_and_b32_e32 v11, 0xffff0000, v46
	v_mul_f32_e32 v11, v11, v12
	v_mul_f32_e32 v10, v6, v10
	v_mul_f32_e32 v6, 0xbfb8aa3b, v7
	v_mul_f32_e32 v7, 0xbfb8aa3b, v12
	v_exp_f32_e32 v6, v6
	v_exp_f32_e32 v7, v7
	v_lshlrev_b32_e32 v12, 16, v47
	v_pk_add_f32 v[6:7], v[6:7], 1.0 op_sel_hi:[1,0]
	s_nop 0
	v_mul_f32_e32 v6, v6, v7
	v_rcp_f32_e32 v6, v6
	v_lshlrev_b32_e32 v7, 16, v43
	v_mul_f32_e32 v6, v11, v6
	v_cvt_pk_bf16_f32 v6, v10, v6
	v_exp_f32_e32 v10, v8
	v_mul_f32_e32 v8, 0xbfb8aa3b, v7
	v_exp_f32_e32 v11, v8
	v_mul_f32_e32 v7, v12, v7
	v_pk_add_f32 v[10:11], v[10:11], 1.0 op_sel_hi:[1,0]
	s_nop 0
	v_mul_f32_e32 v8, v10, v11
	v_rcp_f32_e32 v8, v8
	v_and_b32_e32 v11, 0xffff0000, v43
	v_and_b32_e32 v10, 0xffff0000, v47
	v_mul_f32_e32 v10, v10, v11
	v_mul_f32_e32 v7, v7, v8
	v_mul_f32_e32 v8, 0xbfb8aa3b, v9
	v_mul_f32_e32 v9, 0xbfb8aa3b, v11
	v_exp_f32_e32 v8, v8
	v_exp_f32_e32 v9, v9
	v_lshlrev_b32_e32 v11, 16, v48
	v_pk_add_f32 v[8:9], v[8:9], 1.0 op_sel_hi:[1,0]
	s_nop 0
	v_mul_f32_e32 v8, v8, v9
	v_rcp_f32_e32 v8, v8
	s_nop 0
	v_mul_f32_e32 v8, v10, v8
	v_lshlrev_b32_e32 v10, 16, v44
	v_cvt_pk_bf16_f32 v7, v7, v8
	v_exp_f32_e32 v8, v2
	v_mul_f32_e32 v2, 0xbfb8aa3b, v10
	v_exp_f32_e32 v9, v2
	v_mul_f32_e32 v2, v11, v10
	v_and_b32_e32 v10, 0xffff0000, v44
	v_pk_add_f32 v[8:9], v[8:9], 1.0 op_sel_hi:[1,0]
	s_nop 0
	v_mul_f32_e32 v8, v8, v9
	v_rcp_f32_e32 v8, v8
	v_and_b32_e32 v9, 0xffff0000, v48
	v_mul_f32_e32 v9, v9, v10
	v_mul_f32_e32 v8, v2, v8
	v_mul_f32_e32 v2, 0xbfb8aa3b, v3
	v_mul_f32_e32 v3, 0xbfb8aa3b, v10
	v_exp_f32_e32 v2, v2
	v_exp_f32_e32 v3, v3
	v_lshlrev_b32_e32 v10, 16, v49
	v_pk_add_f32 v[2:3], v[2:3], 1.0 op_sel_hi:[1,0]
	s_nop 0
	v_mul_f32_e32 v2, v2, v3
	v_rcp_f32_e32 v2, v2
	s_nop 0
	v_mul_f32_e32 v2, v9, v2
	v_lshlrev_b32_e32 v9, 16, v45
	v_cvt_pk_bf16_f32 v8, v8, v2
	v_mul_f32_e32 v2, 0xbfb8aa3b, v4
	v_mul_f32_e32 v3, 0xbfb8aa3b, v9
	v_exp_f32_e32 v2, v2
	v_exp_f32_e32 v3, v3
	v_mul_f32_e32 v4, v10, v9
	v_and_b32_e32 v10, 0xffff0000, v45
	v_and_b32_e32 v9, 0xffff0000, v49
	v_pk_add_f32 v[2:3], v[2:3], 1.0 op_sel_hi:[1,0]
	s_nop 0
	v_mul_f32_e32 v2, v2, v3
	v_rcp_f32_e32 v2, v2
	v_mul_f32_e32 v3, 0xbfb8aa3b, v10
	v_exp_f32_e32 v3, v3
	v_mul_f32_e32 v4, v4, v2
	v_mul_f32_e32 v2, 0xbfb8aa3b, v5
	v_exp_f32_e32 v2, v2
	v_mul_f32_e32 v5, v9, v10
	v_pk_add_f32 v[2:3], v[2:3], 1.0 op_sel_hi:[1,0]
	s_nop 0
	v_mul_f32_e32 v2, v2, v3
	v_rcp_f32_e32 v2, v2
	s_nop 0
	v_mul_f32_e32 v2, v5, v2
	v_cvt_pk_bf16_f32 v9, v4, v2
	global_store_dwordx4 v[112:113], v[6:9], off offset:256
	s_cbranch_vccz .LBB0_789
	s_waitcnt vmcnt(0)
	v_readlane_b32 s36, v254, 56
	s_cmpk_gt_u32 s18, 0xff
	v_readlane_b32 s37, v254, 57
	s_cbranch_scc1 .LBB0_800
	s_barrier
